# baseline (speedup 1.0000x reference)
; #define WAIT_V(n) asm volatile("s_waitcnt vmcnt(" #n ")" ::: "memory")
; #define WAIT_L(n) asm volatile("s_waitcnt lgkmcnt(" #n ")" ::: "memory")
; #define BAR __builtin_amdgcn_s_barrier()
; #define SCHED __builtin_amdgcn_sched_barrier(0)
; #define STAGE(P, BASE, br, kt) do { const char* _g = (const char*)((BASE) + (size_t)(br) * GK + (kt) * BK); \
;     __builtin_amdgcn_global_load_lds((const unsigned*)(_g + voff0), (unsigned*)((char*)(P) + tx * 16), 16, 0, 0); \
;     __builtin_amdgcn_global_load_lds((const unsigned*)(_g + voff1), (unsigned*)((char*)(P) + tx * 16 + 8192), 16, 0, 0); } while (0)
; #define LDA(dst, b, h) _Pragma("unroll") for (int m = 0; m < 4; ++m) _Pragma("unroll") for (int k = 0; k < 2; ++k) \
;     dst[m][k] = *reinterpret_cast<const bf16x8*>((char*)shm + abase + (((b) * 2 + (h)) * 16384 + (m * 2 + k) * 1024))
; #define LDB(dst, b, h) _Pragma("unroll") for (int n = 0; n < 2; ++n) _Pragma("unroll") for (int k = 0; k < 2; ++k) \
;     dst[n][k] = *reinterpret_cast<const bf16x8*>((char*)shm + bbase + (((b) * 2 + (h)) * 16384 + (n * 2 + k) * 1024))
; template <bool SWAP>
; __device__ __forceinline__ void gemm_main(const u16* __restrict__ A, const u16* __restrict__ Bt, int brow, int bcol,
;                                           u16* shm, f32x4 (&acc)[2][2][4][2]) {
;     ...
;     LDB(B0, 0, 0); SCHED; LDA(At, 0, 0); STAGE(SA(1, 1), A, brow + HALF, t + 1);
;     WAIT_L(8); BAR; WAIT_L(0); MMA(0, 0, At, B0); BAR; SCHED;
;     LDB(B1, 0, 1); STAGE(SB(0, 0), Bt, bcol, t + 2);
;     BAR; WAIT_L(0); MMA(0, 1, At, B1); BAR;
;     LDA(At, 0, 1); STAGE(SA(0, 0), A, brow, t + 2);
;     BAR; WAIT_L(0); MMA(1, 0, At, B0); BAR; SCHED;
;     STAGE(SB(0, 1), Bt, bcol + HALF, t + 2);
;     WAIT_V(6); BAR; MMA(1, 1, At, B1); BAR;
.LBB0_84:
	ds_read_b128 v[176:179], v128 offset:1024
	ds_read_b128 v[184:187], v128 offset:3072
	ds_read_b128 v[192:195], v128 offset:5120
	ds_read_b128 v[200:203], v128 offset:7168
	v_add_u32_e32 v211, 0, v146
	v_add_u32_e32 v153, 0xc000, v211
	s_add_u32 m0, s29, 0xc000
	s_nop 0
	s_add_u32 vcc_lo, s26, s6
	s_addc_u32 vcc_hi, s27, s7
	global_load_lds_dwordx4 v134, vcc
	v_add_u32_e32 v154, 0xe000, v211
	v_lshl_add_u64 v[224:225], s[26:27], 0, v[136:137]
	s_add_u32 m0, s29, 0xe000
	s_nop 0
	global_load_lds_dwordx4 v136, vcc
	s_waitcnt lgkmcnt(8)
	s_waitcnt vmcnt(8)
	s_setprio 1
	s_barrier
	s_waitcnt lgkmcnt(0)
	v_mfma_f32_16x16x32_bf16 v[124:127], v[172:175], v[156:159], v[124:127]
	v_mfma_f32_16x16x32_bf16 v[120:123], v[172:175], v[164:167], v[120:123]
	v_mfma_f32_16x16x32_bf16 v[116:119], v[180:183], v[156:159], v[116:119]
	v_mfma_f32_16x16x32_bf16 v[112:115], v[180:183], v[164:167], v[112:115]
	v_mfma_f32_16x16x32_bf16 v[108:111], v[188:191], v[156:159], v[108:111]
	v_mfma_f32_16x16x32_bf16 v[104:107], v[188:191], v[164:167], v[104:107]
	v_mfma_f32_16x16x32_bf16 v[100:103], v[196:199], v[156:159], v[100:103]
	v_mfma_f32_16x16x32_bf16 v[96:99], v[196:199], v[164:167], v[96:99]
	v_mfma_f32_16x16x32_bf16 v[124:127], v[176:179], v[160:163], v[124:127]
	v_mfma_f32_16x16x32_bf16 v[120:123], v[176:179], v[168:171], v[120:123]
	v_mfma_f32_16x16x32_bf16 v[116:119], v[184:187], v[160:163], v[116:119]
	v_mfma_f32_16x16x32_bf16 v[112:115], v[184:187], v[168:171], v[112:115]
	v_mfma_f32_16x16x32_bf16 v[108:111], v[192:195], v[160:163], v[108:111]
	v_mfma_f32_16x16x32_bf16 v[104:107], v[192:195], v[168:171], v[104:107]
	v_mfma_f32_16x16x32_bf16 v[100:103], v[200:203], v[160:163], v[100:103]
	v_mfma_f32_16x16x32_bf16 v[96:99], v[200:203], v[168:171], v[96:99]
	s_barrier
	s_setprio 0
	ds_read_b128 v[204:207], v145 offset:16384
	ds_read_b128 v[212:215], v145 offset:17408
	ds_read_b128 v[216:219], v145 offset:18432
	ds_read_b128 v[220:223], v145 offset:19456
	v_lshl_add_u64 v[226:227], s[26:27], 0, v[130:131]
	s_add_u32 m0, s29, s44
	s_nop 0
	s_add_u32 vcc_lo, s26, s8
	s_addc_u32 vcc_hi, s27, s9
	global_load_lds_dwordx4 v130, vcc
	v_lshl_add_u64 v[228:229], s[26:27], 0, v[132:133]
	s_add_u32 m0, s29, s44
	s_add_u32 m0, m0, 0x2000
	s_nop 0
	global_load_lds_dwordx4 v132, vcc
	s_setprio 1
	s_barrier
	s_waitcnt lgkmcnt(0)
	v_mfma_f32_16x16x32_bf16 v[92:95], v[172:175], v[204:207], v[92:95]
	v_mfma_f32_16x16x32_bf16 v[88:91], v[172:175], v[216:219], v[88:91]
	v_mfma_f32_16x16x32_bf16 v[84:87], v[180:183], v[204:207], v[84:87]
	v_mfma_f32_16x16x32_bf16 v[80:83], v[180:183], v[216:219], v[80:83]
	v_mfma_f32_16x16x32_bf16 v[76:79], v[188:191], v[204:207], v[76:79]
	v_mfma_f32_16x16x32_bf16 v[72:75], v[188:191], v[216:219], v[72:75]
	v_mfma_f32_16x16x32_bf16 v[68:71], v[196:199], v[204:207], v[68:71]
	v_mfma_f32_16x16x32_bf16 v[64:67], v[196:199], v[216:219], v[64:67]
	v_mfma_f32_16x16x32_bf16 v[92:95], v[176:179], v[212:215], v[92:95]
	ds_read_b128 v[172:175], v128 offset:16384
	v_mfma_f32_16x16x32_bf16 v[88:91], v[176:179], v[220:223], v[88:91]
	v_mfma_f32_16x16x32_bf16 v[84:87], v[184:187], v[212:215], v[84:87]
	ds_read_b128 v[180:183], v128 offset:18432
	v_mfma_f32_16x16x32_bf16 v[80:83], v[184:187], v[220:223], v[80:83]
	v_mfma_f32_16x16x32_bf16 v[76:79], v[192:195], v[212:215], v[76:79]
	ds_read_b128 v[188:191], v128 offset:20480
	v_mfma_f32_16x16x32_bf16 v[72:75], v[192:195], v[220:223], v[72:75]
	v_mfma_f32_16x16x32_bf16 v[68:71], v[200:203], v[212:215], v[68:71]
	ds_read_b128 v[196:199], v128 offset:22528
	v_mfma_f32_16x16x32_bf16 v[64:67], v[200:203], v[220:223], v[64:67]
	s_barrier
	s_setprio 0
	ds_read_b128 v[176:179], v128 offset:17408
	ds_read_b128 v[184:187], v128 offset:19456
	ds_read_b128 v[192:195], v128 offset:21504
	ds_read_b128 v[200:203], v128 offset:23552
	s_add_u32 m0, s29, 0x0
	s_nop 0
	s_add_u32 vcc_lo, s26, s10
	s_addc_u32 vcc_hi, s27, s11
	global_load_lds_dwordx4 v134, vcc
	s_add_u32 m0, s29, 0x2000
	s_nop 0
	global_load_lds_dwordx4 v136, vcc
	s_waitcnt vmcnt(8)
	s_setprio 1
	s_barrier
	s_waitcnt lgkmcnt(0)
	v_mfma_f32_16x16x32_bf16 v[60:63], v[172:175], v[156:159], v[60:63]
	v_mfma_f32_16x16x32_bf16 v[56:59], v[172:175], v[164:167], v[56:59]
	v_mfma_f32_16x16x32_bf16 v[52:55], v[180:183], v[156:159], v[52:55]
	v_mfma_f32_16x16x32_bf16 v[48:51], v[180:183], v[164:167], v[48:51]
	v_mfma_f32_16x16x32_bf16 v[44:47], v[188:191], v[156:159], v[44:47]
	v_mfma_f32_16x16x32_bf16 v[40:43], v[188:191], v[164:167], v[40:43]
	v_mfma_f32_16x16x32_bf16 v[36:39], v[196:199], v[156:159], v[36:39]
	v_mfma_f32_16x16x32_bf16 v[32:35], v[196:199], v[164:167], v[32:35]
	v_mfma_f32_16x16x32_bf16 v[60:63], v[176:179], v[160:163], v[60:63]
	v_mfma_f32_16x16x32_bf16 v[56:59], v[176:179], v[168:171], v[56:59]
	v_mfma_f32_16x16x32_bf16 v[52:55], v[184:187], v[160:163], v[52:55]
	v_mfma_f32_16x16x32_bf16 v[48:51], v[184:187], v[168:171], v[48:51]
	v_mfma_f32_16x16x32_bf16 v[44:47], v[192:195], v[160:163], v[44:47]
	v_mfma_f32_16x16x32_bf16 v[40:43], v[192:195], v[168:171], v[40:43]
	v_mfma_f32_16x16x32_bf16 v[36:39], v[200:203], v[160:163], v[36:39]
	v_mfma_f32_16x16x32_bf16 v[32:35], v[200:203], v[168:171], v[32:35]
	s_barrier
	s_setprio 0
	ds_read_b128 v[156:159], v145 offset:32768
	ds_read_b128 v[160:163], v145 offset:33792
	ds_read_b128 v[164:167], v145 offset:34816
	ds_read_b128 v[168:171], v145 offset:35840
	s_add_u32 m0, s29, s45
	s_nop 0
	s_add_u32 vcc_lo, s26, s12
	s_addc_u32 vcc_hi, s27, s13
	global_load_lds_dwordx4 v130, vcc
	s_add_u32 m0, s29, s45
	s_add_u32 m0, m0, 0x2000
	s_nop 0
	global_load_lds_dwordx4 v132, vcc
	s_setprio 1
	s_barrier
; #define WAIT_V(n) asm volatile("s_waitcnt vmcnt(" #n ")" ::: "memory")
; #define WAIT_L(n) asm volatile("s_waitcnt lgkmcnt(" #n ")" ::: "memory")
; #define BAR __builtin_amdgcn_s_barrier()
; #define SCHED __builtin_amdgcn_sched_barrier(0)
; #define STAGE(P, BASE, br, kt) do { const char* _g = (const char*)((BASE) + (size_t)(br) * GK + (kt) * BK); \
;     __builtin_amdgcn_global_load_lds((const unsigned*)(_g + voff0), (unsigned*)((char*)(P) + tx * 16), 16, 0, 0); \
;     __builtin_amdgcn_global_load_lds((const unsigned*)(_g + voff1), (unsigned*)((char*)(P) + tx * 16 + 8192), 16, 0, 0); } while (0)
; #define LDA(dst, b, h) _Pragma("unroll") for (int m = 0; m < 4; ++m) _Pragma("unroll") for (int k = 0; k < 2; ++k) \
;     dst[m][k] = *reinterpret_cast<const bf16x8*>((char*)shm + abase + (((b) * 2 + (h)) * 16384 + (m * 2 + k) * 1024))
; #define LDB(dst, b, h) _Pragma("unroll") for (int n = 0; n < 2; ++n) _Pragma("unroll") for (int k = 0; k < 2; ++k) \
;     dst[n][k] = *reinterpret_cast<const bf16x8*>((char*)shm + bbase + (((b) * 2 + (h)) * 16384 + (n * 2 + k) * 1024))
; template <bool SWAP>
; __device__ __forceinline__ void gemm_main(const u16* __restrict__ A, const u16* __restrict__ Bt, int brow, int bcol,
;                                           u16* shm, f32x4 (&acc)[2][2][4][2]) {
;     ...
;     STAGE(SB(0, 1), Bt, bcol + HALF, t + 2);
;     WAIT_V(6); BAR; MMA(1, 1, At, B1); BAR;
;     LDB(B0, 1, 0); SCHED; LDA(At, 1, 0); STAGE(SA(0, 1), A, brow + HALF, t + 2);
;     WAIT_L(8); BAR; WAIT_L(0); MMA(0, 0, At, B0); BAR; SCHED;
;     LDB(B1, 1, 1); STAGE(SB(1, 0), Bt, bcol, t + 3);
;     BAR; WAIT_L(0); MMA(0, 1, At, B1); BAR;
	v_mfma_f32_16x16x32_bf16 v[28:31], v[172:175], v[204:207], v[28:31]
	v_mfma_f32_16x16x32_bf16 v[24:27], v[172:175], v[216:219], v[24:27]
	v_mfma_f32_16x16x32_bf16 v[20:23], v[180:183], v[204:207], v[20:23]
	v_mfma_f32_16x16x32_bf16 v[16:19], v[180:183], v[216:219], v[16:19]
	v_mfma_f32_16x16x32_bf16 v[12:15], v[188:191], v[204:207], v[12:15]
	v_mfma_f32_16x16x32_bf16 v[8:11], v[188:191], v[216:219], v[8:11]
	v_mfma_f32_16x16x32_bf16 v[4:7], v[196:199], v[204:207], v[4:7]
	v_mfma_f32_16x16x32_bf16 v[0:3], v[196:199], v[216:219], v[0:3]
	v_mfma_f32_16x16x32_bf16 v[28:31], v[176:179], v[212:215], v[28:31]
	ds_read_b128 v[172:175], v128 offset:32768
	v_mfma_f32_16x16x32_bf16 v[24:27], v[176:179], v[220:223], v[24:27]
	v_mfma_f32_16x16x32_bf16 v[20:23], v[184:187], v[212:215], v[20:23]
	ds_read_b128 v[180:183], v128 offset:34816
	v_mfma_f32_16x16x32_bf16 v[16:19], v[184:187], v[220:223], v[16:19]
	v_mfma_f32_16x16x32_bf16 v[12:15], v[192:195], v[212:215], v[12:15]
	ds_read_b128 v[188:191], v128 offset:36864
	v_mfma_f32_16x16x32_bf16 v[8:11], v[192:195], v[220:223], v[8:11]
	v_mfma_f32_16x16x32_bf16 v[4:7], v[200:203], v[212:215], v[4:7]
	ds_read_b128 v[196:199], v128 offset:38912
	v_mfma_f32_16x16x32_bf16 v[0:3], v[200:203], v[220:223], v[0:3]
	s_barrier
	s_setprio 0
	ds_read_b128 v[176:179], v128 offset:33792
	ds_read_b128 v[184:187], v128 offset:35840
	ds_read_b128 v[192:195], v128 offset:37888
	ds_read_b128 v[200:203], v128 offset:39936
	s_add_u32 m0, s29, 0x4000
	s_nop 0
	s_add_u32 vcc_lo, s26, s14
	s_addc_u32 vcc_hi, s27, s15
	global_load_lds_dwordx4 v134, vcc
	s_add_u32 m0, s29, 0x6000
	s_nop 0
	global_load_lds_dwordx4 v136, vcc
	s_waitcnt lgkmcnt(8)
	s_waitcnt vmcnt(8)
	s_setprio 1
	s_barrier
	s_waitcnt lgkmcnt(0)
	v_mfma_f32_16x16x32_bf16 v[124:127], v[172:175], v[156:159], v[124:127]
	v_mfma_f32_16x16x32_bf16 v[120:123], v[172:175], v[164:167], v[120:123]
	v_mfma_f32_16x16x32_bf16 v[116:119], v[180:183], v[156:159], v[116:119]
	v_mfma_f32_16x16x32_bf16 v[112:115], v[180:183], v[164:167], v[112:115]
	v_mfma_f32_16x16x32_bf16 v[108:111], v[188:191], v[156:159], v[108:111]
	v_mfma_f32_16x16x32_bf16 v[104:107], v[188:191], v[164:167], v[104:107]
	v_mfma_f32_16x16x32_bf16 v[100:103], v[196:199], v[156:159], v[100:103]
	v_mfma_f32_16x16x32_bf16 v[96:99], v[196:199], v[164:167], v[96:99]
	v_mfma_f32_16x16x32_bf16 v[124:127], v[176:179], v[160:163], v[124:127]
	v_mfma_f32_16x16x32_bf16 v[120:123], v[176:179], v[168:171], v[120:123]
	v_mfma_f32_16x16x32_bf16 v[116:119], v[184:187], v[160:163], v[116:119]
	v_mfma_f32_16x16x32_bf16 v[112:115], v[184:187], v[168:171], v[112:115]
	v_mfma_f32_16x16x32_bf16 v[108:111], v[192:195], v[160:163], v[108:111]
	v_mfma_f32_16x16x32_bf16 v[104:107], v[192:195], v[168:171], v[104:107]
	v_mfma_f32_16x16x32_bf16 v[100:103], v[200:203], v[160:163], v[100:103]
	v_mfma_f32_16x16x32_bf16 v[96:99], v[200:203], v[168:171], v[96:99]
	s_barrier
	s_setprio 0
	ds_read_b128 v[204:207], v145 offset:49152
	ds_read_b128 v[212:215], v145 offset:50176
	ds_read_b128 v[216:219], v145 offset:51200
	ds_read_b128 v[220:223], v145 offset:52224
	s_add_u32 m0, s29, s52
	s_nop 0
	s_add_u32 vcc_lo, s26, s16
	s_addc_u32 vcc_hi, s27, s17
	global_load_lds_dwordx4 v130, vcc
	v_lshl_add_u64 v[230:231], v[228:229], 0, s[16:17]
	s_add_u32 m0, s29, s52
	s_add_u32 m0, m0, 0x2000
	s_nop 0
	global_load_lds_dwordx4 v132, vcc
	s_setprio 1
	s_barrier
	s_waitcnt lgkmcnt(0)
	v_mfma_f32_16x16x32_bf16 v[92:95], v[172:175], v[204:207], v[92:95]
	v_mfma_f32_16x16x32_bf16 v[88:91], v[172:175], v[216:219], v[88:91]
	v_mfma_f32_16x16x32_bf16 v[84:87], v[180:183], v[204:207], v[84:87]
	v_mfma_f32_16x16x32_bf16 v[80:83], v[180:183], v[216:219], v[80:83]
	v_mfma_f32_16x16x32_bf16 v[76:79], v[188:191], v[204:207], v[76:79]
	v_mfma_f32_16x16x32_bf16 v[72:75], v[188:191], v[216:219], v[72:75]
	v_mfma_f32_16x16x32_bf16 v[68:71], v[196:199], v[204:207], v[68:71]
	v_mfma_f32_16x16x32_bf16 v[64:67], v[196:199], v[216:219], v[64:67]
	v_mfma_f32_16x16x32_bf16 v[92:95], v[176:179], v[212:215], v[92:95]
	ds_read_b128 v[172:175], v128 offset:49152
	v_mfma_f32_16x16x32_bf16 v[88:91], v[176:179], v[220:223], v[88:91]
	v_mfma_f32_16x16x32_bf16 v[84:87], v[184:187], v[212:215], v[84:87]
	ds_read_b128 v[180:183], v128 offset:51200
	v_mfma_f32_16x16x32_bf16 v[80:83], v[184:187], v[220:223], v[80:83]
	v_mfma_f32_16x16x32_bf16 v[76:79], v[192:195], v[212:215], v[76:79]
	ds_read_b128 v[188:191], v128 offset:53248
	v_mfma_f32_16x16x32_bf16 v[72:75], v[192:195], v[220:223], v[72:75]
	v_mfma_f32_16x16x32_bf16 v[68:71], v[200:203], v[212:215], v[68:71]
	ds_read_b128 v[196:199], v128 offset:55296
	v_mfma_f32_16x16x32_bf16 v[64:67], v[200:203], v[220:223], v[64:67]
	s_barrier
	s_setprio 0
	ds_read_b128 v[176:179], v128 offset:50176
	ds_read_b128 v[184:187], v128 offset:52224
	ds_read_b128 v[192:195], v128 offset:54272
	ds_read_b128 v[200:203], v128 offset:56320
	s_add_u32 m0, s29, 0x8000
	s_nop 0
	s_add_u32 vcc_lo, s26, s18
	s_addc_u32 vcc_hi, s27, s19
	global_load_lds_dwordx4 v134, vcc
	v_lshl_add_u64 v[208:209], v[224:225], 0, s[18:19]
	s_add_u32 m0, s29, 0xa000
	s_nop 0
	global_load_lds_dwordx4 v136, vcc
	s_waitcnt vmcnt(8)
	s_setprio 1
	s_barrier
; #define WAIT_V(n) asm volatile("s_waitcnt vmcnt(" #n ")" ::: "memory")
; #define WAIT_L(n) asm volatile("s_waitcnt lgkmcnt(" #n ")" ::: "memory")
; #define BAR __builtin_amdgcn_s_barrier()
; #define SCHED __builtin_amdgcn_sched_barrier(0)
; #define STAGE(P, BASE, br, kt) do { const char* _g = (const char*)((BASE) + (size_t)(br) * GK + (kt) * BK); \
;     __builtin_amdgcn_global_load_lds((const unsigned*)(_g + voff0), (unsigned*)((char*)(P) + tx * 16), 16, 0, 0); \
;     __builtin_amdgcn_global_load_lds((const unsigned*)(_g + voff1), (unsigned*)((char*)(P) + tx * 16 + 8192), 16, 0, 0); } while (0)
; #define LDA(dst, b, h) _Pragma("unroll") for (int m = 0; m < 4; ++m) _Pragma("unroll") for (int k = 0; k < 2; ++k) \
;     dst[m][k] = *reinterpret_cast<const bf16x8*>((char*)shm + abase + (((b) * 2 + (h)) * 16384 + (m * 2 + k) * 1024))
; #define LDB(dst, b, h) _Pragma("unroll") for (int n = 0; n < 2; ++n) _Pragma("unroll") for (int k = 0; k < 2; ++k) \
;     dst[n][k] = *reinterpret_cast<const bf16x8*>((char*)shm + bbase + (((b) * 2 + (h)) * 16384 + (n * 2 + k) * 1024))
; template <bool SWAP>
; __device__ __forceinline__ void gemm_main(const u16* __restrict__ A, const u16* __restrict__ Bt, int brow, int bcol,
;                                           u16* shm, f32x4 (&acc)[2][2][4][2]) {
;     ...
;     LDA(At, 1, 1); STAGE(SA(1, 0), A, brow, t + 3);
;     BAR; WAIT_L(0); MMA(1, 0, At, B0); BAR; SCHED;
;     STAGE(SB(1, 1), Bt, bcol + HALF, t + 3);
;     WAIT_V(6); BAR; MMA(1, 1, At, B1); BAR;
;   }
;   { LDB(B0, 0, 0); LDA(At, 0, 0); STAGE(SA(1, 1), A, brow + HALF, nt - 1);
;     BAR; WAIT_L(0); MMA(0, 0, At, B0); BAR;
	s_waitcnt lgkmcnt(0)
	v_mfma_f32_16x16x32_bf16 v[60:63], v[172:175], v[156:159], v[60:63]
	v_mfma_f32_16x16x32_bf16 v[56:59], v[172:175], v[164:167], v[56:59]
	v_mfma_f32_16x16x32_bf16 v[52:55], v[180:183], v[156:159], v[52:55]
	v_mfma_f32_16x16x32_bf16 v[48:51], v[180:183], v[164:167], v[48:51]
	v_mfma_f32_16x16x32_bf16 v[44:47], v[188:191], v[156:159], v[44:47]
	v_mfma_f32_16x16x32_bf16 v[40:43], v[188:191], v[164:167], v[40:43]
	v_mfma_f32_16x16x32_bf16 v[36:39], v[196:199], v[156:159], v[36:39]
	v_mfma_f32_16x16x32_bf16 v[32:35], v[196:199], v[164:167], v[32:35]
	v_mfma_f32_16x16x32_bf16 v[60:63], v[176:179], v[160:163], v[60:63]
	v_mfma_f32_16x16x32_bf16 v[56:59], v[176:179], v[168:171], v[56:59]
	v_mfma_f32_16x16x32_bf16 v[52:55], v[184:187], v[160:163], v[52:55]
	v_mfma_f32_16x16x32_bf16 v[48:51], v[184:187], v[168:171], v[48:51]
	v_mfma_f32_16x16x32_bf16 v[44:47], v[192:195], v[160:163], v[44:47]
	v_mfma_f32_16x16x32_bf16 v[40:43], v[192:195], v[168:171], v[40:43]
	v_mfma_f32_16x16x32_bf16 v[36:39], v[200:203], v[160:163], v[36:39]
	v_mfma_f32_16x16x32_bf16 v[32:35], v[200:203], v[168:171], v[32:35]
	s_barrier
	s_setprio 0
	ds_read_b128 v[156:159], v145
	ds_read_b128 v[160:163], v145 offset:1024
	ds_read_b128 v[164:167], v145 offset:2048
	ds_read_b128 v[168:171], v145 offset:3072
	s_add_u32 m0, s29, s53
	s_nop 0
	s_add_u32 vcc_lo, s26, s20
	s_addc_u32 vcc_hi, s27, s21
	global_load_lds_dwordx4 v130, vcc
	v_lshl_add_u64 v[254:255], v[228:229], 0, s[20:21]
	s_add_u32 m0, s29, s53
	s_add_u32 m0, m0, 0x2000
	s_nop 0
	global_load_lds_dwordx4 v132, vcc
	s_setprio 1
	s_barrier
	v_mfma_f32_16x16x32_bf16 v[28:31], v[172:175], v[204:207], v[28:31]
	v_mfma_f32_16x16x32_bf16 v[24:27], v[172:175], v[216:219], v[24:27]
	v_mfma_f32_16x16x32_bf16 v[20:23], v[180:183], v[204:207], v[20:23]
	v_mfma_f32_16x16x32_bf16 v[16:19], v[180:183], v[216:219], v[16:19]
	v_mfma_f32_16x16x32_bf16 v[12:15], v[188:191], v[204:207], v[12:15]
	v_mfma_f32_16x16x32_bf16 v[8:11], v[188:191], v[216:219], v[8:11]
	v_mfma_f32_16x16x32_bf16 v[4:7], v[196:199], v[204:207], v[4:7]
	v_mfma_f32_16x16x32_bf16 v[0:3], v[196:199], v[216:219], v[0:3]
	v_mfma_f32_16x16x32_bf16 v[28:31], v[176:179], v[212:215], v[28:31]
	ds_read_b128 v[172:175], v128
	v_mfma_f32_16x16x32_bf16 v[24:27], v[176:179], v[220:223], v[24:27]
	v_mfma_f32_16x16x32_bf16 v[20:23], v[184:187], v[212:215], v[20:23]
	ds_read_b128 v[180:183], v128 offset:2048
	v_mfma_f32_16x16x32_bf16 v[16:19], v[184:187], v[220:223], v[16:19]
	v_mfma_f32_16x16x32_bf16 v[12:15], v[192:195], v[212:215], v[12:15]
	ds_read_b128 v[188:191], v128 offset:4096
	v_mfma_f32_16x16x32_bf16 v[8:11], v[192:195], v[220:223], v[8:11]
	v_mfma_f32_16x16x32_bf16 v[4:7], v[200:203], v[212:215], v[4:7]
	ds_read_b128 v[196:199], v128 offset:6144
	v_mfma_f32_16x16x32_bf16 v[0:3], v[200:203], v[220:223], v[0:3]
	s_add_i32 s28, s28, 2
	s_add_u32 s26, s26, 0x100
	s_addc_u32 s27, s27, 0
	s_cmp_lt_u32 s28, 28
	s_barrier
	s_setprio 0
	s_cbranch_scc1 .LBB0_84
	v_lshlrev_b32_e32 v130, 3, v147
	v_lshlrev_b32_e32 v131, 5, v147
	v_and_b32_e32 v130, 0xffff0, v130
	v_and_b32_e32 v131, 32, v131
	v_add_u32_e32 v131, v131, v149
	v_add_lshl_u32 v130, v148, v130, 12
	s_add_u32 s4, s37, s4
	v_lshl_add_u32 v155, v131, 1, v130
	v_lshlrev_b32_e32 v130, 3, v150
	v_lshlrev_b32_e32 v131, 5, v150
	s_addc_u32 s27, s38, 0
	v_and_b32_e32 v130, 0xffff0, v130
	v_and_b32_e32 v131, 32, v131
	s_add_u32 s26, s4, 0x80f80
	v_readfirstlane_b32 s4, v153
	v_add_u32_e32 v131, v131, v152
	v_add_lshl_u32 v130, v151, v130, 12
	s_addc_u32 s27, s27, 0
	s_mov_b32 m0, s4
	v_readfirstlane_b32 s4, v154
	v_lshl_add_u32 v150, v131, 1, v130
	ds_read_b128 v[130:133], v145
	ds_read_b128 v[134:137], v145 offset:1024
	ds_read_b128 v[146:149], v145 offset:2048
	ds_read_b128 v[156:159], v145 offset:3072
	ds_read_b128 v[160:163], v128
	ds_read_b128 v[164:167], v128 offset:1024
	ds_read_b128 v[168:171], v128 offset:2048
	ds_read_b128 v[172:175], v128 offset:3072
	ds_read_b128 v[176:179], v128 offset:4096
	ds_read_b128 v[180:183], v128 offset:5120
	ds_read_b128 v[184:187], v128 offset:6144
	ds_read_b128 v[188:191], v128 offset:7168
	global_load_lds_dwordx4 v155, s[26:27]
	s_mov_b32 m0, s4
	s_nop 0
	global_load_lds_dwordx4 v150, s[26:27]
	s_waitcnt vmcnt(8)
	s_barrier
	s_waitcnt lgkmcnt(0)
	s_setprio 1
	s_waitcnt lgkmcnt(0)
	v_mfma_f32_16x16x32_bf16 v[124:127], v[160:163], v[130:133], v[124:127]
	v_mfma_f32_16x16x32_bf16 v[116:119], v[168:171], v[130:133], v[116:119]
	v_mfma_f32_16x16x32_bf16 v[108:111], v[176:179], v[130:133], v[108:111]
	v_mfma_f32_16x16x32_bf16 v[100:103], v[184:187], v[130:133], v[100:103]
	v_mfma_f32_16x16x32_bf16 v[96:99], v[184:187], v[146:149], v[96:99]
	v_mfma_f32_16x16x32_bf16 v[124:127], v[164:167], v[134:137], v[124:127]
	v_mfma_f32_16x16x32_bf16 v[120:123], v[160:163], v[146:149], v[120:123]
	v_mfma_f32_16x16x32_bf16 v[116:119], v[172:175], v[134:137], v[116:119]
	v_mfma_f32_16x16x32_bf16 v[112:115], v[168:171], v[146:149], v[112:115]
	v_mfma_f32_16x16x32_bf16 v[108:111], v[180:183], v[134:137], v[108:111]
	v_mfma_f32_16x16x32_bf16 v[104:107], v[176:179], v[146:149], v[104:107]
	v_mfma_f32_16x16x32_bf16 v[100:103], v[188:191], v[134:137], v[100:103]
	v_mfma_f32_16x16x32_bf16 v[96:99], v[188:191], v[156:159], v[96:99]
	v_mfma_f32_16x16x32_bf16 v[150:153], v[164:167], v[156:159], v[120:123]
	v_mfma_f32_16x16x32_bf16 v[192:195], v[172:175], v[156:159], v[112:115]
	v_mfma_f32_16x16x32_bf16 v[196:199], v[180:183], v[156:159], v[104:107]
	s_setprio 0
	s_barrier
	s_nop 0
	ds_read_b128 v[104:107], v145 offset:16384
	ds_read_b128 v[112:115], v145 offset:17408
	ds_read_b128 v[120:123], v145 offset:18432
	ds_read_b128 v[200:203], v145 offset:19456
	s_barrier
; #define WAIT_V(n) asm volatile("s_waitcnt vmcnt(" #n ")" ::: "memory")
; #define WAIT_L(n) asm volatile("s_waitcnt lgkmcnt(" #n ")" ::: "memory")
; #define BAR __builtin_amdgcn_s_barrier()
; #define LDA(dst, b, h) _Pragma("unroll") for (int m = 0; m < 4; ++m) _Pragma("unroll") for (int k = 0; k < 2; ++k) \
;     dst[m][k] = *reinterpret_cast<const bf16x8*>((char*)shm + abase + (((b) * 2 + (h)) * 16384 + (m * 2 + k) * 1024))
; #define LDB(dst, b, h) _Pragma("unroll") for (int n = 0; n < 2; ++n) _Pragma("unroll") for (int k = 0; k < 2; ++k) \
;     dst[n][k] = *reinterpret_cast<const bf16x8*>((char*)shm + bbase + (((b) * 2 + (h)) * 16384 + (n * 2 + k) * 1024))
; template <bool SWAP>
; __device__ __forceinline__ void gemm_main(const u16* __restrict__ A, const u16* __restrict__ Bt, int brow, int bcol,
;                                           u16* shm, f32x4 (&acc)[2][2][4][2]) {
;     ...
;     BAR; WAIT_L(0); MMA(0, 0, At, B0); BAR;
;     LDB(B1, 0, 1); BAR; WAIT_L(0); MMA(0, 1, At, B1); BAR;
;     LDA(At, 0, 1); WAIT_V(4); BAR; WAIT_L(0); MMA(1, 0, At, B0); MMA(1, 1, At, B1); BAR; }
;   { LDB(B0, 1, 0); LDA(At, 1, 0); WAIT_V(2); BAR; WAIT_L(0); MMA(0, 0, At, B0); BAR;
	s_waitcnt lgkmcnt(0)
	s_setprio 1
	s_waitcnt lgkmcnt(0)
	v_mfma_f32_16x16x32_bf16 v[84:87], v[168:171], v[104:107], v[84:87]
	v_mfma_f32_16x16x32_bf16 v[76:79], v[176:179], v[104:107], v[76:79]
	v_mfma_f32_16x16x32_bf16 v[68:71], v[184:187], v[104:107], v[68:71]
	v_mfma_f32_16x16x32_bf16 v[92:95], v[160:163], v[104:107], v[92:95]
	v_mfma_f32_16x16x32_bf16 v[88:91], v[160:163], v[120:123], v[88:91]
	v_mfma_f32_16x16x32_bf16 v[84:87], v[172:175], v[112:115], v[84:87]
	v_mfma_f32_16x16x32_bf16 v[80:83], v[168:171], v[120:123], v[80:83]
	v_mfma_f32_16x16x32_bf16 v[76:79], v[180:183], v[112:115], v[76:79]
	v_mfma_f32_16x16x32_bf16 v[72:75], v[176:179], v[120:123], v[72:75]
	v_mfma_f32_16x16x32_bf16 v[68:71], v[188:191], v[112:115], v[68:71]
	v_mfma_f32_16x16x32_bf16 v[64:67], v[184:187], v[120:123], v[64:67]
	v_mfma_f32_16x16x32_bf16 v[204:207], v[164:167], v[112:115], v[92:95]
	v_mfma_f32_16x16x32_bf16 v[160:163], v[164:167], v[200:203], v[88:91]
	v_mfma_f32_16x16x32_bf16 v[164:167], v[172:175], v[200:203], v[80:83]
	v_mfma_f32_16x16x32_bf16 v[168:171], v[180:183], v[200:203], v[72:75]
	v_mfma_f32_16x16x32_bf16 v[172:175], v[188:191], v[200:203], v[64:67]
	s_setprio 0
	s_barrier
	s_nop 0
	ds_read_b128 v[64:67], v128 offset:16384
	ds_read_b128 v[72:75], v128 offset:17408
	ds_read_b128 v[80:83], v128 offset:18432
	ds_read_b128 v[88:91], v128 offset:19456
	ds_read_b128 v[92:95], v128 offset:20480
	ds_read_b128 v[176:179], v128 offset:21504
	ds_read_b128 v[180:183], v128 offset:22528
	ds_read_b128 v[184:187], v128 offset:23552
	s_waitcnt vmcnt(4)
	s_barrier
	s_waitcnt lgkmcnt(0)
	s_setprio 1
	s_waitcnt lgkmcnt(0)
	v_mfma_f32_16x16x32_bf16 v[60:63], v[64:67], v[130:133], v[60:63]
	v_mfma_f32_16x16x32_bf16 v[52:55], v[80:83], v[130:133], v[52:55]
	v_mfma_f32_16x16x32_bf16 v[44:47], v[92:95], v[130:133], v[44:47]
	v_mfma_f32_16x16x32_bf16 v[36:39], v[180:183], v[130:133], v[36:39]
	v_mfma_f32_16x16x32_bf16 v[60:63], v[72:75], v[134:137], v[60:63]
	v_mfma_f32_16x16x32_bf16 v[56:59], v[64:67], v[146:149], v[56:59]
	v_mfma_f32_16x16x32_bf16 v[52:55], v[88:91], v[134:137], v[52:55]
	v_mfma_f32_16x16x32_bf16 v[48:51], v[80:83], v[146:149], v[48:51]
	v_mfma_f32_16x16x32_bf16 v[44:47], v[176:179], v[134:137], v[44:47]
	v_mfma_f32_16x16x32_bf16 v[40:43], v[92:95], v[146:149], v[40:43]
	v_mfma_f32_16x16x32_bf16 v[36:39], v[184:187], v[134:137], v[36:39]
	v_mfma_f32_16x16x32_bf16 v[32:35], v[180:183], v[146:149], v[32:35]
	v_mfma_f32_16x16x32_bf16 v[188:191], v[72:75], v[156:159], v[56:59]
	v_mfma_f32_16x16x32_bf16 v[212:215], v[88:91], v[156:159], v[48:51]
	v_mfma_f32_16x16x32_bf16 v[216:219], v[176:179], v[156:159], v[40:43]
	v_mfma_f32_16x16x32_bf16 v[130:133], v[184:187], v[156:159], v[32:35]
	s_setprio 0
	s_setprio 1
	v_mfma_f32_16x16x32_bf16 v[28:31], v[64:67], v[104:107], v[28:31]
	v_mfma_f32_16x16x32_bf16 v[20:23], v[80:83], v[104:107], v[20:23]
	v_mfma_f32_16x16x32_bf16 v[12:15], v[92:95], v[104:107], v[12:15]
	v_mfma_f32_16x16x32_bf16 v[4:7], v[180:183], v[104:107], v[4:7]
	v_mfma_f32_16x16x32_bf16 v[28:31], v[72:75], v[112:115], v[28:31]
	v_mfma_f32_16x16x32_bf16 v[24:27], v[64:67], v[120:123], v[24:27]
	v_mfma_f32_16x16x32_bf16 v[20:23], v[88:91], v[112:115], v[20:23]
	v_mfma_f32_16x16x32_bf16 v[16:19], v[80:83], v[120:123], v[16:19]
	v_mfma_f32_16x16x32_bf16 v[12:15], v[176:179], v[112:115], v[12:15]
	v_mfma_f32_16x16x32_bf16 v[8:11], v[92:95], v[120:123], v[8:11]
	v_mfma_f32_16x16x32_bf16 v[4:7], v[184:187], v[112:115], v[4:7]
	v_mfma_f32_16x16x32_bf16 v[0:3], v[180:183], v[120:123], v[0:3]
	v_mfma_f32_16x16x32_bf16 v[134:137], v[72:75], v[200:203], v[24:27]
	v_mfma_f32_16x16x32_bf16 v[146:149], v[88:91], v[200:203], v[16:19]
	v_mfma_f32_16x16x32_bf16 v[154:157], v[176:179], v[200:203], v[8:11]
	v_mfma_f32_16x16x32_bf16 v[176:179], v[184:187], v[200:203], v[0:3]
	s_setprio 0
	s_barrier
	s_nop 1
	ds_read_b128 v[0:3], v145 offset:32768
	ds_read_b128 v[8:11], v145 offset:33792
	ds_read_b128 v[16:19], v145 offset:34816
	ds_read_b128 v[24:27], v145 offset:35840
	ds_read_b128 v[32:35], v128 offset:32768
	ds_read_b128 v[40:43], v128 offset:33792
	ds_read_b128 v[48:51], v128 offset:34816
	ds_read_b128 v[56:59], v128 offset:35840
	ds_read_b128 v[64:67], v128 offset:36864
	ds_read_b128 v[180:183], v128 offset:37888
	ds_read_b128 v[184:187], v128 offset:38912
	ds_read_b128 v[200:203], v128 offset:39936
	s_waitcnt vmcnt(2)
	s_barrier
; #define WAIT_V(n) asm volatile("s_waitcnt vmcnt(" #n ")" ::: "memory")
; #define WAIT_L(n) asm volatile("s_waitcnt lgkmcnt(" #n ")" ::: "memory")
; #define BAR __builtin_amdgcn_s_barrier()
; #define LDA(dst, b, h) _Pragma("unroll") for (int m = 0; m < 4; ++m) _Pragma("unroll") for (int k = 0; k < 2; ++k) \
;     dst[m][k] = *reinterpret_cast<const bf16x8*>((char*)shm + abase + (((b) * 2 + (h)) * 16384 + (m * 2 + k) * 1024))
; #define LDB(dst, b, h) _Pragma("unroll") for (int n = 0; n < 2; ++n) _Pragma("unroll") for (int k = 0; k < 2; ++k) \
;     dst[n][k] = *reinterpret_cast<const bf16x8*>((char*)shm + bbase + (((b) * 2 + (h)) * 16384 + (n * 2 + k) * 1024))
; template <bool SWAP>
; __device__ __forceinline__ void gemm_main(const u16* __restrict__ A, const u16* __restrict__ Bt, int brow, int bcol,
;                                           u16* shm, f32x4 (&acc)[2][2][4][2]) {
;     ...
;   { LDB(B0, 1, 0); LDA(At, 1, 0); WAIT_V(2); BAR; WAIT_L(0); MMA(0, 0, At, B0); BAR;
;     LDB(B1, 1, 1); WAIT_V(0); BAR; WAIT_L(0); MMA(0, 1, At, B1); BAR;
;     LDA(At, 1, 1); BAR; WAIT_L(0); MMA(1, 0, At, B0); MMA(1, 1, At, B1); BAR; }
;   if (wr == 0) BAR;
	s_waitcnt lgkmcnt(0)
	s_setprio 1
	s_waitcnt lgkmcnt(0)
	v_mfma_f32_16x16x32_bf16 v[72:75], v[32:35], v[0:3], v[124:127]
	v_mfma_f32_16x16x32_bf16 v[120:123], v[40:43], v[8:11], v[72:75]
	v_mfma_f32_16x16x32_bf16 v[72:75], v[32:35], v[16:19], v[150:153]
	v_mfma_f32_16x16x32_bf16 v[112:115], v[40:43], v[24:27], v[72:75]
	v_mfma_f32_16x16x32_bf16 v[72:75], v[48:51], v[0:3], v[116:119]
	v_mfma_f32_16x16x32_bf16 v[124:127], v[56:59], v[8:11], v[72:75]
	v_mfma_f32_16x16x32_bf16 v[72:75], v[48:51], v[16:19], v[192:195]
	v_mfma_f32_16x16x32_bf16 v[116:119], v[56:59], v[24:27], v[72:75]
	v_mfma_f32_16x16x32_bf16 v[72:75], v[64:67], v[0:3], v[108:111]
	v_mfma_f32_16x16x32_bf16 v[104:107], v[180:183], v[8:11], v[72:75]
	v_mfma_f32_16x16x32_bf16 v[72:75], v[64:67], v[16:19], v[196:199]
	v_mfma_f32_16x16x32_bf16 v[92:95], v[180:183], v[24:27], v[72:75]
	v_mfma_f32_16x16x32_bf16 v[72:75], v[184:187], v[0:3], v[100:103]
	v_mfma_f32_16x16x32_bf16 v[108:111], v[200:203], v[8:11], v[72:75]
	v_mfma_f32_16x16x32_bf16 v[72:75], v[184:187], v[16:19], v[96:99]
	v_mfma_f32_16x16x32_bf16 v[100:103], v[200:203], v[24:27], v[72:75]
	s_setprio 0
	s_barrier
	ds_read_b128 v[150:153], v145 offset:49152
	ds_read_b128 v[192:195], v145 offset:50176
	ds_read_b128 v[196:199], v145 offset:51200
	ds_read_b128 v[220:223], v145 offset:52224
	s_waitcnt vmcnt(0)
	s_barrier
	s_waitcnt lgkmcnt(0)
	s_setprio 1
	s_waitcnt lgkmcnt(0)
	v_mfma_f32_16x16x32_bf16 v[72:75], v[32:35], v[150:153], v[204:207]
	v_mfma_f32_16x16x32_bf16 v[32:35], v[32:35], v[196:199], v[160:163]
	v_mfma_f32_16x16x32_bf16 v[80:83], v[40:43], v[220:223], v[32:35]
	v_mfma_f32_16x16x32_bf16 v[32:35], v[48:51], v[150:153], v[84:87]
	v_mfma_f32_16x16x32_bf16 v[96:99], v[56:59], v[192:195], v[32:35]
	v_mfma_f32_16x16x32_bf16 v[32:35], v[48:51], v[196:199], v[164:167]
	v_mfma_f32_16x16x32_bf16 v[84:87], v[56:59], v[220:223], v[32:35]
	v_mfma_f32_16x16x32_bf16 v[32:35], v[64:67], v[150:153], v[76:79]
	v_mfma_f32_16x16x32_bf16 v[88:91], v[40:43], v[192:195], v[72:75]
	v_mfma_f32_16x16x32_bf16 v[72:75], v[180:183], v[192:195], v[32:35]
	v_mfma_f32_16x16x32_bf16 v[32:35], v[64:67], v[196:199], v[168:171]
	v_mfma_f32_16x16x32_bf16 v[64:67], v[180:183], v[220:223], v[32:35]
	v_mfma_f32_16x16x32_bf16 v[32:35], v[184:187], v[150:153], v[68:71]
	v_mfma_f32_16x16x32_bf16 v[76:79], v[200:203], v[192:195], v[32:35]
	v_mfma_f32_16x16x32_bf16 v[32:35], v[184:187], v[196:199], v[172:175]
	v_mfma_f32_16x16x32_bf16 v[68:71], v[200:203], v[220:223], v[32:35]
	s_setprio 0
	s_barrier
	ds_read_b128 v[158:161], v128 offset:49152
	ds_read_b128 v[162:165], v128 offset:50176
	ds_read_b128 v[166:169], v128 offset:51200
	ds_read_b128 v[170:173], v128 offset:52224
	ds_read_b128 v[180:183], v128 offset:53248
	ds_read_b128 v[184:187], v128 offset:54272
	ds_read_b128 v[200:203], v128 offset:55296
	ds_read_b128 v[204:207], v128 offset:56320
	s_barrier
	s_waitcnt lgkmcnt(0)
	s_setprio 1
	s_waitcnt lgkmcnt(0)
	v_mfma_f32_16x16x32_bf16 v[32:35], v[158:161], v[0:3], v[60:63]
	v_mfma_f32_16x16x32_bf16 v[56:59], v[162:165], v[8:11], v[32:35]
	v_mfma_f32_16x16x32_bf16 v[32:35], v[158:161], v[16:19], v[188:191]
	v_mfma_f32_16x16x32_bf16 v[48:51], v[162:165], v[24:27], v[32:35]
	v_mfma_f32_16x16x32_bf16 v[32:35], v[166:169], v[0:3], v[52:55]
	v_mfma_f32_16x16x32_bf16 v[60:63], v[170:173], v[8:11], v[32:35]
	v_mfma_f32_16x16x32_bf16 v[32:35], v[166:169], v[16:19], v[212:215]
	v_mfma_f32_16x16x32_bf16 v[52:55], v[170:173], v[24:27], v[32:35]
	v_mfma_f32_16x16x32_bf16 v[32:35], v[180:183], v[0:3], v[44:47]
	v_mfma_f32_16x16x32_bf16 v[0:3], v[200:203], v[0:3], v[36:39]
	v_mfma_f32_16x16x32_bf16 v[40:43], v[184:187], v[8:11], v[32:35]
	v_mfma_f32_16x16x32_bf16 v[32:35], v[180:183], v[16:19], v[216:219]
	v_mfma_f32_16x16x32_bf16 v[44:47], v[204:207], v[8:11], v[0:3]
	v_mfma_f32_16x16x32_bf16 v[0:3], v[200:203], v[16:19], v[130:133]
	v_mfma_f32_16x16x32_bf16 v[32:35], v[184:187], v[24:27], v[32:35]
	v_mfma_f32_16x16x32_bf16 v[36:39], v[204:207], v[24:27], v[0:3]
	s_setprio 0
	s_setprio 1
	v_mfma_f32_16x16x32_bf16 v[0:3], v[158:161], v[150:153], v[28:31]
	v_mfma_f32_16x16x32_bf16 v[24:27], v[162:165], v[192:195], v[0:3]
	v_mfma_f32_16x16x32_bf16 v[0:3], v[158:161], v[196:199], v[134:137]
	v_mfma_f32_16x16x32_bf16 v[16:19], v[162:165], v[220:223], v[0:3]
	v_mfma_f32_16x16x32_bf16 v[0:3], v[166:169], v[150:153], v[20:23]
	v_mfma_f32_16x16x32_bf16 v[28:31], v[170:173], v[192:195], v[0:3]
	v_mfma_f32_16x16x32_bf16 v[0:3], v[166:169], v[196:199], v[146:149]
	v_mfma_f32_16x16x32_bf16 v[20:23], v[170:173], v[220:223], v[0:3]
	v_mfma_f32_16x16x32_bf16 v[0:3], v[180:183], v[150:153], v[12:15]
	v_mfma_f32_16x16x32_bf16 v[4:7], v[200:203], v[150:153], v[4:7]
	v_mfma_f32_16x16x32_bf16 v[8:11], v[184:187], v[192:195], v[0:3]
	v_mfma_f32_16x16x32_bf16 v[0:3], v[180:183], v[196:199], v[154:157]
	v_mfma_f32_16x16x32_bf16 v[12:15], v[204:207], v[192:195], v[4:7]
	v_mfma_f32_16x16x32_bf16 v[4:7], v[200:203], v[196:199], v[176:179]
	v_mfma_f32_16x16x32_bf16 v[0:3], v[184:187], v[220:223], v[0:3]
	v_mfma_f32_16x16x32_bf16 v[4:7], v[204:207], v[220:223], v[4:7]
	s_setprio 0
	v_cmp_gt_u32_e32 vcc, s55, v144
	s_barrier
	s_and_saveexec_b64 s[26:27], vcc
	s_cbranch_execz .LBB0_87
	s_barrier

; #define WAIT_V(n) asm volatile("s_waitcnt vmcnt(" #n ")" ::: "memory")
; #define WAIT_L(n) asm volatile("s_waitcnt lgkmcnt(" #n ")" ::: "memory")
; #define BAR __builtin_amdgcn_s_barrier()
; #define SCHED __builtin_amdgcn_sched_barrier(0)
; #define STAGE(P, BASE, br, kt) do { const char* _g = (const char*)((BASE) + (size_t)(br) * GK + (kt) * BK); \
;     __builtin_amdgcn_global_load_lds((const unsigned*)(_g + voff0), (unsigned*)((char*)(P) + tx * 16), 16, 0, 0); \
;     __builtin_amdgcn_global_load_lds((const unsigned*)(_g + voff1), (unsigned*)((char*)(P) + tx * 16 + 8192), 16, 0, 0); } while (0)
; #define LDA(dst, b, h) _Pragma("unroll") for (int m = 0; m < 4; ++m) _Pragma("unroll") for (int k = 0; k < 2; ++k) \
;     dst[m][k] = *reinterpret_cast<const bf16x8*>((char*)shm + abase + (((b) * 2 + (h)) * 16384 + (m * 2 + k) * 1024))
; #define LDB(dst, b, h) _Pragma("unroll") for (int n = 0; n < 2; ++n) _Pragma("unroll") for (int k = 0; k < 2; ++k) \
;     dst[n][k] = *reinterpret_cast<const bf16x8*>((char*)shm + bbase + (((b) * 2 + (h)) * 16384 + (n * 2 + k) * 1024))
; template <bool SWAP>
; __device__ __forceinline__ void gemm_main(const u16* __restrict__ A, const u16* __restrict__ Bt, int brow, int bcol,
;                                           u16* shm, f32x4 (&acc)[2][2][4][2]) {
;     ...
;     LDB(B0, 0, 0); SCHED; LDA(At, 0, 0); STAGE(SA(1, 1), A, brow + HALF, t + 1);
;     WAIT_L(8); BAR; WAIT_L(0); MMA(0, 0, At, B0); BAR; SCHED;
;     LDB(B1, 0, 1); STAGE(SB(0, 0), Bt, bcol, t + 2);
;     BAR; WAIT_L(0); MMA(0, 1, At, B1); BAR;
;     LDA(At, 0, 1); STAGE(SA(0, 0), A, brow, t + 2);
;     BAR; WAIT_L(0); MMA(1, 0, At, B0); BAR; SCHED;
;     STAGE(SB(0, 1), Bt, bcol + HALF, t + 2);
;     WAIT_V(6); BAR; MMA(1, 1, At, B1); BAR;
.LBB0_94:
	ds_read_b128 v[176:179], v145 offset:1024
	ds_read_b128 v[184:187], v145 offset:3072
	ds_read_b128 v[192:195], v145 offset:5120
	ds_read_b128 v[200:203], v145 offset:7168
	v_add_u32_e32 v128, 0, v147
	v_add_u32_e32 v154, 0xc000, v128
	v_add_u32_e32 v155, 0xe000, v128
	s_add_u32 m0, s25, 0xc000
	v_lshl_add_u64 v[224:225], s[28:29], 0, v[132:133]
	s_add_u32 vcc_lo, s28, s6
	s_addc_u32 vcc_hi, s29, s7
	global_load_lds_dwordx4 v136, vcc
	s_add_u32 m0, s25, 0xe000
	s_nop 0
	global_load_lds_dwordx4 v132, vcc
	s_waitcnt lgkmcnt(8)
	s_waitcnt vmcnt(8)
	s_setprio 1
	s_barrier
	s_waitcnt lgkmcnt(0)
	v_mfma_f32_16x16x32_bf16 v[124:127], v[156:159], v[172:175], v[124:127]
	v_mfma_f32_16x16x32_bf16 v[120:123], v[164:167], v[172:175], v[120:123]
	v_mfma_f32_16x16x32_bf16 v[116:119], v[156:159], v[180:183], v[116:119]
	v_mfma_f32_16x16x32_bf16 v[112:115], v[164:167], v[180:183], v[112:115]
	v_mfma_f32_16x16x32_bf16 v[108:111], v[156:159], v[188:191], v[108:111]
	v_mfma_f32_16x16x32_bf16 v[104:107], v[164:167], v[188:191], v[104:107]
	v_mfma_f32_16x16x32_bf16 v[100:103], v[156:159], v[196:199], v[100:103]
	v_mfma_f32_16x16x32_bf16 v[96:99], v[164:167], v[196:199], v[96:99]
	v_mfma_f32_16x16x32_bf16 v[124:127], v[160:163], v[176:179], v[124:127]
	v_mfma_f32_16x16x32_bf16 v[120:123], v[168:171], v[176:179], v[120:123]
	v_mfma_f32_16x16x32_bf16 v[116:119], v[160:163], v[184:187], v[116:119]
	v_mfma_f32_16x16x32_bf16 v[112:115], v[168:171], v[184:187], v[112:115]
	v_mfma_f32_16x16x32_bf16 v[108:111], v[160:163], v[192:195], v[108:111]
	v_mfma_f32_16x16x32_bf16 v[104:107], v[168:171], v[192:195], v[104:107]
	v_mfma_f32_16x16x32_bf16 v[100:103], v[160:163], v[200:203], v[100:103]
	v_mfma_f32_16x16x32_bf16 v[96:99], v[168:171], v[200:203], v[96:99]
	s_barrier
	s_setprio 0
	ds_read_b128 v[204:207], v146 offset:16384
	ds_read_b128 v[212:215], v146 offset:17408
	ds_read_b128 v[216:219], v146 offset:18432
	ds_read_b128 v[220:223], v146 offset:19456
	v_lshl_add_u64 v[226:227], s[28:29], 0, v[134:135]
	s_add_u32 m0, s25, s44
	s_nop 0
	s_add_u32 vcc_lo, s28, s8
	s_addc_u32 vcc_hi, s29, s9
	global_load_lds_dwordx4 v134, vcc
	v_lshl_add_u64 v[228:229], s[28:29], 0, v[130:131]
	s_add_u32 m0, s25, s44
	s_add_u32 m0, m0, 0x2000
	s_nop 0
	global_load_lds_dwordx4 v130, vcc
	s_setprio 1
	s_barrier
	s_waitcnt lgkmcnt(0)
	v_mfma_f32_16x16x32_bf16 v[92:95], v[204:207], v[172:175], v[92:95]
	v_mfma_f32_16x16x32_bf16 v[88:91], v[216:219], v[172:175], v[88:91]
	v_mfma_f32_16x16x32_bf16 v[84:87], v[204:207], v[180:183], v[84:87]
	v_mfma_f32_16x16x32_bf16 v[80:83], v[216:219], v[180:183], v[80:83]
	v_mfma_f32_16x16x32_bf16 v[76:79], v[204:207], v[188:191], v[76:79]
	v_mfma_f32_16x16x32_bf16 v[72:75], v[216:219], v[188:191], v[72:75]
	v_mfma_f32_16x16x32_bf16 v[68:71], v[204:207], v[196:199], v[68:71]
	v_mfma_f32_16x16x32_bf16 v[64:67], v[216:219], v[196:199], v[64:67]
	v_mfma_f32_16x16x32_bf16 v[92:95], v[212:215], v[176:179], v[92:95]
	ds_read_b128 v[172:175], v145 offset:16384
	v_mfma_f32_16x16x32_bf16 v[88:91], v[220:223], v[176:179], v[88:91]
	v_mfma_f32_16x16x32_bf16 v[84:87], v[212:215], v[184:187], v[84:87]
	ds_read_b128 v[180:183], v145 offset:18432
	v_mfma_f32_16x16x32_bf16 v[80:83], v[220:223], v[184:187], v[80:83]
	v_mfma_f32_16x16x32_bf16 v[76:79], v[212:215], v[192:195], v[76:79]
	ds_read_b128 v[188:191], v145 offset:20480
	v_mfma_f32_16x16x32_bf16 v[72:75], v[220:223], v[192:195], v[72:75]
	v_mfma_f32_16x16x32_bf16 v[68:71], v[212:215], v[200:203], v[68:71]
	ds_read_b128 v[196:199], v145 offset:22528
	v_mfma_f32_16x16x32_bf16 v[64:67], v[220:223], v[200:203], v[64:67]
	s_barrier
	s_setprio 0
	ds_read_b128 v[176:179], v145 offset:17408
	ds_read_b128 v[184:187], v145 offset:19456
	ds_read_b128 v[192:195], v145 offset:21504
	ds_read_b128 v[200:203], v145 offset:23552
	s_add_u32 m0, s25, 0x0
	s_nop 0
	s_add_u32 vcc_lo, s28, s10
	s_addc_u32 vcc_hi, s29, s11
	global_load_lds_dwordx4 v136, vcc
	s_add_u32 m0, s25, 0x2000
	s_nop 0
	global_load_lds_dwordx4 v132, vcc
	s_waitcnt vmcnt(8)
	s_setprio 1
	s_barrier
	s_waitcnt lgkmcnt(0)
	v_mfma_f32_16x16x32_bf16 v[60:63], v[156:159], v[172:175], v[60:63]
	v_mfma_f32_16x16x32_bf16 v[56:59], v[164:167], v[172:175], v[56:59]
	v_mfma_f32_16x16x32_bf16 v[52:55], v[156:159], v[180:183], v[52:55]
	v_mfma_f32_16x16x32_bf16 v[48:51], v[164:167], v[180:183], v[48:51]
	v_mfma_f32_16x16x32_bf16 v[44:47], v[156:159], v[188:191], v[44:47]
	v_mfma_f32_16x16x32_bf16 v[40:43], v[164:167], v[188:191], v[40:43]
	v_mfma_f32_16x16x32_bf16 v[36:39], v[156:159], v[196:199], v[36:39]
	v_mfma_f32_16x16x32_bf16 v[32:35], v[164:167], v[196:199], v[32:35]
	v_mfma_f32_16x16x32_bf16 v[60:63], v[160:163], v[176:179], v[60:63]
	v_mfma_f32_16x16x32_bf16 v[56:59], v[168:171], v[176:179], v[56:59]
	v_mfma_f32_16x16x32_bf16 v[52:55], v[160:163], v[184:187], v[52:55]
	v_mfma_f32_16x16x32_bf16 v[48:51], v[168:171], v[184:187], v[48:51]
	v_mfma_f32_16x16x32_bf16 v[44:47], v[160:163], v[192:195], v[44:47]
	v_mfma_f32_16x16x32_bf16 v[40:43], v[168:171], v[192:195], v[40:43]
	v_mfma_f32_16x16x32_bf16 v[36:39], v[160:163], v[200:203], v[36:39]
	v_mfma_f32_16x16x32_bf16 v[32:35], v[168:171], v[200:203], v[32:35]
	s_barrier
	s_setprio 0
	ds_read_b128 v[156:159], v146 offset:32768
	ds_read_b128 v[160:163], v146 offset:33792
	ds_read_b128 v[164:167], v146 offset:34816
	ds_read_b128 v[168:171], v146 offset:35840
	s_add_u32 m0, s25, s45
	s_nop 0
	s_add_u32 vcc_lo, s28, s12
	s_addc_u32 vcc_hi, s29, s13
	global_load_lds_dwordx4 v134, vcc
	s_add_u32 m0, s25, s45
	s_add_u32 m0, m0, 0x2000
	s_nop 0
	global_load_lds_dwordx4 v130, vcc
	s_setprio 1
	s_barrier
; #define WAIT_V(n) asm volatile("s_waitcnt vmcnt(" #n ")" ::: "memory")
; #define WAIT_L(n) asm volatile("s_waitcnt lgkmcnt(" #n ")" ::: "memory")
; #define BAR __builtin_amdgcn_s_barrier()
; #define SCHED __builtin_amdgcn_sched_barrier(0)
; #define STAGE(P, BASE, br, kt) do { const char* _g = (const char*)((BASE) + (size_t)(br) * GK + (kt) * BK); \
;     __builtin_amdgcn_global_load_lds((const unsigned*)(_g + voff0), (unsigned*)((char*)(P) + tx * 16), 16, 0, 0); \
;     __builtin_amdgcn_global_load_lds((const unsigned*)(_g + voff1), (unsigned*)((char*)(P) + tx * 16 + 8192), 16, 0, 0); } while (0)
; #define LDA(dst, b, h) _Pragma("unroll") for (int m = 0; m < 4; ++m) _Pragma("unroll") for (int k = 0; k < 2; ++k) \
;     dst[m][k] = *reinterpret_cast<const bf16x8*>((char*)shm + abase + (((b) * 2 + (h)) * 16384 + (m * 2 + k) * 1024))
; #define LDB(dst, b, h) _Pragma("unroll") for (int n = 0; n < 2; ++n) _Pragma("unroll") for (int k = 0; k < 2; ++k) \
;     dst[n][k] = *reinterpret_cast<const bf16x8*>((char*)shm + bbase + (((b) * 2 + (h)) * 16384 + (n * 2 + k) * 1024))
; template <bool SWAP>
; __device__ __forceinline__ void gemm_main(const u16* __restrict__ A, const u16* __restrict__ Bt, int brow, int bcol,
;                                           u16* shm, f32x4 (&acc)[2][2][4][2]) {
;     ...
;     STAGE(SB(0, 1), Bt, bcol + HALF, t + 2);
;     WAIT_V(6); BAR; MMA(1, 1, At, B1); BAR;
;     LDB(B0, 1, 0); SCHED; LDA(At, 1, 0); STAGE(SA(0, 1), A, brow + HALF, t + 2);
;     WAIT_L(8); BAR; WAIT_L(0); MMA(0, 0, At, B0); BAR; SCHED;
;     LDB(B1, 1, 1); STAGE(SB(1, 0), Bt, bcol, t + 3);
;     BAR; WAIT_L(0); MMA(0, 1, At, B1); BAR;
	v_mfma_f32_16x16x32_bf16 v[28:31], v[204:207], v[172:175], v[28:31]
	v_mfma_f32_16x16x32_bf16 v[24:27], v[216:219], v[172:175], v[24:27]
	v_mfma_f32_16x16x32_bf16 v[20:23], v[204:207], v[180:183], v[20:23]
	v_mfma_f32_16x16x32_bf16 v[16:19], v[216:219], v[180:183], v[16:19]
	v_mfma_f32_16x16x32_bf16 v[12:15], v[204:207], v[188:191], v[12:15]
	v_mfma_f32_16x16x32_bf16 v[8:11], v[216:219], v[188:191], v[8:11]
	v_mfma_f32_16x16x32_bf16 v[4:7], v[204:207], v[196:199], v[4:7]
	v_mfma_f32_16x16x32_bf16 v[0:3], v[216:219], v[196:199], v[0:3]
	v_mfma_f32_16x16x32_bf16 v[28:31], v[212:215], v[176:179], v[28:31]
	ds_read_b128 v[172:175], v145 offset:32768
	v_mfma_f32_16x16x32_bf16 v[24:27], v[220:223], v[176:179], v[24:27]
	v_mfma_f32_16x16x32_bf16 v[20:23], v[212:215], v[184:187], v[20:23]
	ds_read_b128 v[180:183], v145 offset:34816
	v_mfma_f32_16x16x32_bf16 v[16:19], v[220:223], v[184:187], v[16:19]
	v_mfma_f32_16x16x32_bf16 v[12:15], v[212:215], v[192:195], v[12:15]
	ds_read_b128 v[188:191], v145 offset:36864
	v_mfma_f32_16x16x32_bf16 v[8:11], v[220:223], v[192:195], v[8:11]
	v_mfma_f32_16x16x32_bf16 v[4:7], v[212:215], v[200:203], v[4:7]
	ds_read_b128 v[196:199], v145 offset:38912
	v_mfma_f32_16x16x32_bf16 v[0:3], v[220:223], v[200:203], v[0:3]
	s_barrier
	s_setprio 0
	ds_read_b128 v[176:179], v145 offset:33792
	ds_read_b128 v[184:187], v145 offset:35840
	ds_read_b128 v[192:195], v145 offset:37888
	ds_read_b128 v[200:203], v145 offset:39936
	s_add_u32 m0, s25, 0x4000
	s_nop 0
	s_add_u32 vcc_lo, s28, s14
	s_addc_u32 vcc_hi, s29, s15
	global_load_lds_dwordx4 v136, vcc
	s_add_u32 m0, s25, 0x6000
	s_nop 0
	global_load_lds_dwordx4 v132, vcc
	s_waitcnt lgkmcnt(8)
	s_waitcnt vmcnt(8)
	s_setprio 1
	s_barrier
	s_waitcnt lgkmcnt(0)
	v_mfma_f32_16x16x32_bf16 v[124:127], v[156:159], v[172:175], v[124:127]
	v_mfma_f32_16x16x32_bf16 v[120:123], v[164:167], v[172:175], v[120:123]
	v_mfma_f32_16x16x32_bf16 v[116:119], v[156:159], v[180:183], v[116:119]
	v_mfma_f32_16x16x32_bf16 v[112:115], v[164:167], v[180:183], v[112:115]
	v_mfma_f32_16x16x32_bf16 v[108:111], v[156:159], v[188:191], v[108:111]
	v_mfma_f32_16x16x32_bf16 v[104:107], v[164:167], v[188:191], v[104:107]
	v_mfma_f32_16x16x32_bf16 v[100:103], v[156:159], v[196:199], v[100:103]
	v_mfma_f32_16x16x32_bf16 v[96:99], v[164:167], v[196:199], v[96:99]
	v_mfma_f32_16x16x32_bf16 v[124:127], v[160:163], v[176:179], v[124:127]
	v_mfma_f32_16x16x32_bf16 v[120:123], v[168:171], v[176:179], v[120:123]
	v_mfma_f32_16x16x32_bf16 v[116:119], v[160:163], v[184:187], v[116:119]
	v_mfma_f32_16x16x32_bf16 v[112:115], v[168:171], v[184:187], v[112:115]
	v_mfma_f32_16x16x32_bf16 v[108:111], v[160:163], v[192:195], v[108:111]
	v_mfma_f32_16x16x32_bf16 v[104:107], v[168:171], v[192:195], v[104:107]
	v_mfma_f32_16x16x32_bf16 v[100:103], v[160:163], v[200:203], v[100:103]
	v_mfma_f32_16x16x32_bf16 v[96:99], v[168:171], v[200:203], v[96:99]
	s_barrier
	s_setprio 0
	ds_read_b128 v[204:207], v146 offset:49152
	ds_read_b128 v[212:215], v146 offset:50176
	ds_read_b128 v[216:219], v146 offset:51200
	ds_read_b128 v[220:223], v146 offset:52224
	s_add_u32 m0, s25, s52
	s_nop 0
	s_add_u32 vcc_lo, s28, s16
	s_addc_u32 vcc_hi, s29, s17
	global_load_lds_dwordx4 v134, vcc
	v_lshl_add_u64 v[230:231], v[228:229], 0, s[16:17]
	s_add_u32 m0, s25, s52
	s_add_u32 m0, m0, 0x2000
	s_nop 0
	global_load_lds_dwordx4 v130, vcc
	s_setprio 1
	s_barrier
	s_waitcnt lgkmcnt(0)
	v_mfma_f32_16x16x32_bf16 v[92:95], v[204:207], v[172:175], v[92:95]
	v_mfma_f32_16x16x32_bf16 v[88:91], v[216:219], v[172:175], v[88:91]
	v_mfma_f32_16x16x32_bf16 v[84:87], v[204:207], v[180:183], v[84:87]
	v_mfma_f32_16x16x32_bf16 v[80:83], v[216:219], v[180:183], v[80:83]
	v_mfma_f32_16x16x32_bf16 v[76:79], v[204:207], v[188:191], v[76:79]
	v_mfma_f32_16x16x32_bf16 v[72:75], v[216:219], v[188:191], v[72:75]
	v_mfma_f32_16x16x32_bf16 v[68:71], v[204:207], v[196:199], v[68:71]
	v_mfma_f32_16x16x32_bf16 v[64:67], v[216:219], v[196:199], v[64:67]
	v_mfma_f32_16x16x32_bf16 v[92:95], v[212:215], v[176:179], v[92:95]
	ds_read_b128 v[172:175], v145 offset:49152
	v_mfma_f32_16x16x32_bf16 v[88:91], v[220:223], v[176:179], v[88:91]
	v_mfma_f32_16x16x32_bf16 v[84:87], v[212:215], v[184:187], v[84:87]
	ds_read_b128 v[180:183], v145 offset:51200
	v_mfma_f32_16x16x32_bf16 v[80:83], v[220:223], v[184:187], v[80:83]
	v_mfma_f32_16x16x32_bf16 v[76:79], v[212:215], v[192:195], v[76:79]
	ds_read_b128 v[188:191], v145 offset:53248
	v_mfma_f32_16x16x32_bf16 v[72:75], v[220:223], v[192:195], v[72:75]
	v_mfma_f32_16x16x32_bf16 v[68:71], v[212:215], v[200:203], v[68:71]
	ds_read_b128 v[196:199], v145 offset:55296
	v_mfma_f32_16x16x32_bf16 v[64:67], v[220:223], v[200:203], v[64:67]
	s_barrier
	s_setprio 0
	ds_read_b128 v[176:179], v145 offset:50176
	ds_read_b128 v[184:187], v145 offset:52224
	ds_read_b128 v[192:195], v145 offset:54272
	ds_read_b128 v[200:203], v145 offset:56320
	s_add_u32 m0, s25, 0x8000
	s_nop 0
	s_add_u32 vcc_lo, s28, s18
	s_addc_u32 vcc_hi, s29, s19
	global_load_lds_dwordx4 v136, vcc
	v_lshl_add_u64 v[208:209], v[224:225], 0, s[18:19]
	s_add_u32 m0, s25, 0xa000
	s_nop 0
	global_load_lds_dwordx4 v132, vcc
	s_waitcnt vmcnt(8)
	s_setprio 1
	s_barrier
; #define WAIT_V(n) asm volatile("s_waitcnt vmcnt(" #n ")" ::: "memory")
; #define WAIT_L(n) asm volatile("s_waitcnt lgkmcnt(" #n ")" ::: "memory")
; #define BAR __builtin_amdgcn_s_barrier()
; #define SCHED __builtin_amdgcn_sched_barrier(0)
; #define STAGE(P, BASE, br, kt) do { const char* _g = (const char*)((BASE) + (size_t)(br) * GK + (kt) * BK); \
;     __builtin_amdgcn_global_load_lds((const unsigned*)(_g + voff0), (unsigned*)((char*)(P) + tx * 16), 16, 0, 0); \
;     __builtin_amdgcn_global_load_lds((const unsigned*)(_g + voff1), (unsigned*)((char*)(P) + tx * 16 + 8192), 16, 0, 0); } while (0)
; #define LDA(dst, b, h) _Pragma("unroll") for (int m = 0; m < 4; ++m) _Pragma("unroll") for (int k = 0; k < 2; ++k) \
;     dst[m][k] = *reinterpret_cast<const bf16x8*>((char*)shm + abase + (((b) * 2 + (h)) * 16384 + (m * 2 + k) * 1024))
; #define LDB(dst, b, h) _Pragma("unroll") for (int n = 0; n < 2; ++n) _Pragma("unroll") for (int k = 0; k < 2; ++k) \
;     dst[n][k] = *reinterpret_cast<const bf16x8*>((char*)shm + bbase + (((b) * 2 + (h)) * 16384 + (n * 2 + k) * 1024))
; template <bool SWAP>
; __device__ __forceinline__ void gemm_main(const u16* __restrict__ A, const u16* __restrict__ Bt, int brow, int bcol,
;                                           u16* shm, f32x4 (&acc)[2][2][4][2]) {
;     ...
;     LDA(At, 1, 1); STAGE(SA(1, 0), A, brow, t + 3);
;     BAR; WAIT_L(0); MMA(1, 0, At, B0); BAR; SCHED;
;     STAGE(SB(1, 1), Bt, bcol + HALF, t + 3);
;     WAIT_V(6); BAR; MMA(1, 1, At, B1); BAR;
;   }
;   { LDB(B0, 0, 0); LDA(At, 0, 0); STAGE(SA(1, 1), A, brow + HALF, nt - 1);
;     BAR; WAIT_L(0); MMA(0, 0, At, B0); BAR;
	s_waitcnt lgkmcnt(0)
	v_mfma_f32_16x16x32_bf16 v[60:63], v[156:159], v[172:175], v[60:63]
	v_mfma_f32_16x16x32_bf16 v[56:59], v[164:167], v[172:175], v[56:59]
	v_mfma_f32_16x16x32_bf16 v[52:55], v[156:159], v[180:183], v[52:55]
	v_mfma_f32_16x16x32_bf16 v[48:51], v[164:167], v[180:183], v[48:51]
	v_mfma_f32_16x16x32_bf16 v[44:47], v[156:159], v[188:191], v[44:47]
	v_mfma_f32_16x16x32_bf16 v[40:43], v[164:167], v[188:191], v[40:43]
	v_mfma_f32_16x16x32_bf16 v[36:39], v[156:159], v[196:199], v[36:39]
	v_mfma_f32_16x16x32_bf16 v[32:35], v[164:167], v[196:199], v[32:35]
	v_mfma_f32_16x16x32_bf16 v[60:63], v[160:163], v[176:179], v[60:63]
	v_mfma_f32_16x16x32_bf16 v[56:59], v[168:171], v[176:179], v[56:59]
	v_mfma_f32_16x16x32_bf16 v[52:55], v[160:163], v[184:187], v[52:55]
	v_mfma_f32_16x16x32_bf16 v[48:51], v[168:171], v[184:187], v[48:51]
	v_mfma_f32_16x16x32_bf16 v[44:47], v[160:163], v[192:195], v[44:47]
	v_mfma_f32_16x16x32_bf16 v[40:43], v[168:171], v[192:195], v[40:43]
	v_mfma_f32_16x16x32_bf16 v[36:39], v[160:163], v[200:203], v[36:39]
	v_mfma_f32_16x16x32_bf16 v[32:35], v[168:171], v[200:203], v[32:35]
	s_barrier
	s_setprio 0
	ds_read_b128 v[156:159], v146
	ds_read_b128 v[160:163], v146 offset:1024
	ds_read_b128 v[164:167], v146 offset:2048
	ds_read_b128 v[168:171], v146 offset:3072
	s_add_u32 m0, s25, s53
	s_nop 0
	s_add_u32 vcc_lo, s28, s20
	s_addc_u32 vcc_hi, s29, s21
	global_load_lds_dwordx4 v134, vcc
	v_lshl_add_u64 v[254:255], v[228:229], 0, s[20:21]
	s_add_u32 m0, s25, s53
	s_add_u32 m0, m0, 0x2000
	s_nop 0
	global_load_lds_dwordx4 v130, vcc
	s_setprio 1
	s_barrier
	v_mfma_f32_16x16x32_bf16 v[28:31], v[204:207], v[172:175], v[28:31]
	v_mfma_f32_16x16x32_bf16 v[24:27], v[216:219], v[172:175], v[24:27]
	v_mfma_f32_16x16x32_bf16 v[20:23], v[204:207], v[180:183], v[20:23]
	v_mfma_f32_16x16x32_bf16 v[16:19], v[216:219], v[180:183], v[16:19]
	v_mfma_f32_16x16x32_bf16 v[12:15], v[204:207], v[188:191], v[12:15]
	v_mfma_f32_16x16x32_bf16 v[8:11], v[216:219], v[188:191], v[8:11]
	v_mfma_f32_16x16x32_bf16 v[4:7], v[204:207], v[196:199], v[4:7]
	v_mfma_f32_16x16x32_bf16 v[0:3], v[216:219], v[196:199], v[0:3]
	v_mfma_f32_16x16x32_bf16 v[28:31], v[212:215], v[176:179], v[28:31]
	ds_read_b128 v[172:175], v145
	v_mfma_f32_16x16x32_bf16 v[24:27], v[220:223], v[176:179], v[24:27]
	v_mfma_f32_16x16x32_bf16 v[20:23], v[212:215], v[184:187], v[20:23]
	ds_read_b128 v[180:183], v145 offset:2048
	v_mfma_f32_16x16x32_bf16 v[16:19], v[220:223], v[184:187], v[16:19]
	v_mfma_f32_16x16x32_bf16 v[12:15], v[212:215], v[192:195], v[12:15]
	ds_read_b128 v[188:191], v145 offset:4096
	v_mfma_f32_16x16x32_bf16 v[8:11], v[220:223], v[192:195], v[8:11]
	v_mfma_f32_16x16x32_bf16 v[4:7], v[212:215], v[200:203], v[4:7]
	ds_read_b128 v[196:199], v145 offset:6144
	v_mfma_f32_16x16x32_bf16 v[0:3], v[220:223], v[200:203], v[0:3]
	s_add_i32 s4, s4, 2
	s_add_u32 s28, s28, 0x100
	s_addc_u32 s29, s29, 0
	s_cmp_lt_u32 s4, 28
	s_barrier
	s_setprio 0
	s_cbranch_scc1 .LBB0_94
	v_lshlrev_b32_e32 v128, 3, v148
	v_lshlrev_b32_e32 v130, 5, v148
	v_and_b32_e32 v128, 0xffff0, v128
	v_and_b32_e32 v130, 32, v130
	s_or_b32 s28, s26, 0x80
	v_add_u32_e32 v130, v130, v150
	v_add_lshl_u32 v128, v149, v128, 12
	s_ashr_i32 s29, s28, 31
	v_lshl_add_u32 v128, v130, 1, v128
	v_lshlrev_b32_e32 v130, 3, v151
	v_lshlrev_b32_e32 v131, 5, v151
	s_lshl_b64 s[28:29], s[28:29], 12
	v_and_b32_e32 v130, 0xffff0, v130
	v_and_b32_e32 v131, 32, v131
	s_add_u32 s28, s37, s28
	v_add_u32_e32 v131, v131, v153
	v_add_lshl_u32 v130, v152, v130, 12
	s_addc_u32 s29, s38, s29
	v_lshl_add_u32 v152, v131, 1, v130
	v_mov_b32_e32 v153, v129
	v_lshl_add_u64 v[192:193], s[28:29], 0, v[128:129]
	v_readfirstlane_b32 s4, v154
	v_lshl_add_u64 v[192:193], v[192:193], 0, s[22:23]
	s_mov_b32 m0, s4
	v_lshl_add_u64 v[152:153], s[28:29], 0, v[152:153]
	v_readfirstlane_b32 s4, v155
	ds_read_b128 v[130:133], v146
	ds_read_b128 v[134:137], v146 offset:1024
	ds_read_b128 v[148:151], v146 offset:2048
	ds_read_b128 v[156:159], v146 offset:3072
	ds_read_b128 v[160:163], v145
	ds_read_b128 v[164:167], v145 offset:1024
	ds_read_b128 v[168:171], v145 offset:2048
	ds_read_b128 v[172:175], v145 offset:3072
	ds_read_b128 v[176:179], v145 offset:4096
	ds_read_b128 v[180:183], v145 offset:5120
	ds_read_b128 v[184:187], v145 offset:6144
	ds_read_b128 v[188:191], v145 offset:7168
	global_load_lds_dwordx4 v[192:193], off
	v_lshl_add_u64 v[152:153], v[152:153], 0, s[22:23]
	s_mov_b32 m0, s4
	s_nop 0
	global_load_lds_dwordx4 v[152:153], off
	s_waitcnt vmcnt(8)
	s_barrier
	s_waitcnt lgkmcnt(0)
	s_setprio 1
	s_waitcnt lgkmcnt(0)
	v_mfma_f32_16x16x32_bf16 v[124:127], v[130:133], v[160:163], v[124:127]
	v_mfma_f32_16x16x32_bf16 v[116:119], v[130:133], v[168:171], v[116:119]
	v_mfma_f32_16x16x32_bf16 v[108:111], v[130:133], v[176:179], v[108:111]
	v_mfma_f32_16x16x32_bf16 v[100:103], v[130:133], v[184:187], v[100:103]
	v_mfma_f32_16x16x32_bf16 v[124:127], v[134:137], v[164:167], v[124:127]
	v_mfma_f32_16x16x32_bf16 v[120:123], v[148:151], v[160:163], v[120:123]
	v_mfma_f32_16x16x32_bf16 v[116:119], v[134:137], v[172:175], v[116:119]
	v_mfma_f32_16x16x32_bf16 v[112:115], v[148:151], v[168:171], v[112:115]
	v_mfma_f32_16x16x32_bf16 v[108:111], v[134:137], v[180:183], v[108:111]
	v_mfma_f32_16x16x32_bf16 v[104:107], v[148:151], v[176:179], v[104:107]
	v_mfma_f32_16x16x32_bf16 v[100:103], v[134:137], v[188:191], v[100:103]
	v_mfma_f32_16x16x32_bf16 v[96:99], v[148:151], v[184:187], v[96:99]
	v_mfma_f32_16x16x32_bf16 v[152:155], v[156:159], v[164:167], v[120:123]
	v_mfma_f32_16x16x32_bf16 v[192:195], v[156:159], v[172:175], v[112:115]
	v_mfma_f32_16x16x32_bf16 v[196:199], v[156:159], v[180:183], v[104:107]
	v_mfma_f32_16x16x32_bf16 v[200:203], v[156:159], v[188:191], v[96:99]
	s_setprio 0
	s_barrier
; #define WAIT_V(n) asm volatile("s_waitcnt vmcnt(" #n ")" ::: "memory")
; #define WAIT_L(n) asm volatile("s_waitcnt lgkmcnt(" #n ")" ::: "memory")
; #define BAR __builtin_amdgcn_s_barrier()
; #define LDA(dst, b, h) _Pragma("unroll") for (int m = 0; m < 4; ++m) _Pragma("unroll") for (int k = 0; k < 2; ++k) \
;     dst[m][k] = *reinterpret_cast<const bf16x8*>((char*)shm + abase + (((b) * 2 + (h)) * 16384 + (m * 2 + k) * 1024))
; #define LDB(dst, b, h) _Pragma("unroll") for (int n = 0; n < 2; ++n) _Pragma("unroll") for (int k = 0; k < 2; ++k) \
;     dst[n][k] = *reinterpret_cast<const bf16x8*>((char*)shm + bbase + (((b) * 2 + (h)) * 16384 + (n * 2 + k) * 1024))
; template <bool SWAP>
; __device__ __forceinline__ void gemm_main(const u16* __restrict__ A, const u16* __restrict__ Bt, int brow, int bcol,
;                                           u16* shm, f32x4 (&acc)[2][2][4][2]) {
;     ...
;     BAR; WAIT_L(0); MMA(0, 0, At, B0); BAR;
;     LDB(B1, 0, 1); BAR; WAIT_L(0); MMA(0, 1, At, B1); BAR;
;     LDA(At, 0, 1); WAIT_V(4); BAR; WAIT_L(0); MMA(1, 0, At, B0); MMA(1, 1, At, B1); BAR; }
;   { LDB(B0, 1, 0); LDA(At, 1, 0); WAIT_V(2); BAR; WAIT_L(0); MMA(0, 0, At, B0); BAR;
	s_nop 1
	ds_read_b128 v[96:99], v146 offset:16384
	ds_read_b128 v[104:107], v146 offset:17408
	ds_read_b128 v[112:115], v146 offset:18432
	ds_read_b128 v[120:123], v146 offset:19456
	s_barrier
	s_waitcnt lgkmcnt(0)
	s_setprio 1
	s_waitcnt lgkmcnt(0)
	v_mfma_f32_16x16x32_bf16 v[92:95], v[96:99], v[160:163], v[92:95]
	v_mfma_f32_16x16x32_bf16 v[84:87], v[96:99], v[168:171], v[84:87]
	v_mfma_f32_16x16x32_bf16 v[76:79], v[96:99], v[176:179], v[76:79]
	v_mfma_f32_16x16x32_bf16 v[68:71], v[96:99], v[184:187], v[68:71]
	v_mfma_f32_16x16x32_bf16 v[92:95], v[104:107], v[164:167], v[92:95]
	v_mfma_f32_16x16x32_bf16 v[88:91], v[112:115], v[160:163], v[88:91]
	v_mfma_f32_16x16x32_bf16 v[84:87], v[104:107], v[172:175], v[84:87]
	v_mfma_f32_16x16x32_bf16 v[80:83], v[112:115], v[168:171], v[80:83]
	v_mfma_f32_16x16x32_bf16 v[76:79], v[104:107], v[180:183], v[76:79]
	v_mfma_f32_16x16x32_bf16 v[72:75], v[112:115], v[176:179], v[72:75]
	v_mfma_f32_16x16x32_bf16 v[68:71], v[104:107], v[188:191], v[68:71]
	v_mfma_f32_16x16x32_bf16 v[64:67], v[112:115], v[184:187], v[64:67]
	v_mfma_f32_16x16x32_bf16 v[160:163], v[120:123], v[164:167], v[88:91]
	v_mfma_f32_16x16x32_bf16 v[164:167], v[120:123], v[172:175], v[80:83]
	v_mfma_f32_16x16x32_bf16 v[168:171], v[120:123], v[180:183], v[72:75]
	v_mfma_f32_16x16x32_bf16 v[172:175], v[120:123], v[188:191], v[64:67]
	s_setprio 0
	s_barrier
	s_nop 1
	ds_read_b128 v[64:67], v145 offset:16384
	ds_read_b128 v[72:75], v145 offset:17408
	ds_read_b128 v[80:83], v145 offset:18432
	ds_read_b128 v[88:91], v145 offset:19456
	ds_read_b128 v[176:179], v145 offset:20480
	ds_read_b128 v[180:183], v145 offset:21504
	ds_read_b128 v[184:187], v145 offset:22528
	ds_read_b128 v[188:191], v145 offset:23552
	s_waitcnt vmcnt(4)
	s_barrier
	s_waitcnt lgkmcnt(0)
	s_setprio 1
	s_waitcnt lgkmcnt(0)
	v_mfma_f32_16x16x32_bf16 v[60:63], v[130:133], v[64:67], v[60:63]
	v_mfma_f32_16x16x32_bf16 v[52:55], v[130:133], v[80:83], v[52:55]
	v_mfma_f32_16x16x32_bf16 v[44:47], v[130:133], v[176:179], v[44:47]
	v_mfma_f32_16x16x32_bf16 v[36:39], v[130:133], v[184:187], v[36:39]
	v_mfma_f32_16x16x32_bf16 v[60:63], v[134:137], v[72:75], v[60:63]
	v_mfma_f32_16x16x32_bf16 v[56:59], v[148:151], v[64:67], v[56:59]
	v_mfma_f32_16x16x32_bf16 v[52:55], v[134:137], v[88:91], v[52:55]
	v_mfma_f32_16x16x32_bf16 v[48:51], v[148:151], v[80:83], v[48:51]
	v_mfma_f32_16x16x32_bf16 v[44:47], v[134:137], v[180:183], v[44:47]
	v_mfma_f32_16x16x32_bf16 v[40:43], v[148:151], v[176:179], v[40:43]
	v_mfma_f32_16x16x32_bf16 v[36:39], v[134:137], v[188:191], v[36:39]
	v_mfma_f32_16x16x32_bf16 v[32:35], v[148:151], v[184:187], v[32:35]
	v_mfma_f32_16x16x32_bf16 v[204:207], v[156:159], v[72:75], v[56:59]
	v_mfma_f32_16x16x32_bf16 v[212:215], v[156:159], v[88:91], v[48:51]
	v_mfma_f32_16x16x32_bf16 v[216:219], v[156:159], v[180:183], v[40:43]
	v_mfma_f32_16x16x32_bf16 v[130:133], v[156:159], v[188:191], v[32:35]
	s_setprio 0
	s_setprio 1
	v_mfma_f32_16x16x32_bf16 v[28:31], v[96:99], v[64:67], v[28:31]
	v_mfma_f32_16x16x32_bf16 v[20:23], v[96:99], v[80:83], v[20:23]
	v_mfma_f32_16x16x32_bf16 v[12:15], v[96:99], v[176:179], v[12:15]
	v_mfma_f32_16x16x32_bf16 v[4:7], v[96:99], v[184:187], v[4:7]
	v_mfma_f32_16x16x32_bf16 v[28:31], v[104:107], v[72:75], v[28:31]
	v_mfma_f32_16x16x32_bf16 v[24:27], v[112:115], v[64:67], v[24:27]
	v_mfma_f32_16x16x32_bf16 v[20:23], v[104:107], v[88:91], v[20:23]
	v_mfma_f32_16x16x32_bf16 v[16:19], v[112:115], v[80:83], v[16:19]
	v_mfma_f32_16x16x32_bf16 v[12:15], v[104:107], v[180:183], v[12:15]
	v_mfma_f32_16x16x32_bf16 v[8:11], v[112:115], v[176:179], v[8:11]
	v_mfma_f32_16x16x32_bf16 v[4:7], v[104:107], v[188:191], v[4:7]
	v_mfma_f32_16x16x32_bf16 v[0:3], v[112:115], v[184:187], v[0:3]
	v_mfma_f32_16x16x32_bf16 v[134:137], v[120:123], v[72:75], v[24:27]
	v_mfma_f32_16x16x32_bf16 v[148:151], v[120:123], v[88:91], v[16:19]
	v_mfma_f32_16x16x32_bf16 v[156:159], v[120:123], v[180:183], v[8:11]
	v_mfma_f32_16x16x32_bf16 v[176:179], v[120:123], v[188:191], v[0:3]
	s_setprio 0
	s_barrier
	s_nop 1
	ds_read_b128 v[0:3], v146 offset:32768
	ds_read_b128 v[8:11], v146 offset:33792
	ds_read_b128 v[16:19], v146 offset:34816
	ds_read_b128 v[24:27], v146 offset:35840
	ds_read_b128 v[32:35], v145 offset:32768
	ds_read_b128 v[40:43], v145 offset:33792
	ds_read_b128 v[48:51], v145 offset:34816
	ds_read_b128 v[56:59], v145 offset:35840
	ds_read_b128 v[64:67], v145 offset:36864
	ds_read_b128 v[180:183], v145 offset:37888
	ds_read_b128 v[184:187], v145 offset:38912
	ds_read_b128 v[188:191], v145 offset:39936
	s_waitcnt vmcnt(2)
	s_barrier
; #define WAIT_V(n) asm volatile("s_waitcnt vmcnt(" #n ")" ::: "memory")
; #define WAIT_L(n) asm volatile("s_waitcnt lgkmcnt(" #n ")" ::: "memory")
; #define BAR __builtin_amdgcn_s_barrier()
; #define LDA(dst, b, h) _Pragma("unroll") for (int m = 0; m < 4; ++m) _Pragma("unroll") for (int k = 0; k < 2; ++k) \
;     dst[m][k] = *reinterpret_cast<const bf16x8*>((char*)shm + abase + (((b) * 2 + (h)) * 16384 + (m * 2 + k) * 1024))
; #define LDB(dst, b, h) _Pragma("unroll") for (int n = 0; n < 2; ++n) _Pragma("unroll") for (int k = 0; k < 2; ++k) \
;     dst[n][k] = *reinterpret_cast<const bf16x8*>((char*)shm + bbase + (((b) * 2 + (h)) * 16384 + (n * 2 + k) * 1024))
; template <bool SWAP>
; __device__ __forceinline__ void gemm_main(const u16* __restrict__ A, const u16* __restrict__ Bt, int brow, int bcol,
;                                           u16* shm, f32x4 (&acc)[2][2][4][2]) {
;     ...
;   { LDB(B0, 1, 0); LDA(At, 1, 0); WAIT_V(2); BAR; WAIT_L(0); MMA(0, 0, At, B0); BAR;
;     LDB(B1, 1, 1); WAIT_V(0); BAR; WAIT_L(0); MMA(0, 1, At, B1); BAR;
;     LDA(At, 1, 1); BAR; WAIT_L(0); MMA(1, 0, At, B0); MMA(1, 1, At, B1); BAR; }
;   if (wr == 0) BAR;
	s_waitcnt lgkmcnt(0)
	s_setprio 1
	s_waitcnt lgkmcnt(0)
	v_mfma_f32_16x16x32_bf16 v[72:75], v[0:3], v[32:35], v[124:127]
	v_mfma_f32_16x16x32_bf16 v[120:123], v[8:11], v[40:43], v[72:75]
	v_mfma_f32_16x16x32_bf16 v[72:75], v[16:19], v[32:35], v[152:155]
	v_mfma_f32_16x16x32_bf16 v[124:127], v[24:27], v[40:43], v[72:75]
	v_mfma_f32_16x16x32_bf16 v[72:75], v[0:3], v[48:51], v[116:119]
	v_mfma_f32_16x16x32_bf16 v[112:115], v[8:11], v[56:59], v[72:75]
	v_mfma_f32_16x16x32_bf16 v[72:75], v[16:19], v[48:51], v[192:195]
	v_mfma_f32_16x16x32_bf16 v[116:119], v[24:27], v[56:59], v[72:75]
	v_mfma_f32_16x16x32_bf16 v[72:75], v[0:3], v[64:67], v[108:111]
	v_mfma_f32_16x16x32_bf16 v[104:107], v[8:11], v[180:183], v[72:75]
	v_mfma_f32_16x16x32_bf16 v[72:75], v[16:19], v[64:67], v[196:199]
	v_mfma_f32_16x16x32_bf16 v[108:111], v[24:27], v[180:183], v[72:75]
	v_mfma_f32_16x16x32_bf16 v[72:75], v[0:3], v[184:187], v[100:103]
	v_mfma_f32_16x16x32_bf16 v[96:99], v[8:11], v[188:191], v[72:75]
	v_mfma_f32_16x16x32_bf16 v[72:75], v[16:19], v[184:187], v[200:203]
	v_mfma_f32_16x16x32_bf16 v[100:103], v[24:27], v[188:191], v[72:75]
	s_setprio 0
	s_barrier
	ds_read_b128 v[152:155], v146 offset:49152
	ds_read_b128 v[192:195], v146 offset:50176
	ds_read_b128 v[196:199], v146 offset:51200
	ds_read_b128 v[200:203], v146 offset:52224
	s_waitcnt vmcnt(0)
	s_barrier
	s_waitcnt lgkmcnt(0)
	s_setprio 1
	s_waitcnt lgkmcnt(0)
	v_mfma_f32_16x16x32_bf16 v[72:75], v[152:155], v[32:35], v[92:95]
	v_mfma_f32_16x16x32_bf16 v[32:35], v[196:199], v[32:35], v[160:163]
	v_mfma_f32_16x16x32_bf16 v[92:95], v[200:203], v[40:43], v[32:35]
	v_mfma_f32_16x16x32_bf16 v[32:35], v[152:155], v[48:51], v[84:87]
	v_mfma_f32_16x16x32_bf16 v[80:83], v[192:195], v[56:59], v[32:35]
	v_mfma_f32_16x16x32_bf16 v[32:35], v[196:199], v[48:51], v[164:167]
	v_mfma_f32_16x16x32_bf16 v[84:87], v[200:203], v[56:59], v[32:35]
	v_mfma_f32_16x16x32_bf16 v[32:35], v[152:155], v[64:67], v[76:79]
	v_mfma_f32_16x16x32_bf16 v[88:91], v[192:195], v[40:43], v[72:75]
	v_mfma_f32_16x16x32_bf16 v[72:75], v[192:195], v[180:183], v[32:35]
	v_mfma_f32_16x16x32_bf16 v[32:35], v[196:199], v[64:67], v[168:171]
	v_mfma_f32_16x16x32_bf16 v[76:79], v[200:203], v[180:183], v[32:35]
	v_mfma_f32_16x16x32_bf16 v[32:35], v[152:155], v[184:187], v[68:71]
	v_mfma_f32_16x16x32_bf16 v[64:67], v[192:195], v[188:191], v[32:35]
	v_mfma_f32_16x16x32_bf16 v[32:35], v[196:199], v[184:187], v[172:175]
	v_mfma_f32_16x16x32_bf16 v[68:71], v[200:203], v[188:191], v[32:35]
	s_setprio 0
	s_barrier
	ds_read_b128 v[160:163], v145 offset:49152
	ds_read_b128 v[164:167], v145 offset:50176
	ds_read_b128 v[168:171], v145 offset:51200
	ds_read_b128 v[172:175], v145 offset:52224
	ds_read_b128 v[180:183], v145 offset:53248
	ds_read_b128 v[184:187], v145 offset:54272
	ds_read_b128 v[188:191], v145 offset:55296
	ds_read_b128 v[220:223], v145 offset:56320
	s_barrier
	s_waitcnt lgkmcnt(0)
	s_setprio 1
	s_waitcnt lgkmcnt(0)
	v_mfma_f32_16x16x32_bf16 v[32:35], v[0:3], v[160:163], v[60:63]
	v_mfma_f32_16x16x32_bf16 v[56:59], v[8:11], v[164:167], v[32:35]
	v_mfma_f32_16x16x32_bf16 v[32:35], v[16:19], v[160:163], v[204:207]
	v_mfma_f32_16x16x32_bf16 v[60:63], v[24:27], v[164:167], v[32:35]
	v_mfma_f32_16x16x32_bf16 v[32:35], v[0:3], v[168:171], v[52:55]
	v_mfma_f32_16x16x32_bf16 v[48:51], v[8:11], v[172:175], v[32:35]
	v_mfma_f32_16x16x32_bf16 v[32:35], v[16:19], v[168:171], v[212:215]
	v_mfma_f32_16x16x32_bf16 v[52:55], v[24:27], v[172:175], v[32:35]
	v_mfma_f32_16x16x32_bf16 v[32:35], v[0:3], v[180:183], v[44:47]
	v_mfma_f32_16x16x32_bf16 v[40:43], v[8:11], v[184:187], v[32:35]
	v_mfma_f32_16x16x32_bf16 v[32:35], v[16:19], v[180:183], v[216:219]
	v_mfma_f32_16x16x32_bf16 v[0:3], v[0:3], v[188:191], v[36:39]
	v_mfma_f32_16x16x32_bf16 v[44:47], v[24:27], v[184:187], v[32:35]
	v_mfma_f32_16x16x32_bf16 v[32:35], v[8:11], v[220:223], v[0:3]
	v_mfma_f32_16x16x32_bf16 v[0:3], v[16:19], v[188:191], v[130:133]
	v_mfma_f32_16x16x32_bf16 v[36:39], v[24:27], v[220:223], v[0:3]
	s_setprio 0
	s_setprio 1
	v_mfma_f32_16x16x32_bf16 v[0:3], v[152:155], v[160:163], v[28:31]
	v_mfma_f32_16x16x32_bf16 v[24:27], v[192:195], v[164:167], v[0:3]
	v_mfma_f32_16x16x32_bf16 v[0:3], v[196:199], v[160:163], v[134:137]
	v_mfma_f32_16x16x32_bf16 v[28:31], v[200:203], v[164:167], v[0:3]
	v_mfma_f32_16x16x32_bf16 v[0:3], v[152:155], v[168:171], v[20:23]
	v_mfma_f32_16x16x32_bf16 v[16:19], v[192:195], v[172:175], v[0:3]
	v_mfma_f32_16x16x32_bf16 v[0:3], v[196:199], v[168:171], v[148:151]
	v_mfma_f32_16x16x32_bf16 v[20:23], v[200:203], v[172:175], v[0:3]
	v_mfma_f32_16x16x32_bf16 v[0:3], v[152:155], v[180:183], v[12:15]
	v_mfma_f32_16x16x32_bf16 v[8:11], v[192:195], v[184:187], v[0:3]
	v_mfma_f32_16x16x32_bf16 v[0:3], v[196:199], v[180:183], v[156:159]
	v_mfma_f32_16x16x32_bf16 v[12:15], v[200:203], v[184:187], v[0:3]
	v_mfma_f32_16x16x32_bf16 v[0:3], v[152:155], v[188:191], v[4:7]
	v_mfma_f32_16x16x32_bf16 v[4:7], v[196:199], v[188:191], v[176:179]
	v_mfma_f32_16x16x32_bf16 v[0:3], v[192:195], v[220:223], v[0:3]
	v_mfma_f32_16x16x32_bf16 v[4:7], v[200:203], v[220:223], v[4:7]
	s_setprio 0
	v_cmp_gt_u32_e32 vcc, s55, v144
	s_barrier
	s_and_saveexec_b64 s[28:29], vcc
	s_cbranch_execz .LBB0_97
	s_barrier

; #define WAIT_V(n) asm volatile("s_waitcnt vmcnt(" #n ")" ::: "memory")
; #define WAIT_L(n) asm volatile("s_waitcnt lgkmcnt(" #n ")" ::: "memory")
; #define BAR __builtin_amdgcn_s_barrier()
; #define SCHED __builtin_amdgcn_sched_barrier(0)
; #define STAGE(P, BASE, br, kt) do { const char* _g = (const char*)((BASE) + (size_t)(br) * GK + (kt) * BK); \
;     __builtin_amdgcn_global_load_lds((const unsigned*)(_g + voff0), (unsigned*)((char*)(P) + tx * 16), 16, 0, 0); \
;     __builtin_amdgcn_global_load_lds((const unsigned*)(_g + voff1), (unsigned*)((char*)(P) + tx * 16 + 8192), 16, 0, 0); } while (0)
; #define LDA(dst, b, h) _Pragma("unroll") for (int m = 0; m < 4; ++m) _Pragma("unroll") for (int k = 0; k < 2; ++k) \
;     dst[m][k] = *reinterpret_cast<const bf16x8*>((char*)shm + abase + (((b) * 2 + (h)) * 16384 + (m * 2 + k) * 1024))
; #define LDB(dst, b, h) _Pragma("unroll") for (int n = 0; n < 2; ++n) _Pragma("unroll") for (int k = 0; k < 2; ++k) \
;     dst[n][k] = *reinterpret_cast<const bf16x8*>((char*)shm + bbase + (((b) * 2 + (h)) * 16384 + (n * 2 + k) * 1024))
; template <bool SWAP>
; __device__ __forceinline__ void gemm_main(const u16* __restrict__ A, const u16* __restrict__ Bt, int brow, int bcol,
;                                           u16* shm, f32x4 (&acc)[2][2][4][2]) {
;     ...
;     LDB(B0, 0, 0); SCHED; LDA(At, 0, 0); STAGE(SA(1, 1), A, brow + HALF, t + 1);
;     WAIT_L(8); BAR; WAIT_L(0); MMA(0, 0, At, B0); BAR; SCHED;
;     LDB(B1, 0, 1); STAGE(SB(0, 0), Bt, bcol, t + 2);
;     BAR; WAIT_L(0); MMA(0, 1, At, B1); BAR;
;     LDA(At, 0, 1); STAGE(SA(0, 0), A, brow, t + 2);
;     BAR; WAIT_L(0); MMA(1, 0, At, B0); BAR; SCHED;
;     STAGE(SB(0, 1), Bt, bcol + HALF, t + 2);
;     WAIT_V(6); BAR; MMA(1, 1, At, B1); BAR;
.LBB0_114:
	ds_read_b128 v[182:185], v137 offset:1024
	ds_read_b128 v[194:197], v137 offset:3072
	ds_read_b128 v[202:205], v137 offset:5120
	ds_read_b128 v[222:225], v137 offset:7168
	v_add_u32_e32 v192, 0, v153
	v_add_u32_e32 v160, 0xc000, v192
	v_add_u32_e32 v161, 0xe000, v192
	s_add_u32 m0, s4, 0xc000
	v_lshl_add_u64 v[242:243], s[0:1], 0, v[134:135]
	s_add_u32 vcc_lo, s0, s82
	s_addc_u32 vcc_hi, s1, s83
	global_load_lds_dwordx4 v132, vcc
	s_add_u32 m0, s4, 0xe000
	s_nop 0
	global_load_lds_dwordx4 v134, vcc
	s_waitcnt lgkmcnt(8)
	s_waitcnt vmcnt(8)
	s_setprio 1
	s_barrier
	s_waitcnt lgkmcnt(0)
	v_mfma_f32_16x16x32_bf16 v[124:127], v[178:181], v[162:165], v[124:127]
	v_mfma_f32_16x16x32_bf16 v[120:123], v[178:181], v[170:173], v[120:123]
	v_mfma_f32_16x16x32_bf16 v[116:119], v[186:189], v[162:165], v[116:119]
	v_mfma_f32_16x16x32_bf16 v[112:115], v[186:189], v[170:173], v[112:115]
	v_mfma_f32_16x16x32_bf16 v[108:111], v[198:201], v[162:165], v[108:111]
	v_mfma_f32_16x16x32_bf16 v[104:107], v[198:201], v[170:173], v[104:107]
	v_mfma_f32_16x16x32_bf16 v[100:103], v[206:209], v[162:165], v[100:103]
	v_mfma_f32_16x16x32_bf16 v[96:99], v[206:209], v[170:173], v[96:99]
	v_mfma_f32_16x16x32_bf16 v[124:127], v[182:185], v[166:169], v[124:127]
	v_mfma_f32_16x16x32_bf16 v[120:123], v[182:185], v[174:177], v[120:123]
	v_mfma_f32_16x16x32_bf16 v[116:119], v[194:197], v[166:169], v[116:119]
	v_mfma_f32_16x16x32_bf16 v[112:115], v[194:197], v[174:177], v[112:115]
	v_mfma_f32_16x16x32_bf16 v[108:111], v[202:205], v[166:169], v[108:111]
	v_mfma_f32_16x16x32_bf16 v[104:107], v[202:205], v[174:177], v[104:107]
	v_mfma_f32_16x16x32_bf16 v[100:103], v[222:225], v[166:169], v[100:103]
	v_mfma_f32_16x16x32_bf16 v[96:99], v[222:225], v[174:177], v[96:99]
	s_barrier
	s_setprio 0
	ds_read_b128 v[226:229], v152 offset:16384
	ds_read_b128 v[230:233], v152 offset:17408
	ds_read_b128 v[234:237], v152 offset:18432
	ds_read_b128 v[238:241], v152 offset:19456
	v_lshl_add_u64 v[244:245], s[0:1], 0, v[128:129]
	s_add_u32 m0, s4, s28
	s_nop 0
	s_add_u32 vcc_lo, s0, s74
	s_addc_u32 vcc_hi, s1, s75
	global_load_lds_dwordx4 v128, vcc
	v_lshl_add_u64 v[246:247], s[0:1], 0, v[130:131]
	s_add_u32 m0, s4, s28
	s_add_u32 m0, m0, 0x2000
	s_nop 0
	global_load_lds_dwordx4 v130, vcc
	s_setprio 1
	s_barrier
	s_waitcnt lgkmcnt(0)
	v_mfma_f32_16x16x32_bf16 v[92:95], v[178:181], v[226:229], v[92:95]
	v_mfma_f32_16x16x32_bf16 v[88:91], v[178:181], v[234:237], v[88:91]
	v_mfma_f32_16x16x32_bf16 v[84:87], v[186:189], v[226:229], v[84:87]
	v_mfma_f32_16x16x32_bf16 v[80:83], v[186:189], v[234:237], v[80:83]
	v_mfma_f32_16x16x32_bf16 v[76:79], v[198:201], v[226:229], v[76:79]
	v_mfma_f32_16x16x32_bf16 v[72:75], v[198:201], v[234:237], v[72:75]
	v_mfma_f32_16x16x32_bf16 v[68:71], v[206:209], v[226:229], v[68:71]
	v_mfma_f32_16x16x32_bf16 v[64:67], v[206:209], v[234:237], v[64:67]
	v_mfma_f32_16x16x32_bf16 v[92:95], v[182:185], v[230:233], v[92:95]
	ds_read_b128 v[178:181], v137 offset:16384
	v_mfma_f32_16x16x32_bf16 v[88:91], v[182:185], v[238:241], v[88:91]
	v_mfma_f32_16x16x32_bf16 v[84:87], v[194:197], v[230:233], v[84:87]
	ds_read_b128 v[186:189], v137 offset:18432
	v_mfma_f32_16x16x32_bf16 v[80:83], v[194:197], v[238:241], v[80:83]
	v_mfma_f32_16x16x32_bf16 v[76:79], v[202:205], v[230:233], v[76:79]
	ds_read_b128 v[198:201], v137 offset:20480
	v_mfma_f32_16x16x32_bf16 v[72:75], v[202:205], v[238:241], v[72:75]
	v_mfma_f32_16x16x32_bf16 v[68:71], v[222:225], v[230:233], v[68:71]
	ds_read_b128 v[206:209], v137 offset:22528
	v_mfma_f32_16x16x32_bf16 v[64:67], v[222:225], v[238:241], v[64:67]
	s_barrier
	s_setprio 0
	ds_read_b128 v[182:185], v137 offset:17408
	ds_read_b128 v[194:197], v137 offset:19456
	ds_read_b128 v[202:205], v137 offset:21504
	ds_read_b128 v[222:225], v137 offset:23552
	s_add_u32 m0, s4, 0x0
	s_nop 0
	s_add_u32 vcc_lo, s0, s76
	s_addc_u32 vcc_hi, s1, s77
	global_load_lds_dwordx4 v132, vcc
	s_add_u32 m0, s4, 0x2000
	s_nop 0
	global_load_lds_dwordx4 v134, vcc
	s_waitcnt vmcnt(8)
	s_setprio 1
	s_barrier
	s_waitcnt lgkmcnt(0)
	v_mfma_f32_16x16x32_bf16 v[60:63], v[178:181], v[162:165], v[60:63]
	v_mfma_f32_16x16x32_bf16 v[56:59], v[178:181], v[170:173], v[56:59]
	v_mfma_f32_16x16x32_bf16 v[52:55], v[186:189], v[162:165], v[52:55]
	v_mfma_f32_16x16x32_bf16 v[48:51], v[186:189], v[170:173], v[48:51]
	v_mfma_f32_16x16x32_bf16 v[44:47], v[198:201], v[162:165], v[44:47]
	v_mfma_f32_16x16x32_bf16 v[40:43], v[198:201], v[170:173], v[40:43]
	v_mfma_f32_16x16x32_bf16 v[36:39], v[206:209], v[162:165], v[36:39]
	v_mfma_f32_16x16x32_bf16 v[32:35], v[206:209], v[170:173], v[32:35]
	v_mfma_f32_16x16x32_bf16 v[60:63], v[182:185], v[166:169], v[60:63]
	v_mfma_f32_16x16x32_bf16 v[56:59], v[182:185], v[174:177], v[56:59]
	v_mfma_f32_16x16x32_bf16 v[52:55], v[194:197], v[166:169], v[52:55]
	v_mfma_f32_16x16x32_bf16 v[48:51], v[194:197], v[174:177], v[48:51]
	v_mfma_f32_16x16x32_bf16 v[44:47], v[202:205], v[166:169], v[44:47]
	v_mfma_f32_16x16x32_bf16 v[40:43], v[202:205], v[174:177], v[40:43]
	v_mfma_f32_16x16x32_bf16 v[36:39], v[222:225], v[166:169], v[36:39]
	v_mfma_f32_16x16x32_bf16 v[32:35], v[222:225], v[174:177], v[32:35]
	s_barrier
	s_setprio 0
	ds_read_b128 v[162:165], v152 offset:32768
	ds_read_b128 v[166:169], v152 offset:33792
	ds_read_b128 v[170:173], v152 offset:34816
	ds_read_b128 v[174:177], v152 offset:35840
	s_add_u32 m0, s4, s29
	s_nop 0
	s_add_u32 vcc_lo, s0, s70
	s_addc_u32 vcc_hi, s1, s71
	global_load_lds_dwordx4 v128, vcc
	s_add_u32 m0, s4, s29
	s_add_u32 m0, m0, 0x2000
	s_nop 0
	global_load_lds_dwordx4 v130, vcc
	s_setprio 1
	s_barrier
; #define WAIT_V(n) asm volatile("s_waitcnt vmcnt(" #n ")" ::: "memory")
; #define WAIT_L(n) asm volatile("s_waitcnt lgkmcnt(" #n ")" ::: "memory")
; #define BAR __builtin_amdgcn_s_barrier()
; #define SCHED __builtin_amdgcn_sched_barrier(0)
; #define STAGE(P, BASE, br, kt) do { const char* _g = (const char*)((BASE) + (size_t)(br) * GK + (kt) * BK); \
;     __builtin_amdgcn_global_load_lds((const unsigned*)(_g + voff0), (unsigned*)((char*)(P) + tx * 16), 16, 0, 0); \
;     __builtin_amdgcn_global_load_lds((const unsigned*)(_g + voff1), (unsigned*)((char*)(P) + tx * 16 + 8192), 16, 0, 0); } while (0)
; #define LDA(dst, b, h) _Pragma("unroll") for (int m = 0; m < 4; ++m) _Pragma("unroll") for (int k = 0; k < 2; ++k) \
;     dst[m][k] = *reinterpret_cast<const bf16x8*>((char*)shm + abase + (((b) * 2 + (h)) * 16384 + (m * 2 + k) * 1024))
; #define LDB(dst, b, h) _Pragma("unroll") for (int n = 0; n < 2; ++n) _Pragma("unroll") for (int k = 0; k < 2; ++k) \
;     dst[n][k] = *reinterpret_cast<const bf16x8*>((char*)shm + bbase + (((b) * 2 + (h)) * 16384 + (n * 2 + k) * 1024))
; template <bool SWAP>
; __device__ __forceinline__ void gemm_main(const u16* __restrict__ A, const u16* __restrict__ Bt, int brow, int bcol,
;                                           u16* shm, f32x4 (&acc)[2][2][4][2]) {
;     ...
;     STAGE(SB(0, 1), Bt, bcol + HALF, t + 2);
;     WAIT_V(6); BAR; MMA(1, 1, At, B1); BAR;
;     LDB(B0, 1, 0); SCHED; LDA(At, 1, 0); STAGE(SA(0, 1), A, brow + HALF, t + 2);
;     WAIT_L(8); BAR; WAIT_L(0); MMA(0, 0, At, B0); BAR; SCHED;
;     LDB(B1, 1, 1); STAGE(SB(1, 0), Bt, bcol, t + 3);
;     BAR; WAIT_L(0); MMA(0, 1, At, B1); BAR;
	v_mfma_f32_16x16x32_bf16 v[28:31], v[178:181], v[226:229], v[28:31]
	v_mfma_f32_16x16x32_bf16 v[24:27], v[178:181], v[234:237], v[24:27]
	v_mfma_f32_16x16x32_bf16 v[20:23], v[186:189], v[226:229], v[20:23]
	v_mfma_f32_16x16x32_bf16 v[16:19], v[186:189], v[234:237], v[16:19]
	v_mfma_f32_16x16x32_bf16 v[12:15], v[198:201], v[226:229], v[12:15]
	v_mfma_f32_16x16x32_bf16 v[8:11], v[198:201], v[234:237], v[8:11]
	v_mfma_f32_16x16x32_bf16 v[4:7], v[206:209], v[226:229], v[4:7]
	v_mfma_f32_16x16x32_bf16 v[0:3], v[206:209], v[234:237], v[0:3]
	v_mfma_f32_16x16x32_bf16 v[28:31], v[182:185], v[230:233], v[28:31]
	ds_read_b128 v[178:181], v137 offset:32768
	v_mfma_f32_16x16x32_bf16 v[24:27], v[182:185], v[238:241], v[24:27]
	v_mfma_f32_16x16x32_bf16 v[20:23], v[194:197], v[230:233], v[20:23]
	ds_read_b128 v[186:189], v137 offset:34816
	v_mfma_f32_16x16x32_bf16 v[16:19], v[194:197], v[238:241], v[16:19]
	v_mfma_f32_16x16x32_bf16 v[12:15], v[202:205], v[230:233], v[12:15]
	ds_read_b128 v[198:201], v137 offset:36864
	v_mfma_f32_16x16x32_bf16 v[8:11], v[202:205], v[238:241], v[8:11]
	v_mfma_f32_16x16x32_bf16 v[4:7], v[222:225], v[230:233], v[4:7]
	ds_read_b128 v[206:209], v137 offset:38912
	v_mfma_f32_16x16x32_bf16 v[0:3], v[222:225], v[238:241], v[0:3]
	s_barrier
	s_setprio 0
	ds_read_b128 v[182:185], v137 offset:33792
	ds_read_b128 v[194:197], v137 offset:35840
	ds_read_b128 v[202:205], v137 offset:37888
	ds_read_b128 v[222:225], v137 offset:39936
	s_add_u32 m0, s4, 0x4000
	s_nop 0
	s_add_u32 vcc_lo, s0, s96
	s_addc_u32 vcc_hi, s1, s97
	global_load_lds_dwordx4 v132, vcc
	s_add_u32 m0, s4, 0x6000
	s_nop 0
	global_load_lds_dwordx4 v134, vcc
	s_waitcnt lgkmcnt(8)
	s_waitcnt vmcnt(8)
	s_setprio 1
	s_barrier
	s_waitcnt lgkmcnt(0)
	v_mfma_f32_16x16x32_bf16 v[124:127], v[178:181], v[162:165], v[124:127]
	v_mfma_f32_16x16x32_bf16 v[120:123], v[178:181], v[170:173], v[120:123]
	v_mfma_f32_16x16x32_bf16 v[116:119], v[186:189], v[162:165], v[116:119]
	v_mfma_f32_16x16x32_bf16 v[112:115], v[186:189], v[170:173], v[112:115]
	v_mfma_f32_16x16x32_bf16 v[108:111], v[198:201], v[162:165], v[108:111]
	v_mfma_f32_16x16x32_bf16 v[104:107], v[198:201], v[170:173], v[104:107]
	v_mfma_f32_16x16x32_bf16 v[100:103], v[206:209], v[162:165], v[100:103]
	v_mfma_f32_16x16x32_bf16 v[96:99], v[206:209], v[170:173], v[96:99]
	v_mfma_f32_16x16x32_bf16 v[124:127], v[182:185], v[166:169], v[124:127]
	v_mfma_f32_16x16x32_bf16 v[120:123], v[182:185], v[174:177], v[120:123]
	v_mfma_f32_16x16x32_bf16 v[116:119], v[194:197], v[166:169], v[116:119]
	v_mfma_f32_16x16x32_bf16 v[112:115], v[194:197], v[174:177], v[112:115]
	v_mfma_f32_16x16x32_bf16 v[108:111], v[202:205], v[166:169], v[108:111]
	v_mfma_f32_16x16x32_bf16 v[104:107], v[202:205], v[174:177], v[104:107]
	v_mfma_f32_16x16x32_bf16 v[100:103], v[222:225], v[166:169], v[100:103]
	v_mfma_f32_16x16x32_bf16 v[96:99], v[222:225], v[174:177], v[96:99]
	s_barrier
	s_setprio 0
	ds_read_b128 v[226:229], v152 offset:49152
	ds_read_b128 v[230:233], v152 offset:50176
	ds_read_b128 v[234:237], v152 offset:51200
	ds_read_b128 v[238:241], v152 offset:52224
	v_add_u32_e32 v250, s30, v153
	v_add_u32_e32 v250, 0x2000, v250
	s_add_u32 m0, s4, s30
	s_nop 0
	s_add_u32 vcc_lo, s0, s34
	s_addc_u32 vcc_hi, s1, s35
	global_load_lds_dwordx4 v128, vcc
	v_lshl_add_u64 v[248:249], v[246:247], 0, s[34:35]
	s_add_u32 m0, s4, s30
	s_add_u32 m0, m0, 0x2000
	s_nop 0
	global_load_lds_dwordx4 v130, vcc
	s_setprio 1
	s_barrier
	s_waitcnt lgkmcnt(0)
	v_mfma_f32_16x16x32_bf16 v[92:95], v[178:181], v[226:229], v[92:95]
	v_mfma_f32_16x16x32_bf16 v[88:91], v[178:181], v[234:237], v[88:91]
	v_mfma_f32_16x16x32_bf16 v[84:87], v[186:189], v[226:229], v[84:87]
	v_mfma_f32_16x16x32_bf16 v[80:83], v[186:189], v[234:237], v[80:83]
	v_mfma_f32_16x16x32_bf16 v[76:79], v[198:201], v[226:229], v[76:79]
	v_mfma_f32_16x16x32_bf16 v[72:75], v[198:201], v[234:237], v[72:75]
	v_mfma_f32_16x16x32_bf16 v[68:71], v[206:209], v[226:229], v[68:71]
	v_mfma_f32_16x16x32_bf16 v[64:67], v[206:209], v[234:237], v[64:67]
	v_mfma_f32_16x16x32_bf16 v[92:95], v[182:185], v[230:233], v[92:95]
	ds_read_b128 v[178:181], v137 offset:49152
	v_mfma_f32_16x16x32_bf16 v[88:91], v[182:185], v[238:241], v[88:91]
	v_mfma_f32_16x16x32_bf16 v[84:87], v[194:197], v[230:233], v[84:87]
	ds_read_b128 v[186:189], v137 offset:51200
	v_mfma_f32_16x16x32_bf16 v[80:83], v[194:197], v[238:241], v[80:83]
	v_mfma_f32_16x16x32_bf16 v[76:79], v[202:205], v[230:233], v[76:79]
	ds_read_b128 v[198:201], v137 offset:53248
	v_mfma_f32_16x16x32_bf16 v[72:75], v[202:205], v[238:241], v[72:75]
	v_mfma_f32_16x16x32_bf16 v[68:71], v[222:225], v[230:233], v[68:71]
	ds_read_b128 v[206:209], v137 offset:55296
	v_mfma_f32_16x16x32_bf16 v[64:67], v[222:225], v[238:241], v[64:67]
	s_barrier
	s_setprio 0
	ds_read_b128 v[182:185], v137 offset:50176
	ds_read_b128 v[194:197], v137 offset:52224
	ds_read_b128 v[202:205], v137 offset:54272
	ds_read_b128 v[222:225], v137 offset:56320
	v_add_u32_e32 v248, 0x8000, v192
	s_add_u32 m0, s4, 0x8000
	s_nop 0
	s_add_u32 vcc_lo, s0, s36
	s_addc_u32 vcc_hi, s1, s37
	global_load_lds_dwordx4 v132, vcc
	s_add_u32 m0, s4, 0xa000
	s_nop 0
	global_load_lds_dwordx4 v134, vcc
	s_waitcnt vmcnt(8)
	s_setprio 1
	s_barrier
; #define WAIT_V(n) asm volatile("s_waitcnt vmcnt(" #n ")" ::: "memory")
; #define WAIT_L(n) asm volatile("s_waitcnt lgkmcnt(" #n ")" ::: "memory")
; #define BAR __builtin_amdgcn_s_barrier()
; #define SCHED __builtin_amdgcn_sched_barrier(0)
; #define STAGE(P, BASE, br, kt) do { const char* _g = (const char*)((BASE) + (size_t)(br) * GK + (kt) * BK); \
;     __builtin_amdgcn_global_load_lds((const unsigned*)(_g + voff0), (unsigned*)((char*)(P) + tx * 16), 16, 0, 0); \
;     __builtin_amdgcn_global_load_lds((const unsigned*)(_g + voff1), (unsigned*)((char*)(P) + tx * 16 + 8192), 16, 0, 0); } while (0)
; #define LDA(dst, b, h) _Pragma("unroll") for (int m = 0; m < 4; ++m) _Pragma("unroll") for (int k = 0; k < 2; ++k) \
;     dst[m][k] = *reinterpret_cast<const bf16x8*>((char*)shm + abase + (((b) * 2 + (h)) * 16384 + (m * 2 + k) * 1024))
; #define LDB(dst, b, h) _Pragma("unroll") for (int n = 0; n < 2; ++n) _Pragma("unroll") for (int k = 0; k < 2; ++k) \
;     dst[n][k] = *reinterpret_cast<const bf16x8*>((char*)shm + bbase + (((b) * 2 + (h)) * 16384 + (n * 2 + k) * 1024))
; template <bool SWAP>
; __device__ __forceinline__ void gemm_main(const u16* __restrict__ A, const u16* __restrict__ Bt, int brow, int bcol,
;                                           u16* shm, f32x4 (&acc)[2][2][4][2]) {
;     ...
;     LDA(At, 1, 1); STAGE(SA(1, 0), A, brow, t + 3);
;     BAR; WAIT_L(0); MMA(1, 0, At, B0); BAR; SCHED;
;     STAGE(SB(1, 1), Bt, bcol + HALF, t + 3);
;     WAIT_V(6); BAR; MMA(1, 1, At, B1); BAR;
;   }
;   { LDB(B0, 0, 0); LDA(At, 0, 0); STAGE(SA(1, 1), A, brow + HALF, nt - 1);
;     BAR; WAIT_L(0); MMA(0, 0, At, B0); BAR;
	s_waitcnt lgkmcnt(0)
	v_mfma_f32_16x16x32_bf16 v[60:63], v[178:181], v[162:165], v[60:63]
	v_mfma_f32_16x16x32_bf16 v[56:59], v[178:181], v[170:173], v[56:59]
	v_mfma_f32_16x16x32_bf16 v[52:55], v[186:189], v[162:165], v[52:55]
	v_mfma_f32_16x16x32_bf16 v[48:51], v[186:189], v[170:173], v[48:51]
	v_mfma_f32_16x16x32_bf16 v[44:47], v[198:201], v[162:165], v[44:47]
	v_mfma_f32_16x16x32_bf16 v[40:43], v[198:201], v[170:173], v[40:43]
	v_mfma_f32_16x16x32_bf16 v[36:39], v[206:209], v[162:165], v[36:39]
	v_mfma_f32_16x16x32_bf16 v[32:35], v[206:209], v[170:173], v[32:35]
	v_mfma_f32_16x16x32_bf16 v[60:63], v[182:185], v[166:169], v[60:63]
	v_mfma_f32_16x16x32_bf16 v[56:59], v[182:185], v[174:177], v[56:59]
	v_mfma_f32_16x16x32_bf16 v[52:55], v[194:197], v[166:169], v[52:55]
	v_mfma_f32_16x16x32_bf16 v[48:51], v[194:197], v[174:177], v[48:51]
	v_mfma_f32_16x16x32_bf16 v[44:47], v[202:205], v[166:169], v[44:47]
	v_mfma_f32_16x16x32_bf16 v[40:43], v[202:205], v[174:177], v[40:43]
	v_mfma_f32_16x16x32_bf16 v[36:39], v[222:225], v[166:169], v[36:39]
	v_mfma_f32_16x16x32_bf16 v[32:35], v[222:225], v[174:177], v[32:35]
	s_barrier
	s_setprio 0
	ds_read_b128 v[162:165], v152
	ds_read_b128 v[166:169], v152 offset:1024
	ds_read_b128 v[170:173], v152 offset:2048
	ds_read_b128 v[174:177], v152 offset:3072
	s_add_u32 m0, s4, s31
	s_nop 0
	s_add_u32 vcc_lo, s0, s64
	s_addc_u32 vcc_hi, s1, s65
	global_load_lds_dwordx4 v128, vcc
	v_lshl_add_u64 v[254:255], v[246:247], 0, s[64:65]
	s_add_u32 m0, s4, s31
	s_add_u32 m0, m0, 0x2000
	s_nop 0
	global_load_lds_dwordx4 v130, vcc
	s_setprio 1
	s_barrier
	v_mfma_f32_16x16x32_bf16 v[28:31], v[178:181], v[226:229], v[28:31]
	v_mfma_f32_16x16x32_bf16 v[24:27], v[178:181], v[234:237], v[24:27]
	v_mfma_f32_16x16x32_bf16 v[20:23], v[186:189], v[226:229], v[20:23]
	v_mfma_f32_16x16x32_bf16 v[16:19], v[186:189], v[234:237], v[16:19]
	v_mfma_f32_16x16x32_bf16 v[12:15], v[198:201], v[226:229], v[12:15]
	v_mfma_f32_16x16x32_bf16 v[8:11], v[198:201], v[234:237], v[8:11]
	v_mfma_f32_16x16x32_bf16 v[4:7], v[206:209], v[226:229], v[4:7]
	v_mfma_f32_16x16x32_bf16 v[0:3], v[206:209], v[234:237], v[0:3]
	v_mfma_f32_16x16x32_bf16 v[28:31], v[182:185], v[230:233], v[28:31]
	ds_read_b128 v[178:181], v137
	v_mfma_f32_16x16x32_bf16 v[24:27], v[182:185], v[238:241], v[24:27]
	v_mfma_f32_16x16x32_bf16 v[20:23], v[194:197], v[230:233], v[20:23]
	ds_read_b128 v[186:189], v137 offset:2048
	v_mfma_f32_16x16x32_bf16 v[16:19], v[194:197], v[238:241], v[16:19]
	v_mfma_f32_16x16x32_bf16 v[12:15], v[202:205], v[230:233], v[12:15]
	ds_read_b128 v[198:201], v137 offset:4096
	v_mfma_f32_16x16x32_bf16 v[8:11], v[202:205], v[238:241], v[8:11]
	v_mfma_f32_16x16x32_bf16 v[4:7], v[222:225], v[230:233], v[4:7]
	ds_read_b128 v[206:209], v137 offset:6144
	v_mfma_f32_16x16x32_bf16 v[0:3], v[222:225], v[238:241], v[0:3]
	s_add_i32 s3, s3, 2
	s_add_u32 s0, s0, 0x100
	s_addc_u32 s1, s1, 0
	s_cmp_lt_u32 s3, 28
	s_barrier
	s_setprio 0
	s_cbranch_scc1 .LBB0_114
	v_lshlrev_b32_e32 v128, 3, v154
	v_lshlrev_b32_e32 v129, 5, v154
	v_and_b32_e32 v128, 0xffff0, v128
	v_and_b32_e32 v129, 32, v129
	s_or_b32 s0, s24, 0x80
	v_add_u32_e32 v129, v129, v156
	v_add_lshl_u32 v128, v155, v128, 12
	s_ashr_i32 s1, s0, 31
	v_lshl_add_u32 v192, v129, 1, v128
	v_lshlrev_b32_e32 v128, 3, v157
	v_lshlrev_b32_e32 v129, 5, v157
	s_mov_b32 s22, s0
	s_lshl_b64 s[0:1], s[0:1], 12
	v_readlane_b32 s4, v253, 35
	v_and_b32_e32 v128, 0xffff0, v128
	v_and_b32_e32 v129, 32, v129
	v_readlane_b32 s5, v253, 36
	s_add_u32 s0, s4, s0
	v_add_u32_e32 v129, v129, v159
	v_add_lshl_u32 v128, v158, v128, 12
	s_addc_u32 s1, s5, s1
	v_lshl_add_u32 v158, v129, 1, v128
	v_mov_b32_e32 v159, v193
	v_lshl_add_u64 v[190:191], s[0:1], 0, v[192:193]
	s_mov_b64 s[4:5], 0xf80
	v_readfirstlane_b32 s3, v160
	v_lshl_add_u64 v[190:191], v[190:191], 0, s[4:5]
	s_mov_b32 m0, s3
	v_lshl_add_u64 v[158:159], s[0:1], 0, v[158:159]
	v_readfirstlane_b32 s0, v161
	ds_read_b128 v[128:131], v152
	ds_read_b128 v[132:135], v152 offset:1024
	ds_read_b128 v[154:157], v152 offset:2048
	ds_read_b128 v[162:165], v152 offset:3072
	ds_read_b128 v[166:169], v137
	ds_read_b128 v[170:173], v137 offset:1024
	ds_read_b128 v[174:177], v137 offset:2048
	ds_read_b128 v[178:181], v137 offset:3072
	ds_read_b128 v[182:185], v137 offset:4096
	ds_read_b128 v[186:189], v137 offset:5120
	ds_read_b128 v[194:197], v137 offset:6144
	ds_read_b128 v[198:201], v137 offset:7168
	global_load_lds_dwordx4 v[190:191], off
	v_lshl_add_u64 v[158:159], v[158:159], 0, s[4:5]
	s_mov_b32 m0, s0
	s_nop 0
	global_load_lds_dwordx4 v[158:159], off
	s_waitcnt vmcnt(8)
	s_barrier
	s_waitcnt lgkmcnt(0)
	s_setprio 1
	s_waitcnt lgkmcnt(0)
	v_mfma_f32_16x16x32_bf16 v[124:127], v[166:169], v[128:131], v[124:127]
	v_mfma_f32_16x16x32_bf16 v[120:123], v[166:169], v[154:157], v[120:123]
	v_mfma_f32_16x16x32_bf16 v[116:119], v[174:177], v[128:131], v[116:119]
	v_mfma_f32_16x16x32_bf16 v[112:115], v[174:177], v[154:157], v[112:115]
	v_mfma_f32_16x16x32_bf16 v[108:111], v[182:185], v[128:131], v[108:111]
	v_mfma_f32_16x16x32_bf16 v[104:107], v[182:185], v[154:157], v[104:107]
	v_mfma_f32_16x16x32_bf16 v[100:103], v[194:197], v[128:131], v[100:103]
	v_mfma_f32_16x16x32_bf16 v[96:99], v[194:197], v[154:157], v[96:99]
	v_mfma_f32_16x16x32_bf16 v[124:127], v[170:173], v[132:135], v[124:127]
	v_mfma_f32_16x16x32_bf16 v[120:123], v[170:173], v[162:165], v[120:123]
	v_mfma_f32_16x16x32_bf16 v[116:119], v[178:181], v[132:135], v[116:119]
	v_mfma_f32_16x16x32_bf16 v[112:115], v[178:181], v[162:165], v[112:115]
	v_mfma_f32_16x16x32_bf16 v[108:111], v[186:189], v[132:135], v[108:111]
	v_mfma_f32_16x16x32_bf16 v[104:107], v[186:189], v[162:165], v[104:107]
	v_mfma_f32_16x16x32_bf16 v[100:103], v[198:201], v[132:135], v[100:103]
	v_mfma_f32_16x16x32_bf16 v[96:99], v[198:201], v[162:165], v[96:99]
	s_setprio 0
	s_barrier
; #define WAIT_V(n) asm volatile("s_waitcnt vmcnt(" #n ")" ::: "memory")
; #define WAIT_L(n) asm volatile("s_waitcnt lgkmcnt(" #n ")" ::: "memory")
; #define BAR __builtin_amdgcn_s_barrier()
; #define LDA(dst, b, h) _Pragma("unroll") for (int m = 0; m < 4; ++m) _Pragma("unroll") for (int k = 0; k < 2; ++k) \
;     dst[m][k] = *reinterpret_cast<const bf16x8*>((char*)shm + abase + (((b) * 2 + (h)) * 16384 + (m * 2 + k) * 1024))
; #define LDB(dst, b, h) _Pragma("unroll") for (int n = 0; n < 2; ++n) _Pragma("unroll") for (int k = 0; k < 2; ++k) \
;     dst[n][k] = *reinterpret_cast<const bf16x8*>((char*)shm + bbase + (((b) * 2 + (h)) * 16384 + (n * 2 + k) * 1024))
; template <bool SWAP>
; __device__ __forceinline__ void gemm_main(const u16* __restrict__ A, const u16* __restrict__ Bt, int brow, int bcol,
;                                           u16* shm, f32x4 (&acc)[2][2][4][2]) {
;     ...
;     BAR; WAIT_L(0); MMA(0, 0, At, B0); BAR;
;     LDB(B1, 0, 1); BAR; WAIT_L(0); MMA(0, 1, At, B1); BAR;
;     LDA(At, 0, 1); WAIT_V(4); BAR; WAIT_L(0); MMA(1, 0, At, B0); MMA(1, 1, At, B1); BAR; }
;   { LDB(B0, 1, 0); LDA(At, 1, 0); WAIT_V(2); BAR; WAIT_L(0); MMA(0, 0, At, B0); BAR;
	ds_read_b128 v[158:161], v152 offset:16384
	ds_read_b128 v[202:205], v152 offset:17408
	ds_read_b128 v[206:209], v152 offset:18432
	ds_read_b128 v[222:225], v152 offset:19456
	s_barrier
	s_waitcnt lgkmcnt(0)
	s_setprio 1
	s_waitcnt lgkmcnt(0)
	v_mfma_f32_16x16x32_bf16 v[92:95], v[166:169], v[158:161], v[92:95]
	v_mfma_f32_16x16x32_bf16 v[88:91], v[166:169], v[206:209], v[88:91]
	v_mfma_f32_16x16x32_bf16 v[84:87], v[174:177], v[158:161], v[84:87]
	v_mfma_f32_16x16x32_bf16 v[80:83], v[174:177], v[206:209], v[80:83]
	v_mfma_f32_16x16x32_bf16 v[76:79], v[182:185], v[158:161], v[76:79]
	v_mfma_f32_16x16x32_bf16 v[72:75], v[182:185], v[206:209], v[72:75]
	v_mfma_f32_16x16x32_bf16 v[68:71], v[194:197], v[158:161], v[68:71]
	v_mfma_f32_16x16x32_bf16 v[64:67], v[194:197], v[206:209], v[64:67]
	v_mfma_f32_16x16x32_bf16 v[92:95], v[170:173], v[202:205], v[92:95]
	v_mfma_f32_16x16x32_bf16 v[88:91], v[170:173], v[222:225], v[88:91]
	v_mfma_f32_16x16x32_bf16 v[84:87], v[178:181], v[202:205], v[84:87]
	v_mfma_f32_16x16x32_bf16 v[80:83], v[178:181], v[222:225], v[80:83]
	v_mfma_f32_16x16x32_bf16 v[76:79], v[186:189], v[202:205], v[76:79]
	v_mfma_f32_16x16x32_bf16 v[72:75], v[186:189], v[222:225], v[72:75]
	v_mfma_f32_16x16x32_bf16 v[68:71], v[198:201], v[202:205], v[68:71]
	v_mfma_f32_16x16x32_bf16 v[64:67], v[198:201], v[222:225], v[64:67]
	s_setprio 0
	s_barrier
	ds_read_b128 v[166:169], v137 offset:16384
	ds_read_b128 v[170:173], v137 offset:17408
	ds_read_b128 v[174:177], v137 offset:18432
	ds_read_b128 v[178:181], v137 offset:19456
	ds_read_b128 v[182:185], v137 offset:20480
	ds_read_b128 v[186:189], v137 offset:21504
	ds_read_b128 v[194:197], v137 offset:22528
	ds_read_b128 v[198:201], v137 offset:23552
	s_waitcnt vmcnt(4)
	s_barrier
	s_waitcnt lgkmcnt(0)
	s_setprio 1
	s_waitcnt lgkmcnt(0)
	v_mfma_f32_16x16x32_bf16 v[60:63], v[166:169], v[128:131], v[60:63]
	v_mfma_f32_16x16x32_bf16 v[56:59], v[166:169], v[154:157], v[56:59]
	v_mfma_f32_16x16x32_bf16 v[52:55], v[174:177], v[128:131], v[52:55]
	v_mfma_f32_16x16x32_bf16 v[48:51], v[174:177], v[154:157], v[48:51]
	v_mfma_f32_16x16x32_bf16 v[44:47], v[182:185], v[128:131], v[44:47]
	v_mfma_f32_16x16x32_bf16 v[40:43], v[182:185], v[154:157], v[40:43]
	v_mfma_f32_16x16x32_bf16 v[36:39], v[194:197], v[128:131], v[36:39]
	v_mfma_f32_16x16x32_bf16 v[32:35], v[194:197], v[154:157], v[32:35]
	v_mfma_f32_16x16x32_bf16 v[60:63], v[170:173], v[132:135], v[60:63]
	v_mfma_f32_16x16x32_bf16 v[56:59], v[170:173], v[162:165], v[56:59]
	v_mfma_f32_16x16x32_bf16 v[52:55], v[178:181], v[132:135], v[52:55]
	v_mfma_f32_16x16x32_bf16 v[48:51], v[178:181], v[162:165], v[48:51]
	v_mfma_f32_16x16x32_bf16 v[44:47], v[186:189], v[132:135], v[44:47]
	v_mfma_f32_16x16x32_bf16 v[40:43], v[186:189], v[162:165], v[40:43]
	v_mfma_f32_16x16x32_bf16 v[36:39], v[198:201], v[132:135], v[36:39]
	v_mfma_f32_16x16x32_bf16 v[32:35], v[198:201], v[162:165], v[32:35]
	s_setprio 0
	s_setprio 1
	v_mfma_f32_16x16x32_bf16 v[28:31], v[166:169], v[158:161], v[28:31]
	v_mfma_f32_16x16x32_bf16 v[24:27], v[166:169], v[206:209], v[24:27]
	v_mfma_f32_16x16x32_bf16 v[20:23], v[174:177], v[158:161], v[20:23]
	v_mfma_f32_16x16x32_bf16 v[16:19], v[174:177], v[206:209], v[16:19]
	v_mfma_f32_16x16x32_bf16 v[12:15], v[182:185], v[158:161], v[12:15]
	v_mfma_f32_16x16x32_bf16 v[8:11], v[182:185], v[206:209], v[8:11]
	v_mfma_f32_16x16x32_bf16 v[4:7], v[194:197], v[158:161], v[4:7]
	v_mfma_f32_16x16x32_bf16 v[0:3], v[194:197], v[206:209], v[0:3]
	v_mfma_f32_16x16x32_bf16 v[28:31], v[170:173], v[202:205], v[28:31]
	v_mfma_f32_16x16x32_bf16 v[24:27], v[170:173], v[222:225], v[24:27]
	v_mfma_f32_16x16x32_bf16 v[20:23], v[178:181], v[202:205], v[20:23]
	v_mfma_f32_16x16x32_bf16 v[16:19], v[178:181], v[222:225], v[16:19]
	v_mfma_f32_16x16x32_bf16 v[12:15], v[186:189], v[202:205], v[12:15]
	v_mfma_f32_16x16x32_bf16 v[8:11], v[186:189], v[222:225], v[8:11]
	v_mfma_f32_16x16x32_bf16 v[4:7], v[198:201], v[202:205], v[4:7]
	v_mfma_f32_16x16x32_bf16 v[0:3], v[198:201], v[222:225], v[0:3]
	s_setprio 0
	s_barrier
	ds_read_b128 v[128:131], v152 offset:32768
	ds_read_b128 v[132:135], v152 offset:33792
	ds_read_b128 v[154:157], v152 offset:34816
	ds_read_b128 v[158:161], v152 offset:35840
	ds_read_b128 v[162:165], v137 offset:32768
	ds_read_b128 v[166:169], v137 offset:33792
	ds_read_b128 v[170:173], v137 offset:34816
	ds_read_b128 v[174:177], v137 offset:35840
	ds_read_b128 v[178:181], v137 offset:36864
	ds_read_b128 v[182:185], v137 offset:37888
	ds_read_b128 v[186:189], v137 offset:38912
	ds_read_b128 v[194:197], v137 offset:39936
	s_waitcnt vmcnt(2)
	s_barrier
; #define WAIT_V(n) asm volatile("s_waitcnt vmcnt(" #n ")" ::: "memory")
; #define WAIT_L(n) asm volatile("s_waitcnt lgkmcnt(" #n ")" ::: "memory")
; #define BAR __builtin_amdgcn_s_barrier()
; #define LDA(dst, b, h) _Pragma("unroll") for (int m = 0; m < 4; ++m) _Pragma("unroll") for (int k = 0; k < 2; ++k) \
;     dst[m][k] = *reinterpret_cast<const bf16x8*>((char*)shm + abase + (((b) * 2 + (h)) * 16384 + (m * 2 + k) * 1024))
; #define LDB(dst, b, h) _Pragma("unroll") for (int n = 0; n < 2; ++n) _Pragma("unroll") for (int k = 0; k < 2; ++k) \
;     dst[n][k] = *reinterpret_cast<const bf16x8*>((char*)shm + bbase + (((b) * 2 + (h)) * 16384 + (n * 2 + k) * 1024))
; template <bool SWAP>
; __device__ __forceinline__ void gemm_main(const u16* __restrict__ A, const u16* __restrict__ Bt, int brow, int bcol,
;                                           u16* shm, f32x4 (&acc)[2][2][4][2]) {
;     ...
;   { LDB(B0, 1, 0); LDA(At, 1, 0); WAIT_V(2); BAR; WAIT_L(0); MMA(0, 0, At, B0); BAR;
;     LDB(B1, 1, 1); WAIT_V(0); BAR; WAIT_L(0); MMA(0, 1, At, B1); BAR;
;     LDA(At, 1, 1); BAR; WAIT_L(0); MMA(1, 0, At, B0); MMA(1, 1, At, B1); BAR; }
;   if (wr == 0) BAR;
; __device__ __forceinline__ void phase_inproj1(const Params& p, char* smem) {
;     ...
;       if (nt < 16) {
	s_waitcnt lgkmcnt(0)
	s_setprio 1
	s_waitcnt lgkmcnt(0)
	v_mfma_f32_16x16x32_bf16 v[124:127], v[162:165], v[128:131], v[124:127]
	v_mfma_f32_16x16x32_bf16 v[120:123], v[162:165], v[154:157], v[120:123]
	v_mfma_f32_16x16x32_bf16 v[116:119], v[170:173], v[128:131], v[116:119]
	v_mfma_f32_16x16x32_bf16 v[112:115], v[170:173], v[154:157], v[112:115]
	v_mfma_f32_16x16x32_bf16 v[108:111], v[178:181], v[128:131], v[108:111]
	v_mfma_f32_16x16x32_bf16 v[104:107], v[178:181], v[154:157], v[104:107]
	v_mfma_f32_16x16x32_bf16 v[100:103], v[186:189], v[128:131], v[100:103]
	v_mfma_f32_16x16x32_bf16 v[96:99], v[186:189], v[154:157], v[96:99]
	v_mfma_f32_16x16x32_bf16 v[124:127], v[166:169], v[132:135], v[124:127]
	v_mfma_f32_16x16x32_bf16 v[120:123], v[166:169], v[158:161], v[120:123]
	v_mfma_f32_16x16x32_bf16 v[116:119], v[174:177], v[132:135], v[116:119]
	v_mfma_f32_16x16x32_bf16 v[112:115], v[174:177], v[158:161], v[112:115]
	v_mfma_f32_16x16x32_bf16 v[108:111], v[182:185], v[132:135], v[108:111]
	v_mfma_f32_16x16x32_bf16 v[104:107], v[182:185], v[158:161], v[104:107]
	v_mfma_f32_16x16x32_bf16 v[100:103], v[194:197], v[132:135], v[100:103]
	v_mfma_f32_16x16x32_bf16 v[96:99], v[194:197], v[158:161], v[96:99]
	s_setprio 0
	s_barrier
	ds_read_b128 v[198:201], v152 offset:49152
	ds_read_b128 v[202:205], v152 offset:50176
	ds_read_b128 v[206:209], v152 offset:51200
	ds_read_b128 v[222:225], v152 offset:52224
	s_waitcnt vmcnt(0)
	s_barrier
	s_waitcnt lgkmcnt(0)
	s_setprio 1
	s_waitcnt lgkmcnt(0)
	v_mfma_f32_16x16x32_bf16 v[92:95], v[162:165], v[198:201], v[92:95]
	v_mfma_f32_16x16x32_bf16 v[88:91], v[162:165], v[206:209], v[88:91]
	v_mfma_f32_16x16x32_bf16 v[84:87], v[170:173], v[198:201], v[84:87]
	v_mfma_f32_16x16x32_bf16 v[80:83], v[170:173], v[206:209], v[80:83]
	v_mfma_f32_16x16x32_bf16 v[76:79], v[178:181], v[198:201], v[76:79]
	v_mfma_f32_16x16x32_bf16 v[72:75], v[178:181], v[206:209], v[72:75]
	v_mfma_f32_16x16x32_bf16 v[68:71], v[186:189], v[198:201], v[68:71]
	v_mfma_f32_16x16x32_bf16 v[64:67], v[186:189], v[206:209], v[64:67]
	v_mfma_f32_16x16x32_bf16 v[92:95], v[166:169], v[202:205], v[92:95]
	v_mfma_f32_16x16x32_bf16 v[88:91], v[166:169], v[222:225], v[88:91]
	v_mfma_f32_16x16x32_bf16 v[84:87], v[174:177], v[202:205], v[84:87]
	v_mfma_f32_16x16x32_bf16 v[80:83], v[174:177], v[222:225], v[80:83]
	v_mfma_f32_16x16x32_bf16 v[76:79], v[182:185], v[202:205], v[76:79]
	v_mfma_f32_16x16x32_bf16 v[72:75], v[182:185], v[222:225], v[72:75]
	v_mfma_f32_16x16x32_bf16 v[68:71], v[194:197], v[202:205], v[68:71]
	v_mfma_f32_16x16x32_bf16 v[64:67], v[194:197], v[222:225], v[64:67]
	s_setprio 0
	s_barrier
	ds_read_b128 v[162:165], v137 offset:49152
	ds_read_b128 v[166:169], v137 offset:50176
	ds_read_b128 v[170:173], v137 offset:51200
	ds_read_b128 v[174:177], v137 offset:52224
	ds_read_b128 v[178:181], v137 offset:53248
	ds_read_b128 v[182:185], v137 offset:54272
	ds_read_b128 v[186:189], v137 offset:55296
	ds_read_b128 v[194:197], v137 offset:56320
	s_barrier
	s_waitcnt lgkmcnt(0)
	s_setprio 1
	s_waitcnt lgkmcnt(0)
	v_mfma_f32_16x16x32_bf16 v[60:63], v[162:165], v[128:131], v[60:63]
	v_mfma_f32_16x16x32_bf16 v[56:59], v[162:165], v[154:157], v[56:59]
	v_mfma_f32_16x16x32_bf16 v[52:55], v[170:173], v[128:131], v[52:55]
	v_mfma_f32_16x16x32_bf16 v[48:51], v[170:173], v[154:157], v[48:51]
	v_mfma_f32_16x16x32_bf16 v[44:47], v[178:181], v[128:131], v[44:47]
	v_mfma_f32_16x16x32_bf16 v[40:43], v[178:181], v[154:157], v[40:43]
	v_mfma_f32_16x16x32_bf16 v[36:39], v[186:189], v[128:131], v[36:39]
	v_mfma_f32_16x16x32_bf16 v[32:35], v[186:189], v[154:157], v[32:35]
	v_mfma_f32_16x16x32_bf16 v[60:63], v[166:169], v[132:135], v[60:63]
	v_mfma_f32_16x16x32_bf16 v[56:59], v[166:169], v[158:161], v[56:59]
	v_mfma_f32_16x16x32_bf16 v[52:55], v[174:177], v[132:135], v[52:55]
	v_mfma_f32_16x16x32_bf16 v[48:51], v[174:177], v[158:161], v[48:51]
	v_mfma_f32_16x16x32_bf16 v[44:47], v[182:185], v[132:135], v[44:47]
	v_mfma_f32_16x16x32_bf16 v[40:43], v[182:185], v[158:161], v[40:43]
	v_mfma_f32_16x16x32_bf16 v[36:39], v[194:197], v[132:135], v[36:39]
	v_mfma_f32_16x16x32_bf16 v[32:35], v[194:197], v[158:161], v[32:35]
	s_setprio 0
	s_setprio 1
	v_mfma_f32_16x16x32_bf16 v[28:31], v[162:165], v[198:201], v[28:31]
	v_mfma_f32_16x16x32_bf16 v[24:27], v[162:165], v[206:209], v[24:27]
	v_mfma_f32_16x16x32_bf16 v[20:23], v[170:173], v[198:201], v[20:23]
	v_mfma_f32_16x16x32_bf16 v[16:19], v[170:173], v[206:209], v[16:19]
	v_mfma_f32_16x16x32_bf16 v[12:15], v[178:181], v[198:201], v[12:15]
	v_mfma_f32_16x16x32_bf16 v[8:11], v[178:181], v[206:209], v[8:11]
	v_mfma_f32_16x16x32_bf16 v[4:7], v[186:189], v[198:201], v[4:7]
	v_mfma_f32_16x16x32_bf16 v[0:3], v[186:189], v[206:209], v[0:3]
	v_mfma_f32_16x16x32_bf16 v[28:31], v[166:169], v[202:205], v[28:31]
	v_mfma_f32_16x16x32_bf16 v[24:27], v[166:169], v[222:225], v[24:27]
	v_mfma_f32_16x16x32_bf16 v[20:23], v[174:177], v[202:205], v[20:23]
	v_mfma_f32_16x16x32_bf16 v[16:19], v[174:177], v[222:225], v[16:19]
	v_mfma_f32_16x16x32_bf16 v[12:15], v[182:185], v[202:205], v[12:15]
	v_mfma_f32_16x16x32_bf16 v[8:11], v[182:185], v[222:225], v[8:11]
	v_mfma_f32_16x16x32_bf16 v[4:7], v[194:197], v[202:205], v[4:7]
	v_mfma_f32_16x16x32_bf16 v[0:3], v[194:197], v[222:225], v[0:3]
	s_setprio 0
	s_movk_i32 s0, 0x100
	v_cmp_gt_u32_e32 vcc, s0, v136
	s_barrier
	s_and_saveexec_b64 s[0:1], vcc
	s_cbranch_execz .LBB0_118
	s_barrier
	s_or_b64 exec, exec, s[0:1]
	s_cmp_gt_u32 s2, 15
	s_mov_b64 s[0:1], -1
	s_cbranch_scc1 .LBB0_119

; #define WAIT_V(n) asm volatile("s_waitcnt vmcnt(" #n ")" ::: "memory")
; #define WAIT_L(n) asm volatile("s_waitcnt lgkmcnt(" #n ")" ::: "memory")
; #define BAR __builtin_amdgcn_s_barrier()
; #define SCHED __builtin_amdgcn_sched_barrier(0)
; #define STAGE(P, BASE, br, kt) do { const char* _g = (const char*)((BASE) + (size_t)(br) * GK + (kt) * BK); \
;     __builtin_amdgcn_global_load_lds((const unsigned*)(_g + voff0), (unsigned*)((char*)(P) + tx * 16), 16, 0, 0); \
;     __builtin_amdgcn_global_load_lds((const unsigned*)(_g + voff1), (unsigned*)((char*)(P) + tx * 16 + 8192), 16, 0, 0); } while (0)
; #define LDA(dst, b, h) _Pragma("unroll") for (int m = 0; m < 4; ++m) _Pragma("unroll") for (int k = 0; k < 2; ++k) \
;     dst[m][k] = *reinterpret_cast<const bf16x8*>((char*)shm + abase + (((b) * 2 + (h)) * 16384 + (m * 2 + k) * 1024))
; #define LDB(dst, b, h) _Pragma("unroll") for (int n = 0; n < 2; ++n) _Pragma("unroll") for (int k = 0; k < 2; ++k) \
;     dst[n][k] = *reinterpret_cast<const bf16x8*>((char*)shm + bbase + (((b) * 2 + (h)) * 16384 + (n * 2 + k) * 1024))
; template <bool SWAP>
; __device__ __forceinline__ void gemm_main(const u16* __restrict__ A, const u16* __restrict__ Bt, int brow, int bcol,
;                                           u16* shm, f32x4 (&acc)[2][2][4][2]) {
;     ...
;     LDB(B0, 0, 0); SCHED; LDA(At, 0, 0); STAGE(SA(1, 1), A, brow + HALF, t + 1);
;     WAIT_L(8); BAR; WAIT_L(0); MMA(0, 0, At, B0); BAR; SCHED;
;     LDB(B1, 0, 1); STAGE(SB(0, 0), Bt, bcol, t + 2);
;     BAR; WAIT_L(0); MMA(0, 1, At, B1); BAR;
;     LDA(At, 0, 1); STAGE(SA(0, 0), A, brow, t + 2);
;     BAR; WAIT_L(0); MMA(1, 0, At, B0); BAR; SCHED;
;     STAGE(SB(0, 1), Bt, bcol + HALF, t + 2);
;     WAIT_V(6); BAR; MMA(1, 1, At, B1); BAR;
.LBB0_200:
	ds_read_b128 v[182:185], v137 offset:1024
	ds_read_b128 v[194:197], v137 offset:3072
	ds_read_b128 v[202:205], v137 offset:5120
	ds_read_b128 v[222:225], v137 offset:7168
	v_add_u32_e32 v192, 0, v153
	v_add_u32_e32 v160, 0xc000, v192
	v_add_u32_e32 v161, 0xe000, v192
	s_add_u32 m0, s3, 0xc000
	v_lshl_add_u64 v[242:243], s[0:1], 0, v[134:135]
	s_add_u32 vcc_lo, s0, s82
	s_addc_u32 vcc_hi, s1, s83
	global_load_lds_dwordx4 v132, vcc
	s_add_u32 m0, s3, 0xe000
	s_nop 0
	global_load_lds_dwordx4 v134, vcc
	s_waitcnt lgkmcnt(8)
	s_waitcnt vmcnt(8)
	s_setprio 1
	s_barrier
	s_waitcnt lgkmcnt(0)
	v_mfma_f32_16x16x32_bf16 v[124:127], v[162:165], v[178:181], v[124:127]
	v_mfma_f32_16x16x32_bf16 v[120:123], v[170:173], v[178:181], v[120:123]
	v_mfma_f32_16x16x32_bf16 v[116:119], v[162:165], v[186:189], v[116:119]
	v_mfma_f32_16x16x32_bf16 v[112:115], v[170:173], v[186:189], v[112:115]
	v_mfma_f32_16x16x32_bf16 v[108:111], v[162:165], v[198:201], v[108:111]
	v_mfma_f32_16x16x32_bf16 v[104:107], v[170:173], v[198:201], v[104:107]
	v_mfma_f32_16x16x32_bf16 v[100:103], v[162:165], v[206:209], v[100:103]
	v_mfma_f32_16x16x32_bf16 v[96:99], v[170:173], v[206:209], v[96:99]
	v_mfma_f32_16x16x32_bf16 v[124:127], v[166:169], v[182:185], v[124:127]
	v_mfma_f32_16x16x32_bf16 v[120:123], v[174:177], v[182:185], v[120:123]
	v_mfma_f32_16x16x32_bf16 v[116:119], v[166:169], v[194:197], v[116:119]
	v_mfma_f32_16x16x32_bf16 v[112:115], v[174:177], v[194:197], v[112:115]
	v_mfma_f32_16x16x32_bf16 v[108:111], v[166:169], v[202:205], v[108:111]
	v_mfma_f32_16x16x32_bf16 v[104:107], v[174:177], v[202:205], v[104:107]
	v_mfma_f32_16x16x32_bf16 v[100:103], v[166:169], v[222:225], v[100:103]
	v_mfma_f32_16x16x32_bf16 v[96:99], v[174:177], v[222:225], v[96:99]
	s_barrier
	s_setprio 0
	ds_read_b128 v[226:229], v152 offset:16384
	ds_read_b128 v[230:233], v152 offset:17408
	ds_read_b128 v[234:237], v152 offset:18432
	ds_read_b128 v[238:241], v152 offset:19456
	v_lshl_add_u64 v[244:245], s[0:1], 0, v[128:129]
	s_add_u32 m0, s3, s28
	s_nop 0
	s_add_u32 vcc_lo, s0, s74
	s_addc_u32 vcc_hi, s1, s75
	global_load_lds_dwordx4 v128, vcc
	v_lshl_add_u64 v[246:247], s[0:1], 0, v[130:131]
	s_add_u32 m0, s3, s28
	s_add_u32 m0, m0, 0x2000
	s_nop 0
	global_load_lds_dwordx4 v130, vcc
	s_setprio 1
	s_barrier
	s_waitcnt lgkmcnt(0)
	v_mfma_f32_16x16x32_bf16 v[92:95], v[226:229], v[178:181], v[92:95]
	v_mfma_f32_16x16x32_bf16 v[88:91], v[234:237], v[178:181], v[88:91]
	v_mfma_f32_16x16x32_bf16 v[84:87], v[226:229], v[186:189], v[84:87]
	v_mfma_f32_16x16x32_bf16 v[80:83], v[234:237], v[186:189], v[80:83]
	v_mfma_f32_16x16x32_bf16 v[76:79], v[226:229], v[198:201], v[76:79]
	v_mfma_f32_16x16x32_bf16 v[72:75], v[234:237], v[198:201], v[72:75]
	v_mfma_f32_16x16x32_bf16 v[68:71], v[226:229], v[206:209], v[68:71]
	v_mfma_f32_16x16x32_bf16 v[64:67], v[234:237], v[206:209], v[64:67]
	v_mfma_f32_16x16x32_bf16 v[92:95], v[230:233], v[182:185], v[92:95]
	ds_read_b128 v[178:181], v137 offset:16384
	v_mfma_f32_16x16x32_bf16 v[88:91], v[238:241], v[182:185], v[88:91]
	v_mfma_f32_16x16x32_bf16 v[84:87], v[230:233], v[194:197], v[84:87]
	ds_read_b128 v[186:189], v137 offset:18432
	v_mfma_f32_16x16x32_bf16 v[80:83], v[238:241], v[194:197], v[80:83]
	v_mfma_f32_16x16x32_bf16 v[76:79], v[230:233], v[202:205], v[76:79]
	ds_read_b128 v[198:201], v137 offset:20480
	v_mfma_f32_16x16x32_bf16 v[72:75], v[238:241], v[202:205], v[72:75]
	v_mfma_f32_16x16x32_bf16 v[68:71], v[230:233], v[222:225], v[68:71]
	ds_read_b128 v[206:209], v137 offset:22528
	v_mfma_f32_16x16x32_bf16 v[64:67], v[238:241], v[222:225], v[64:67]
	s_barrier
	s_setprio 0
	ds_read_b128 v[182:185], v137 offset:17408
	ds_read_b128 v[194:197], v137 offset:19456
	ds_read_b128 v[202:205], v137 offset:21504
	ds_read_b128 v[222:225], v137 offset:23552
	s_add_u32 m0, s3, 0x0
	s_nop 0
	s_add_u32 vcc_lo, s0, s76
	s_addc_u32 vcc_hi, s1, s77
	global_load_lds_dwordx4 v132, vcc
	s_add_u32 m0, s3, 0x2000
	s_nop 0
	global_load_lds_dwordx4 v134, vcc
	s_waitcnt vmcnt(8)
	s_setprio 1
	s_barrier
	s_waitcnt lgkmcnt(0)
	v_mfma_f32_16x16x32_bf16 v[60:63], v[162:165], v[178:181], v[60:63]
	v_mfma_f32_16x16x32_bf16 v[56:59], v[170:173], v[178:181], v[56:59]
	v_mfma_f32_16x16x32_bf16 v[52:55], v[162:165], v[186:189], v[52:55]
	v_mfma_f32_16x16x32_bf16 v[48:51], v[170:173], v[186:189], v[48:51]
	v_mfma_f32_16x16x32_bf16 v[44:47], v[162:165], v[198:201], v[44:47]
	v_mfma_f32_16x16x32_bf16 v[40:43], v[170:173], v[198:201], v[40:43]
	v_mfma_f32_16x16x32_bf16 v[36:39], v[162:165], v[206:209], v[36:39]
	v_mfma_f32_16x16x32_bf16 v[32:35], v[170:173], v[206:209], v[32:35]
	v_mfma_f32_16x16x32_bf16 v[60:63], v[166:169], v[182:185], v[60:63]
	v_mfma_f32_16x16x32_bf16 v[56:59], v[174:177], v[182:185], v[56:59]
	v_mfma_f32_16x16x32_bf16 v[52:55], v[166:169], v[194:197], v[52:55]
	v_mfma_f32_16x16x32_bf16 v[48:51], v[174:177], v[194:197], v[48:51]
	v_mfma_f32_16x16x32_bf16 v[44:47], v[166:169], v[202:205], v[44:47]
	v_mfma_f32_16x16x32_bf16 v[40:43], v[174:177], v[202:205], v[40:43]
	v_mfma_f32_16x16x32_bf16 v[36:39], v[166:169], v[222:225], v[36:39]
	v_mfma_f32_16x16x32_bf16 v[32:35], v[174:177], v[222:225], v[32:35]
	s_barrier
	s_setprio 0
	ds_read_b128 v[162:165], v152 offset:32768
	ds_read_b128 v[166:169], v152 offset:33792
	ds_read_b128 v[170:173], v152 offset:34816
	ds_read_b128 v[174:177], v152 offset:35840
	s_add_u32 m0, s3, s29
	s_nop 0
	s_add_u32 vcc_lo, s0, s70
	s_addc_u32 vcc_hi, s1, s71
	global_load_lds_dwordx4 v128, vcc
	s_add_u32 m0, s3, s29
	s_add_u32 m0, m0, 0x2000
	s_nop 0
	global_load_lds_dwordx4 v130, vcc
	s_setprio 1
	s_barrier
; #define WAIT_V(n) asm volatile("s_waitcnt vmcnt(" #n ")" ::: "memory")
; #define WAIT_L(n) asm volatile("s_waitcnt lgkmcnt(" #n ")" ::: "memory")
; #define BAR __builtin_amdgcn_s_barrier()
; #define SCHED __builtin_amdgcn_sched_barrier(0)
; #define STAGE(P, BASE, br, kt) do { const char* _g = (const char*)((BASE) + (size_t)(br) * GK + (kt) * BK); \
;     __builtin_amdgcn_global_load_lds((const unsigned*)(_g + voff0), (unsigned*)((char*)(P) + tx * 16), 16, 0, 0); \
;     __builtin_amdgcn_global_load_lds((const unsigned*)(_g + voff1), (unsigned*)((char*)(P) + tx * 16 + 8192), 16, 0, 0); } while (0)
; #define LDA(dst, b, h) _Pragma("unroll") for (int m = 0; m < 4; ++m) _Pragma("unroll") for (int k = 0; k < 2; ++k) \
;     dst[m][k] = *reinterpret_cast<const bf16x8*>((char*)shm + abase + (((b) * 2 + (h)) * 16384 + (m * 2 + k) * 1024))
; #define LDB(dst, b, h) _Pragma("unroll") for (int n = 0; n < 2; ++n) _Pragma("unroll") for (int k = 0; k < 2; ++k) \
;     dst[n][k] = *reinterpret_cast<const bf16x8*>((char*)shm + bbase + (((b) * 2 + (h)) * 16384 + (n * 2 + k) * 1024))
; template <bool SWAP>
; __device__ __forceinline__ void gemm_main(const u16* __restrict__ A, const u16* __restrict__ Bt, int brow, int bcol,
;                                           u16* shm, f32x4 (&acc)[2][2][4][2]) {
;     ...
;     STAGE(SB(0, 1), Bt, bcol + HALF, t + 2);
;     WAIT_V(6); BAR; MMA(1, 1, At, B1); BAR;
;     LDB(B0, 1, 0); SCHED; LDA(At, 1, 0); STAGE(SA(0, 1), A, brow + HALF, t + 2);
;     WAIT_L(8); BAR; WAIT_L(0); MMA(0, 0, At, B0); BAR; SCHED;
;     LDB(B1, 1, 1); STAGE(SB(1, 0), Bt, bcol, t + 3);
;     BAR; WAIT_L(0); MMA(0, 1, At, B1); BAR;
	v_mfma_f32_16x16x32_bf16 v[28:31], v[226:229], v[178:181], v[28:31]
	v_mfma_f32_16x16x32_bf16 v[24:27], v[234:237], v[178:181], v[24:27]
	v_mfma_f32_16x16x32_bf16 v[20:23], v[226:229], v[186:189], v[20:23]
	v_mfma_f32_16x16x32_bf16 v[16:19], v[234:237], v[186:189], v[16:19]
	v_mfma_f32_16x16x32_bf16 v[12:15], v[226:229], v[198:201], v[12:15]
	v_mfma_f32_16x16x32_bf16 v[8:11], v[234:237], v[198:201], v[8:11]
	v_mfma_f32_16x16x32_bf16 v[4:7], v[226:229], v[206:209], v[4:7]
	v_mfma_f32_16x16x32_bf16 v[0:3], v[234:237], v[206:209], v[0:3]
	v_mfma_f32_16x16x32_bf16 v[28:31], v[230:233], v[182:185], v[28:31]
	ds_read_b128 v[178:181], v137 offset:32768
	v_mfma_f32_16x16x32_bf16 v[24:27], v[238:241], v[182:185], v[24:27]
	v_mfma_f32_16x16x32_bf16 v[20:23], v[230:233], v[194:197], v[20:23]
	ds_read_b128 v[186:189], v137 offset:34816
	v_mfma_f32_16x16x32_bf16 v[16:19], v[238:241], v[194:197], v[16:19]
	v_mfma_f32_16x16x32_bf16 v[12:15], v[230:233], v[202:205], v[12:15]
	ds_read_b128 v[198:201], v137 offset:36864
	v_mfma_f32_16x16x32_bf16 v[8:11], v[238:241], v[202:205], v[8:11]
	v_mfma_f32_16x16x32_bf16 v[4:7], v[230:233], v[222:225], v[4:7]
	ds_read_b128 v[206:209], v137 offset:38912
	v_mfma_f32_16x16x32_bf16 v[0:3], v[238:241], v[222:225], v[0:3]
	s_barrier
	s_setprio 0
	ds_read_b128 v[182:185], v137 offset:33792
	ds_read_b128 v[194:197], v137 offset:35840
	ds_read_b128 v[202:205], v137 offset:37888
	ds_read_b128 v[222:225], v137 offset:39936
	s_add_u32 m0, s3, 0x4000
	s_nop 0
	s_add_u32 vcc_lo, s0, s96
	s_addc_u32 vcc_hi, s1, s97
	global_load_lds_dwordx4 v132, vcc
	s_add_u32 m0, s3, 0x6000
	s_nop 0
	global_load_lds_dwordx4 v134, vcc
	s_waitcnt lgkmcnt(8)
	s_waitcnt vmcnt(8)
	s_setprio 1
	s_barrier
	s_waitcnt lgkmcnt(0)
	v_mfma_f32_16x16x32_bf16 v[124:127], v[162:165], v[178:181], v[124:127]
	v_mfma_f32_16x16x32_bf16 v[120:123], v[170:173], v[178:181], v[120:123]
	v_mfma_f32_16x16x32_bf16 v[116:119], v[162:165], v[186:189], v[116:119]
	v_mfma_f32_16x16x32_bf16 v[112:115], v[170:173], v[186:189], v[112:115]
	v_mfma_f32_16x16x32_bf16 v[108:111], v[162:165], v[198:201], v[108:111]
	v_mfma_f32_16x16x32_bf16 v[104:107], v[170:173], v[198:201], v[104:107]
	v_mfma_f32_16x16x32_bf16 v[100:103], v[162:165], v[206:209], v[100:103]
	v_mfma_f32_16x16x32_bf16 v[96:99], v[170:173], v[206:209], v[96:99]
	v_mfma_f32_16x16x32_bf16 v[124:127], v[166:169], v[182:185], v[124:127]
	v_mfma_f32_16x16x32_bf16 v[120:123], v[174:177], v[182:185], v[120:123]
	v_mfma_f32_16x16x32_bf16 v[116:119], v[166:169], v[194:197], v[116:119]
	v_mfma_f32_16x16x32_bf16 v[112:115], v[174:177], v[194:197], v[112:115]
	v_mfma_f32_16x16x32_bf16 v[108:111], v[166:169], v[202:205], v[108:111]
	v_mfma_f32_16x16x32_bf16 v[104:107], v[174:177], v[202:205], v[104:107]
	v_mfma_f32_16x16x32_bf16 v[100:103], v[166:169], v[222:225], v[100:103]
	v_mfma_f32_16x16x32_bf16 v[96:99], v[174:177], v[222:225], v[96:99]
	s_barrier
	s_setprio 0
	ds_read_b128 v[226:229], v152 offset:49152
	ds_read_b128 v[230:233], v152 offset:50176
	ds_read_b128 v[234:237], v152 offset:51200
	ds_read_b128 v[238:241], v152 offset:52224
	v_add_u32_e32 v250, s30, v153
	v_add_u32_e32 v250, 0x2000, v250
	s_add_u32 m0, s3, s30
	s_nop 0
	s_add_u32 vcc_lo, s0, s34
	s_addc_u32 vcc_hi, s1, s35
	global_load_lds_dwordx4 v128, vcc
	v_lshl_add_u64 v[248:249], v[246:247], 0, s[34:35]
	s_add_u32 m0, s3, s30
	s_add_u32 m0, m0, 0x2000
	s_nop 0
	global_load_lds_dwordx4 v130, vcc
	s_setprio 1
	s_barrier
	s_waitcnt lgkmcnt(0)
	v_mfma_f32_16x16x32_bf16 v[92:95], v[226:229], v[178:181], v[92:95]
	v_mfma_f32_16x16x32_bf16 v[88:91], v[234:237], v[178:181], v[88:91]
	v_mfma_f32_16x16x32_bf16 v[84:87], v[226:229], v[186:189], v[84:87]
	v_mfma_f32_16x16x32_bf16 v[80:83], v[234:237], v[186:189], v[80:83]
	v_mfma_f32_16x16x32_bf16 v[76:79], v[226:229], v[198:201], v[76:79]
	v_mfma_f32_16x16x32_bf16 v[72:75], v[234:237], v[198:201], v[72:75]
	v_mfma_f32_16x16x32_bf16 v[68:71], v[226:229], v[206:209], v[68:71]
	v_mfma_f32_16x16x32_bf16 v[64:67], v[234:237], v[206:209], v[64:67]
	v_mfma_f32_16x16x32_bf16 v[92:95], v[230:233], v[182:185], v[92:95]
	ds_read_b128 v[178:181], v137 offset:49152
	v_mfma_f32_16x16x32_bf16 v[88:91], v[238:241], v[182:185], v[88:91]
	v_mfma_f32_16x16x32_bf16 v[84:87], v[230:233], v[194:197], v[84:87]
	ds_read_b128 v[186:189], v137 offset:51200
	v_mfma_f32_16x16x32_bf16 v[80:83], v[238:241], v[194:197], v[80:83]
	v_mfma_f32_16x16x32_bf16 v[76:79], v[230:233], v[202:205], v[76:79]
	ds_read_b128 v[198:201], v137 offset:53248
	v_mfma_f32_16x16x32_bf16 v[72:75], v[238:241], v[202:205], v[72:75]
	v_mfma_f32_16x16x32_bf16 v[68:71], v[230:233], v[222:225], v[68:71]
	ds_read_b128 v[206:209], v137 offset:55296
	v_mfma_f32_16x16x32_bf16 v[64:67], v[238:241], v[222:225], v[64:67]
	s_barrier
	s_setprio 0
	ds_read_b128 v[182:185], v137 offset:50176
	ds_read_b128 v[194:197], v137 offset:52224
	ds_read_b128 v[202:205], v137 offset:54272
	ds_read_b128 v[222:225], v137 offset:56320
	v_add_u32_e32 v248, 0x8000, v192
	s_add_u32 m0, s3, 0x8000
	s_nop 0
	s_add_u32 vcc_lo, s0, s36
	s_addc_u32 vcc_hi, s1, s37
	global_load_lds_dwordx4 v132, vcc
	s_add_u32 m0, s3, 0xa000
	s_nop 0
	global_load_lds_dwordx4 v134, vcc
	s_waitcnt vmcnt(8)
	s_setprio 1
	s_barrier
; #define WAIT_V(n) asm volatile("s_waitcnt vmcnt(" #n ")" ::: "memory")
; #define WAIT_L(n) asm volatile("s_waitcnt lgkmcnt(" #n ")" ::: "memory")
; #define BAR __builtin_amdgcn_s_barrier()
; #define SCHED __builtin_amdgcn_sched_barrier(0)
; #define STAGE(P, BASE, br, kt) do { const char* _g = (const char*)((BASE) + (size_t)(br) * GK + (kt) * BK); \
;     __builtin_amdgcn_global_load_lds((const unsigned*)(_g + voff0), (unsigned*)((char*)(P) + tx * 16), 16, 0, 0); \
;     __builtin_amdgcn_global_load_lds((const unsigned*)(_g + voff1), (unsigned*)((char*)(P) + tx * 16 + 8192), 16, 0, 0); } while (0)
; #define LDA(dst, b, h) _Pragma("unroll") for (int m = 0; m < 4; ++m) _Pragma("unroll") for (int k = 0; k < 2; ++k) \
;     dst[m][k] = *reinterpret_cast<const bf16x8*>((char*)shm + abase + (((b) * 2 + (h)) * 16384 + (m * 2 + k) * 1024))
; #define LDB(dst, b, h) _Pragma("unroll") for (int n = 0; n < 2; ++n) _Pragma("unroll") for (int k = 0; k < 2; ++k) \
;     dst[n][k] = *reinterpret_cast<const bf16x8*>((char*)shm + bbase + (((b) * 2 + (h)) * 16384 + (n * 2 + k) * 1024))
; template <bool SWAP>
; __device__ __forceinline__ void gemm_main(const u16* __restrict__ A, const u16* __restrict__ Bt, int brow, int bcol,
;                                           u16* shm, f32x4 (&acc)[2][2][4][2]) {
;     ...
;     LDA(At, 1, 1); STAGE(SA(1, 0), A, brow, t + 3);
;     BAR; WAIT_L(0); MMA(1, 0, At, B0); BAR; SCHED;
;     STAGE(SB(1, 1), Bt, bcol + HALF, t + 3);
;     WAIT_V(6); BAR; MMA(1, 1, At, B1); BAR;
;   }
;   { LDB(B0, 0, 0); LDA(At, 0, 0); STAGE(SA(1, 1), A, brow + HALF, nt - 1);
;     BAR; WAIT_L(0); MMA(0, 0, At, B0); BAR;
	s_waitcnt lgkmcnt(0)
	v_mfma_f32_16x16x32_bf16 v[60:63], v[162:165], v[178:181], v[60:63]
	v_mfma_f32_16x16x32_bf16 v[56:59], v[170:173], v[178:181], v[56:59]
	v_mfma_f32_16x16x32_bf16 v[52:55], v[162:165], v[186:189], v[52:55]
	v_mfma_f32_16x16x32_bf16 v[48:51], v[170:173], v[186:189], v[48:51]
	v_mfma_f32_16x16x32_bf16 v[44:47], v[162:165], v[198:201], v[44:47]
	v_mfma_f32_16x16x32_bf16 v[40:43], v[170:173], v[198:201], v[40:43]
	v_mfma_f32_16x16x32_bf16 v[36:39], v[162:165], v[206:209], v[36:39]
	v_mfma_f32_16x16x32_bf16 v[32:35], v[170:173], v[206:209], v[32:35]
	v_mfma_f32_16x16x32_bf16 v[60:63], v[166:169], v[182:185], v[60:63]
	v_mfma_f32_16x16x32_bf16 v[56:59], v[174:177], v[182:185], v[56:59]
	v_mfma_f32_16x16x32_bf16 v[52:55], v[166:169], v[194:197], v[52:55]
	v_mfma_f32_16x16x32_bf16 v[48:51], v[174:177], v[194:197], v[48:51]
	v_mfma_f32_16x16x32_bf16 v[44:47], v[166:169], v[202:205], v[44:47]
	v_mfma_f32_16x16x32_bf16 v[40:43], v[174:177], v[202:205], v[40:43]
	v_mfma_f32_16x16x32_bf16 v[36:39], v[166:169], v[222:225], v[36:39]
	v_mfma_f32_16x16x32_bf16 v[32:35], v[174:177], v[222:225], v[32:35]
	s_barrier
	s_setprio 0
	ds_read_b128 v[162:165], v152
	ds_read_b128 v[166:169], v152 offset:1024
	ds_read_b128 v[170:173], v152 offset:2048
	ds_read_b128 v[174:177], v152 offset:3072
	s_add_u32 m0, s3, s31
	s_nop 0
	s_add_u32 vcc_lo, s0, s64
	s_addc_u32 vcc_hi, s1, s65
	global_load_lds_dwordx4 v128, vcc
	v_lshl_add_u64 v[254:255], v[246:247], 0, s[64:65]
	s_add_u32 m0, s3, s31
	s_add_u32 m0, m0, 0x2000
	s_nop 0
	global_load_lds_dwordx4 v130, vcc
	s_setprio 1
	s_barrier
	v_mfma_f32_16x16x32_bf16 v[28:31], v[226:229], v[178:181], v[28:31]
	v_mfma_f32_16x16x32_bf16 v[24:27], v[234:237], v[178:181], v[24:27]
	v_mfma_f32_16x16x32_bf16 v[20:23], v[226:229], v[186:189], v[20:23]
	v_mfma_f32_16x16x32_bf16 v[16:19], v[234:237], v[186:189], v[16:19]
	v_mfma_f32_16x16x32_bf16 v[12:15], v[226:229], v[198:201], v[12:15]
	v_mfma_f32_16x16x32_bf16 v[8:11], v[234:237], v[198:201], v[8:11]
	v_mfma_f32_16x16x32_bf16 v[4:7], v[226:229], v[206:209], v[4:7]
	v_mfma_f32_16x16x32_bf16 v[0:3], v[234:237], v[206:209], v[0:3]
	v_mfma_f32_16x16x32_bf16 v[28:31], v[230:233], v[182:185], v[28:31]
	ds_read_b128 v[178:181], v137
	v_mfma_f32_16x16x32_bf16 v[24:27], v[238:241], v[182:185], v[24:27]
	v_mfma_f32_16x16x32_bf16 v[20:23], v[230:233], v[194:197], v[20:23]
	ds_read_b128 v[186:189], v137 offset:2048
	v_mfma_f32_16x16x32_bf16 v[16:19], v[238:241], v[194:197], v[16:19]
	v_mfma_f32_16x16x32_bf16 v[12:15], v[230:233], v[202:205], v[12:15]
	ds_read_b128 v[198:201], v137 offset:4096
	v_mfma_f32_16x16x32_bf16 v[8:11], v[238:241], v[202:205], v[8:11]
	v_mfma_f32_16x16x32_bf16 v[4:7], v[230:233], v[222:225], v[4:7]
	ds_read_b128 v[206:209], v137 offset:6144
	v_mfma_f32_16x16x32_bf16 v[0:3], v[238:241], v[222:225], v[0:3]
	s_add_i32 s2, s2, 2
	s_add_u32 s0, s0, 0x100
	s_addc_u32 s1, s1, 0
	s_cmp_lt_u32 s2, 28
	s_barrier
	s_setprio 0
	s_cbranch_scc1 .LBB0_200
	v_lshlrev_b32_e32 v128, 3, v154
	v_lshlrev_b32_e32 v129, 5, v154
	v_and_b32_e32 v128, 0xffff0, v128
	v_and_b32_e32 v129, 32, v129
	s_or_b32 s0, s24, 0x80
	v_add_u32_e32 v129, v129, v156
	v_add_lshl_u32 v128, v155, v128, 12
	s_ashr_i32 s1, s0, 31
	v_lshl_add_u32 v192, v129, 1, v128
	v_lshlrev_b32_e32 v128, 3, v157
	v_lshlrev_b32_e32 v129, 5, v157
	s_lshl_b64 s[0:1], s[0:1], 12
	v_readlane_b32 s2, v253, 35
	v_and_b32_e32 v128, 0xffff0, v128
	v_and_b32_e32 v129, 32, v129
	v_readlane_b32 s3, v253, 36
	s_add_u32 s0, s2, s0
	v_add_u32_e32 v129, v129, v159
	v_add_lshl_u32 v128, v158, v128, 12
	s_addc_u32 s1, s3, s1
	v_lshl_add_u32 v158, v129, 1, v128
	v_mov_b32_e32 v159, v193
	v_lshl_add_u64 v[190:191], s[0:1], 0, v[192:193]
	s_mov_b64 s[4:5], 0xf80
	v_readfirstlane_b32 s2, v160
	v_lshl_add_u64 v[190:191], v[190:191], 0, s[4:5]
	s_mov_b32 m0, s2
	v_lshl_add_u64 v[158:159], s[0:1], 0, v[158:159]
	v_readfirstlane_b32 s0, v161
	ds_read_b128 v[128:131], v152
	ds_read_b128 v[132:135], v152 offset:1024
	ds_read_b128 v[154:157], v152 offset:2048
	ds_read_b128 v[162:165], v152 offset:3072
	ds_read_b128 v[166:169], v137
	ds_read_b128 v[170:173], v137 offset:1024
	ds_read_b128 v[174:177], v137 offset:2048
	ds_read_b128 v[178:181], v137 offset:3072
	ds_read_b128 v[182:185], v137 offset:4096
	ds_read_b128 v[186:189], v137 offset:5120
	ds_read_b128 v[194:197], v137 offset:6144
	ds_read_b128 v[198:201], v137 offset:7168
	global_load_lds_dwordx4 v[190:191], off
	v_lshl_add_u64 v[158:159], v[158:159], 0, s[4:5]
	s_mov_b32 m0, s0
	s_nop 0
	global_load_lds_dwordx4 v[158:159], off
	s_waitcnt vmcnt(8)
	s_barrier
	s_waitcnt lgkmcnt(0)
	s_setprio 1
	s_waitcnt lgkmcnt(0)
	v_mfma_f32_16x16x32_bf16 v[124:127], v[128:131], v[166:169], v[124:127]
	v_mfma_f32_16x16x32_bf16 v[116:119], v[128:131], v[174:177], v[116:119]
	v_mfma_f32_16x16x32_bf16 v[108:111], v[128:131], v[182:185], v[108:111]
	v_mfma_f32_16x16x32_bf16 v[100:103], v[128:131], v[194:197], v[100:103]
	v_mfma_f32_16x16x32_bf16 v[124:127], v[132:135], v[170:173], v[124:127]
	v_mfma_f32_16x16x32_bf16 v[120:123], v[154:157], v[166:169], v[120:123]
	v_mfma_f32_16x16x32_bf16 v[116:119], v[132:135], v[178:181], v[116:119]
	v_mfma_f32_16x16x32_bf16 v[112:115], v[154:157], v[174:177], v[112:115]
	v_mfma_f32_16x16x32_bf16 v[108:111], v[132:135], v[186:189], v[108:111]
	v_mfma_f32_16x16x32_bf16 v[104:107], v[154:157], v[182:185], v[104:107]
	v_mfma_f32_16x16x32_bf16 v[100:103], v[132:135], v[198:201], v[100:103]
	v_mfma_f32_16x16x32_bf16 v[96:99], v[154:157], v[194:197], v[96:99]
	v_mfma_f32_16x16x32_bf16 v[158:161], v[162:165], v[170:173], v[120:123]
	v_mfma_f32_16x16x32_bf16 v[202:205], v[162:165], v[178:181], v[112:115]
	v_mfma_f32_16x16x32_bf16 v[206:209], v[162:165], v[186:189], v[104:107]
	v_mfma_f32_16x16x32_bf16 v[222:225], v[162:165], v[198:201], v[96:99]
	s_setprio 0
	s_barrier
; #define WAIT_V(n) asm volatile("s_waitcnt vmcnt(" #n ")" ::: "memory")
; #define WAIT_L(n) asm volatile("s_waitcnt lgkmcnt(" #n ")" ::: "memory")
; #define BAR __builtin_amdgcn_s_barrier()
; #define LDA(dst, b, h) _Pragma("unroll") for (int m = 0; m < 4; ++m) _Pragma("unroll") for (int k = 0; k < 2; ++k) \
;     dst[m][k] = *reinterpret_cast<const bf16x8*>((char*)shm + abase + (((b) * 2 + (h)) * 16384 + (m * 2 + k) * 1024))
; #define LDB(dst, b, h) _Pragma("unroll") for (int n = 0; n < 2; ++n) _Pragma("unroll") for (int k = 0; k < 2; ++k) \
;     dst[n][k] = *reinterpret_cast<const bf16x8*>((char*)shm + bbase + (((b) * 2 + (h)) * 16384 + (n * 2 + k) * 1024))
; template <bool SWAP>
; __device__ __forceinline__ void gemm_main(const u16* __restrict__ A, const u16* __restrict__ Bt, int brow, int bcol,
;                                           u16* shm, f32x4 (&acc)[2][2][4][2]) {
;     ...
;     BAR; WAIT_L(0); MMA(0, 0, At, B0); BAR;
;     LDB(B1, 0, 1); BAR; WAIT_L(0); MMA(0, 1, At, B1); BAR;
;     LDA(At, 0, 1); WAIT_V(4); BAR; WAIT_L(0); MMA(1, 0, At, B0); MMA(1, 1, At, B1); BAR; }
;   { LDB(B0, 1, 0); LDA(At, 1, 0); WAIT_V(2); BAR; WAIT_L(0); MMA(0, 0, At, B0); BAR;
	s_nop 1
	ds_read_b128 v[96:99], v152 offset:16384
	ds_read_b128 v[104:107], v152 offset:17408
	ds_read_b128 v[112:115], v152 offset:18432
	ds_read_b128 v[120:123], v152 offset:19456
	s_barrier
	s_waitcnt lgkmcnt(0)
	s_setprio 1
	s_waitcnt lgkmcnt(0)
	v_mfma_f32_16x16x32_bf16 v[92:95], v[96:99], v[166:169], v[92:95]
	v_mfma_f32_16x16x32_bf16 v[84:87], v[96:99], v[174:177], v[84:87]
	v_mfma_f32_16x16x32_bf16 v[76:79], v[96:99], v[182:185], v[76:79]
	v_mfma_f32_16x16x32_bf16 v[68:71], v[96:99], v[194:197], v[68:71]
	v_mfma_f32_16x16x32_bf16 v[92:95], v[104:107], v[170:173], v[92:95]
	v_mfma_f32_16x16x32_bf16 v[88:91], v[112:115], v[166:169], v[88:91]
	v_mfma_f32_16x16x32_bf16 v[84:87], v[104:107], v[178:181], v[84:87]
	v_mfma_f32_16x16x32_bf16 v[80:83], v[112:115], v[174:177], v[80:83]
	v_mfma_f32_16x16x32_bf16 v[76:79], v[104:107], v[186:189], v[76:79]
	v_mfma_f32_16x16x32_bf16 v[72:75], v[112:115], v[182:185], v[72:75]
	v_mfma_f32_16x16x32_bf16 v[68:71], v[104:107], v[198:201], v[68:71]
	v_mfma_f32_16x16x32_bf16 v[64:67], v[112:115], v[194:197], v[64:67]
	v_mfma_f32_16x16x32_bf16 v[166:169], v[120:123], v[170:173], v[88:91]
	v_mfma_f32_16x16x32_bf16 v[170:173], v[120:123], v[178:181], v[80:83]
	v_mfma_f32_16x16x32_bf16 v[174:177], v[120:123], v[186:189], v[72:75]
	v_mfma_f32_16x16x32_bf16 v[178:181], v[120:123], v[198:201], v[64:67]
	s_setprio 0
	s_barrier
	s_nop 1
	ds_read_b128 v[64:67], v137 offset:16384
	ds_read_b128 v[72:75], v137 offset:17408
	ds_read_b128 v[80:83], v137 offset:18432
	ds_read_b128 v[88:91], v137 offset:19456
	ds_read_b128 v[182:185], v137 offset:20480
	ds_read_b128 v[186:189], v137 offset:21504
	ds_read_b128 v[194:197], v137 offset:22528
	ds_read_b128 v[198:201], v137 offset:23552
	s_waitcnt vmcnt(4)
	s_barrier
	s_waitcnt lgkmcnt(0)
	s_setprio 1
	s_waitcnt lgkmcnt(0)
	v_mfma_f32_16x16x32_bf16 v[60:63], v[128:131], v[64:67], v[60:63]
	v_mfma_f32_16x16x32_bf16 v[52:55], v[128:131], v[80:83], v[52:55]
	v_mfma_f32_16x16x32_bf16 v[44:47], v[128:131], v[182:185], v[44:47]
	v_mfma_f32_16x16x32_bf16 v[36:39], v[128:131], v[194:197], v[36:39]
	v_mfma_f32_16x16x32_bf16 v[60:63], v[132:135], v[72:75], v[60:63]
	v_mfma_f32_16x16x32_bf16 v[56:59], v[154:157], v[64:67], v[56:59]
	v_mfma_f32_16x16x32_bf16 v[52:55], v[132:135], v[88:91], v[52:55]
	v_mfma_f32_16x16x32_bf16 v[48:51], v[154:157], v[80:83], v[48:51]
	v_mfma_f32_16x16x32_bf16 v[44:47], v[132:135], v[186:189], v[44:47]
	v_mfma_f32_16x16x32_bf16 v[40:43], v[154:157], v[182:185], v[40:43]
	v_mfma_f32_16x16x32_bf16 v[36:39], v[132:135], v[198:201], v[36:39]
	v_mfma_f32_16x16x32_bf16 v[32:35], v[154:157], v[194:197], v[32:35]
	v_mfma_f32_16x16x32_bf16 v[226:229], v[162:165], v[72:75], v[56:59]
	v_mfma_f32_16x16x32_bf16 v[230:233], v[162:165], v[88:91], v[48:51]
	v_mfma_f32_16x16x32_bf16 v[234:237], v[162:165], v[186:189], v[40:43]
	v_mfma_f32_16x16x32_bf16 v[128:131], v[162:165], v[198:201], v[32:35]
	s_setprio 0
	s_setprio 1
	v_mfma_f32_16x16x32_bf16 v[28:31], v[96:99], v[64:67], v[28:31]
	v_mfma_f32_16x16x32_bf16 v[20:23], v[96:99], v[80:83], v[20:23]
	v_mfma_f32_16x16x32_bf16 v[12:15], v[96:99], v[182:185], v[12:15]
	v_mfma_f32_16x16x32_bf16 v[4:7], v[96:99], v[194:197], v[4:7]
	v_mfma_f32_16x16x32_bf16 v[28:31], v[104:107], v[72:75], v[28:31]
	v_mfma_f32_16x16x32_bf16 v[24:27], v[112:115], v[64:67], v[24:27]
	v_mfma_f32_16x16x32_bf16 v[20:23], v[104:107], v[88:91], v[20:23]
	v_mfma_f32_16x16x32_bf16 v[16:19], v[112:115], v[80:83], v[16:19]
	v_mfma_f32_16x16x32_bf16 v[12:15], v[104:107], v[186:189], v[12:15]
	v_mfma_f32_16x16x32_bf16 v[8:11], v[112:115], v[182:185], v[8:11]
	v_mfma_f32_16x16x32_bf16 v[4:7], v[104:107], v[198:201], v[4:7]
	v_mfma_f32_16x16x32_bf16 v[0:3], v[112:115], v[194:197], v[0:3]
	v_mfma_f32_16x16x32_bf16 v[132:135], v[120:123], v[72:75], v[24:27]
	v_mfma_f32_16x16x32_bf16 v[154:157], v[120:123], v[88:91], v[16:19]
	v_mfma_f32_16x16x32_bf16 v[162:165], v[120:123], v[186:189], v[8:11]
	v_mfma_f32_16x16x32_bf16 v[182:185], v[120:123], v[198:201], v[0:3]
	s_setprio 0
	s_barrier
	s_nop 1
	ds_read_b128 v[0:3], v152 offset:32768
	ds_read_b128 v[8:11], v152 offset:33792
	ds_read_b128 v[16:19], v152 offset:34816
	ds_read_b128 v[24:27], v152 offset:35840
	ds_read_b128 v[32:35], v137 offset:32768
	ds_read_b128 v[40:43], v137 offset:33792
	ds_read_b128 v[48:51], v137 offset:34816
	ds_read_b128 v[56:59], v137 offset:35840
	ds_read_b128 v[64:67], v137 offset:36864
	ds_read_b128 v[186:189], v137 offset:37888
	ds_read_b128 v[194:197], v137 offset:38912
	ds_read_b128 v[198:201], v137 offset:39936
	s_waitcnt vmcnt(2)
	s_barrier
; #define WAIT_V(n) asm volatile("s_waitcnt vmcnt(" #n ")" ::: "memory")
; #define WAIT_L(n) asm volatile("s_waitcnt lgkmcnt(" #n ")" ::: "memory")
; #define BAR __builtin_amdgcn_s_barrier()
; #define LDA(dst, b, h) _Pragma("unroll") for (int m = 0; m < 4; ++m) _Pragma("unroll") for (int k = 0; k < 2; ++k) \
;     dst[m][k] = *reinterpret_cast<const bf16x8*>((char*)shm + abase + (((b) * 2 + (h)) * 16384 + (m * 2 + k) * 1024))
; #define LDB(dst, b, h) _Pragma("unroll") for (int n = 0; n < 2; ++n) _Pragma("unroll") for (int k = 0; k < 2; ++k) \
;     dst[n][k] = *reinterpret_cast<const bf16x8*>((char*)shm + bbase + (((b) * 2 + (h)) * 16384 + (n * 2 + k) * 1024))
; template <bool SWAP>
; __device__ __forceinline__ void gemm_main(const u16* __restrict__ A, const u16* __restrict__ Bt, int brow, int bcol,
;                                           u16* shm, f32x4 (&acc)[2][2][4][2]) {
;     ...
;   { LDB(B0, 1, 0); LDA(At, 1, 0); WAIT_V(2); BAR; WAIT_L(0); MMA(0, 0, At, B0); BAR;
;     LDB(B1, 1, 1); WAIT_V(0); BAR; WAIT_L(0); MMA(0, 1, At, B1); BAR;
;     LDA(At, 1, 1); BAR; WAIT_L(0); MMA(1, 0, At, B0); MMA(1, 1, At, B1); BAR; }
;   if (wr == 0) BAR;
	s_waitcnt lgkmcnt(0)
	s_setprio 1
	s_waitcnt lgkmcnt(0)
	v_mfma_f32_16x16x32_bf16 v[72:75], v[0:3], v[32:35], v[124:127]
	v_mfma_f32_16x16x32_bf16 v[120:123], v[8:11], v[40:43], v[72:75]
	v_mfma_f32_16x16x32_bf16 v[72:75], v[16:19], v[32:35], v[158:161]
	v_mfma_f32_16x16x32_bf16 v[124:127], v[24:27], v[40:43], v[72:75]
	v_mfma_f32_16x16x32_bf16 v[72:75], v[0:3], v[48:51], v[116:119]
	v_mfma_f32_16x16x32_bf16 v[112:115], v[8:11], v[56:59], v[72:75]
	v_mfma_f32_16x16x32_bf16 v[72:75], v[16:19], v[48:51], v[202:205]
	v_mfma_f32_16x16x32_bf16 v[116:119], v[24:27], v[56:59], v[72:75]
	v_mfma_f32_16x16x32_bf16 v[72:75], v[0:3], v[64:67], v[108:111]
	v_mfma_f32_16x16x32_bf16 v[104:107], v[8:11], v[186:189], v[72:75]
	v_mfma_f32_16x16x32_bf16 v[72:75], v[16:19], v[64:67], v[206:209]
	v_mfma_f32_16x16x32_bf16 v[108:111], v[24:27], v[186:189], v[72:75]
	v_mfma_f32_16x16x32_bf16 v[72:75], v[0:3], v[194:197], v[100:103]
	v_mfma_f32_16x16x32_bf16 v[96:99], v[8:11], v[198:201], v[72:75]
	v_mfma_f32_16x16x32_bf16 v[72:75], v[16:19], v[194:197], v[222:225]
	v_mfma_f32_16x16x32_bf16 v[100:103], v[24:27], v[198:201], v[72:75]
	s_setprio 0
	s_barrier
	ds_read_b128 v[158:161], v152 offset:49152
	ds_read_b128 v[202:205], v152 offset:50176
	ds_read_b128 v[206:209], v152 offset:51200
	ds_read_b128 v[222:225], v152 offset:52224
	s_waitcnt vmcnt(0)
	s_barrier
	s_waitcnt lgkmcnt(0)
	s_setprio 1
	s_waitcnt lgkmcnt(0)
	v_mfma_f32_16x16x32_bf16 v[72:75], v[158:161], v[32:35], v[92:95]
	v_mfma_f32_16x16x32_bf16 v[32:35], v[206:209], v[32:35], v[166:169]
	v_mfma_f32_16x16x32_bf16 v[92:95], v[222:225], v[40:43], v[32:35]
	v_mfma_f32_16x16x32_bf16 v[32:35], v[158:161], v[48:51], v[84:87]
	v_mfma_f32_16x16x32_bf16 v[80:83], v[202:205], v[56:59], v[32:35]
	v_mfma_f32_16x16x32_bf16 v[32:35], v[206:209], v[48:51], v[170:173]
	v_mfma_f32_16x16x32_bf16 v[84:87], v[222:225], v[56:59], v[32:35]
	v_mfma_f32_16x16x32_bf16 v[32:35], v[158:161], v[64:67], v[76:79]
	v_mfma_f32_16x16x32_bf16 v[88:91], v[202:205], v[40:43], v[72:75]
	v_mfma_f32_16x16x32_bf16 v[72:75], v[202:205], v[186:189], v[32:35]
	v_mfma_f32_16x16x32_bf16 v[32:35], v[206:209], v[64:67], v[174:177]
	v_mfma_f32_16x16x32_bf16 v[76:79], v[222:225], v[186:189], v[32:35]
	v_mfma_f32_16x16x32_bf16 v[32:35], v[158:161], v[194:197], v[68:71]
	v_mfma_f32_16x16x32_bf16 v[64:67], v[202:205], v[198:201], v[32:35]
	v_mfma_f32_16x16x32_bf16 v[32:35], v[206:209], v[194:197], v[178:181]
	v_mfma_f32_16x16x32_bf16 v[68:71], v[222:225], v[198:201], v[32:35]
	s_setprio 0
	s_barrier
	ds_read_b128 v[166:169], v137 offset:49152
	ds_read_b128 v[170:173], v137 offset:50176
	ds_read_b128 v[174:177], v137 offset:51200
	ds_read_b128 v[178:181], v137 offset:52224
	ds_read_b128 v[186:189], v137 offset:53248
	ds_read_b128 v[194:197], v137 offset:54272
	ds_read_b128 v[198:201], v137 offset:55296
	ds_read_b128 v[238:241], v137 offset:56320
	s_barrier
	s_waitcnt lgkmcnt(0)
	s_setprio 1
	s_waitcnt lgkmcnt(0)
	v_mfma_f32_16x16x32_bf16 v[32:35], v[0:3], v[166:169], v[60:63]
	v_mfma_f32_16x16x32_bf16 v[56:59], v[8:11], v[170:173], v[32:35]
	v_mfma_f32_16x16x32_bf16 v[32:35], v[16:19], v[166:169], v[226:229]
	v_mfma_f32_16x16x32_bf16 v[60:63], v[24:27], v[170:173], v[32:35]
	v_mfma_f32_16x16x32_bf16 v[32:35], v[0:3], v[174:177], v[52:55]
	v_mfma_f32_16x16x32_bf16 v[48:51], v[8:11], v[178:181], v[32:35]
	v_mfma_f32_16x16x32_bf16 v[32:35], v[16:19], v[174:177], v[230:233]
	v_mfma_f32_16x16x32_bf16 v[52:55], v[24:27], v[178:181], v[32:35]
	v_mfma_f32_16x16x32_bf16 v[32:35], v[0:3], v[186:189], v[44:47]
	v_mfma_f32_16x16x32_bf16 v[40:43], v[8:11], v[194:197], v[32:35]
	v_mfma_f32_16x16x32_bf16 v[32:35], v[16:19], v[186:189], v[234:237]
	v_mfma_f32_16x16x32_bf16 v[0:3], v[0:3], v[198:201], v[36:39]
	v_mfma_f32_16x16x32_bf16 v[44:47], v[24:27], v[194:197], v[32:35]
	v_mfma_f32_16x16x32_bf16 v[32:35], v[8:11], v[238:241], v[0:3]
	v_mfma_f32_16x16x32_bf16 v[0:3], v[16:19], v[198:201], v[128:131]
	v_mfma_f32_16x16x32_bf16 v[36:39], v[24:27], v[238:241], v[0:3]
	s_setprio 0
	s_setprio 1
	v_mfma_f32_16x16x32_bf16 v[0:3], v[158:161], v[166:169], v[28:31]
	v_mfma_f32_16x16x32_bf16 v[24:27], v[202:205], v[170:173], v[0:3]
	v_mfma_f32_16x16x32_bf16 v[0:3], v[206:209], v[166:169], v[132:135]
	v_mfma_f32_16x16x32_bf16 v[28:31], v[222:225], v[170:173], v[0:3]
	v_mfma_f32_16x16x32_bf16 v[0:3], v[158:161], v[174:177], v[20:23]
	v_mfma_f32_16x16x32_bf16 v[16:19], v[202:205], v[178:181], v[0:3]
	v_mfma_f32_16x16x32_bf16 v[0:3], v[206:209], v[174:177], v[154:157]
	v_mfma_f32_16x16x32_bf16 v[20:23], v[222:225], v[178:181], v[0:3]
	v_mfma_f32_16x16x32_bf16 v[0:3], v[158:161], v[186:189], v[12:15]
	v_mfma_f32_16x16x32_bf16 v[8:11], v[202:205], v[194:197], v[0:3]
	v_mfma_f32_16x16x32_bf16 v[0:3], v[206:209], v[186:189], v[162:165]
	v_mfma_f32_16x16x32_bf16 v[12:15], v[222:225], v[194:197], v[0:3]
	v_mfma_f32_16x16x32_bf16 v[0:3], v[158:161], v[198:201], v[4:7]
	v_mfma_f32_16x16x32_bf16 v[4:7], v[206:209], v[198:201], v[182:185]
	v_mfma_f32_16x16x32_bf16 v[0:3], v[202:205], v[238:241], v[0:3]
	v_mfma_f32_16x16x32_bf16 v[4:7], v[222:225], v[238:241], v[4:7]
	s_setprio 0
	s_movk_i32 s0, 0x100
	v_cmp_gt_u32_e32 vcc, s0, v136
	s_barrier
	s_and_saveexec_b64 s[0:1], vcc
	s_cbranch_execz .LBB0_203
	s_barrier

; #define WAIT_V(n) asm volatile("s_waitcnt vmcnt(" #n ")" ::: "memory")
; #define WAIT_L(n) asm volatile("s_waitcnt lgkmcnt(" #n ")" ::: "memory")
; #define BAR __builtin_amdgcn_s_barrier()
; #define SCHED __builtin_amdgcn_sched_barrier(0)
; #define STAGE(P, BASE, br, kt) do { const char* _g = (const char*)((BASE) + (size_t)(br) * GK + (kt) * BK); \
;     __builtin_amdgcn_global_load_lds((const unsigned*)(_g + voff0), (unsigned*)((char*)(P) + tx * 16), 16, 0, 0); \
;     __builtin_amdgcn_global_load_lds((const unsigned*)(_g + voff1), (unsigned*)((char*)(P) + tx * 16 + 8192), 16, 0, 0); } while (0)
; #define LDA(dst, b, h) _Pragma("unroll") for (int m = 0; m < 4; ++m) _Pragma("unroll") for (int k = 0; k < 2; ++k) \
;     dst[m][k] = *reinterpret_cast<const bf16x8*>((char*)shm + abase + (((b) * 2 + (h)) * 16384 + (m * 2 + k) * 1024))
; #define LDB(dst, b, h) _Pragma("unroll") for (int n = 0; n < 2; ++n) _Pragma("unroll") for (int k = 0; k < 2; ++k) \
;     dst[n][k] = *reinterpret_cast<const bf16x8*>((char*)shm + bbase + (((b) * 2 + (h)) * 16384 + (n * 2 + k) * 1024))
; template <bool SWAP>
; __device__ __forceinline__ void gemm_main(const u16* __restrict__ A, const u16* __restrict__ Bt, int brow, int bcol,
;                                           u16* shm, f32x4 (&acc)[2][2][4][2]) {
;     ...
;     LDB(B0, 0, 0); SCHED; LDA(At, 0, 0); STAGE(SA(1, 1), A, brow + HALF, t + 1);
;     WAIT_L(8); BAR; WAIT_L(0); MMA(0, 0, At, B0); BAR; SCHED;
;     LDB(B1, 0, 1); STAGE(SB(0, 0), Bt, bcol, t + 2);
;     BAR; WAIT_L(0); MMA(0, 1, At, B1); BAR;
;     LDA(At, 0, 1); STAGE(SA(0, 0), A, brow, t + 2);
;     BAR; WAIT_L(0); MMA(1, 0, At, B0); BAR; SCHED;
;     STAGE(SB(0, 1), Bt, bcol + HALF, t + 2);
;     WAIT_V(6); BAR; MMA(1, 1, At, B1); BAR;
.LBB0_436:
	ds_read_b128 v[170:173], v137 offset:1024
	ds_read_b128 v[178:181], v137 offset:3072
	ds_read_b128 v[186:189], v137 offset:5120
	ds_read_b128 v[198:201], v137 offset:7168
	v_add_u32_e32 v192, 0, v139
	v_add_u32_e32 v148, 0xc000, v192
	v_add_u32_e32 v149, 0xe000, v192
	s_add_u32 m0, s2, 0xc000
	v_lshl_add_u64 v[232:233], s[50:51], 0, v[134:135]
	s_add_u32 vcc_lo, s50, s82
	s_addc_u32 vcc_hi, s51, s83
	global_load_lds_dwordx4 v132, vcc
	s_add_u32 m0, s2, 0xe000
	s_nop 0
	global_load_lds_dwordx4 v134, vcc
	s_waitcnt lgkmcnt(8)
	s_waitcnt vmcnt(8)
	s_setprio 1
	s_barrier
	s_waitcnt lgkmcnt(0)
	v_mfma_f32_16x16x32_bf16 v[124:127], v[150:153], v[166:169], v[124:127]
	v_mfma_f32_16x16x32_bf16 v[120:123], v[158:161], v[166:169], v[120:123]
	v_mfma_f32_16x16x32_bf16 v[116:119], v[150:153], v[174:177], v[116:119]
	v_mfma_f32_16x16x32_bf16 v[112:115], v[158:161], v[174:177], v[112:115]
	v_mfma_f32_16x16x32_bf16 v[108:111], v[150:153], v[182:185], v[108:111]
	v_mfma_f32_16x16x32_bf16 v[104:107], v[158:161], v[182:185], v[104:107]
	v_mfma_f32_16x16x32_bf16 v[100:103], v[150:153], v[194:197], v[100:103]
	v_mfma_f32_16x16x32_bf16 v[96:99], v[158:161], v[194:197], v[96:99]
	v_mfma_f32_16x16x32_bf16 v[124:127], v[154:157], v[170:173], v[124:127]
	v_mfma_f32_16x16x32_bf16 v[120:123], v[162:165], v[170:173], v[120:123]
	v_mfma_f32_16x16x32_bf16 v[116:119], v[154:157], v[178:181], v[116:119]
	v_mfma_f32_16x16x32_bf16 v[112:115], v[162:165], v[178:181], v[112:115]
	v_mfma_f32_16x16x32_bf16 v[108:111], v[154:157], v[186:189], v[108:111]
	v_mfma_f32_16x16x32_bf16 v[104:107], v[162:165], v[186:189], v[104:107]
	v_mfma_f32_16x16x32_bf16 v[100:103], v[154:157], v[198:201], v[100:103]
	v_mfma_f32_16x16x32_bf16 v[96:99], v[162:165], v[198:201], v[96:99]
	s_barrier
	s_setprio 0
	ds_read_b128 v[202:205], v138 offset:16384
	ds_read_b128 v[206:209], v138 offset:17408
	ds_read_b128 v[224:227], v138 offset:18432
	ds_read_b128 v[228:231], v138 offset:19456
	s_add_u32 m0, s2, s28
	s_nop 0
	s_add_u32 vcc_lo, s50, s74
	s_addc_u32 vcc_hi, s51, s75
	global_load_lds_dwordx4 v128, vcc
	v_lshl_add_u64 v[236:237], s[50:51], 0, v[130:131]
	s_add_u32 m0, s2, s28
	s_add_u32 m0, m0, 0x2000
	s_nop 0
	global_load_lds_dwordx4 v130, vcc
	s_setprio 1
	s_barrier
	s_waitcnt lgkmcnt(0)
	v_mfma_f32_16x16x32_bf16 v[92:95], v[202:205], v[166:169], v[92:95]
	v_mfma_f32_16x16x32_bf16 v[88:91], v[224:227], v[166:169], v[88:91]
	v_mfma_f32_16x16x32_bf16 v[84:87], v[202:205], v[174:177], v[84:87]
	v_mfma_f32_16x16x32_bf16 v[80:83], v[224:227], v[174:177], v[80:83]
	v_mfma_f32_16x16x32_bf16 v[76:79], v[202:205], v[182:185], v[76:79]
	v_mfma_f32_16x16x32_bf16 v[72:75], v[224:227], v[182:185], v[72:75]
	v_mfma_f32_16x16x32_bf16 v[68:71], v[202:205], v[194:197], v[68:71]
	v_mfma_f32_16x16x32_bf16 v[64:67], v[224:227], v[194:197], v[64:67]
	v_mfma_f32_16x16x32_bf16 v[92:95], v[206:209], v[170:173], v[92:95]
	ds_read_b128 v[166:169], v137 offset:16384
	v_mfma_f32_16x16x32_bf16 v[88:91], v[228:231], v[170:173], v[88:91]
	v_mfma_f32_16x16x32_bf16 v[84:87], v[206:209], v[178:181], v[84:87]
	ds_read_b128 v[174:177], v137 offset:18432
	v_mfma_f32_16x16x32_bf16 v[80:83], v[228:231], v[178:181], v[80:83]
	v_mfma_f32_16x16x32_bf16 v[76:79], v[206:209], v[186:189], v[76:79]
	ds_read_b128 v[182:185], v137 offset:20480
	v_mfma_f32_16x16x32_bf16 v[72:75], v[228:231], v[186:189], v[72:75]
	v_mfma_f32_16x16x32_bf16 v[68:71], v[206:209], v[198:201], v[68:71]
	ds_read_b128 v[194:197], v137 offset:22528
	v_mfma_f32_16x16x32_bf16 v[64:67], v[228:231], v[198:201], v[64:67]
	s_barrier
	s_setprio 0
	ds_read_b128 v[170:173], v137 offset:17408
	ds_read_b128 v[178:181], v137 offset:19456
	ds_read_b128 v[186:189], v137 offset:21504
	ds_read_b128 v[198:201], v137 offset:23552
	s_add_u32 m0, s2, 0x0
	s_nop 0
	s_add_u32 vcc_lo, s50, s76
	s_addc_u32 vcc_hi, s51, s77
	global_load_lds_dwordx4 v132, vcc
	s_add_u32 m0, s2, 0x2000
	s_nop 0
	global_load_lds_dwordx4 v134, vcc
	s_waitcnt vmcnt(8)
	s_setprio 1
	s_barrier
	s_waitcnt lgkmcnt(0)
	v_mfma_f32_16x16x32_bf16 v[60:63], v[150:153], v[166:169], v[60:63]
	v_mfma_f32_16x16x32_bf16 v[56:59], v[158:161], v[166:169], v[56:59]
	v_mfma_f32_16x16x32_bf16 v[52:55], v[150:153], v[174:177], v[52:55]
	v_mfma_f32_16x16x32_bf16 v[48:51], v[158:161], v[174:177], v[48:51]
	v_mfma_f32_16x16x32_bf16 v[44:47], v[150:153], v[182:185], v[44:47]
	v_mfma_f32_16x16x32_bf16 v[40:43], v[158:161], v[182:185], v[40:43]
	v_mfma_f32_16x16x32_bf16 v[36:39], v[150:153], v[194:197], v[36:39]
	v_mfma_f32_16x16x32_bf16 v[32:35], v[158:161], v[194:197], v[32:35]
	v_mfma_f32_16x16x32_bf16 v[60:63], v[154:157], v[170:173], v[60:63]
	v_mfma_f32_16x16x32_bf16 v[56:59], v[162:165], v[170:173], v[56:59]
	v_mfma_f32_16x16x32_bf16 v[52:55], v[154:157], v[178:181], v[52:55]
	v_mfma_f32_16x16x32_bf16 v[48:51], v[162:165], v[178:181], v[48:51]
	v_mfma_f32_16x16x32_bf16 v[44:47], v[154:157], v[186:189], v[44:47]
	v_mfma_f32_16x16x32_bf16 v[40:43], v[162:165], v[186:189], v[40:43]
	v_mfma_f32_16x16x32_bf16 v[36:39], v[154:157], v[198:201], v[36:39]
	v_mfma_f32_16x16x32_bf16 v[32:35], v[162:165], v[198:201], v[32:35]
	s_barrier
	s_setprio 0
	ds_read_b128 v[150:153], v138 offset:32768
	ds_read_b128 v[154:157], v138 offset:33792
	ds_read_b128 v[158:161], v138 offset:34816
	ds_read_b128 v[162:165], v138 offset:35840
	s_add_u32 m0, s2, s29
	s_nop 0
	s_add_u32 vcc_lo, s50, s70
	s_addc_u32 vcc_hi, s51, s71
	global_load_lds_dwordx4 v128, vcc
	s_add_u32 m0, s2, s29
	s_add_u32 m0, m0, 0x2000
	s_nop 0
	global_load_lds_dwordx4 v130, vcc
	s_setprio 1
	s_barrier
; #define WAIT_V(n) asm volatile("s_waitcnt vmcnt(" #n ")" ::: "memory")
; #define WAIT_L(n) asm volatile("s_waitcnt lgkmcnt(" #n ")" ::: "memory")
; #define BAR __builtin_amdgcn_s_barrier()
; #define SCHED __builtin_amdgcn_sched_barrier(0)
; #define STAGE(P, BASE, br, kt) do { const char* _g = (const char*)((BASE) + (size_t)(br) * GK + (kt) * BK); \
;     __builtin_amdgcn_global_load_lds((const unsigned*)(_g + voff0), (unsigned*)((char*)(P) + tx * 16), 16, 0, 0); \
;     __builtin_amdgcn_global_load_lds((const unsigned*)(_g + voff1), (unsigned*)((char*)(P) + tx * 16 + 8192), 16, 0, 0); } while (0)
; #define LDA(dst, b, h) _Pragma("unroll") for (int m = 0; m < 4; ++m) _Pragma("unroll") for (int k = 0; k < 2; ++k) \
;     dst[m][k] = *reinterpret_cast<const bf16x8*>((char*)shm + abase + (((b) * 2 + (h)) * 16384 + (m * 2 + k) * 1024))
; #define LDB(dst, b, h) _Pragma("unroll") for (int n = 0; n < 2; ++n) _Pragma("unroll") for (int k = 0; k < 2; ++k) \
;     dst[n][k] = *reinterpret_cast<const bf16x8*>((char*)shm + bbase + (((b) * 2 + (h)) * 16384 + (n * 2 + k) * 1024))
; template <bool SWAP>
; __device__ __forceinline__ void gemm_main(const u16* __restrict__ A, const u16* __restrict__ Bt, int brow, int bcol,
;                                           u16* shm, f32x4 (&acc)[2][2][4][2]) {
;     ...
;     WAIT_V(6); BAR; MMA(1, 1, At, B1); BAR;
;     LDB(B0, 1, 0); SCHED; LDA(At, 1, 0); STAGE(SA(0, 1), A, brow + HALF, t + 2);
;     WAIT_L(8); BAR; WAIT_L(0); MMA(0, 0, At, B0); BAR; SCHED;
;     LDB(B1, 1, 1); STAGE(SB(1, 0), Bt, bcol, t + 3);
;     BAR; WAIT_L(0); MMA(0, 1, At, B1); BAR;
;     LDA(At, 1, 1); STAGE(SA(1, 0), A, brow, t + 3);
;     BAR; WAIT_L(0); MMA(1, 0, At, B0); BAR; SCHED;
;     STAGE(SB(1, 1), Bt, bcol + HALF, t + 3);
;     WAIT_V(6); BAR; MMA(1, 1, At, B1); BAR;
	v_mfma_f32_16x16x32_bf16 v[28:31], v[202:205], v[166:169], v[28:31]
	v_mfma_f32_16x16x32_bf16 v[24:27], v[224:227], v[166:169], v[24:27]
	v_mfma_f32_16x16x32_bf16 v[20:23], v[202:205], v[174:177], v[20:23]
	v_mfma_f32_16x16x32_bf16 v[16:19], v[224:227], v[174:177], v[16:19]
	v_mfma_f32_16x16x32_bf16 v[12:15], v[202:205], v[182:185], v[12:15]
	v_mfma_f32_16x16x32_bf16 v[8:11], v[224:227], v[182:185], v[8:11]
	v_mfma_f32_16x16x32_bf16 v[4:7], v[202:205], v[194:197], v[4:7]
	v_mfma_f32_16x16x32_bf16 v[0:3], v[224:227], v[194:197], v[0:3]
	v_mfma_f32_16x16x32_bf16 v[28:31], v[206:209], v[170:173], v[28:31]
	ds_read_b128 v[166:169], v137 offset:32768
	v_mfma_f32_16x16x32_bf16 v[24:27], v[228:231], v[170:173], v[24:27]
	v_mfma_f32_16x16x32_bf16 v[20:23], v[206:209], v[178:181], v[20:23]
	ds_read_b128 v[174:177], v137 offset:34816
	v_mfma_f32_16x16x32_bf16 v[16:19], v[228:231], v[178:181], v[16:19]
	v_mfma_f32_16x16x32_bf16 v[12:15], v[206:209], v[186:189], v[12:15]
	ds_read_b128 v[182:185], v137 offset:36864
	v_mfma_f32_16x16x32_bf16 v[8:11], v[228:231], v[186:189], v[8:11]
	v_mfma_f32_16x16x32_bf16 v[4:7], v[206:209], v[198:201], v[4:7]
	ds_read_b128 v[194:197], v137 offset:38912
	v_mfma_f32_16x16x32_bf16 v[0:3], v[228:231], v[198:201], v[0:3]
	s_barrier
	s_setprio 0
	ds_read_b128 v[170:173], v137 offset:33792
	ds_read_b128 v[178:181], v137 offset:35840
	ds_read_b128 v[186:189], v137 offset:37888
	ds_read_b128 v[198:201], v137 offset:39936
	s_add_u32 m0, s2, 0x4000
	s_nop 0
	s_add_u32 vcc_lo, s50, s96
	s_addc_u32 vcc_hi, s51, s97
	global_load_lds_dwordx4 v132, vcc
	s_add_u32 m0, s2, 0x6000
	s_nop 0
	global_load_lds_dwordx4 v134, vcc
	s_waitcnt lgkmcnt(8)
	s_waitcnt vmcnt(8)
	s_setprio 1
	s_barrier
	s_waitcnt lgkmcnt(0)
	v_mfma_f32_16x16x32_bf16 v[124:127], v[150:153], v[166:169], v[124:127]
	v_mfma_f32_16x16x32_bf16 v[120:123], v[158:161], v[166:169], v[120:123]
	v_mfma_f32_16x16x32_bf16 v[116:119], v[150:153], v[174:177], v[116:119]
	v_mfma_f32_16x16x32_bf16 v[112:115], v[158:161], v[174:177], v[112:115]
	v_mfma_f32_16x16x32_bf16 v[108:111], v[150:153], v[182:185], v[108:111]
	v_mfma_f32_16x16x32_bf16 v[104:107], v[158:161], v[182:185], v[104:107]
	v_mfma_f32_16x16x32_bf16 v[100:103], v[150:153], v[194:197], v[100:103]
	v_mfma_f32_16x16x32_bf16 v[96:99], v[158:161], v[194:197], v[96:99]
	v_mfma_f32_16x16x32_bf16 v[124:127], v[154:157], v[170:173], v[124:127]
	v_mfma_f32_16x16x32_bf16 v[120:123], v[162:165], v[170:173], v[120:123]
	v_mfma_f32_16x16x32_bf16 v[116:119], v[154:157], v[178:181], v[116:119]
	v_mfma_f32_16x16x32_bf16 v[112:115], v[162:165], v[178:181], v[112:115]
	v_mfma_f32_16x16x32_bf16 v[108:111], v[154:157], v[186:189], v[108:111]
	v_mfma_f32_16x16x32_bf16 v[104:107], v[162:165], v[186:189], v[104:107]
	v_mfma_f32_16x16x32_bf16 v[100:103], v[154:157], v[198:201], v[100:103]
	v_mfma_f32_16x16x32_bf16 v[96:99], v[162:165], v[198:201], v[96:99]
	s_barrier
	s_setprio 0
	ds_read_b128 v[202:205], v138 offset:49152
	ds_read_b128 v[206:209], v138 offset:50176
	ds_read_b128 v[224:227], v138 offset:51200
	ds_read_b128 v[228:231], v138 offset:52224
	s_add_u32 m0, s2, s30
	s_nop 0
	s_add_u32 vcc_lo, s50, s34
	s_addc_u32 vcc_hi, s51, s35
	global_load_lds_dwordx4 v128, vcc
	v_lshl_add_u64 v[238:239], v[236:237], 0, s[34:35]
	s_add_u32 m0, s2, s30
	s_add_u32 m0, m0, 0x2000
	s_nop 0
	global_load_lds_dwordx4 v130, vcc
	s_setprio 1
	s_barrier
	s_waitcnt lgkmcnt(0)
	v_mfma_f32_16x16x32_bf16 v[92:95], v[202:205], v[166:169], v[92:95]
	v_mfma_f32_16x16x32_bf16 v[88:91], v[224:227], v[166:169], v[88:91]
	v_mfma_f32_16x16x32_bf16 v[84:87], v[202:205], v[174:177], v[84:87]
	v_mfma_f32_16x16x32_bf16 v[80:83], v[224:227], v[174:177], v[80:83]
	v_mfma_f32_16x16x32_bf16 v[76:79], v[202:205], v[182:185], v[76:79]
	v_mfma_f32_16x16x32_bf16 v[72:75], v[224:227], v[182:185], v[72:75]
	v_mfma_f32_16x16x32_bf16 v[68:71], v[202:205], v[194:197], v[68:71]
	v_mfma_f32_16x16x32_bf16 v[64:67], v[224:227], v[194:197], v[64:67]
	v_mfma_f32_16x16x32_bf16 v[92:95], v[206:209], v[170:173], v[92:95]
	ds_read_b128 v[166:169], v137 offset:49152
	v_mfma_f32_16x16x32_bf16 v[88:91], v[228:231], v[170:173], v[88:91]
	v_mfma_f32_16x16x32_bf16 v[84:87], v[206:209], v[178:181], v[84:87]
	ds_read_b128 v[174:177], v137 offset:51200
	v_mfma_f32_16x16x32_bf16 v[80:83], v[228:231], v[178:181], v[80:83]
	v_mfma_f32_16x16x32_bf16 v[76:79], v[206:209], v[186:189], v[76:79]
	ds_read_b128 v[182:185], v137 offset:53248
	v_mfma_f32_16x16x32_bf16 v[72:75], v[228:231], v[186:189], v[72:75]
	v_mfma_f32_16x16x32_bf16 v[68:71], v[206:209], v[198:201], v[68:71]
	ds_read_b128 v[194:197], v137 offset:55296
	v_mfma_f32_16x16x32_bf16 v[64:67], v[228:231], v[198:201], v[64:67]
	s_barrier
	s_setprio 0
	ds_read_b128 v[170:173], v137 offset:50176
	ds_read_b128 v[178:181], v137 offset:52224
	ds_read_b128 v[186:189], v137 offset:54272
	ds_read_b128 v[198:201], v137 offset:56320
	v_add_u32_e32 v223, 0x8000, v192
	s_add_u32 m0, s2, 0x8000
	s_nop 0
	s_add_u32 vcc_lo, s50, s36
	s_addc_u32 vcc_hi, s51, s37
	global_load_lds_dwordx4 v132, vcc
	v_lshl_add_u64 v[190:191], v[232:233], 0, s[36:37]
	s_add_u32 m0, s2, 0xa000
	s_nop 0
	global_load_lds_dwordx4 v134, vcc
	s_waitcnt vmcnt(8)
	s_setprio 1
	s_barrier
; #define WAIT_V(n) asm volatile("s_waitcnt vmcnt(" #n ")" ::: "memory")
; #define WAIT_L(n) asm volatile("s_waitcnt lgkmcnt(" #n ")" ::: "memory")
; #define BAR __builtin_amdgcn_s_barrier()
; #define SCHED __builtin_amdgcn_sched_barrier(0)
; #define STAGE(P, BASE, br, kt) do { const char* _g = (const char*)((BASE) + (size_t)(br) * GK + (kt) * BK); \
;     __builtin_amdgcn_global_load_lds((const unsigned*)(_g + voff0), (unsigned*)((char*)(P) + tx * 16), 16, 0, 0); \
;     __builtin_amdgcn_global_load_lds((const unsigned*)(_g + voff1), (unsigned*)((char*)(P) + tx * 16 + 8192), 16, 0, 0); } while (0)
; #define LDA(dst, b, h) _Pragma("unroll") for (int m = 0; m < 4; ++m) _Pragma("unroll") for (int k = 0; k < 2; ++k) \
;     dst[m][k] = *reinterpret_cast<const bf16x8*>((char*)shm + abase + (((b) * 2 + (h)) * 16384 + (m * 2 + k) * 1024))
; #define LDB(dst, b, h) _Pragma("unroll") for (int n = 0; n < 2; ++n) _Pragma("unroll") for (int k = 0; k < 2; ++k) \
;     dst[n][k] = *reinterpret_cast<const bf16x8*>((char*)shm + bbase + (((b) * 2 + (h)) * 16384 + (n * 2 + k) * 1024))
; template <bool SWAP>
; __device__ __forceinline__ void gemm_main(const u16* __restrict__ A, const u16* __restrict__ Bt, int brow, int bcol,
;                                           u16* shm, f32x4 (&acc)[2][2][4][2]) {
;     ...
;     LDA(At, 1, 1); STAGE(SA(1, 0), A, brow, t + 3);
;     BAR; WAIT_L(0); MMA(1, 0, At, B0); BAR; SCHED;
;     STAGE(SB(1, 1), Bt, bcol + HALF, t + 3);
;     WAIT_V(6); BAR; MMA(1, 1, At, B1); BAR;
;   }
;   { LDB(B0, 0, 0); LDA(At, 0, 0); STAGE(SA(1, 1), A, brow + HALF, nt - 1);
;     BAR; WAIT_L(0); MMA(0, 0, At, B0); BAR;
	s_waitcnt lgkmcnt(0)
	v_mfma_f32_16x16x32_bf16 v[60:63], v[150:153], v[166:169], v[60:63]
	v_mfma_f32_16x16x32_bf16 v[56:59], v[158:161], v[166:169], v[56:59]
	v_mfma_f32_16x16x32_bf16 v[52:55], v[150:153], v[174:177], v[52:55]
	v_mfma_f32_16x16x32_bf16 v[48:51], v[158:161], v[174:177], v[48:51]
	v_mfma_f32_16x16x32_bf16 v[44:47], v[150:153], v[182:185], v[44:47]
	v_mfma_f32_16x16x32_bf16 v[40:43], v[158:161], v[182:185], v[40:43]
	v_mfma_f32_16x16x32_bf16 v[36:39], v[150:153], v[194:197], v[36:39]
	v_mfma_f32_16x16x32_bf16 v[32:35], v[158:161], v[194:197], v[32:35]
	v_mfma_f32_16x16x32_bf16 v[60:63], v[154:157], v[170:173], v[60:63]
	v_mfma_f32_16x16x32_bf16 v[56:59], v[162:165], v[170:173], v[56:59]
	v_mfma_f32_16x16x32_bf16 v[52:55], v[154:157], v[178:181], v[52:55]
	v_mfma_f32_16x16x32_bf16 v[48:51], v[162:165], v[178:181], v[48:51]
	v_mfma_f32_16x16x32_bf16 v[44:47], v[154:157], v[186:189], v[44:47]
	v_mfma_f32_16x16x32_bf16 v[40:43], v[162:165], v[186:189], v[40:43]
	v_mfma_f32_16x16x32_bf16 v[36:39], v[154:157], v[198:201], v[36:39]
	v_mfma_f32_16x16x32_bf16 v[32:35], v[162:165], v[198:201], v[32:35]
	s_barrier
	s_setprio 0
	ds_read_b128 v[150:153], v138
	ds_read_b128 v[154:157], v138 offset:1024
	ds_read_b128 v[158:161], v138 offset:2048
	ds_read_b128 v[162:165], v138 offset:3072
	s_add_u32 m0, s2, s31
	s_nop 0
	s_add_u32 vcc_lo, s50, s64
	s_addc_u32 vcc_hi, s51, s65
	global_load_lds_dwordx4 v128, vcc
	v_lshl_add_u64 v[254:255], v[236:237], 0, s[64:65]
	s_add_u32 m0, s2, s31
	s_add_u32 m0, m0, 0x2000
	s_nop 0
	global_load_lds_dwordx4 v130, vcc
	s_setprio 1
	s_barrier
	v_mfma_f32_16x16x32_bf16 v[28:31], v[202:205], v[166:169], v[28:31]
	v_mfma_f32_16x16x32_bf16 v[24:27], v[224:227], v[166:169], v[24:27]
	v_mfma_f32_16x16x32_bf16 v[20:23], v[202:205], v[174:177], v[20:23]
	v_mfma_f32_16x16x32_bf16 v[16:19], v[224:227], v[174:177], v[16:19]
	v_mfma_f32_16x16x32_bf16 v[12:15], v[202:205], v[182:185], v[12:15]
	v_mfma_f32_16x16x32_bf16 v[8:11], v[224:227], v[182:185], v[8:11]
	v_mfma_f32_16x16x32_bf16 v[4:7], v[202:205], v[194:197], v[4:7]
	v_mfma_f32_16x16x32_bf16 v[0:3], v[224:227], v[194:197], v[0:3]
	v_mfma_f32_16x16x32_bf16 v[28:31], v[206:209], v[170:173], v[28:31]
	ds_read_b128 v[166:169], v137
	v_mfma_f32_16x16x32_bf16 v[24:27], v[228:231], v[170:173], v[24:27]
	v_mfma_f32_16x16x32_bf16 v[20:23], v[206:209], v[178:181], v[20:23]
	ds_read_b128 v[174:177], v137 offset:2048
	v_mfma_f32_16x16x32_bf16 v[16:19], v[228:231], v[178:181], v[16:19]
	v_mfma_f32_16x16x32_bf16 v[12:15], v[206:209], v[186:189], v[12:15]
	ds_read_b128 v[182:185], v137 offset:4096
	v_mfma_f32_16x16x32_bf16 v[8:11], v[228:231], v[186:189], v[8:11]
	v_mfma_f32_16x16x32_bf16 v[4:7], v[206:209], v[198:201], v[4:7]
	ds_read_b128 v[194:197], v137 offset:6144
	v_mfma_f32_16x16x32_bf16 v[0:3], v[228:231], v[198:201], v[0:3]
	s_add_i32 s1, s1, 2
	v_lshl_add_u64 v[128:129], v[128:129], 0, s[74:75]
	v_lshl_add_u64 v[130:131], v[130:131], 0, s[74:75]
	v_lshl_add_u64 v[132:133], v[132:133], 0, s[74:75]
	s_cmp_lt_u32 s1, 28
	v_lshl_add_u64 v[134:135], v[134:135], 0, s[74:75]
	s_barrier
	s_setprio 0
	s_cbranch_scc1 .LBB0_436
	v_lshlrev_b32_e32 v128, 3, v142
	v_lshlrev_b32_e32 v129, 5, v142
	v_and_b32_e32 v128, 0xffff0, v128
	v_and_b32_e32 v129, 32, v129
	s_or_b32 s2, s0, 0x80
	v_add_u32_e32 v129, v129, v144
	v_add_lshl_u32 v128, v143, v128, 12
	s_ashr_i32 s3, s2, 31
	v_lshl_add_u32 v192, v129, 1, v128
	v_lshlrev_b32_e32 v128, 3, v145
	v_lshlrev_b32_e32 v129, 5, v145
	s_lshl_b64 s[2:3], s[2:3], 12
	v_and_b32_e32 v128, 0xffff0, v128
	v_and_b32_e32 v129, 32, v129
	s_add_u32 s2, s16, s2
	v_add_u32_e32 v129, v129, v147
	v_add_lshl_u32 v128, v146, v128, 12
	s_addc_u32 s3, s17, s3
	v_lshl_add_u32 v146, v129, 1, v128
	v_mov_b32_e32 v147, v193
	v_lshl_add_u64 v[186:187], s[2:3], 0, v[192:193]
	s_mov_b64 s[8:9], 0xf80
	v_readfirstlane_b32 s1, v148
	v_lshl_add_u64 v[186:187], v[186:187], 0, s[8:9]
	s_mov_b32 m0, s1
	v_lshl_add_u64 v[146:147], s[2:3], 0, v[146:147]
	v_readfirstlane_b32 s1, v149
	ds_read_b128 v[128:131], v138
	ds_read_b128 v[132:135], v138 offset:1024
	ds_read_b128 v[142:145], v138 offset:2048
	ds_read_b128 v[150:153], v138 offset:3072
	ds_read_b128 v[154:157], v137
	ds_read_b128 v[158:161], v137 offset:1024
	ds_read_b128 v[162:165], v137 offset:2048
	ds_read_b128 v[166:169], v137 offset:3072
	ds_read_b128 v[170:173], v137 offset:4096
	ds_read_b128 v[174:177], v137 offset:5120
	ds_read_b128 v[178:181], v137 offset:6144
	ds_read_b128 v[182:185], v137 offset:7168
	global_load_lds_dwordx4 v[186:187], off
	v_lshl_add_u64 v[146:147], v[146:147], 0, s[8:9]
	s_mov_b32 m0, s1
	s_nop 0
	global_load_lds_dwordx4 v[146:147], off
	s_waitcnt vmcnt(8)
	s_barrier
	s_waitcnt lgkmcnt(0)
	s_setprio 1
	s_waitcnt lgkmcnt(0)
	v_mfma_f32_16x16x32_bf16 v[124:127], v[128:131], v[154:157], v[124:127]
	v_mfma_f32_16x16x32_bf16 v[112:115], v[142:145], v[162:165], v[112:115]
	v_mfma_f32_16x16x32_bf16 v[104:107], v[142:145], v[170:173], v[104:107]
	v_mfma_f32_16x16x32_bf16 v[96:99], v[142:145], v[178:181], v[96:99]
	v_mfma_f32_16x16x32_bf16 v[124:127], v[132:135], v[158:161], v[124:127]
	v_mfma_f32_16x16x32_bf16 v[120:123], v[142:145], v[154:157], v[120:123]
	v_mfma_f32_16x16x32_bf16 v[116:119], v[128:131], v[162:165], v[116:119]
	v_mfma_f32_16x16x32_bf16 v[112:115], v[150:153], v[166:169], v[112:115]
	v_mfma_f32_16x16x32_bf16 v[108:111], v[128:131], v[170:173], v[108:111]
	v_mfma_f32_16x16x32_bf16 v[104:107], v[150:153], v[174:177], v[104:107]
	v_mfma_f32_16x16x32_bf16 v[100:103], v[128:131], v[178:181], v[100:103]
	v_mfma_f32_16x16x32_bf16 v[96:99], v[150:153], v[182:185], v[96:99]
	v_mfma_f32_16x16x32_bf16 v[146:149], v[150:153], v[158:161], v[120:123]
	v_mfma_f32_16x16x32_bf16 v[186:189], v[132:135], v[166:169], v[116:119]
	v_mfma_f32_16x16x32_bf16 v[194:197], v[132:135], v[174:177], v[108:111]
	v_mfma_f32_16x16x32_bf16 v[198:201], v[132:135], v[182:185], v[100:103]
	s_setprio 0
	s_barrier
; #define WAIT_V(n) asm volatile("s_waitcnt vmcnt(" #n ")" ::: "memory")
; #define WAIT_L(n) asm volatile("s_waitcnt lgkmcnt(" #n ")" ::: "memory")
; #define BAR __builtin_amdgcn_s_barrier()
; #define LDA(dst, b, h) _Pragma("unroll") for (int m = 0; m < 4; ++m) _Pragma("unroll") for (int k = 0; k < 2; ++k) \
;     dst[m][k] = *reinterpret_cast<const bf16x8*>((char*)shm + abase + (((b) * 2 + (h)) * 16384 + (m * 2 + k) * 1024))
; #define LDB(dst, b, h) _Pragma("unroll") for (int n = 0; n < 2; ++n) _Pragma("unroll") for (int k = 0; k < 2; ++k) \
;     dst[n][k] = *reinterpret_cast<const bf16x8*>((char*)shm + bbase + (((b) * 2 + (h)) * 16384 + (n * 2 + k) * 1024))
; template <bool SWAP>
; __device__ __forceinline__ void gemm_main(const u16* __restrict__ A, const u16* __restrict__ Bt, int brow, int bcol,
;                                           u16* shm, f32x4 (&acc)[2][2][4][2]) {
;     ...
;     BAR; WAIT_L(0); MMA(0, 0, At, B0); BAR;
;     LDB(B1, 0, 1); BAR; WAIT_L(0); MMA(0, 1, At, B1); BAR;
;     LDA(At, 0, 1); WAIT_V(4); BAR; WAIT_L(0); MMA(1, 0, At, B0); MMA(1, 1, At, B1); BAR; }
;   { LDB(B0, 1, 0); LDA(At, 1, 0); WAIT_V(2); BAR; WAIT_L(0); MMA(0, 0, At, B0); BAR;
	s_nop 0
	ds_read_b128 v[100:103], v138 offset:16384
	ds_read_b128 v[108:111], v138 offset:17408
	ds_read_b128 v[116:119], v138 offset:18432
	ds_read_b128 v[120:123], v138 offset:19456
	s_barrier
	s_waitcnt lgkmcnt(0)
	s_setprio 1
	s_waitcnt lgkmcnt(0)
	v_mfma_f32_16x16x32_bf16 v[88:91], v[116:119], v[154:157], v[88:91]
	v_mfma_f32_16x16x32_bf16 v[80:83], v[116:119], v[162:165], v[80:83]
	v_mfma_f32_16x16x32_bf16 v[72:75], v[116:119], v[170:173], v[72:75]
	v_mfma_f32_16x16x32_bf16 v[64:67], v[116:119], v[178:181], v[64:67]
	v_mfma_f32_16x16x32_bf16 v[92:95], v[100:103], v[154:157], v[92:95]
	v_mfma_f32_16x16x32_bf16 v[88:91], v[120:123], v[158:161], v[88:91]
	v_mfma_f32_16x16x32_bf16 v[84:87], v[100:103], v[162:165], v[84:87]
	v_mfma_f32_16x16x32_bf16 v[80:83], v[120:123], v[166:169], v[80:83]
	v_mfma_f32_16x16x32_bf16 v[76:79], v[100:103], v[170:173], v[76:79]
	v_mfma_f32_16x16x32_bf16 v[72:75], v[120:123], v[174:177], v[72:75]
	v_mfma_f32_16x16x32_bf16 v[68:71], v[100:103], v[178:181], v[68:71]
	v_mfma_f32_16x16x32_bf16 v[64:67], v[120:123], v[182:185], v[64:67]
	v_mfma_f32_16x16x32_bf16 v[202:205], v[108:111], v[158:161], v[92:95]
	v_mfma_f32_16x16x32_bf16 v[154:157], v[108:111], v[166:169], v[84:87]
	v_mfma_f32_16x16x32_bf16 v[158:161], v[108:111], v[174:177], v[76:79]
	v_mfma_f32_16x16x32_bf16 v[162:165], v[108:111], v[182:185], v[68:71]
	s_setprio 0
	s_barrier
	s_nop 0
	ds_read_b128 v[68:71], v137 offset:16384
	ds_read_b128 v[76:79], v137 offset:17408
	ds_read_b128 v[84:87], v137 offset:18432
	ds_read_b128 v[92:95], v137 offset:19456
	ds_read_b128 v[166:169], v137 offset:20480
	ds_read_b128 v[170:173], v137 offset:21504
	ds_read_b128 v[174:177], v137 offset:22528
	ds_read_b128 v[178:181], v137 offset:23552
	s_waitcnt vmcnt(4)
	s_barrier
	s_waitcnt lgkmcnt(0)
	s_setprio 1
	s_waitcnt lgkmcnt(0)
	v_mfma_f32_16x16x32_bf16 v[60:63], v[128:131], v[68:71], v[60:63]
	v_mfma_f32_16x16x32_bf16 v[56:59], v[142:145], v[68:71], v[56:59]
	v_mfma_f32_16x16x32_bf16 v[48:51], v[142:145], v[84:87], v[48:51]
	v_mfma_f32_16x16x32_bf16 v[40:43], v[142:145], v[166:169], v[40:43]
	v_mfma_f32_16x16x32_bf16 v[32:35], v[142:145], v[174:177], v[32:35]
	v_mfma_f32_16x16x32_bf16 v[60:63], v[132:135], v[76:79], v[60:63]
	v_mfma_f32_16x16x32_bf16 v[56:59], v[150:153], v[76:79], v[56:59]
	v_mfma_f32_16x16x32_bf16 v[52:55], v[128:131], v[84:87], v[52:55]
	v_mfma_f32_16x16x32_bf16 v[48:51], v[150:153], v[92:95], v[48:51]
	v_mfma_f32_16x16x32_bf16 v[44:47], v[128:131], v[166:169], v[44:47]
	v_mfma_f32_16x16x32_bf16 v[40:43], v[150:153], v[170:173], v[40:43]
	v_mfma_f32_16x16x32_bf16 v[36:39], v[128:131], v[174:177], v[36:39]
	v_mfma_f32_16x16x32_bf16 v[32:35], v[150:153], v[178:181], v[32:35]
	v_mfma_f32_16x16x32_bf16 v[182:185], v[132:135], v[92:95], v[52:55]
	v_mfma_f32_16x16x32_bf16 v[206:209], v[132:135], v[170:173], v[44:47]
	v_mfma_f32_16x16x32_bf16 v[128:131], v[132:135], v[178:181], v[36:39]
	s_setprio 0
	s_setprio 1
	v_mfma_f32_16x16x32_bf16 v[24:27], v[116:119], v[68:71], v[24:27]
	v_mfma_f32_16x16x32_bf16 v[16:19], v[116:119], v[84:87], v[16:19]
	v_mfma_f32_16x16x32_bf16 v[8:11], v[116:119], v[166:169], v[8:11]
	v_mfma_f32_16x16x32_bf16 v[0:3], v[116:119], v[174:177], v[0:3]
	v_mfma_f32_16x16x32_bf16 v[28:31], v[100:103], v[68:71], v[28:31]
	v_mfma_f32_16x16x32_bf16 v[24:27], v[120:123], v[76:79], v[24:27]
	v_mfma_f32_16x16x32_bf16 v[20:23], v[100:103], v[84:87], v[20:23]
	v_mfma_f32_16x16x32_bf16 v[16:19], v[120:123], v[92:95], v[16:19]
	v_mfma_f32_16x16x32_bf16 v[12:15], v[100:103], v[166:169], v[12:15]
	v_mfma_f32_16x16x32_bf16 v[8:11], v[120:123], v[170:173], v[8:11]
	v_mfma_f32_16x16x32_bf16 v[4:7], v[100:103], v[174:177], v[4:7]
	v_mfma_f32_16x16x32_bf16 v[0:3], v[120:123], v[178:181], v[0:3]
	v_mfma_f32_16x16x32_bf16 v[132:135], v[108:111], v[76:79], v[28:31]
	v_mfma_f32_16x16x32_bf16 v[142:145], v[108:111], v[92:95], v[20:23]
	v_mfma_f32_16x16x32_bf16 v[150:153], v[108:111], v[170:173], v[12:15]
	v_mfma_f32_16x16x32_bf16 v[166:169], v[108:111], v[178:181], v[4:7]
	s_setprio 0
	s_barrier
	s_nop 0
	ds_read_b128 v[4:7], v138 offset:32768
	ds_read_b128 v[12:15], v138 offset:33792
	ds_read_b128 v[170:173], v138 offset:34816
	ds_read_b128 v[174:177], v138 offset:35840
	ds_read_b128 v[20:23], v137 offset:32768
	ds_read_b128 v[28:31], v137 offset:33792
	ds_read_b128 v[36:39], v137 offset:34816
	ds_read_b128 v[44:47], v137 offset:35840
	ds_read_b128 v[52:55], v137 offset:36864
	ds_read_b128 v[178:181], v137 offset:37888
	ds_read_b128 v[224:227], v137 offset:38912
	ds_read_b128 v[228:231], v137 offset:39936
	s_waitcnt vmcnt(2)
	s_barrier
; #define WAIT_V(n) asm volatile("s_waitcnt vmcnt(" #n ")" ::: "memory")
; #define WAIT_L(n) asm volatile("s_waitcnt lgkmcnt(" #n ")" ::: "memory")
; #define BAR __builtin_amdgcn_s_barrier()
; #define LDA(dst, b, h) _Pragma("unroll") for (int m = 0; m < 4; ++m) _Pragma("unroll") for (int k = 0; k < 2; ++k) \
;     dst[m][k] = *reinterpret_cast<const bf16x8*>((char*)shm + abase + (((b) * 2 + (h)) * 16384 + (m * 2 + k) * 1024))
; #define LDB(dst, b, h) _Pragma("unroll") for (int n = 0; n < 2; ++n) _Pragma("unroll") for (int k = 0; k < 2; ++k) \
;     dst[n][k] = *reinterpret_cast<const bf16x8*>((char*)shm + bbase + (((b) * 2 + (h)) * 16384 + (n * 2 + k) * 1024))
; template <bool SWAP>
; __device__ __forceinline__ void gemm_main(const u16* __restrict__ A, const u16* __restrict__ Bt, int brow, int bcol,
;                                           u16* shm, f32x4 (&acc)[2][2][4][2]) {
;     ...
;   { LDB(B0, 1, 0); LDA(At, 1, 0); WAIT_V(2); BAR; WAIT_L(0); MMA(0, 0, At, B0); BAR;
;     LDB(B1, 1, 1); WAIT_V(0); BAR; WAIT_L(0); MMA(0, 1, At, B1); BAR;
;     LDA(At, 1, 1); BAR; WAIT_L(0); MMA(1, 0, At, B0); MMA(1, 1, At, B1); BAR; }
;   if (wr == 0) BAR;
	s_waitcnt lgkmcnt(0)
	s_setprio 1
	s_waitcnt lgkmcnt(0)
	v_mfma_f32_16x16x32_bf16 v[68:71], v[4:7], v[20:23], v[124:127]
	v_mfma_f32_16x16x32_bf16 v[120:123], v[12:15], v[28:31], v[68:71]
	v_mfma_f32_16x16x32_bf16 v[68:71], v[170:173], v[20:23], v[146:149]
	v_mfma_f32_16x16x32_bf16 v[116:119], v[174:177], v[28:31], v[68:71]
	v_mfma_f32_16x16x32_bf16 v[68:71], v[4:7], v[36:39], v[186:189]
	v_mfma_f32_16x16x32_bf16 v[108:111], v[12:15], v[44:47], v[68:71]
	v_mfma_f32_16x16x32_bf16 v[68:71], v[170:173], v[36:39], v[112:115]
	v_mfma_f32_16x16x32_bf16 v[100:103], v[174:177], v[44:47], v[68:71]
	v_mfma_f32_16x16x32_bf16 v[68:71], v[4:7], v[52:55], v[194:197]
	v_mfma_f32_16x16x32_bf16 v[92:95], v[12:15], v[178:181], v[68:71]
	v_mfma_f32_16x16x32_bf16 v[68:71], v[170:173], v[52:55], v[104:107]
	v_mfma_f32_16x16x32_bf16 v[84:87], v[174:177], v[178:181], v[68:71]
	v_mfma_f32_16x16x32_bf16 v[68:71], v[4:7], v[224:227], v[198:201]
	v_mfma_f32_16x16x32_bf16 v[76:79], v[12:15], v[228:231], v[68:71]
	v_mfma_f32_16x16x32_bf16 v[68:71], v[170:173], v[224:227], v[96:99]
	v_mfma_f32_16x16x32_bf16 v[68:71], v[174:177], v[228:231], v[68:71]
	s_setprio 0
	s_barrier
	ds_read_b128 v[146:149], v138 offset:49152
	ds_read_b128 v[186:189], v138 offset:50176
	ds_read_b128 v[194:197], v138 offset:51200
	ds_read_b128 v[198:201], v138 offset:52224
	s_waitcnt vmcnt(0)
	s_barrier
	s_waitcnt lgkmcnt(0)
	s_setprio 1
	s_waitcnt lgkmcnt(0)
	v_mfma_f32_16x16x32_bf16 v[96:99], v[146:149], v[20:23], v[202:205]
	v_mfma_f32_16x16x32_bf16 v[20:23], v[194:197], v[20:23], v[88:91]
	v_mfma_f32_16x16x32_bf16 v[112:115], v[198:201], v[28:31], v[20:23]
	v_mfma_f32_16x16x32_bf16 v[20:23], v[146:149], v[36:39], v[154:157]
	v_mfma_f32_16x16x32_bf16 v[104:107], v[186:189], v[44:47], v[20:23]
	v_mfma_f32_16x16x32_bf16 v[20:23], v[194:197], v[36:39], v[80:83]
	v_mfma_f32_16x16x32_bf16 v[124:127], v[186:189], v[28:31], v[96:99]
	v_mfma_f32_16x16x32_bf16 v[96:99], v[198:201], v[44:47], v[20:23]
	v_mfma_f32_16x16x32_bf16 v[20:23], v[146:149], v[52:55], v[158:161]
	v_mfma_f32_16x16x32_bf16 v[88:91], v[186:189], v[178:181], v[20:23]
	v_mfma_f32_16x16x32_bf16 v[20:23], v[194:197], v[52:55], v[72:75]
	v_mfma_f32_16x16x32_bf16 v[80:83], v[198:201], v[178:181], v[20:23]
	v_mfma_f32_16x16x32_bf16 v[20:23], v[146:149], v[224:227], v[162:165]
	v_mfma_f32_16x16x32_bf16 v[72:75], v[186:189], v[228:231], v[20:23]
	v_mfma_f32_16x16x32_bf16 v[20:23], v[194:197], v[224:227], v[64:67]
	v_mfma_f32_16x16x32_bf16 v[64:67], v[198:201], v[228:231], v[20:23]
	s_setprio 0
	s_barrier
	ds_read_b128 v[154:157], v137 offset:49152
	ds_read_b128 v[158:161], v137 offset:50176
	ds_read_b128 v[162:165], v137 offset:51200
	ds_read_b128 v[178:181], v137 offset:52224
	ds_read_b128 v[202:205], v137 offset:53248
	ds_read_b128 v[224:227], v137 offset:54272
	ds_read_b128 v[228:231], v137 offset:55296
	ds_read_b128 v[232:235], v137 offset:56320
	s_barrier
	s_waitcnt lgkmcnt(0)
	s_setprio 1
	s_waitcnt lgkmcnt(0)
	v_mfma_f32_16x16x32_bf16 v[20:23], v[4:7], v[154:157], v[60:63]
	v_mfma_f32_16x16x32_bf16 v[60:63], v[12:15], v[158:161], v[20:23]
	v_mfma_f32_16x16x32_bf16 v[20:23], v[170:173], v[154:157], v[56:59]
	v_mfma_f32_16x16x32_bf16 v[52:55], v[174:177], v[158:161], v[20:23]
	v_mfma_f32_16x16x32_bf16 v[20:23], v[4:7], v[162:165], v[182:185]
	v_mfma_f32_16x16x32_bf16 v[44:47], v[12:15], v[178:181], v[20:23]
	v_mfma_f32_16x16x32_bf16 v[20:23], v[170:173], v[162:165], v[48:51]
	v_mfma_f32_16x16x32_bf16 v[36:39], v[174:177], v[178:181], v[20:23]
	v_mfma_f32_16x16x32_bf16 v[20:23], v[4:7], v[202:205], v[206:209]
	v_mfma_f32_16x16x32_bf16 v[4:7], v[4:7], v[228:231], v[128:131]
	v_mfma_f32_16x16x32_bf16 v[28:31], v[12:15], v[224:227], v[20:23]
	v_mfma_f32_16x16x32_bf16 v[20:23], v[170:173], v[202:205], v[40:43]
	v_mfma_f32_16x16x32_bf16 v[12:15], v[12:15], v[232:235], v[4:7]
	v_mfma_f32_16x16x32_bf16 v[4:7], v[170:173], v[228:231], v[32:35]
	v_mfma_f32_16x16x32_bf16 v[20:23], v[174:177], v[224:227], v[20:23]
	v_mfma_f32_16x16x32_bf16 v[4:7], v[174:177], v[232:235], v[4:7]
	s_setprio 0
	s_setprio 1
	v_mfma_f32_16x16x32_bf16 v[32:35], v[146:149], v[154:157], v[132:135]
	v_mfma_f32_16x16x32_bf16 v[24:27], v[194:197], v[154:157], v[24:27]
	v_mfma_f32_16x16x32_bf16 v[16:19], v[194:197], v[162:165], v[16:19]
	v_mfma_f32_16x16x32_bf16 v[56:59], v[186:189], v[158:161], v[32:35]
	v_mfma_f32_16x16x32_bf16 v[48:51], v[198:201], v[158:161], v[24:27]
	v_mfma_f32_16x16x32_bf16 v[24:27], v[146:149], v[162:165], v[142:145]
	v_mfma_f32_16x16x32_bf16 v[32:35], v[198:201], v[178:181], v[16:19]
	v_mfma_f32_16x16x32_bf16 v[16:19], v[146:149], v[202:205], v[150:153]
	v_mfma_f32_16x16x32_bf16 v[8:11], v[194:197], v[202:205], v[8:11]
	v_mfma_f32_16x16x32_bf16 v[40:43], v[186:189], v[178:181], v[24:27]
	v_mfma_f32_16x16x32_bf16 v[24:27], v[186:189], v[224:227], v[16:19]
	v_mfma_f32_16x16x32_bf16 v[16:19], v[198:201], v[224:227], v[8:11]
	v_mfma_f32_16x16x32_bf16 v[8:11], v[146:149], v[228:231], v[166:169]
	v_mfma_f32_16x16x32_bf16 v[0:3], v[194:197], v[228:231], v[0:3]
	v_mfma_f32_16x16x32_bf16 v[8:11], v[186:189], v[232:235], v[8:11]
	v_mfma_f32_16x16x32_bf16 v[0:3], v[198:201], v[232:235], v[0:3]
	s_setprio 0
	s_movk_i32 s1, 0x100
	v_cmp_gt_u32_e32 vcc, s1, v136
	s_barrier
	s_and_saveexec_b64 s[8:9], vcc
	s_cbranch_execz .LBB0_439
	s_barrier

; #define WAIT_V(n) asm volatile("s_waitcnt vmcnt(" #n ")" ::: "memory")
; #define WAIT_L(n) asm volatile("s_waitcnt lgkmcnt(" #n ")" ::: "memory")
; #define BAR __builtin_amdgcn_s_barrier()
; #define SCHED __builtin_amdgcn_sched_barrier(0)
; #define STAGE(P, BASE, br, kt) do { const char* _g = (const char*)((BASE) + (size_t)(br) * GK + (kt) * BK); \
;     __builtin_amdgcn_global_load_lds((const unsigned*)(_g + voff0), (unsigned*)((char*)(P) + tx * 16), 16, 0, 0); \
;     __builtin_amdgcn_global_load_lds((const unsigned*)(_g + voff1), (unsigned*)((char*)(P) + tx * 16 + 8192), 16, 0, 0); } while (0)
; #define LDA(dst, b, h) _Pragma("unroll") for (int m = 0; m < 4; ++m) _Pragma("unroll") for (int k = 0; k < 2; ++k) \
;     dst[m][k] = *reinterpret_cast<const bf16x8*>((char*)shm + abase + (((b) * 2 + (h)) * 16384 + (m * 2 + k) * 1024))
; #define LDB(dst, b, h) _Pragma("unroll") for (int n = 0; n < 2; ++n) _Pragma("unroll") for (int k = 0; k < 2; ++k) \
;     dst[n][k] = *reinterpret_cast<const bf16x8*>((char*)shm + bbase + (((b) * 2 + (h)) * 16384 + (n * 2 + k) * 1024))
; template <bool SWAP>
; __device__ __forceinline__ void gemm_main(const u16* __restrict__ A, const u16* __restrict__ Bt, int brow, int bcol,
;                                           u16* shm, f32x4 (&acc)[2][2][4][2]) {
;     ...
;   for (int t = 0; t < nt - 2; t += 2) {
;     LDB(B0, 0, 0); SCHED; LDA(At, 0, 0); STAGE(SA(1, 1), A, brow + HALF, t + 1);
;     WAIT_L(8); BAR; WAIT_L(0); MMA(0, 0, At, B0); BAR; SCHED;
;     LDB(B1, 0, 1); STAGE(SB(0, 0), Bt, bcol, t + 2);
;     BAR; WAIT_L(0); MMA(0, 1, At, B1); BAR;
;     LDA(At, 0, 1); STAGE(SA(0, 0), A, brow, t + 2);
;     BAR; WAIT_L(0); MMA(1, 0, At, B0); BAR; SCHED;
;     STAGE(SB(0, 1), Bt, bcol + HALF, t + 2);
;     WAIT_V(6); BAR; MMA(1, 1, At, B1); BAR;
.LBB0_564:
	ds_read_b128 v[168:171], v137 offset:1024
	ds_read_b128 v[176:179], v137 offset:3072
	ds_read_b128 v[184:187], v137 offset:5120
	ds_read_b128 v[194:197], v137 offset:7168
	v_add_u32_e32 v192, 0, v141
	v_add_u32_e32 v146, 0xc000, v192
	v_lshl_add_u64 v[230:231], s[0:1], 0, v[132:133]
	v_add_u32_e32 v147, 0xe000, v192
	v_lshl_add_u64 v[198:199], v[230:231], 0, s[8:9]
	s_add_u32 m0, s4, 0xc000
	v_lshl_add_u64 v[232:233], s[0:1], 0, v[134:135]
	global_load_lds_dwordx4 v[198:199], off
	v_lshl_add_u64 v[198:199], v[232:233], 0, s[8:9]
	s_add_u32 m0, s4, 0xe000
	s_nop 0
	global_load_lds_dwordx4 v[198:199], off
	s_waitcnt lgkmcnt(8)
	s_waitcnt vmcnt(8)
	s_setprio 1
	s_barrier
	s_waitcnt lgkmcnt(0)
	v_mfma_f32_16x16x32_bf16 v[124:127], v[148:151], v[164:167], v[124:127]
	v_mfma_f32_16x16x32_bf16 v[120:123], v[156:159], v[164:167], v[120:123]
	v_mfma_f32_16x16x32_bf16 v[116:119], v[148:151], v[172:175], v[116:119]
	v_mfma_f32_16x16x32_bf16 v[112:115], v[156:159], v[172:175], v[112:115]
	v_mfma_f32_16x16x32_bf16 v[108:111], v[148:151], v[180:183], v[108:111]
	v_mfma_f32_16x16x32_bf16 v[104:107], v[156:159], v[180:183], v[104:107]
	v_mfma_f32_16x16x32_bf16 v[100:103], v[148:151], v[188:191], v[100:103]
	v_mfma_f32_16x16x32_bf16 v[96:99], v[156:159], v[188:191], v[96:99]
	v_mfma_f32_16x16x32_bf16 v[124:127], v[152:155], v[168:171], v[124:127]
	v_mfma_f32_16x16x32_bf16 v[120:123], v[160:163], v[168:171], v[120:123]
	v_mfma_f32_16x16x32_bf16 v[116:119], v[152:155], v[176:179], v[116:119]
	v_mfma_f32_16x16x32_bf16 v[112:115], v[160:163], v[176:179], v[112:115]
	v_mfma_f32_16x16x32_bf16 v[108:111], v[152:155], v[184:187], v[108:111]
	v_mfma_f32_16x16x32_bf16 v[104:107], v[160:163], v[184:187], v[104:107]
	v_mfma_f32_16x16x32_bf16 v[100:103], v[152:155], v[194:197], v[100:103]
	v_mfma_f32_16x16x32_bf16 v[96:99], v[160:163], v[194:197], v[96:99]
	s_barrier
	s_setprio 0
	ds_read_b128 v[198:201], v138 offset:16384
	ds_read_b128 v[202:205], v138 offset:17408
	ds_read_b128 v[206:209], v138 offset:18432
	ds_read_b128 v[226:229], v138 offset:19456
	v_lshl_add_u64 v[234:235], s[0:1], 0, v[128:129]
	v_lshl_add_u64 v[236:237], v[234:235], 0, s[12:13]
	s_add_u32 m0, s4, s28
	s_nop 0
	global_load_lds_dwordx4 v[236:237], off
	v_lshl_add_u64 v[236:237], s[0:1], 0, v[130:131]
	v_lshl_add_u64 v[238:239], v[236:237], 0, s[12:13]
	s_add_u32 m0, s4, s28
	s_add_u32 m0, m0, 0x2000
	s_nop 0
	global_load_lds_dwordx4 v[238:239], off
	s_setprio 1
	s_barrier
	s_waitcnt lgkmcnt(0)
	v_mfma_f32_16x16x32_bf16 v[92:95], v[198:201], v[164:167], v[92:95]
	v_mfma_f32_16x16x32_bf16 v[88:91], v[206:209], v[164:167], v[88:91]
	v_mfma_f32_16x16x32_bf16 v[84:87], v[198:201], v[172:175], v[84:87]
	v_mfma_f32_16x16x32_bf16 v[80:83], v[206:209], v[172:175], v[80:83]
	v_mfma_f32_16x16x32_bf16 v[76:79], v[198:201], v[180:183], v[76:79]
	v_mfma_f32_16x16x32_bf16 v[72:75], v[206:209], v[180:183], v[72:75]
	v_mfma_f32_16x16x32_bf16 v[68:71], v[198:201], v[188:191], v[68:71]
	v_mfma_f32_16x16x32_bf16 v[64:67], v[206:209], v[188:191], v[64:67]
	v_mfma_f32_16x16x32_bf16 v[92:95], v[202:205], v[168:171], v[92:95]
	ds_read_b128 v[164:167], v137 offset:16384
	v_mfma_f32_16x16x32_bf16 v[88:91], v[226:229], v[168:171], v[88:91]
	v_mfma_f32_16x16x32_bf16 v[84:87], v[202:205], v[176:179], v[84:87]
	ds_read_b128 v[172:175], v137 offset:18432
	v_mfma_f32_16x16x32_bf16 v[80:83], v[226:229], v[176:179], v[80:83]
	v_mfma_f32_16x16x32_bf16 v[76:79], v[202:205], v[184:187], v[76:79]
	ds_read_b128 v[180:183], v137 offset:20480
	v_mfma_f32_16x16x32_bf16 v[72:75], v[226:229], v[184:187], v[72:75]
	v_mfma_f32_16x16x32_bf16 v[68:71], v[202:205], v[194:197], v[68:71]
	ds_read_b128 v[188:191], v137 offset:22528
	v_mfma_f32_16x16x32_bf16 v[64:67], v[226:229], v[194:197], v[64:67]
	s_barrier
	s_setprio 0
	ds_read_b128 v[168:171], v137 offset:17408
	ds_read_b128 v[176:179], v137 offset:19456
	ds_read_b128 v[184:187], v137 offset:21504
	ds_read_b128 v[194:197], v137 offset:23552
	v_lshl_add_u64 v[238:239], v[230:231], 0, s[14:15]
	s_add_u32 m0, s4, 0x0
	s_nop 0
	global_load_lds_dwordx4 v[238:239], off
	v_lshl_add_u64 v[238:239], v[232:233], 0, s[14:15]
	s_add_u32 m0, s4, 0x2000
	s_nop 0
	global_load_lds_dwordx4 v[238:239], off
	s_waitcnt vmcnt(8)
	s_setprio 1
	s_barrier
	s_waitcnt lgkmcnt(0)
	v_mfma_f32_16x16x32_bf16 v[60:63], v[148:151], v[164:167], v[60:63]
	v_mfma_f32_16x16x32_bf16 v[56:59], v[156:159], v[164:167], v[56:59]
	v_mfma_f32_16x16x32_bf16 v[52:55], v[148:151], v[172:175], v[52:55]
	v_mfma_f32_16x16x32_bf16 v[48:51], v[156:159], v[172:175], v[48:51]
	v_mfma_f32_16x16x32_bf16 v[44:47], v[148:151], v[180:183], v[44:47]
	v_mfma_f32_16x16x32_bf16 v[40:43], v[156:159], v[180:183], v[40:43]
	v_mfma_f32_16x16x32_bf16 v[36:39], v[148:151], v[188:191], v[36:39]
	v_mfma_f32_16x16x32_bf16 v[32:35], v[156:159], v[188:191], v[32:35]
	v_mfma_f32_16x16x32_bf16 v[60:63], v[152:155], v[168:171], v[60:63]
	v_mfma_f32_16x16x32_bf16 v[56:59], v[160:163], v[168:171], v[56:59]
	v_mfma_f32_16x16x32_bf16 v[52:55], v[152:155], v[176:179], v[52:55]
	v_mfma_f32_16x16x32_bf16 v[48:51], v[160:163], v[176:179], v[48:51]
	v_mfma_f32_16x16x32_bf16 v[44:47], v[152:155], v[184:187], v[44:47]
	v_mfma_f32_16x16x32_bf16 v[40:43], v[160:163], v[184:187], v[40:43]
	v_mfma_f32_16x16x32_bf16 v[36:39], v[152:155], v[194:197], v[36:39]
	v_mfma_f32_16x16x32_bf16 v[32:35], v[160:163], v[194:197], v[32:35]
	s_barrier
; #define WAIT_V(n) asm volatile("s_waitcnt vmcnt(" #n ")" ::: "memory")
; #define WAIT_L(n) asm volatile("s_waitcnt lgkmcnt(" #n ")" ::: "memory")
; #define BAR __builtin_amdgcn_s_barrier()
; #define SCHED __builtin_amdgcn_sched_barrier(0)
; #define STAGE(P, BASE, br, kt) do { const char* _g = (const char*)((BASE) + (size_t)(br) * GK + (kt) * BK); \
;     __builtin_amdgcn_global_load_lds((const unsigned*)(_g + voff0), (unsigned*)((char*)(P) + tx * 16), 16, 0, 0); \
;     __builtin_amdgcn_global_load_lds((const unsigned*)(_g + voff1), (unsigned*)((char*)(P) + tx * 16 + 8192), 16, 0, 0); } while (0)
; #define LDA(dst, b, h) _Pragma("unroll") for (int m = 0; m < 4; ++m) _Pragma("unroll") for (int k = 0; k < 2; ++k) \
;     dst[m][k] = *reinterpret_cast<const bf16x8*>((char*)shm + abase + (((b) * 2 + (h)) * 16384 + (m * 2 + k) * 1024))
; #define LDB(dst, b, h) _Pragma("unroll") for (int n = 0; n < 2; ++n) _Pragma("unroll") for (int k = 0; k < 2; ++k) \
;     dst[n][k] = *reinterpret_cast<const bf16x8*>((char*)shm + bbase + (((b) * 2 + (h)) * 16384 + (n * 2 + k) * 1024))
; template <bool SWAP>
; __device__ __forceinline__ void gemm_main(const u16* __restrict__ A, const u16* __restrict__ Bt, int brow, int bcol,
;                                           u16* shm, f32x4 (&acc)[2][2][4][2]) {
;     ...
;     BAR; WAIT_L(0); MMA(1, 0, At, B0); BAR; SCHED;
;     STAGE(SB(0, 1), Bt, bcol + HALF, t + 2);
;     WAIT_V(6); BAR; MMA(1, 1, At, B1); BAR;
;     LDB(B0, 1, 0); SCHED; LDA(At, 1, 0); STAGE(SA(0, 1), A, brow + HALF, t + 2);
;     WAIT_L(8); BAR; WAIT_L(0); MMA(0, 0, At, B0); BAR; SCHED;
;     LDB(B1, 1, 1); STAGE(SB(1, 0), Bt, bcol, t + 3);
;     BAR; WAIT_L(0); MMA(0, 1, At, B1); BAR;
;     LDA(At, 1, 1); STAGE(SA(1, 0), A, brow, t + 3);
;     BAR; WAIT_L(0); MMA(1, 0, At, B0); BAR; SCHED;
	s_setprio 0
	ds_read_b128 v[148:151], v138 offset:32768
	ds_read_b128 v[152:155], v138 offset:33792
	ds_read_b128 v[156:159], v138 offset:34816
	ds_read_b128 v[160:163], v138 offset:35840
	v_lshl_add_u64 v[254:255], v[234:235], 0, s[16:17]
	s_add_u32 m0, s4, s29
	s_nop 0
	global_load_lds_dwordx4 v[254:255], off
	v_lshl_add_u64 v[254:255], v[236:237], 0, s[16:17]
	s_add_u32 m0, s4, s29
	s_add_u32 m0, m0, 0x2000
	s_nop 0
	global_load_lds_dwordx4 v[254:255], off
	s_setprio 1
	s_barrier
	v_mfma_f32_16x16x32_bf16 v[28:31], v[198:201], v[164:167], v[28:31]
	v_mfma_f32_16x16x32_bf16 v[24:27], v[206:209], v[164:167], v[24:27]
	v_mfma_f32_16x16x32_bf16 v[20:23], v[198:201], v[172:175], v[20:23]
	v_mfma_f32_16x16x32_bf16 v[16:19], v[206:209], v[172:175], v[16:19]
	v_mfma_f32_16x16x32_bf16 v[12:15], v[198:201], v[180:183], v[12:15]
	v_mfma_f32_16x16x32_bf16 v[8:11], v[206:209], v[180:183], v[8:11]
	v_mfma_f32_16x16x32_bf16 v[4:7], v[198:201], v[188:191], v[4:7]
	v_mfma_f32_16x16x32_bf16 v[0:3], v[206:209], v[188:191], v[0:3]
	v_mfma_f32_16x16x32_bf16 v[28:31], v[202:205], v[168:171], v[28:31]
	ds_read_b128 v[164:167], v137 offset:32768
	v_mfma_f32_16x16x32_bf16 v[24:27], v[226:229], v[168:171], v[24:27]
	v_mfma_f32_16x16x32_bf16 v[20:23], v[202:205], v[176:179], v[20:23]
	ds_read_b128 v[172:175], v137 offset:34816
	v_mfma_f32_16x16x32_bf16 v[16:19], v[226:229], v[176:179], v[16:19]
	v_mfma_f32_16x16x32_bf16 v[12:15], v[202:205], v[184:187], v[12:15]
	ds_read_b128 v[180:183], v137 offset:36864
	v_mfma_f32_16x16x32_bf16 v[8:11], v[226:229], v[184:187], v[8:11]
	v_mfma_f32_16x16x32_bf16 v[4:7], v[202:205], v[194:197], v[4:7]
	ds_read_b128 v[188:191], v137 offset:38912
	v_mfma_f32_16x16x32_bf16 v[0:3], v[226:229], v[194:197], v[0:3]
	s_barrier
	s_setprio 0
	ds_read_b128 v[168:171], v137 offset:33792
	ds_read_b128 v[176:179], v137 offset:35840
	ds_read_b128 v[184:187], v137 offset:37888
	ds_read_b128 v[194:197], v137 offset:39936
	v_lshl_add_u64 v[198:199], v[230:231], 0, s[18:19]
	s_add_u32 m0, s4, 0x4000
	s_nop 0
	global_load_lds_dwordx4 v[198:199], off
	v_lshl_add_u64 v[198:199], v[232:233], 0, s[18:19]
	s_add_u32 m0, s4, 0x6000
	s_nop 0
	global_load_lds_dwordx4 v[198:199], off
	s_waitcnt lgkmcnt(8)
	s_waitcnt vmcnt(8)
	s_setprio 1
	s_barrier
	s_waitcnt lgkmcnt(0)
	v_mfma_f32_16x16x32_bf16 v[124:127], v[148:151], v[164:167], v[124:127]
	v_mfma_f32_16x16x32_bf16 v[120:123], v[156:159], v[164:167], v[120:123]
	v_mfma_f32_16x16x32_bf16 v[116:119], v[148:151], v[172:175], v[116:119]
	v_mfma_f32_16x16x32_bf16 v[112:115], v[156:159], v[172:175], v[112:115]
	v_mfma_f32_16x16x32_bf16 v[108:111], v[148:151], v[180:183], v[108:111]
	v_mfma_f32_16x16x32_bf16 v[104:107], v[156:159], v[180:183], v[104:107]
	v_mfma_f32_16x16x32_bf16 v[100:103], v[148:151], v[188:191], v[100:103]
	v_mfma_f32_16x16x32_bf16 v[96:99], v[156:159], v[188:191], v[96:99]
	v_mfma_f32_16x16x32_bf16 v[124:127], v[152:155], v[168:171], v[124:127]
	v_mfma_f32_16x16x32_bf16 v[120:123], v[160:163], v[168:171], v[120:123]
	v_mfma_f32_16x16x32_bf16 v[116:119], v[152:155], v[176:179], v[116:119]
	v_mfma_f32_16x16x32_bf16 v[112:115], v[160:163], v[176:179], v[112:115]
	v_mfma_f32_16x16x32_bf16 v[108:111], v[152:155], v[184:187], v[108:111]
	v_mfma_f32_16x16x32_bf16 v[104:107], v[160:163], v[184:187], v[104:107]
	v_mfma_f32_16x16x32_bf16 v[100:103], v[152:155], v[194:197], v[100:103]
	v_mfma_f32_16x16x32_bf16 v[96:99], v[160:163], v[194:197], v[96:99]
	s_barrier
	s_setprio 0
	ds_read_b128 v[198:201], v138 offset:49152
	ds_read_b128 v[202:205], v138 offset:50176
	ds_read_b128 v[206:209], v138 offset:51200
	ds_read_b128 v[226:229], v138 offset:52224
	v_lshl_add_u64 v[238:239], v[234:235], 0, s[24:25]
	s_add_u32 m0, s4, s30
	s_nop 0
	global_load_lds_dwordx4 v[238:239], off
	v_lshl_add_u64 v[238:239], v[236:237], 0, s[24:25]
	s_add_u32 m0, s4, s30
	s_add_u32 m0, m0, 0x2000
	s_nop 0
	global_load_lds_dwordx4 v[238:239], off
	s_setprio 1
	s_barrier
	s_waitcnt lgkmcnt(0)
	v_mfma_f32_16x16x32_bf16 v[92:95], v[198:201], v[164:167], v[92:95]
	v_mfma_f32_16x16x32_bf16 v[88:91], v[206:209], v[164:167], v[88:91]
	v_mfma_f32_16x16x32_bf16 v[84:87], v[198:201], v[172:175], v[84:87]
	v_mfma_f32_16x16x32_bf16 v[80:83], v[206:209], v[172:175], v[80:83]
	v_mfma_f32_16x16x32_bf16 v[76:79], v[198:201], v[180:183], v[76:79]
	v_mfma_f32_16x16x32_bf16 v[72:75], v[206:209], v[180:183], v[72:75]
	v_mfma_f32_16x16x32_bf16 v[68:71], v[198:201], v[188:191], v[68:71]
	v_mfma_f32_16x16x32_bf16 v[64:67], v[206:209], v[188:191], v[64:67]
	v_mfma_f32_16x16x32_bf16 v[92:95], v[202:205], v[168:171], v[92:95]
	ds_read_b128 v[164:167], v137 offset:49152
	v_mfma_f32_16x16x32_bf16 v[88:91], v[226:229], v[168:171], v[88:91]
	v_mfma_f32_16x16x32_bf16 v[84:87], v[202:205], v[176:179], v[84:87]
	ds_read_b128 v[172:175], v137 offset:51200
	v_mfma_f32_16x16x32_bf16 v[80:83], v[226:229], v[176:179], v[80:83]
	v_mfma_f32_16x16x32_bf16 v[76:79], v[202:205], v[184:187], v[76:79]
	ds_read_b128 v[180:183], v137 offset:53248
	v_mfma_f32_16x16x32_bf16 v[72:75], v[226:229], v[184:187], v[72:75]
	v_mfma_f32_16x16x32_bf16 v[68:71], v[202:205], v[194:197], v[68:71]
	ds_read_b128 v[188:191], v137 offset:55296
	v_mfma_f32_16x16x32_bf16 v[64:67], v[226:229], v[194:197], v[64:67]
	s_barrier
	s_setprio 0
	ds_read_b128 v[168:171], v137 offset:50176
	ds_read_b128 v[176:179], v137 offset:52224
	ds_read_b128 v[184:187], v137 offset:54272
	ds_read_b128 v[194:197], v137 offset:56320
	v_add_u32_e32 v225, 0x8000, v192
	v_lshl_add_u64 v[230:231], v[230:231], 0, vcc
	s_add_u32 m0, s4, 0x8000
	s_nop 0
	global_load_lds_dwordx4 v[230:231], off
	v_lshl_add_u64 v[230:231], v[232:233], 0, vcc
	s_add_u32 m0, s4, 0xa000
	s_nop 0
	global_load_lds_dwordx4 v[230:231], off
	s_waitcnt vmcnt(8)
	s_setprio 1
	s_barrier
; #define WAIT_V(n) asm volatile("s_waitcnt vmcnt(" #n ")" ::: "memory")
; #define WAIT_L(n) asm volatile("s_waitcnt lgkmcnt(" #n ")" ::: "memory")
; #define BAR __builtin_amdgcn_s_barrier()
; #define SCHED __builtin_amdgcn_sched_barrier(0)
; #define STAGE(P, BASE, br, kt) do { const char* _g = (const char*)((BASE) + (size_t)(br) * GK + (kt) * BK); \
;     __builtin_amdgcn_global_load_lds((const unsigned*)(_g + voff0), (unsigned*)((char*)(P) + tx * 16), 16, 0, 0); \
;     __builtin_amdgcn_global_load_lds((const unsigned*)(_g + voff1), (unsigned*)((char*)(P) + tx * 16 + 8192), 16, 0, 0); } while (0)
; #define LDA(dst, b, h) _Pragma("unroll") for (int m = 0; m < 4; ++m) _Pragma("unroll") for (int k = 0; k < 2; ++k) \
;     dst[m][k] = *reinterpret_cast<const bf16x8*>((char*)shm + abase + (((b) * 2 + (h)) * 16384 + (m * 2 + k) * 1024))
; #define LDB(dst, b, h) _Pragma("unroll") for (int n = 0; n < 2; ++n) _Pragma("unroll") for (int k = 0; k < 2; ++k) \
;     dst[n][k] = *reinterpret_cast<const bf16x8*>((char*)shm + bbase + (((b) * 2 + (h)) * 16384 + (n * 2 + k) * 1024))
; template <bool SWAP>
; __device__ __forceinline__ void gemm_main(const u16* __restrict__ A, const u16* __restrict__ Bt, int brow, int bcol,
;                                           u16* shm, f32x4 (&acc)[2][2][4][2]) {
;     ...
;     BAR; WAIT_L(0); MMA(1, 0, At, B0); BAR; SCHED;
;     STAGE(SB(1, 1), Bt, bcol + HALF, t + 3);
;     WAIT_V(6); BAR; MMA(1, 1, At, B1); BAR;
;   }
;   { LDB(B0, 0, 0); LDA(At, 0, 0); STAGE(SA(1, 1), A, brow + HALF, nt - 1);
;     BAR; WAIT_L(0); MMA(0, 0, At, B0); BAR;
	s_waitcnt lgkmcnt(0)
	v_mfma_f32_16x16x32_bf16 v[60:63], v[148:151], v[164:167], v[60:63]
	v_mfma_f32_16x16x32_bf16 v[56:59], v[156:159], v[164:167], v[56:59]
	v_mfma_f32_16x16x32_bf16 v[52:55], v[148:151], v[172:175], v[52:55]
	v_mfma_f32_16x16x32_bf16 v[48:51], v[156:159], v[172:175], v[48:51]
	v_mfma_f32_16x16x32_bf16 v[44:47], v[148:151], v[180:183], v[44:47]
	v_mfma_f32_16x16x32_bf16 v[40:43], v[156:159], v[180:183], v[40:43]
	v_mfma_f32_16x16x32_bf16 v[36:39], v[148:151], v[188:191], v[36:39]
	v_mfma_f32_16x16x32_bf16 v[32:35], v[156:159], v[188:191], v[32:35]
	v_mfma_f32_16x16x32_bf16 v[60:63], v[152:155], v[168:171], v[60:63]
	v_mfma_f32_16x16x32_bf16 v[56:59], v[160:163], v[168:171], v[56:59]
	v_mfma_f32_16x16x32_bf16 v[52:55], v[152:155], v[176:179], v[52:55]
	v_mfma_f32_16x16x32_bf16 v[48:51], v[160:163], v[176:179], v[48:51]
	v_mfma_f32_16x16x32_bf16 v[44:47], v[152:155], v[184:187], v[44:47]
	v_mfma_f32_16x16x32_bf16 v[40:43], v[160:163], v[184:187], v[40:43]
	v_mfma_f32_16x16x32_bf16 v[36:39], v[152:155], v[194:197], v[36:39]
	v_mfma_f32_16x16x32_bf16 v[32:35], v[160:163], v[194:197], v[32:35]
	s_barrier
	s_setprio 0
	ds_read_b128 v[148:151], v138
	ds_read_b128 v[152:155], v138 offset:1024
	ds_read_b128 v[156:159], v138 offset:2048
	ds_read_b128 v[160:163], v138 offset:3072
	v_lshl_add_u64 v[254:255], v[234:235], 0, s[42:43]
	s_add_u32 m0, s4, s31
	s_nop 0
	global_load_lds_dwordx4 v[254:255], off
	v_lshl_add_u64 v[254:255], v[236:237], 0, s[42:43]
	s_add_u32 m0, s4, s31
	s_add_u32 m0, m0, 0x2000
	s_nop 0
	global_load_lds_dwordx4 v[254:255], off
	s_setprio 1
	s_barrier
	v_mfma_f32_16x16x32_bf16 v[28:31], v[198:201], v[164:167], v[28:31]
	v_mfma_f32_16x16x32_bf16 v[24:27], v[206:209], v[164:167], v[24:27]
	v_mfma_f32_16x16x32_bf16 v[20:23], v[198:201], v[172:175], v[20:23]
	v_mfma_f32_16x16x32_bf16 v[16:19], v[206:209], v[172:175], v[16:19]
	v_mfma_f32_16x16x32_bf16 v[12:15], v[198:201], v[180:183], v[12:15]
	v_mfma_f32_16x16x32_bf16 v[8:11], v[206:209], v[180:183], v[8:11]
	v_mfma_f32_16x16x32_bf16 v[4:7], v[198:201], v[188:191], v[4:7]
	v_mfma_f32_16x16x32_bf16 v[0:3], v[206:209], v[188:191], v[0:3]
	v_mfma_f32_16x16x32_bf16 v[28:31], v[202:205], v[168:171], v[28:31]
	ds_read_b128 v[164:167], v137
	v_mfma_f32_16x16x32_bf16 v[24:27], v[226:229], v[168:171], v[24:27]
	v_mfma_f32_16x16x32_bf16 v[20:23], v[202:205], v[176:179], v[20:23]
	ds_read_b128 v[172:175], v137 offset:2048
	v_mfma_f32_16x16x32_bf16 v[16:19], v[226:229], v[176:179], v[16:19]
	v_mfma_f32_16x16x32_bf16 v[12:15], v[202:205], v[184:187], v[12:15]
	ds_read_b128 v[180:183], v137 offset:4096
	v_mfma_f32_16x16x32_bf16 v[8:11], v[226:229], v[184:187], v[8:11]
	v_mfma_f32_16x16x32_bf16 v[4:7], v[202:205], v[194:197], v[4:7]
	ds_read_b128 v[188:191], v137 offset:6144
	v_mfma_f32_16x16x32_bf16 v[0:3], v[226:229], v[194:197], v[0:3]
	s_add_i32 s3, s3, 2
	s_add_u32 s0, s0, 0x100
	s_addc_u32 s1, s1, 0
	s_cmp_lt_u32 s3, 28
	s_barrier
	s_setprio 0
	s_cbranch_scc1 .LBB0_564
	s_and_b32 s0, s2, 0xffffe0
	s_and_b32 s1, s54, 31
	s_or_b32 s0, s0, s1
	s_lshl_b32 s8, s0, 8
	v_lshlrev_b32_e32 v128, 3, v139
	v_lshlrev_b32_e32 v129, 5, v139
	v_and_b32_e32 v128, 0xffff0, v128
	v_and_b32_e32 v129, 32, v129
	s_or_b32 s0, s8, 0x80
	v_add_u32_e32 v129, v129, v142
	v_add_lshl_u32 v128, v140, v128, 12
	s_ashr_i32 s1, s0, 31
	v_lshl_add_u32 v192, v129, 1, v128
	v_lshlrev_b32_e32 v128, 3, v143
	v_lshlrev_b32_e32 v129, 5, v143
	s_lshl_b64 s[12:13], s[0:1], 12
	v_readlane_b32 s0, v251, 36
	v_and_b32_e32 v128, 0xffff0, v128
	v_and_b32_e32 v129, 32, v129
	v_readlane_b32 s1, v251, 37
	s_add_u32 s0, s0, s12
	v_add_u32_e32 v129, v129, v145
	v_add_lshl_u32 v128, v144, v128, 12
	s_addc_u32 s1, s1, s13
	v_lshl_add_u32 v144, v129, 1, v128
	v_mov_b32_e32 v145, v193
	v_lshl_add_u64 v[184:185], s[0:1], 0, v[192:193]
	s_mov_b64 s[4:5], 0xf80
	v_readfirstlane_b32 s2, v146
	v_lshl_add_u64 v[184:185], v[184:185], 0, s[4:5]
	s_mov_b32 m0, s2
	v_lshl_add_u64 v[144:145], s[0:1], 0, v[144:145]
	v_readfirstlane_b32 s0, v147
	ds_read_b128 v[128:131], v138
	ds_read_b128 v[132:135], v138 offset:1024
	ds_read_b128 v[140:143], v138 offset:2048
	ds_read_b128 v[148:151], v138 offset:3072
	ds_read_b128 v[152:155], v137
	ds_read_b128 v[156:159], v137 offset:1024
	ds_read_b128 v[160:163], v137 offset:2048
	ds_read_b128 v[164:167], v137 offset:3072
	ds_read_b128 v[168:171], v137 offset:4096
	ds_read_b128 v[172:175], v137 offset:5120
	ds_read_b128 v[176:179], v137 offset:6144
	ds_read_b128 v[180:183], v137 offset:7168
	global_load_lds_dwordx4 v[184:185], off
	v_lshl_add_u64 v[144:145], v[144:145], 0, s[4:5]
	s_mov_b32 m0, s0
	s_nop 0
	global_load_lds_dwordx4 v[144:145], off
	s_waitcnt vmcnt(8)
	s_barrier
	s_waitcnt lgkmcnt(0)
	s_setprio 1
	s_waitcnt lgkmcnt(0)
	v_mfma_f32_16x16x32_bf16 v[124:127], v[128:131], v[152:155], v[124:127]
	v_mfma_f32_16x16x32_bf16 v[116:119], v[128:131], v[160:163], v[116:119]
	v_mfma_f32_16x16x32_bf16 v[112:115], v[140:143], v[160:163], v[112:115]
	v_mfma_f32_16x16x32_bf16 v[108:111], v[128:131], v[168:171], v[108:111]
	v_mfma_f32_16x16x32_bf16 v[104:107], v[140:143], v[168:171], v[104:107]
	v_mfma_f32_16x16x32_bf16 v[100:103], v[128:131], v[176:179], v[100:103]
	v_mfma_f32_16x16x32_bf16 v[96:99], v[140:143], v[176:179], v[96:99]
	v_mfma_f32_16x16x32_bf16 v[124:127], v[132:135], v[156:159], v[124:127]
	v_mfma_f32_16x16x32_bf16 v[120:123], v[140:143], v[152:155], v[120:123]
	v_mfma_f32_16x16x32_bf16 v[116:119], v[132:135], v[164:167], v[116:119]
	v_mfma_f32_16x16x32_bf16 v[112:115], v[148:151], v[164:167], v[112:115]
	v_mfma_f32_16x16x32_bf16 v[108:111], v[132:135], v[172:175], v[108:111]
	v_mfma_f32_16x16x32_bf16 v[104:107], v[148:151], v[172:175], v[104:107]
	v_mfma_f32_16x16x32_bf16 v[100:103], v[132:135], v[180:183], v[100:103]
	v_mfma_f32_16x16x32_bf16 v[96:99], v[148:151], v[180:183], v[96:99]
	v_mfma_f32_16x16x32_bf16 v[120:123], v[148:151], v[156:159], v[120:123]
	s_setprio 0
	s_barrier
; #define WAIT_V(n) asm volatile("s_waitcnt vmcnt(" #n ")" ::: "memory")
; #define WAIT_L(n) asm volatile("s_waitcnt lgkmcnt(" #n ")" ::: "memory")
; #define BAR __builtin_amdgcn_s_barrier()
; #define LDA(dst, b, h) _Pragma("unroll") for (int m = 0; m < 4; ++m) _Pragma("unroll") for (int k = 0; k < 2; ++k) \
;     dst[m][k] = *reinterpret_cast<const bf16x8*>((char*)shm + abase + (((b) * 2 + (h)) * 16384 + (m * 2 + k) * 1024))
; #define LDB(dst, b, h) _Pragma("unroll") for (int n = 0; n < 2; ++n) _Pragma("unroll") for (int k = 0; k < 2; ++k) \
;     dst[n][k] = *reinterpret_cast<const bf16x8*>((char*)shm + bbase + (((b) * 2 + (h)) * 16384 + (n * 2 + k) * 1024))
; template <bool SWAP>
; __device__ __forceinline__ void gemm_main(const u16* __restrict__ A, const u16* __restrict__ Bt, int brow, int bcol,
;                                           u16* shm, f32x4 (&acc)[2][2][4][2]) {
;     ...
;     BAR; WAIT_L(0); MMA(0, 0, At, B0); BAR;
;     LDB(B1, 0, 1); BAR; WAIT_L(0); MMA(0, 1, At, B1); BAR;
;     LDA(At, 0, 1); WAIT_V(4); BAR; WAIT_L(0); MMA(1, 0, At, B0); MMA(1, 1, At, B1); BAR; }
;   { LDB(B0, 1, 0); LDA(At, 1, 0); WAIT_V(2); BAR; WAIT_L(0); MMA(0, 0, At, B0); BAR;
	ds_read_b128 v[144:147], v138 offset:16384
	ds_read_b128 v[184:187], v138 offset:17408
	ds_read_b128 v[188:191], v138 offset:18432
	ds_read_b128 v[194:197], v138 offset:19456
	s_barrier
	s_waitcnt lgkmcnt(0)
	s_setprio 1
	s_waitcnt lgkmcnt(0)
	v_mfma_f32_16x16x32_bf16 v[92:95], v[144:147], v[152:155], v[92:95]
	v_mfma_f32_16x16x32_bf16 v[88:91], v[188:191], v[152:155], v[88:91]
	v_mfma_f32_16x16x32_bf16 v[84:87], v[144:147], v[160:163], v[84:87]
	v_mfma_f32_16x16x32_bf16 v[80:83], v[188:191], v[160:163], v[80:83]
	v_mfma_f32_16x16x32_bf16 v[76:79], v[144:147], v[168:171], v[76:79]
	v_mfma_f32_16x16x32_bf16 v[72:75], v[188:191], v[168:171], v[72:75]
	v_mfma_f32_16x16x32_bf16 v[68:71], v[144:147], v[176:179], v[68:71]
	v_mfma_f32_16x16x32_bf16 v[64:67], v[188:191], v[176:179], v[64:67]
	v_mfma_f32_16x16x32_bf16 v[92:95], v[184:187], v[156:159], v[92:95]
	v_mfma_f32_16x16x32_bf16 v[88:91], v[194:197], v[156:159], v[88:91]
	v_mfma_f32_16x16x32_bf16 v[84:87], v[184:187], v[164:167], v[84:87]
	v_mfma_f32_16x16x32_bf16 v[80:83], v[194:197], v[164:167], v[80:83]
	v_mfma_f32_16x16x32_bf16 v[76:79], v[184:187], v[172:175], v[76:79]
	v_mfma_f32_16x16x32_bf16 v[72:75], v[194:197], v[172:175], v[72:75]
	v_mfma_f32_16x16x32_bf16 v[68:71], v[184:187], v[180:183], v[68:71]
	v_mfma_f32_16x16x32_bf16 v[64:67], v[194:197], v[180:183], v[64:67]
	s_setprio 0
	s_barrier
	ds_read_b128 v[152:155], v137 offset:16384
	ds_read_b128 v[156:159], v137 offset:17408
	ds_read_b128 v[160:163], v137 offset:18432
	ds_read_b128 v[164:167], v137 offset:19456
	ds_read_b128 v[168:171], v137 offset:20480
	ds_read_b128 v[172:175], v137 offset:21504
	ds_read_b128 v[176:179], v137 offset:22528
	ds_read_b128 v[180:183], v137 offset:23552
	s_waitcnt vmcnt(4)
	s_barrier
	s_waitcnt lgkmcnt(0)
	s_setprio 1
	s_waitcnt lgkmcnt(0)
	v_mfma_f32_16x16x32_bf16 v[60:63], v[128:131], v[152:155], v[60:63]
	v_mfma_f32_16x16x32_bf16 v[56:59], v[140:143], v[152:155], v[56:59]
	v_mfma_f32_16x16x32_bf16 v[52:55], v[128:131], v[160:163], v[52:55]
	v_mfma_f32_16x16x32_bf16 v[48:51], v[140:143], v[160:163], v[48:51]
	v_mfma_f32_16x16x32_bf16 v[44:47], v[128:131], v[168:171], v[44:47]
	v_mfma_f32_16x16x32_bf16 v[40:43], v[140:143], v[168:171], v[40:43]
	v_mfma_f32_16x16x32_bf16 v[36:39], v[128:131], v[176:179], v[36:39]
	v_mfma_f32_16x16x32_bf16 v[32:35], v[140:143], v[176:179], v[32:35]
	v_mfma_f32_16x16x32_bf16 v[60:63], v[132:135], v[156:159], v[60:63]
	v_mfma_f32_16x16x32_bf16 v[56:59], v[148:151], v[156:159], v[56:59]
	v_mfma_f32_16x16x32_bf16 v[52:55], v[132:135], v[164:167], v[52:55]
	v_mfma_f32_16x16x32_bf16 v[48:51], v[148:151], v[164:167], v[48:51]
	v_mfma_f32_16x16x32_bf16 v[44:47], v[132:135], v[172:175], v[44:47]
	v_mfma_f32_16x16x32_bf16 v[40:43], v[148:151], v[172:175], v[40:43]
	v_mfma_f32_16x16x32_bf16 v[36:39], v[132:135], v[180:183], v[36:39]
	v_mfma_f32_16x16x32_bf16 v[32:35], v[148:151], v[180:183], v[32:35]
	s_setprio 0
	s_setprio 1
	v_mfma_f32_16x16x32_bf16 v[28:31], v[144:147], v[152:155], v[28:31]
	v_mfma_f32_16x16x32_bf16 v[24:27], v[188:191], v[152:155], v[24:27]
	v_mfma_f32_16x16x32_bf16 v[20:23], v[144:147], v[160:163], v[20:23]
	v_mfma_f32_16x16x32_bf16 v[16:19], v[188:191], v[160:163], v[16:19]
	v_mfma_f32_16x16x32_bf16 v[12:15], v[144:147], v[168:171], v[12:15]
	v_mfma_f32_16x16x32_bf16 v[8:11], v[188:191], v[168:171], v[8:11]
	v_mfma_f32_16x16x32_bf16 v[4:7], v[144:147], v[176:179], v[4:7]
	v_mfma_f32_16x16x32_bf16 v[0:3], v[188:191], v[176:179], v[0:3]
	v_mfma_f32_16x16x32_bf16 v[28:31], v[184:187], v[156:159], v[28:31]
	v_mfma_f32_16x16x32_bf16 v[24:27], v[194:197], v[156:159], v[24:27]
	v_mfma_f32_16x16x32_bf16 v[20:23], v[184:187], v[164:167], v[20:23]
	v_mfma_f32_16x16x32_bf16 v[16:19], v[194:197], v[164:167], v[16:19]
	v_mfma_f32_16x16x32_bf16 v[12:15], v[184:187], v[172:175], v[12:15]
	v_mfma_f32_16x16x32_bf16 v[8:11], v[194:197], v[172:175], v[8:11]
	v_mfma_f32_16x16x32_bf16 v[4:7], v[184:187], v[180:183], v[4:7]
	v_mfma_f32_16x16x32_bf16 v[0:3], v[194:197], v[180:183], v[0:3]
	s_setprio 0
	s_barrier
	ds_read_b128 v[132:135], v138 offset:32768
	ds_read_b128 v[140:143], v138 offset:33792
	ds_read_b128 v[144:147], v138 offset:34816
	ds_read_b128 v[148:151], v138 offset:35840
	ds_read_b128 v[152:155], v137 offset:32768
	ds_read_b128 v[156:159], v137 offset:33792
	ds_read_b128 v[160:163], v137 offset:34816
	ds_read_b128 v[164:167], v137 offset:35840
	ds_read_b128 v[168:171], v137 offset:36864
	ds_read_b128 v[172:175], v137 offset:37888
	ds_read_b128 v[176:179], v137 offset:38912
	ds_read_b128 v[180:183], v137 offset:39936
	s_waitcnt vmcnt(2)
	s_barrier
; #define WAIT_V(n) asm volatile("s_waitcnt vmcnt(" #n ")" ::: "memory")
; #define WAIT_L(n) asm volatile("s_waitcnt lgkmcnt(" #n ")" ::: "memory")
; #define BAR __builtin_amdgcn_s_barrier()
; #define LDA(dst, b, h) _Pragma("unroll") for (int m = 0; m < 4; ++m) _Pragma("unroll") for (int k = 0; k < 2; ++k) \
;     dst[m][k] = *reinterpret_cast<const bf16x8*>((char*)shm + abase + (((b) * 2 + (h)) * 16384 + (m * 2 + k) * 1024))
; #define LDB(dst, b, h) _Pragma("unroll") for (int n = 0; n < 2; ++n) _Pragma("unroll") for (int k = 0; k < 2; ++k) \
;     dst[n][k] = *reinterpret_cast<const bf16x8*>((char*)shm + bbase + (((b) * 2 + (h)) * 16384 + (n * 2 + k) * 1024))
; template <bool SWAP>
; __device__ __forceinline__ void gemm_main(const u16* __restrict__ A, const u16* __restrict__ Bt, int brow, int bcol,
;                                           u16* shm, f32x4 (&acc)[2][2][4][2]) {
;     ...
;   { LDB(B0, 1, 0); LDA(At, 1, 0); WAIT_V(2); BAR; WAIT_L(0); MMA(0, 0, At, B0); BAR;
;     LDB(B1, 1, 1); WAIT_V(0); BAR; WAIT_L(0); MMA(0, 1, At, B1); BAR;
;     LDA(At, 1, 1); BAR; WAIT_L(0); MMA(1, 0, At, B0); MMA(1, 1, At, B1); BAR; }
;   if (wr == 0) BAR;
	s_waitcnt lgkmcnt(0)
	s_setprio 1
	s_waitcnt lgkmcnt(0)
	v_mfma_f32_16x16x32_bf16 v[124:127], v[132:135], v[152:155], v[124:127]
	v_mfma_f32_16x16x32_bf16 v[120:123], v[144:147], v[152:155], v[120:123]
	v_mfma_f32_16x16x32_bf16 v[116:119], v[132:135], v[160:163], v[116:119]
	v_mfma_f32_16x16x32_bf16 v[112:115], v[144:147], v[160:163], v[112:115]
	v_mfma_f32_16x16x32_bf16 v[108:111], v[132:135], v[168:171], v[108:111]
	v_mfma_f32_16x16x32_bf16 v[104:107], v[144:147], v[168:171], v[104:107]
	v_mfma_f32_16x16x32_bf16 v[100:103], v[132:135], v[176:179], v[100:103]
	v_mfma_f32_16x16x32_bf16 v[96:99], v[144:147], v[176:179], v[96:99]
	v_mfma_f32_16x16x32_bf16 v[128:131], v[140:143], v[156:159], v[124:127]
	v_mfma_f32_16x16x32_bf16 v[124:127], v[148:151], v[156:159], v[120:123]
	v_mfma_f32_16x16x32_bf16 v[116:119], v[140:143], v[164:167], v[116:119]
	v_mfma_f32_16x16x32_bf16 v[112:115], v[148:151], v[164:167], v[112:115]
	v_mfma_f32_16x16x32_bf16 v[108:111], v[140:143], v[172:175], v[108:111]
	v_mfma_f32_16x16x32_bf16 v[104:107], v[148:151], v[172:175], v[104:107]
	v_mfma_f32_16x16x32_bf16 v[100:103], v[140:143], v[180:183], v[100:103]
	v_mfma_f32_16x16x32_bf16 v[96:99], v[148:151], v[180:183], v[96:99]
	s_setprio 0
	s_barrier
	ds_read_b128 v[120:123], v138 offset:49152
	ds_read_b128 v[184:187], v138 offset:50176
	ds_read_b128 v[188:191], v138 offset:51200
	ds_read_b128 v[194:197], v138 offset:52224
	s_waitcnt vmcnt(0)
	s_barrier
	s_waitcnt lgkmcnt(0)
	s_setprio 1
	s_waitcnt lgkmcnt(0)
	v_mfma_f32_16x16x32_bf16 v[92:95], v[120:123], v[152:155], v[92:95]
	v_mfma_f32_16x16x32_bf16 v[88:91], v[188:191], v[152:155], v[88:91]
	v_mfma_f32_16x16x32_bf16 v[84:87], v[120:123], v[160:163], v[84:87]
	v_mfma_f32_16x16x32_bf16 v[80:83], v[188:191], v[160:163], v[80:83]
	v_mfma_f32_16x16x32_bf16 v[76:79], v[120:123], v[168:171], v[76:79]
	v_mfma_f32_16x16x32_bf16 v[72:75], v[188:191], v[168:171], v[72:75]
	v_mfma_f32_16x16x32_bf16 v[68:71], v[120:123], v[176:179], v[68:71]
	v_mfma_f32_16x16x32_bf16 v[64:67], v[188:191], v[176:179], v[64:67]
	v_mfma_f32_16x16x32_bf16 v[92:95], v[184:187], v[156:159], v[92:95]
	v_mfma_f32_16x16x32_bf16 v[88:91], v[194:197], v[156:159], v[88:91]
	v_mfma_f32_16x16x32_bf16 v[84:87], v[184:187], v[164:167], v[84:87]
	v_mfma_f32_16x16x32_bf16 v[80:83], v[194:197], v[164:167], v[80:83]
	v_mfma_f32_16x16x32_bf16 v[76:79], v[184:187], v[172:175], v[76:79]
	v_mfma_f32_16x16x32_bf16 v[72:75], v[194:197], v[172:175], v[72:75]
	v_mfma_f32_16x16x32_bf16 v[68:71], v[184:187], v[180:183], v[68:71]
	v_mfma_f32_16x16x32_bf16 v[64:67], v[194:197], v[180:183], v[64:67]
	s_setprio 0
	s_barrier
	ds_read_b128 v[152:155], v137 offset:49152
	ds_read_b128 v[156:159], v137 offset:50176
	ds_read_b128 v[160:163], v137 offset:51200
	ds_read_b128 v[164:167], v137 offset:52224
	ds_read_b128 v[168:171], v137 offset:53248
	ds_read_b128 v[172:175], v137 offset:54272
	ds_read_b128 v[176:179], v137 offset:55296
	ds_read_b128 v[180:183], v137 offset:56320
	s_barrier
	s_waitcnt lgkmcnt(0)
	s_setprio 1
	s_waitcnt lgkmcnt(0)
	v_mfma_f32_16x16x32_bf16 v[60:63], v[132:135], v[152:155], v[60:63]
	v_mfma_f32_16x16x32_bf16 v[56:59], v[144:147], v[152:155], v[56:59]
	v_mfma_f32_16x16x32_bf16 v[52:55], v[132:135], v[160:163], v[52:55]
	v_mfma_f32_16x16x32_bf16 v[48:51], v[144:147], v[160:163], v[48:51]
	v_mfma_f32_16x16x32_bf16 v[44:47], v[132:135], v[168:171], v[44:47]
	v_mfma_f32_16x16x32_bf16 v[40:43], v[144:147], v[168:171], v[40:43]
	v_mfma_f32_16x16x32_bf16 v[36:39], v[132:135], v[176:179], v[36:39]
	v_mfma_f32_16x16x32_bf16 v[32:35], v[144:147], v[176:179], v[32:35]
	v_mfma_f32_16x16x32_bf16 v[60:63], v[140:143], v[156:159], v[60:63]
	v_mfma_f32_16x16x32_bf16 v[56:59], v[148:151], v[156:159], v[56:59]
	v_mfma_f32_16x16x32_bf16 v[52:55], v[140:143], v[164:167], v[52:55]
	v_mfma_f32_16x16x32_bf16 v[48:51], v[148:151], v[164:167], v[48:51]
	v_mfma_f32_16x16x32_bf16 v[44:47], v[140:143], v[172:175], v[44:47]
	v_mfma_f32_16x16x32_bf16 v[40:43], v[148:151], v[172:175], v[40:43]
	v_mfma_f32_16x16x32_bf16 v[36:39], v[140:143], v[180:183], v[36:39]
	v_mfma_f32_16x16x32_bf16 v[32:35], v[148:151], v[180:183], v[32:35]
	s_setprio 0
	s_setprio 1
	v_mfma_f32_16x16x32_bf16 v[28:31], v[120:123], v[152:155], v[28:31]
	v_mfma_f32_16x16x32_bf16 v[24:27], v[188:191], v[152:155], v[24:27]
	v_mfma_f32_16x16x32_bf16 v[20:23], v[120:123], v[160:163], v[20:23]
	v_mfma_f32_16x16x32_bf16 v[16:19], v[188:191], v[160:163], v[16:19]
	v_mfma_f32_16x16x32_bf16 v[12:15], v[120:123], v[168:171], v[12:15]
	v_mfma_f32_16x16x32_bf16 v[8:11], v[188:191], v[168:171], v[8:11]
	v_mfma_f32_16x16x32_bf16 v[4:7], v[120:123], v[176:179], v[4:7]
	v_mfma_f32_16x16x32_bf16 v[0:3], v[188:191], v[176:179], v[0:3]
	v_mfma_f32_16x16x32_bf16 v[28:31], v[184:187], v[156:159], v[28:31]
	v_mfma_f32_16x16x32_bf16 v[24:27], v[194:197], v[156:159], v[24:27]
	v_mfma_f32_16x16x32_bf16 v[20:23], v[184:187], v[164:167], v[20:23]
	v_mfma_f32_16x16x32_bf16 v[16:19], v[194:197], v[164:167], v[16:19]
	v_mfma_f32_16x16x32_bf16 v[12:15], v[184:187], v[172:175], v[12:15]
	v_mfma_f32_16x16x32_bf16 v[8:11], v[194:197], v[172:175], v[8:11]
	v_mfma_f32_16x16x32_bf16 v[4:7], v[184:187], v[180:183], v[4:7]
	v_mfma_f32_16x16x32_bf16 v[0:3], v[194:197], v[180:183], v[0:3]
	s_setprio 0
	s_movk_i32 s0, 0x100
	v_cmp_gt_u32_e32 vcc, s0, v136
	s_barrier
	s_and_saveexec_b64 s[0:1], vcc
	s_cbranch_execz .LBB0_567
	s_barrier

; #define WAIT_V(n) asm volatile("s_waitcnt vmcnt(" #n ")" ::: "memory")
; #define WAIT_L(n) asm volatile("s_waitcnt lgkmcnt(" #n ")" ::: "memory")
; #define BAR __builtin_amdgcn_s_barrier()
; #define SCHED __builtin_amdgcn_sched_barrier(0)
; #define STAGE(P, BASE, br, kt) do { const char* _g = (const char*)((BASE) + (size_t)(br) * GK + (kt) * BK); \
;     __builtin_amdgcn_global_load_lds((const unsigned*)(_g + voff0), (unsigned*)((char*)(P) + tx * 16), 16, 0, 0); \
;     __builtin_amdgcn_global_load_lds((const unsigned*)(_g + voff1), (unsigned*)((char*)(P) + tx * 16 + 8192), 16, 0, 0); } while (0)
; #define LDA(dst, b, h) _Pragma("unroll") for (int m = 0; m < 4; ++m) _Pragma("unroll") for (int k = 0; k < 2; ++k) \
;     dst[m][k] = *reinterpret_cast<const bf16x8*>((char*)shm + abase + (((b) * 2 + (h)) * 16384 + (m * 2 + k) * 1024))
; #define LDB(dst, b, h) _Pragma("unroll") for (int n = 0; n < 2; ++n) _Pragma("unroll") for (int k = 0; k < 2; ++k) \
;     dst[n][k] = *reinterpret_cast<const bf16x8*>((char*)shm + bbase + (((b) * 2 + (h)) * 16384 + (n * 2 + k) * 1024))
; template <bool SWAP>
; __device__ __forceinline__ void gemm_main(const u16* __restrict__ A, const u16* __restrict__ Bt, int brow, int bcol,
;                                           u16* shm, f32x4 (&acc)[2][2][4][2]) {
;     ...
;   for (int t = 0; t < nt - 2; t += 2) {
;     LDB(B0, 0, 0); SCHED; LDA(At, 0, 0); STAGE(SA(1, 1), A, brow + HALF, t + 1);
;     WAIT_L(8); BAR; WAIT_L(0); MMA(0, 0, At, B0); BAR; SCHED;
;     LDB(B1, 0, 1); STAGE(SB(0, 0), Bt, bcol, t + 2);
;     BAR; WAIT_L(0); MMA(0, 1, At, B1); BAR;
;     LDA(At, 0, 1); STAGE(SA(0, 0), A, brow, t + 2);
;     BAR; WAIT_L(0); MMA(1, 0, At, B0); BAR; SCHED;
;     STAGE(SB(0, 1), Bt, bcol + HALF, t + 2);
;     WAIT_V(6); BAR; MMA(1, 1, At, B1); BAR;
.LBB0_570:
	ds_read_b128 v[168:171], v137 offset:1024
	ds_read_b128 v[176:179], v137 offset:3072
	ds_read_b128 v[184:187], v137 offset:5120
	ds_read_b128 v[194:197], v137 offset:7168
	v_add_u32_e32 v192, 0, v140
	v_add_u32_e32 v146, 0xc000, v192
	v_lshl_add_u64 v[230:231], vcc, 0, v[132:133]
	v_add_u32_e32 v147, 0xe000, v192
	v_lshl_add_u64 v[198:199], v[230:231], 0, s[14:15]
	s_add_u32 m0, s24, 0xc000
	v_lshl_add_u64 v[232:233], vcc, 0, v[134:135]
	global_load_lds_dwordx4 v[198:199], off
	v_lshl_add_u64 v[198:199], v[232:233], 0, s[14:15]
	s_add_u32 m0, s24, 0xe000
	s_nop 0
	global_load_lds_dwordx4 v[198:199], off
	s_waitcnt lgkmcnt(8)
	s_waitcnt vmcnt(8)
	s_setprio 1
	s_barrier
	s_waitcnt lgkmcnt(0)
	v_mfma_f32_16x16x32_bf16 v[124:127], v[148:151], v[164:167], v[124:127]
	v_mfma_f32_16x16x32_bf16 v[120:123], v[156:159], v[164:167], v[120:123]
	v_mfma_f32_16x16x32_bf16 v[116:119], v[148:151], v[172:175], v[116:119]
	v_mfma_f32_16x16x32_bf16 v[112:115], v[156:159], v[172:175], v[112:115]
	v_mfma_f32_16x16x32_bf16 v[108:111], v[148:151], v[180:183], v[108:111]
	v_mfma_f32_16x16x32_bf16 v[104:107], v[156:159], v[180:183], v[104:107]
	v_mfma_f32_16x16x32_bf16 v[100:103], v[148:151], v[188:191], v[100:103]
	v_mfma_f32_16x16x32_bf16 v[96:99], v[156:159], v[188:191], v[96:99]
	v_mfma_f32_16x16x32_bf16 v[124:127], v[152:155], v[168:171], v[124:127]
	v_mfma_f32_16x16x32_bf16 v[120:123], v[160:163], v[168:171], v[120:123]
	v_mfma_f32_16x16x32_bf16 v[116:119], v[152:155], v[176:179], v[116:119]
	v_mfma_f32_16x16x32_bf16 v[112:115], v[160:163], v[176:179], v[112:115]
	v_mfma_f32_16x16x32_bf16 v[108:111], v[152:155], v[184:187], v[108:111]
	v_mfma_f32_16x16x32_bf16 v[104:107], v[160:163], v[184:187], v[104:107]
	v_mfma_f32_16x16x32_bf16 v[100:103], v[152:155], v[194:197], v[100:103]
	v_mfma_f32_16x16x32_bf16 v[96:99], v[160:163], v[194:197], v[96:99]
	s_barrier
	s_setprio 0
	ds_read_b128 v[198:201], v138 offset:16384
	ds_read_b128 v[202:205], v138 offset:17408
	ds_read_b128 v[206:209], v138 offset:18432
	ds_read_b128 v[226:229], v138 offset:19456
	v_lshl_add_u64 v[234:235], vcc, 0, v[128:129]
	v_lshl_add_u64 v[236:237], v[234:235], 0, s[16:17]
	s_add_u32 m0, s24, s28
	s_nop 0
	global_load_lds_dwordx4 v[236:237], off
	v_lshl_add_u64 v[236:237], vcc, 0, v[130:131]
	v_lshl_add_u64 v[238:239], v[236:237], 0, s[16:17]
	s_add_u32 m0, s24, s28
	s_add_u32 m0, m0, 0x2000
	s_nop 0
	global_load_lds_dwordx4 v[238:239], off
	s_setprio 1
	s_barrier
	s_waitcnt lgkmcnt(0)
	v_mfma_f32_16x16x32_bf16 v[92:95], v[198:201], v[164:167], v[92:95]
	v_mfma_f32_16x16x32_bf16 v[88:91], v[206:209], v[164:167], v[88:91]
	v_mfma_f32_16x16x32_bf16 v[84:87], v[198:201], v[172:175], v[84:87]
	v_mfma_f32_16x16x32_bf16 v[80:83], v[206:209], v[172:175], v[80:83]
	v_mfma_f32_16x16x32_bf16 v[76:79], v[198:201], v[180:183], v[76:79]
	v_mfma_f32_16x16x32_bf16 v[72:75], v[206:209], v[180:183], v[72:75]
	v_mfma_f32_16x16x32_bf16 v[68:71], v[198:201], v[188:191], v[68:71]
	v_mfma_f32_16x16x32_bf16 v[64:67], v[206:209], v[188:191], v[64:67]
	v_mfma_f32_16x16x32_bf16 v[92:95], v[202:205], v[168:171], v[92:95]
	ds_read_b128 v[164:167], v137 offset:16384
	v_mfma_f32_16x16x32_bf16 v[88:91], v[226:229], v[168:171], v[88:91]
	v_mfma_f32_16x16x32_bf16 v[84:87], v[202:205], v[176:179], v[84:87]
	ds_read_b128 v[172:175], v137 offset:18432
	v_mfma_f32_16x16x32_bf16 v[80:83], v[226:229], v[176:179], v[80:83]
	v_mfma_f32_16x16x32_bf16 v[76:79], v[202:205], v[184:187], v[76:79]
	ds_read_b128 v[180:183], v137 offset:20480
	v_mfma_f32_16x16x32_bf16 v[72:75], v[226:229], v[184:187], v[72:75]
	v_mfma_f32_16x16x32_bf16 v[68:71], v[202:205], v[194:197], v[68:71]
	ds_read_b128 v[188:191], v137 offset:22528
	v_mfma_f32_16x16x32_bf16 v[64:67], v[226:229], v[194:197], v[64:67]
	s_barrier
	s_setprio 0
	ds_read_b128 v[168:171], v137 offset:17408
	ds_read_b128 v[176:179], v137 offset:19456
	ds_read_b128 v[184:187], v137 offset:21504
	ds_read_b128 v[194:197], v137 offset:23552
	v_lshl_add_u64 v[238:239], v[230:231], 0, s[18:19]
	s_add_u32 m0, s24, 0x0
	s_nop 0
	global_load_lds_dwordx4 v[238:239], off
	v_lshl_add_u64 v[238:239], v[232:233], 0, s[18:19]
	s_add_u32 m0, s24, 0x2000
	s_nop 0
	global_load_lds_dwordx4 v[238:239], off
	s_waitcnt vmcnt(8)
	s_setprio 1
	s_barrier
	s_waitcnt lgkmcnt(0)
	v_mfma_f32_16x16x32_bf16 v[60:63], v[148:151], v[164:167], v[60:63]
	v_mfma_f32_16x16x32_bf16 v[56:59], v[156:159], v[164:167], v[56:59]
	v_mfma_f32_16x16x32_bf16 v[52:55], v[148:151], v[172:175], v[52:55]
	v_mfma_f32_16x16x32_bf16 v[48:51], v[156:159], v[172:175], v[48:51]
	v_mfma_f32_16x16x32_bf16 v[44:47], v[148:151], v[180:183], v[44:47]
	v_mfma_f32_16x16x32_bf16 v[40:43], v[156:159], v[180:183], v[40:43]
	v_mfma_f32_16x16x32_bf16 v[36:39], v[148:151], v[188:191], v[36:39]
	v_mfma_f32_16x16x32_bf16 v[32:35], v[156:159], v[188:191], v[32:35]
	v_mfma_f32_16x16x32_bf16 v[60:63], v[152:155], v[168:171], v[60:63]
	v_mfma_f32_16x16x32_bf16 v[56:59], v[160:163], v[168:171], v[56:59]
	v_mfma_f32_16x16x32_bf16 v[52:55], v[152:155], v[176:179], v[52:55]
	v_mfma_f32_16x16x32_bf16 v[48:51], v[160:163], v[176:179], v[48:51]
	v_mfma_f32_16x16x32_bf16 v[44:47], v[152:155], v[184:187], v[44:47]
	v_mfma_f32_16x16x32_bf16 v[40:43], v[160:163], v[184:187], v[40:43]
	v_mfma_f32_16x16x32_bf16 v[36:39], v[152:155], v[194:197], v[36:39]
	v_mfma_f32_16x16x32_bf16 v[32:35], v[160:163], v[194:197], v[32:35]
	s_barrier
; #define WAIT_V(n) asm volatile("s_waitcnt vmcnt(" #n ")" ::: "memory")
; #define WAIT_L(n) asm volatile("s_waitcnt lgkmcnt(" #n ")" ::: "memory")
; #define BAR __builtin_amdgcn_s_barrier()
; #define SCHED __builtin_amdgcn_sched_barrier(0)
; #define STAGE(P, BASE, br, kt) do { const char* _g = (const char*)((BASE) + (size_t)(br) * GK + (kt) * BK); \
;     __builtin_amdgcn_global_load_lds((const unsigned*)(_g + voff0), (unsigned*)((char*)(P) + tx * 16), 16, 0, 0); \
;     __builtin_amdgcn_global_load_lds((const unsigned*)(_g + voff1), (unsigned*)((char*)(P) + tx * 16 + 8192), 16, 0, 0); } while (0)
; #define LDA(dst, b, h) _Pragma("unroll") for (int m = 0; m < 4; ++m) _Pragma("unroll") for (int k = 0; k < 2; ++k) \
;     dst[m][k] = *reinterpret_cast<const bf16x8*>((char*)shm + abase + (((b) * 2 + (h)) * 16384 + (m * 2 + k) * 1024))
; #define LDB(dst, b, h) _Pragma("unroll") for (int n = 0; n < 2; ++n) _Pragma("unroll") for (int k = 0; k < 2; ++k) \
;     dst[n][k] = *reinterpret_cast<const bf16x8*>((char*)shm + bbase + (((b) * 2 + (h)) * 16384 + (n * 2 + k) * 1024))
; template <bool SWAP>
; __device__ __forceinline__ void gemm_main(const u16* __restrict__ A, const u16* __restrict__ Bt, int brow, int bcol,
;                                           u16* shm, f32x4 (&acc)[2][2][4][2]) {
;     ...
;     BAR; WAIT_L(0); MMA(1, 0, At, B0); BAR; SCHED;
;     STAGE(SB(0, 1), Bt, bcol + HALF, t + 2);
;     WAIT_V(6); BAR; MMA(1, 1, At, B1); BAR;
;     LDB(B0, 1, 0); SCHED; LDA(At, 1, 0); STAGE(SA(0, 1), A, brow + HALF, t + 2);
;     WAIT_L(8); BAR; WAIT_L(0); MMA(0, 0, At, B0); BAR; SCHED;
;     LDB(B1, 1, 1); STAGE(SB(1, 0), Bt, bcol, t + 3);
;     BAR; WAIT_L(0); MMA(0, 1, At, B1); BAR;
;     LDA(At, 1, 1); STAGE(SA(1, 0), A, brow, t + 3);
;     BAR; WAIT_L(0); MMA(1, 0, At, B0); BAR; SCHED;
	s_setprio 0
	ds_read_b128 v[148:151], v138 offset:32768
	ds_read_b128 v[152:155], v138 offset:33792
	ds_read_b128 v[156:159], v138 offset:34816
	ds_read_b128 v[160:163], v138 offset:35840
	v_lshl_add_u64 v[254:255], v[234:235], 0, s[42:43]
	s_add_u32 m0, s24, s29
	s_nop 0
	global_load_lds_dwordx4 v[254:255], off
	v_lshl_add_u64 v[254:255], v[236:237], 0, s[42:43]
	s_add_u32 m0, s24, s29
	s_add_u32 m0, m0, 0x2000
	s_nop 0
	global_load_lds_dwordx4 v[254:255], off
	s_setprio 1
	s_barrier
	v_mfma_f32_16x16x32_bf16 v[28:31], v[198:201], v[164:167], v[28:31]
	v_mfma_f32_16x16x32_bf16 v[24:27], v[206:209], v[164:167], v[24:27]
	v_mfma_f32_16x16x32_bf16 v[20:23], v[198:201], v[172:175], v[20:23]
	v_mfma_f32_16x16x32_bf16 v[16:19], v[206:209], v[172:175], v[16:19]
	v_mfma_f32_16x16x32_bf16 v[12:15], v[198:201], v[180:183], v[12:15]
	v_mfma_f32_16x16x32_bf16 v[8:11], v[206:209], v[180:183], v[8:11]
	v_mfma_f32_16x16x32_bf16 v[4:7], v[198:201], v[188:191], v[4:7]
	v_mfma_f32_16x16x32_bf16 v[0:3], v[206:209], v[188:191], v[0:3]
	v_mfma_f32_16x16x32_bf16 v[28:31], v[202:205], v[168:171], v[28:31]
	ds_read_b128 v[164:167], v137 offset:32768
	v_mfma_f32_16x16x32_bf16 v[24:27], v[226:229], v[168:171], v[24:27]
	v_mfma_f32_16x16x32_bf16 v[20:23], v[202:205], v[176:179], v[20:23]
	ds_read_b128 v[172:175], v137 offset:34816
	v_mfma_f32_16x16x32_bf16 v[16:19], v[226:229], v[176:179], v[16:19]
	v_mfma_f32_16x16x32_bf16 v[12:15], v[202:205], v[184:187], v[12:15]
	ds_read_b128 v[180:183], v137 offset:36864
	v_mfma_f32_16x16x32_bf16 v[8:11], v[226:229], v[184:187], v[8:11]
	v_mfma_f32_16x16x32_bf16 v[4:7], v[202:205], v[194:197], v[4:7]
	ds_read_b128 v[188:191], v137 offset:38912
	v_mfma_f32_16x16x32_bf16 v[0:3], v[226:229], v[194:197], v[0:3]
	s_barrier
	s_setprio 0
	ds_read_b128 v[168:171], v137 offset:33792
	ds_read_b128 v[176:179], v137 offset:35840
	ds_read_b128 v[184:187], v137 offset:37888
	ds_read_b128 v[194:197], v137 offset:39936
	v_lshl_add_u64 v[198:199], v[230:231], 0, s[22:23]
	s_add_u32 m0, s24, 0x4000
	s_nop 0
	global_load_lds_dwordx4 v[198:199], off
	v_lshl_add_u64 v[198:199], v[232:233], 0, s[22:23]
	s_add_u32 m0, s24, 0x6000
	s_nop 0
	global_load_lds_dwordx4 v[198:199], off
	s_waitcnt lgkmcnt(8)
	s_waitcnt vmcnt(8)
	s_setprio 1
	s_barrier
	s_waitcnt lgkmcnt(0)
	v_mfma_f32_16x16x32_bf16 v[124:127], v[148:151], v[164:167], v[124:127]
	v_mfma_f32_16x16x32_bf16 v[120:123], v[156:159], v[164:167], v[120:123]
	v_mfma_f32_16x16x32_bf16 v[116:119], v[148:151], v[172:175], v[116:119]
	v_mfma_f32_16x16x32_bf16 v[112:115], v[156:159], v[172:175], v[112:115]
	v_mfma_f32_16x16x32_bf16 v[108:111], v[148:151], v[180:183], v[108:111]
	v_mfma_f32_16x16x32_bf16 v[104:107], v[156:159], v[180:183], v[104:107]
	v_mfma_f32_16x16x32_bf16 v[100:103], v[148:151], v[188:191], v[100:103]
	v_mfma_f32_16x16x32_bf16 v[96:99], v[156:159], v[188:191], v[96:99]
	v_mfma_f32_16x16x32_bf16 v[124:127], v[152:155], v[168:171], v[124:127]
	v_mfma_f32_16x16x32_bf16 v[120:123], v[160:163], v[168:171], v[120:123]
	v_mfma_f32_16x16x32_bf16 v[116:119], v[152:155], v[176:179], v[116:119]
	v_mfma_f32_16x16x32_bf16 v[112:115], v[160:163], v[176:179], v[112:115]
	v_mfma_f32_16x16x32_bf16 v[108:111], v[152:155], v[184:187], v[108:111]
	v_mfma_f32_16x16x32_bf16 v[104:107], v[160:163], v[184:187], v[104:107]
	v_mfma_f32_16x16x32_bf16 v[100:103], v[152:155], v[194:197], v[100:103]
	v_mfma_f32_16x16x32_bf16 v[96:99], v[160:163], v[194:197], v[96:99]
	s_barrier
	s_setprio 0
	ds_read_b128 v[198:201], v138 offset:49152
	ds_read_b128 v[202:205], v138 offset:50176
	ds_read_b128 v[206:209], v138 offset:51200
	ds_read_b128 v[226:229], v138 offset:52224
	v_lshl_add_u64 v[238:239], v[234:235], 0, s[20:21]
	s_add_u32 m0, s24, s30
	s_nop 0
	global_load_lds_dwordx4 v[238:239], off
	v_lshl_add_u64 v[238:239], v[236:237], 0, s[20:21]
	s_add_u32 m0, s24, s30
	s_add_u32 m0, m0, 0x2000
	s_nop 0
	global_load_lds_dwordx4 v[238:239], off
	s_setprio 1
	s_barrier
	s_waitcnt lgkmcnt(0)
	v_mfma_f32_16x16x32_bf16 v[92:95], v[198:201], v[164:167], v[92:95]
	v_mfma_f32_16x16x32_bf16 v[88:91], v[206:209], v[164:167], v[88:91]
	v_mfma_f32_16x16x32_bf16 v[84:87], v[198:201], v[172:175], v[84:87]
	v_mfma_f32_16x16x32_bf16 v[80:83], v[206:209], v[172:175], v[80:83]
	v_mfma_f32_16x16x32_bf16 v[76:79], v[198:201], v[180:183], v[76:79]
	v_mfma_f32_16x16x32_bf16 v[72:75], v[206:209], v[180:183], v[72:75]
	v_mfma_f32_16x16x32_bf16 v[68:71], v[198:201], v[188:191], v[68:71]
	v_mfma_f32_16x16x32_bf16 v[64:67], v[206:209], v[188:191], v[64:67]
	v_mfma_f32_16x16x32_bf16 v[92:95], v[202:205], v[168:171], v[92:95]
	ds_read_b128 v[164:167], v137 offset:49152
	v_mfma_f32_16x16x32_bf16 v[88:91], v[226:229], v[168:171], v[88:91]
	v_mfma_f32_16x16x32_bf16 v[84:87], v[202:205], v[176:179], v[84:87]
	ds_read_b128 v[172:175], v137 offset:51200
	v_mfma_f32_16x16x32_bf16 v[80:83], v[226:229], v[176:179], v[80:83]
	v_mfma_f32_16x16x32_bf16 v[76:79], v[202:205], v[184:187], v[76:79]
	ds_read_b128 v[180:183], v137 offset:53248
	v_mfma_f32_16x16x32_bf16 v[72:75], v[226:229], v[184:187], v[72:75]
	v_mfma_f32_16x16x32_bf16 v[68:71], v[202:205], v[194:197], v[68:71]
	ds_read_b128 v[188:191], v137 offset:55296
	v_mfma_f32_16x16x32_bf16 v[64:67], v[226:229], v[194:197], v[64:67]
	s_barrier
	s_setprio 0
	ds_read_b128 v[168:171], v137 offset:50176
	ds_read_b128 v[176:179], v137 offset:52224
	ds_read_b128 v[184:187], v137 offset:54272
	ds_read_b128 v[194:197], v137 offset:56320
	v_lshl_add_u64 v[230:231], v[230:231], 0, s[92:93]
	s_add_u32 m0, s24, 0x8000
	s_nop 0
	global_load_lds_dwordx4 v[230:231], off
	v_lshl_add_u64 v[230:231], v[232:233], 0, s[92:93]
	s_add_u32 m0, s24, 0xa000
	s_nop 0
	global_load_lds_dwordx4 v[230:231], off
	s_waitcnt vmcnt(8)
	s_setprio 1
	s_barrier
; #define WAIT_V(n) asm volatile("s_waitcnt vmcnt(" #n ")" ::: "memory")
; #define WAIT_L(n) asm volatile("s_waitcnt lgkmcnt(" #n ")" ::: "memory")
; #define BAR __builtin_amdgcn_s_barrier()
; #define SCHED __builtin_amdgcn_sched_barrier(0)
; #define STAGE(P, BASE, br, kt) do { const char* _g = (const char*)((BASE) + (size_t)(br) * GK + (kt) * BK); \
;     __builtin_amdgcn_global_load_lds((const unsigned*)(_g + voff0), (unsigned*)((char*)(P) + tx * 16), 16, 0, 0); \
;     __builtin_amdgcn_global_load_lds((const unsigned*)(_g + voff1), (unsigned*)((char*)(P) + tx * 16 + 8192), 16, 0, 0); } while (0)
; #define LDA(dst, b, h) _Pragma("unroll") for (int m = 0; m < 4; ++m) _Pragma("unroll") for (int k = 0; k < 2; ++k) \
;     dst[m][k] = *reinterpret_cast<const bf16x8*>((char*)shm + abase + (((b) * 2 + (h)) * 16384 + (m * 2 + k) * 1024))
; #define LDB(dst, b, h) _Pragma("unroll") for (int n = 0; n < 2; ++n) _Pragma("unroll") for (int k = 0; k < 2; ++k) \
;     dst[n][k] = *reinterpret_cast<const bf16x8*>((char*)shm + bbase + (((b) * 2 + (h)) * 16384 + (n * 2 + k) * 1024))
; template <bool SWAP>
; __device__ __forceinline__ void gemm_main(const u16* __restrict__ A, const u16* __restrict__ Bt, int brow, int bcol,
;                                           u16* shm, f32x4 (&acc)[2][2][4][2]) {
;     ...
;     BAR; WAIT_L(0); MMA(1, 0, At, B0); BAR; SCHED;
;     STAGE(SB(1, 1), Bt, bcol + HALF, t + 3);
;     WAIT_V(6); BAR; MMA(1, 1, At, B1); BAR;
;   }
;   { LDB(B0, 0, 0); LDA(At, 0, 0); STAGE(SA(1, 1), A, brow + HALF, nt - 1);
;     BAR; WAIT_L(0); MMA(0, 0, At, B0); BAR;
	s_waitcnt lgkmcnt(0)
	v_mfma_f32_16x16x32_bf16 v[60:63], v[148:151], v[164:167], v[60:63]
	v_mfma_f32_16x16x32_bf16 v[56:59], v[156:159], v[164:167], v[56:59]
	v_mfma_f32_16x16x32_bf16 v[52:55], v[148:151], v[172:175], v[52:55]
	v_mfma_f32_16x16x32_bf16 v[48:51], v[156:159], v[172:175], v[48:51]
	v_mfma_f32_16x16x32_bf16 v[44:47], v[148:151], v[180:183], v[44:47]
	v_mfma_f32_16x16x32_bf16 v[40:43], v[156:159], v[180:183], v[40:43]
	v_mfma_f32_16x16x32_bf16 v[36:39], v[148:151], v[188:191], v[36:39]
	v_mfma_f32_16x16x32_bf16 v[32:35], v[156:159], v[188:191], v[32:35]
	v_mfma_f32_16x16x32_bf16 v[60:63], v[152:155], v[168:171], v[60:63]
	v_mfma_f32_16x16x32_bf16 v[56:59], v[160:163], v[168:171], v[56:59]
	v_mfma_f32_16x16x32_bf16 v[52:55], v[152:155], v[176:179], v[52:55]
	v_mfma_f32_16x16x32_bf16 v[48:51], v[160:163], v[176:179], v[48:51]
	v_mfma_f32_16x16x32_bf16 v[44:47], v[152:155], v[184:187], v[44:47]
	v_mfma_f32_16x16x32_bf16 v[40:43], v[160:163], v[184:187], v[40:43]
	v_mfma_f32_16x16x32_bf16 v[36:39], v[152:155], v[194:197], v[36:39]
	v_mfma_f32_16x16x32_bf16 v[32:35], v[160:163], v[194:197], v[32:35]
	s_barrier
	s_setprio 0
	ds_read_b128 v[148:151], v138
	ds_read_b128 v[152:155], v138 offset:1024
	ds_read_b128 v[156:159], v138 offset:2048
	ds_read_b128 v[160:163], v138 offset:3072
	v_lshl_add_u64 v[254:255], v[234:235], 0, s[72:73]
	s_add_u32 m0, s24, s31
	s_nop 0
	global_load_lds_dwordx4 v[254:255], off
	v_lshl_add_u64 v[254:255], v[236:237], 0, s[72:73]
	s_add_u32 m0, s24, s31
	s_add_u32 m0, m0, 0x2000
	s_nop 0
	global_load_lds_dwordx4 v[254:255], off
	s_setprio 1
	s_barrier
	v_mfma_f32_16x16x32_bf16 v[28:31], v[198:201], v[164:167], v[28:31]
	v_mfma_f32_16x16x32_bf16 v[24:27], v[206:209], v[164:167], v[24:27]
	v_mfma_f32_16x16x32_bf16 v[20:23], v[198:201], v[172:175], v[20:23]
	v_mfma_f32_16x16x32_bf16 v[16:19], v[206:209], v[172:175], v[16:19]
	v_mfma_f32_16x16x32_bf16 v[12:15], v[198:201], v[180:183], v[12:15]
	v_mfma_f32_16x16x32_bf16 v[8:11], v[206:209], v[180:183], v[8:11]
	v_mfma_f32_16x16x32_bf16 v[4:7], v[198:201], v[188:191], v[4:7]
	v_mfma_f32_16x16x32_bf16 v[0:3], v[206:209], v[188:191], v[0:3]
	v_mfma_f32_16x16x32_bf16 v[28:31], v[202:205], v[168:171], v[28:31]
	ds_read_b128 v[164:167], v137
	v_mfma_f32_16x16x32_bf16 v[24:27], v[226:229], v[168:171], v[24:27]
	v_mfma_f32_16x16x32_bf16 v[20:23], v[202:205], v[176:179], v[20:23]
	ds_read_b128 v[172:175], v137 offset:2048
	v_mfma_f32_16x16x32_bf16 v[16:19], v[226:229], v[176:179], v[16:19]
	v_mfma_f32_16x16x32_bf16 v[12:15], v[202:205], v[184:187], v[12:15]
	ds_read_b128 v[180:183], v137 offset:4096
	v_mfma_f32_16x16x32_bf16 v[8:11], v[226:229], v[184:187], v[8:11]
	v_mfma_f32_16x16x32_bf16 v[4:7], v[202:205], v[194:197], v[4:7]
	ds_read_b128 v[188:191], v137 offset:6144
	v_mfma_f32_16x16x32_bf16 v[0:3], v[226:229], v[194:197], v[0:3]
	s_add_i32 s3, s3, 2
	s_add_u32 vcc_lo, vcc_lo, 0x100
	s_addc_u32 vcc_hi, vcc_hi, 0
	s_cmp_lt_u32 s3, 28
	s_barrier
	s_setprio 0
	s_cbranch_scc1 .LBB0_570
	v_lshlrev_b32_e32 v128, 3, v139
	v_lshlrev_b32_e32 v129, 5, v139
	v_and_b32_e32 v128, 0xffff0, v128
	v_and_b32_e32 v129, 32, v129
	v_add_u32_e32 v129, v129, v142
	v_add_lshl_u32 v128, v141, v128, 12
	v_lshl_add_u32 v192, v129, 1, v128
	v_lshlrev_b32_e32 v128, 3, v143
	v_lshlrev_b32_e32 v129, 5, v143
	v_and_b32_e32 v128, 0xffff0, v128
	v_and_b32_e32 v129, 32, v129
	v_add_u32_e32 v129, v129, v145
	v_add_lshl_u32 v128, v144, v128, 12
	v_lshl_add_u32 v144, v129, 1, v128
	v_mov_b32_e32 v145, v193
	v_lshl_add_u64 v[184:185], s[4:5], 0, v[192:193]
	s_mov_b64 s[14:15], 0xf80
	v_readfirstlane_b32 s3, v146
	v_lshl_add_u64 v[184:185], v[184:185], 0, s[14:15]
	s_mov_b32 m0, s3
	v_lshl_add_u64 v[144:145], s[4:5], 0, v[144:145]
	v_readfirstlane_b32 s3, v147
	ds_read_b128 v[128:131], v138
	ds_read_b128 v[132:135], v138 offset:1024
	ds_read_b128 v[140:143], v138 offset:2048
	ds_read_b128 v[148:151], v138 offset:3072
	ds_read_b128 v[152:155], v137
	ds_read_b128 v[156:159], v137 offset:1024
	ds_read_b128 v[160:163], v137 offset:2048
	ds_read_b128 v[164:167], v137 offset:3072
	ds_read_b128 v[168:171], v137 offset:4096
	ds_read_b128 v[172:175], v137 offset:5120
	ds_read_b128 v[176:179], v137 offset:6144
	ds_read_b128 v[180:183], v137 offset:7168
	global_load_lds_dwordx4 v[184:185], off
	v_lshl_add_u64 v[144:145], v[144:145], 0, s[14:15]
	s_mov_b32 m0, s3
	s_nop 0
	global_load_lds_dwordx4 v[144:145], off
	s_waitcnt vmcnt(8)
	s_barrier
	s_waitcnt lgkmcnt(0)
	s_setprio 1
	s_waitcnt lgkmcnt(0)
	v_mfma_f32_16x16x32_bf16 v[116:119], v[128:131], v[160:163], v[116:119]
	v_mfma_f32_16x16x32_bf16 v[112:115], v[140:143], v[160:163], v[112:115]
	v_mfma_f32_16x16x32_bf16 v[100:103], v[128:131], v[176:179], v[100:103]
	v_mfma_f32_16x16x32_bf16 v[96:99], v[140:143], v[176:179], v[96:99]
	v_mfma_f32_16x16x32_bf16 v[124:127], v[128:131], v[152:155], v[124:127]
	v_mfma_f32_16x16x32_bf16 v[120:123], v[140:143], v[152:155], v[120:123]
	v_mfma_f32_16x16x32_bf16 v[116:119], v[132:135], v[164:167], v[116:119]
	v_mfma_f32_16x16x32_bf16 v[112:115], v[148:151], v[164:167], v[112:115]
	v_mfma_f32_16x16x32_bf16 v[108:111], v[128:131], v[168:171], v[108:111]
	v_mfma_f32_16x16x32_bf16 v[104:107], v[140:143], v[168:171], v[104:107]
	v_mfma_f32_16x16x32_bf16 v[100:103], v[132:135], v[180:183], v[100:103]
	v_mfma_f32_16x16x32_bf16 v[96:99], v[148:151], v[180:183], v[96:99]
	v_mfma_f32_16x16x32_bf16 v[124:127], v[132:135], v[156:159], v[124:127]
	v_mfma_f32_16x16x32_bf16 v[120:123], v[148:151], v[156:159], v[120:123]
	v_mfma_f32_16x16x32_bf16 v[108:111], v[132:135], v[172:175], v[108:111]
	v_mfma_f32_16x16x32_bf16 v[104:107], v[148:151], v[172:175], v[104:107]
	s_setprio 0
	s_barrier
; #define WAIT_V(n) asm volatile("s_waitcnt vmcnt(" #n ")" ::: "memory")
; #define WAIT_L(n) asm volatile("s_waitcnt lgkmcnt(" #n ")" ::: "memory")
; #define BAR __builtin_amdgcn_s_barrier()
; #define LDA(dst, b, h) _Pragma("unroll") for (int m = 0; m < 4; ++m) _Pragma("unroll") for (int k = 0; k < 2; ++k) \
;     dst[m][k] = *reinterpret_cast<const bf16x8*>((char*)shm + abase + (((b) * 2 + (h)) * 16384 + (m * 2 + k) * 1024))
; #define LDB(dst, b, h) _Pragma("unroll") for (int n = 0; n < 2; ++n) _Pragma("unroll") for (int k = 0; k < 2; ++k) \
;     dst[n][k] = *reinterpret_cast<const bf16x8*>((char*)shm + bbase + (((b) * 2 + (h)) * 16384 + (n * 2 + k) * 1024))
; template <bool SWAP>
; __device__ __forceinline__ void gemm_main(const u16* __restrict__ A, const u16* __restrict__ Bt, int brow, int bcol,
;                                           u16* shm, f32x4 (&acc)[2][2][4][2]) {
;     ...
;     BAR; WAIT_L(0); MMA(0, 0, At, B0); BAR;
;     LDB(B1, 0, 1); BAR; WAIT_L(0); MMA(0, 1, At, B1); BAR;
;     LDA(At, 0, 1); WAIT_V(4); BAR; WAIT_L(0); MMA(1, 0, At, B0); MMA(1, 1, At, B1); BAR; }
;   { LDB(B0, 1, 0); LDA(At, 1, 0); WAIT_V(2); BAR; WAIT_L(0); MMA(0, 0, At, B0); BAR;
	ds_read_b128 v[144:147], v138 offset:16384
	ds_read_b128 v[184:187], v138 offset:17408
	ds_read_b128 v[188:191], v138 offset:18432
	ds_read_b128 v[194:197], v138 offset:19456
	s_barrier
	s_waitcnt lgkmcnt(0)
	s_setprio 1
	s_waitcnt lgkmcnt(0)
	v_mfma_f32_16x16x32_bf16 v[92:95], v[144:147], v[152:155], v[92:95]
	v_mfma_f32_16x16x32_bf16 v[88:91], v[188:191], v[152:155], v[88:91]
	v_mfma_f32_16x16x32_bf16 v[84:87], v[144:147], v[160:163], v[84:87]
	v_mfma_f32_16x16x32_bf16 v[80:83], v[188:191], v[160:163], v[80:83]
	v_mfma_f32_16x16x32_bf16 v[76:79], v[144:147], v[168:171], v[76:79]
	v_mfma_f32_16x16x32_bf16 v[72:75], v[188:191], v[168:171], v[72:75]
	v_mfma_f32_16x16x32_bf16 v[68:71], v[144:147], v[176:179], v[68:71]
	v_mfma_f32_16x16x32_bf16 v[64:67], v[188:191], v[176:179], v[64:67]
	v_mfma_f32_16x16x32_bf16 v[92:95], v[184:187], v[156:159], v[92:95]
	v_mfma_f32_16x16x32_bf16 v[88:91], v[194:197], v[156:159], v[88:91]
	v_mfma_f32_16x16x32_bf16 v[84:87], v[184:187], v[164:167], v[84:87]
	v_mfma_f32_16x16x32_bf16 v[80:83], v[194:197], v[164:167], v[80:83]
	v_mfma_f32_16x16x32_bf16 v[76:79], v[184:187], v[172:175], v[76:79]
	v_mfma_f32_16x16x32_bf16 v[72:75], v[194:197], v[172:175], v[72:75]
	v_mfma_f32_16x16x32_bf16 v[68:71], v[184:187], v[180:183], v[68:71]
	v_mfma_f32_16x16x32_bf16 v[64:67], v[194:197], v[180:183], v[64:67]
	s_setprio 0
	s_barrier
	ds_read_b128 v[152:155], v137 offset:16384
	ds_read_b128 v[156:159], v137 offset:17408
	ds_read_b128 v[160:163], v137 offset:18432
	ds_read_b128 v[164:167], v137 offset:19456
	ds_read_b128 v[168:171], v137 offset:20480
	ds_read_b128 v[172:175], v137 offset:21504
	ds_read_b128 v[176:179], v137 offset:22528
	ds_read_b128 v[180:183], v137 offset:23552
	s_waitcnt vmcnt(4)
	s_barrier
	s_waitcnt lgkmcnt(0)
	s_setprio 1
	s_waitcnt lgkmcnt(0)
	v_mfma_f32_16x16x32_bf16 v[60:63], v[128:131], v[152:155], v[60:63]
	v_mfma_f32_16x16x32_bf16 v[56:59], v[140:143], v[152:155], v[56:59]
	v_mfma_f32_16x16x32_bf16 v[52:55], v[128:131], v[160:163], v[52:55]
	v_mfma_f32_16x16x32_bf16 v[48:51], v[140:143], v[160:163], v[48:51]
	v_mfma_f32_16x16x32_bf16 v[44:47], v[128:131], v[168:171], v[44:47]
	v_mfma_f32_16x16x32_bf16 v[40:43], v[140:143], v[168:171], v[40:43]
	v_mfma_f32_16x16x32_bf16 v[36:39], v[128:131], v[176:179], v[36:39]
	v_mfma_f32_16x16x32_bf16 v[32:35], v[140:143], v[176:179], v[32:35]
	v_mfma_f32_16x16x32_bf16 v[60:63], v[132:135], v[156:159], v[60:63]
	v_mfma_f32_16x16x32_bf16 v[56:59], v[148:151], v[156:159], v[56:59]
	v_mfma_f32_16x16x32_bf16 v[52:55], v[132:135], v[164:167], v[52:55]
	v_mfma_f32_16x16x32_bf16 v[48:51], v[148:151], v[164:167], v[48:51]
	v_mfma_f32_16x16x32_bf16 v[44:47], v[132:135], v[172:175], v[44:47]
	v_mfma_f32_16x16x32_bf16 v[40:43], v[148:151], v[172:175], v[40:43]
	v_mfma_f32_16x16x32_bf16 v[36:39], v[132:135], v[180:183], v[36:39]
	v_mfma_f32_16x16x32_bf16 v[32:35], v[148:151], v[180:183], v[32:35]
	s_setprio 0
	s_setprio 1
	v_mfma_f32_16x16x32_bf16 v[28:31], v[144:147], v[152:155], v[28:31]
	v_mfma_f32_16x16x32_bf16 v[24:27], v[188:191], v[152:155], v[24:27]
	v_mfma_f32_16x16x32_bf16 v[20:23], v[144:147], v[160:163], v[20:23]
	v_mfma_f32_16x16x32_bf16 v[16:19], v[188:191], v[160:163], v[16:19]
	v_mfma_f32_16x16x32_bf16 v[12:15], v[144:147], v[168:171], v[12:15]
	v_mfma_f32_16x16x32_bf16 v[8:11], v[188:191], v[168:171], v[8:11]
	v_mfma_f32_16x16x32_bf16 v[4:7], v[144:147], v[176:179], v[4:7]
	v_mfma_f32_16x16x32_bf16 v[0:3], v[188:191], v[176:179], v[0:3]
	v_mfma_f32_16x16x32_bf16 v[28:31], v[184:187], v[156:159], v[28:31]
	v_mfma_f32_16x16x32_bf16 v[24:27], v[194:197], v[156:159], v[24:27]
	v_mfma_f32_16x16x32_bf16 v[20:23], v[184:187], v[164:167], v[20:23]
	v_mfma_f32_16x16x32_bf16 v[16:19], v[194:197], v[164:167], v[16:19]
	v_mfma_f32_16x16x32_bf16 v[12:15], v[184:187], v[172:175], v[12:15]
	v_mfma_f32_16x16x32_bf16 v[8:11], v[194:197], v[172:175], v[8:11]
	v_mfma_f32_16x16x32_bf16 v[4:7], v[184:187], v[180:183], v[4:7]
	v_mfma_f32_16x16x32_bf16 v[0:3], v[194:197], v[180:183], v[0:3]
	s_setprio 0
	s_barrier
	ds_read_b128 v[140:143], v138 offset:32768
	ds_read_b128 v[152:155], v138 offset:33792
	ds_read_b128 v[156:159], v138 offset:34816
	ds_read_b128 v[160:163], v138 offset:35840
	ds_read_b128 v[164:167], v137 offset:32768
	ds_read_b128 v[168:171], v137 offset:33792
	ds_read_b128 v[172:175], v137 offset:34816
	ds_read_b128 v[176:179], v137 offset:35840
	ds_read_b128 v[180:183], v137 offset:36864
	ds_read_b128 v[184:187], v137 offset:37888
	ds_read_b128 v[188:191], v137 offset:38912
	ds_read_b128 v[194:197], v137 offset:39936
	s_waitcnt vmcnt(2)
	s_barrier
; #define WAIT_V(n) asm volatile("s_waitcnt vmcnt(" #n ")" ::: "memory")
; #define WAIT_L(n) asm volatile("s_waitcnt lgkmcnt(" #n ")" ::: "memory")
; #define BAR __builtin_amdgcn_s_barrier()
; #define LDA(dst, b, h) _Pragma("unroll") for (int m = 0; m < 4; ++m) _Pragma("unroll") for (int k = 0; k < 2; ++k) \
;     dst[m][k] = *reinterpret_cast<const bf16x8*>((char*)shm + abase + (((b) * 2 + (h)) * 16384 + (m * 2 + k) * 1024))
; #define LDB(dst, b, h) _Pragma("unroll") for (int n = 0; n < 2; ++n) _Pragma("unroll") for (int k = 0; k < 2; ++k) \
;     dst[n][k] = *reinterpret_cast<const bf16x8*>((char*)shm + bbase + (((b) * 2 + (h)) * 16384 + (n * 2 + k) * 1024))
; template <bool SWAP>
; __device__ __forceinline__ void gemm_main(const u16* __restrict__ A, const u16* __restrict__ Bt, int brow, int bcol,
;                                           u16* shm, f32x4 (&acc)[2][2][4][2]) {
;     ...
;   { LDB(B0, 1, 0); LDA(At, 1, 0); WAIT_V(2); BAR; WAIT_L(0); MMA(0, 0, At, B0); BAR;
;     LDB(B1, 1, 1); WAIT_V(0); BAR; WAIT_L(0); MMA(0, 1, At, B1); BAR;
;     LDA(At, 1, 1); BAR; WAIT_L(0); MMA(1, 0, At, B0); MMA(1, 1, At, B1); BAR; }
;   if (wr == 0) BAR;
	s_waitcnt lgkmcnt(0)
	s_setprio 1
	s_waitcnt lgkmcnt(0)
	v_mfma_f32_16x16x32_bf16 v[124:127], v[140:143], v[164:167], v[124:127]
	v_mfma_f32_16x16x32_bf16 v[120:123], v[156:159], v[164:167], v[120:123]
	v_mfma_f32_16x16x32_bf16 v[116:119], v[140:143], v[172:175], v[116:119]
	v_mfma_f32_16x16x32_bf16 v[112:115], v[156:159], v[172:175], v[112:115]
	v_mfma_f32_16x16x32_bf16 v[108:111], v[140:143], v[180:183], v[108:111]
	v_mfma_f32_16x16x32_bf16 v[104:107], v[156:159], v[180:183], v[104:107]
	v_mfma_f32_16x16x32_bf16 v[100:103], v[140:143], v[188:191], v[100:103]
	v_mfma_f32_16x16x32_bf16 v[96:99], v[156:159], v[188:191], v[96:99]
	v_mfma_f32_16x16x32_bf16 v[148:151], v[152:155], v[168:171], v[124:127]
	v_mfma_f32_16x16x32_bf16 v[144:147], v[160:163], v[168:171], v[120:123]
	v_mfma_f32_16x16x32_bf16 v[132:135], v[152:155], v[176:179], v[116:119]
	v_mfma_f32_16x16x32_bf16 v[128:131], v[160:163], v[176:179], v[112:115]
	v_mfma_f32_16x16x32_bf16 v[116:119], v[152:155], v[184:187], v[108:111]
	v_mfma_f32_16x16x32_bf16 v[112:115], v[160:163], v[184:187], v[104:107]
	v_mfma_f32_16x16x32_bf16 v[100:103], v[152:155], v[194:197], v[100:103]
	v_mfma_f32_16x16x32_bf16 v[96:99], v[160:163], v[194:197], v[96:99]
	s_setprio 0
	s_barrier
	ds_read_b128 v[104:107], v138 offset:49152
	ds_read_b128 v[108:111], v138 offset:50176
	ds_read_b128 v[120:123], v138 offset:51200
	ds_read_b128 v[124:127], v138 offset:52224
	s_waitcnt vmcnt(0)
	s_barrier
	s_waitcnt lgkmcnt(0)
	s_setprio 1
	s_waitcnt lgkmcnt(0)
	v_mfma_f32_16x16x32_bf16 v[92:95], v[104:107], v[164:167], v[92:95]
	v_mfma_f32_16x16x32_bf16 v[88:91], v[120:123], v[164:167], v[88:91]
	v_mfma_f32_16x16x32_bf16 v[84:87], v[104:107], v[172:175], v[84:87]
	v_mfma_f32_16x16x32_bf16 v[80:83], v[120:123], v[172:175], v[80:83]
	v_mfma_f32_16x16x32_bf16 v[76:79], v[104:107], v[180:183], v[76:79]
	v_mfma_f32_16x16x32_bf16 v[72:75], v[120:123], v[180:183], v[72:75]
	v_mfma_f32_16x16x32_bf16 v[68:71], v[104:107], v[188:191], v[68:71]
	v_mfma_f32_16x16x32_bf16 v[64:67], v[120:123], v[188:191], v[64:67]
	v_mfma_f32_16x16x32_bf16 v[92:95], v[108:111], v[168:171], v[92:95]
	v_mfma_f32_16x16x32_bf16 v[88:91], v[124:127], v[168:171], v[88:91]
	v_mfma_f32_16x16x32_bf16 v[84:87], v[108:111], v[176:179], v[84:87]
	v_mfma_f32_16x16x32_bf16 v[80:83], v[124:127], v[176:179], v[80:83]
	v_mfma_f32_16x16x32_bf16 v[76:79], v[108:111], v[184:187], v[76:79]
	v_mfma_f32_16x16x32_bf16 v[72:75], v[124:127], v[184:187], v[72:75]
	v_mfma_f32_16x16x32_bf16 v[68:71], v[108:111], v[194:197], v[68:71]
	v_mfma_f32_16x16x32_bf16 v[64:67], v[124:127], v[194:197], v[64:67]
	s_setprio 0
	s_barrier
	ds_read_b128 v[164:167], v137 offset:49152
	ds_read_b128 v[168:171], v137 offset:50176
	ds_read_b128 v[172:175], v137 offset:51200
	ds_read_b128 v[176:179], v137 offset:52224
	ds_read_b128 v[180:183], v137 offset:53248
	ds_read_b128 v[184:187], v137 offset:54272
	ds_read_b128 v[188:191], v137 offset:55296
	ds_read_b128 v[194:197], v137 offset:56320
	s_barrier
	s_waitcnt lgkmcnt(0)
	s_setprio 1
	s_waitcnt lgkmcnt(0)
	v_mfma_f32_16x16x32_bf16 v[60:63], v[140:143], v[164:167], v[60:63]
	v_mfma_f32_16x16x32_bf16 v[56:59], v[156:159], v[164:167], v[56:59]
	v_mfma_f32_16x16x32_bf16 v[52:55], v[140:143], v[172:175], v[52:55]
	v_mfma_f32_16x16x32_bf16 v[48:51], v[156:159], v[172:175], v[48:51]
	v_mfma_f32_16x16x32_bf16 v[44:47], v[140:143], v[180:183], v[44:47]
	v_mfma_f32_16x16x32_bf16 v[40:43], v[156:159], v[180:183], v[40:43]
	v_mfma_f32_16x16x32_bf16 v[36:39], v[140:143], v[188:191], v[36:39]
	v_mfma_f32_16x16x32_bf16 v[32:35], v[156:159], v[188:191], v[32:35]
	v_mfma_f32_16x16x32_bf16 v[60:63], v[152:155], v[168:171], v[60:63]
	v_mfma_f32_16x16x32_bf16 v[56:59], v[160:163], v[168:171], v[56:59]
	v_mfma_f32_16x16x32_bf16 v[52:55], v[152:155], v[176:179], v[52:55]
	v_mfma_f32_16x16x32_bf16 v[48:51], v[160:163], v[176:179], v[48:51]
	v_mfma_f32_16x16x32_bf16 v[44:47], v[152:155], v[184:187], v[44:47]
	v_mfma_f32_16x16x32_bf16 v[40:43], v[160:163], v[184:187], v[40:43]
	v_mfma_f32_16x16x32_bf16 v[36:39], v[152:155], v[194:197], v[36:39]
	v_mfma_f32_16x16x32_bf16 v[32:35], v[160:163], v[194:197], v[32:35]
	s_setprio 0
	s_setprio 1
	v_mfma_f32_16x16x32_bf16 v[28:31], v[104:107], v[164:167], v[28:31]
	v_mfma_f32_16x16x32_bf16 v[24:27], v[120:123], v[164:167], v[24:27]
	v_mfma_f32_16x16x32_bf16 v[20:23], v[104:107], v[172:175], v[20:23]
	v_mfma_f32_16x16x32_bf16 v[16:19], v[120:123], v[172:175], v[16:19]
	v_mfma_f32_16x16x32_bf16 v[12:15], v[104:107], v[180:183], v[12:15]
	v_mfma_f32_16x16x32_bf16 v[8:11], v[120:123], v[180:183], v[8:11]
	v_mfma_f32_16x16x32_bf16 v[4:7], v[104:107], v[188:191], v[4:7]
	v_mfma_f32_16x16x32_bf16 v[0:3], v[120:123], v[188:191], v[0:3]
	v_mfma_f32_16x16x32_bf16 v[28:31], v[108:111], v[168:171], v[28:31]
	v_mfma_f32_16x16x32_bf16 v[24:27], v[124:127], v[168:171], v[24:27]
	v_mfma_f32_16x16x32_bf16 v[20:23], v[108:111], v[176:179], v[20:23]
	v_mfma_f32_16x16x32_bf16 v[16:19], v[124:127], v[176:179], v[16:19]
	v_mfma_f32_16x16x32_bf16 v[12:15], v[108:111], v[184:187], v[12:15]
	v_mfma_f32_16x16x32_bf16 v[8:11], v[124:127], v[184:187], v[8:11]
	v_mfma_f32_16x16x32_bf16 v[4:7], v[108:111], v[194:197], v[4:7]
	v_mfma_f32_16x16x32_bf16 v[0:3], v[124:127], v[194:197], v[0:3]
	s_setprio 0
	s_movk_i32 s3, 0x100
	v_cmp_gt_u32_e32 vcc, s3, v136
	s_barrier
	s_and_saveexec_b64 s[4:5], vcc
	s_cbranch_execz .LBB0_573
	s_barrier

; #define WAIT_V(n) asm volatile("s_waitcnt vmcnt(" #n ")" ::: "memory")
; #define WAIT_L(n) asm volatile("s_waitcnt lgkmcnt(" #n ")" ::: "memory")
; #define BAR __builtin_amdgcn_s_barrier()
; #define SCHED __builtin_amdgcn_sched_barrier(0)
; #define STAGE(P, BASE, br, kt) do { const char* _g = (const char*)((BASE) + (size_t)(br) * GK + (kt) * BK); \
;     __builtin_amdgcn_global_load_lds((const unsigned*)(_g + voff0), (unsigned*)((char*)(P) + tx * 16), 16, 0, 0); \
;     __builtin_amdgcn_global_load_lds((const unsigned*)(_g + voff1), (unsigned*)((char*)(P) + tx * 16 + 8192), 16, 0, 0); } while (0)
; #define LDA(dst, b, h) _Pragma("unroll") for (int m = 0; m < 4; ++m) _Pragma("unroll") for (int k = 0; k < 2; ++k) \
;     dst[m][k] = *reinterpret_cast<const bf16x8*>((char*)shm + abase + (((b) * 2 + (h)) * 16384 + (m * 2 + k) * 1024))
; #define LDB(dst, b, h) _Pragma("unroll") for (int n = 0; n < 2; ++n) _Pragma("unroll") for (int k = 0; k < 2; ++k) \
;     dst[n][k] = *reinterpret_cast<const bf16x8*>((char*)shm + bbase + (((b) * 2 + (h)) * 16384 + (n * 2 + k) * 1024))
; template <bool SWAP>
; __device__ __forceinline__ void gemm_main(const u16* __restrict__ A, const u16* __restrict__ Bt, int brow, int bcol,
;                                           u16* shm, f32x4 (&acc)[2][2][4][2]) {
;     ...
;   for (int t = 0; t < nt - 2; t += 2) {
;     LDB(B0, 0, 0); SCHED; LDA(At, 0, 0); STAGE(SA(1, 1), A, brow + HALF, t + 1);
;     WAIT_L(8); BAR; WAIT_L(0); MMA(0, 0, At, B0); BAR; SCHED;
;     LDB(B1, 0, 1); STAGE(SB(0, 0), Bt, bcol, t + 2);
;     BAR; WAIT_L(0); MMA(0, 1, At, B1); BAR;
;     LDA(At, 0, 1); STAGE(SA(0, 0), A, brow, t + 2);
;     BAR; WAIT_L(0); MMA(1, 0, At, B0); BAR; SCHED;
;     STAGE(SB(0, 1), Bt, bcol + HALF, t + 2);
;     WAIT_V(6); BAR; MMA(1, 1, At, B1); BAR;
.LBB0_576:
	ds_read_b128 v[168:171], v137 offset:1024
	ds_read_b128 v[176:179], v137 offset:3072
	ds_read_b128 v[184:187], v137 offset:5120
	ds_read_b128 v[194:197], v137 offset:7168
	v_add_u32_e32 v192, 0, v140
	v_add_u32_e32 v146, 0xc000, v192
	v_add_u32_e32 v147, 0xe000, v192
	s_add_u32 m0, s3, 0xc000
	v_lshl_add_u64 v[232:233], s[4:5], 0, v[134:135]
	s_add_u32 vcc_lo, s4, s10
	s_addc_u32 vcc_hi, s5, s11
	global_load_lds_dwordx4 v132, vcc
	s_add_u32 m0, s3, 0xe000
	s_nop 0
	global_load_lds_dwordx4 v134, vcc
	s_waitcnt lgkmcnt(8)
	s_waitcnt vmcnt(8)
	s_setprio 1
	s_barrier
	s_waitcnt lgkmcnt(0)
	v_mfma_f32_16x16x32_bf16 v[124:127], v[148:151], v[164:167], v[124:127]
	v_mfma_f32_16x16x32_bf16 v[120:123], v[156:159], v[164:167], v[120:123]
	v_mfma_f32_16x16x32_bf16 v[116:119], v[148:151], v[172:175], v[116:119]
	v_mfma_f32_16x16x32_bf16 v[112:115], v[156:159], v[172:175], v[112:115]
	v_mfma_f32_16x16x32_bf16 v[108:111], v[148:151], v[180:183], v[108:111]
	v_mfma_f32_16x16x32_bf16 v[104:107], v[156:159], v[180:183], v[104:107]
	v_mfma_f32_16x16x32_bf16 v[100:103], v[148:151], v[188:191], v[100:103]
	v_mfma_f32_16x16x32_bf16 v[96:99], v[156:159], v[188:191], v[96:99]
	v_mfma_f32_16x16x32_bf16 v[124:127], v[152:155], v[168:171], v[124:127]
	v_mfma_f32_16x16x32_bf16 v[120:123], v[160:163], v[168:171], v[120:123]
	v_mfma_f32_16x16x32_bf16 v[116:119], v[152:155], v[176:179], v[116:119]
	v_mfma_f32_16x16x32_bf16 v[112:115], v[160:163], v[176:179], v[112:115]
	v_mfma_f32_16x16x32_bf16 v[108:111], v[152:155], v[184:187], v[108:111]
	v_mfma_f32_16x16x32_bf16 v[104:107], v[160:163], v[184:187], v[104:107]
	v_mfma_f32_16x16x32_bf16 v[100:103], v[152:155], v[194:197], v[100:103]
	v_mfma_f32_16x16x32_bf16 v[96:99], v[160:163], v[194:197], v[96:99]
	s_barrier
	s_setprio 0
	ds_read_b128 v[198:201], v138 offset:16384
	ds_read_b128 v[202:205], v138 offset:17408
	ds_read_b128 v[206:209], v138 offset:18432
	ds_read_b128 v[226:229], v138 offset:19456
	v_lshl_add_u64 v[234:235], s[4:5], 0, v[128:129]
	s_add_u32 m0, s3, s28
	s_nop 0
	s_add_u32 vcc_lo, s4, s12
	s_addc_u32 vcc_hi, s5, s13
	global_load_lds_dwordx4 v128, vcc
	v_lshl_add_u64 v[236:237], s[4:5], 0, v[130:131]
	s_add_u32 m0, s3, s28
	s_add_u32 m0, m0, 0x2000
	s_nop 0
	global_load_lds_dwordx4 v130, vcc
	s_setprio 1
	s_barrier
	s_waitcnt lgkmcnt(0)
	v_mfma_f32_16x16x32_bf16 v[92:95], v[198:201], v[164:167], v[92:95]
	v_mfma_f32_16x16x32_bf16 v[88:91], v[206:209], v[164:167], v[88:91]
	v_mfma_f32_16x16x32_bf16 v[84:87], v[198:201], v[172:175], v[84:87]
	v_mfma_f32_16x16x32_bf16 v[80:83], v[206:209], v[172:175], v[80:83]
	v_mfma_f32_16x16x32_bf16 v[76:79], v[198:201], v[180:183], v[76:79]
	v_mfma_f32_16x16x32_bf16 v[72:75], v[206:209], v[180:183], v[72:75]
	v_mfma_f32_16x16x32_bf16 v[68:71], v[198:201], v[188:191], v[68:71]
	v_mfma_f32_16x16x32_bf16 v[64:67], v[206:209], v[188:191], v[64:67]
	v_mfma_f32_16x16x32_bf16 v[92:95], v[202:205], v[168:171], v[92:95]
	ds_read_b128 v[164:167], v137 offset:16384
	v_mfma_f32_16x16x32_bf16 v[88:91], v[226:229], v[168:171], v[88:91]
	v_mfma_f32_16x16x32_bf16 v[84:87], v[202:205], v[176:179], v[84:87]
	ds_read_b128 v[172:175], v137 offset:18432
	v_mfma_f32_16x16x32_bf16 v[80:83], v[226:229], v[176:179], v[80:83]
	v_mfma_f32_16x16x32_bf16 v[76:79], v[202:205], v[184:187], v[76:79]
	ds_read_b128 v[180:183], v137 offset:20480
	v_mfma_f32_16x16x32_bf16 v[72:75], v[226:229], v[184:187], v[72:75]
	v_mfma_f32_16x16x32_bf16 v[68:71], v[202:205], v[194:197], v[68:71]
	ds_read_b128 v[188:191], v137 offset:22528
	v_mfma_f32_16x16x32_bf16 v[64:67], v[226:229], v[194:197], v[64:67]
	s_barrier
	s_setprio 0
	ds_read_b128 v[168:171], v137 offset:17408
	ds_read_b128 v[176:179], v137 offset:19456
	ds_read_b128 v[184:187], v137 offset:21504
	ds_read_b128 v[194:197], v137 offset:23552
	s_add_u32 m0, s3, 0x0
	s_nop 0
	s_add_u32 vcc_lo, s4, s14
	s_addc_u32 vcc_hi, s5, s15
	global_load_lds_dwordx4 v132, vcc
	s_add_u32 m0, s3, 0x2000
	s_nop 0
	global_load_lds_dwordx4 v134, vcc
	s_waitcnt vmcnt(8)
	s_setprio 1
	s_barrier
	s_waitcnt lgkmcnt(0)
	v_mfma_f32_16x16x32_bf16 v[60:63], v[148:151], v[164:167], v[60:63]
	v_mfma_f32_16x16x32_bf16 v[56:59], v[156:159], v[164:167], v[56:59]
	v_mfma_f32_16x16x32_bf16 v[52:55], v[148:151], v[172:175], v[52:55]
	v_mfma_f32_16x16x32_bf16 v[48:51], v[156:159], v[172:175], v[48:51]
	v_mfma_f32_16x16x32_bf16 v[44:47], v[148:151], v[180:183], v[44:47]
	v_mfma_f32_16x16x32_bf16 v[40:43], v[156:159], v[180:183], v[40:43]
	v_mfma_f32_16x16x32_bf16 v[36:39], v[148:151], v[188:191], v[36:39]
	v_mfma_f32_16x16x32_bf16 v[32:35], v[156:159], v[188:191], v[32:35]
	v_mfma_f32_16x16x32_bf16 v[60:63], v[152:155], v[168:171], v[60:63]
	v_mfma_f32_16x16x32_bf16 v[56:59], v[160:163], v[168:171], v[56:59]
	v_mfma_f32_16x16x32_bf16 v[52:55], v[152:155], v[176:179], v[52:55]
	v_mfma_f32_16x16x32_bf16 v[48:51], v[160:163], v[176:179], v[48:51]
	v_mfma_f32_16x16x32_bf16 v[44:47], v[152:155], v[184:187], v[44:47]
	v_mfma_f32_16x16x32_bf16 v[40:43], v[160:163], v[184:187], v[40:43]
	v_mfma_f32_16x16x32_bf16 v[36:39], v[152:155], v[194:197], v[36:39]
	v_mfma_f32_16x16x32_bf16 v[32:35], v[160:163], v[194:197], v[32:35]
	s_barrier
	s_setprio 0
	ds_read_b128 v[148:151], v138 offset:32768
	ds_read_b128 v[152:155], v138 offset:33792
	ds_read_b128 v[156:159], v138 offset:34816
	ds_read_b128 v[160:163], v138 offset:35840
	s_add_u32 m0, s3, s29
	s_nop 0
	s_add_u32 vcc_lo, s4, s80
	s_addc_u32 vcc_hi, s5, s81
	global_load_lds_dwordx4 v128, vcc
	s_add_u32 m0, s3, s29
	s_add_u32 m0, m0, 0x2000
	s_nop 0
	global_load_lds_dwordx4 v130, vcc
	s_setprio 1
	s_barrier
; #define WAIT_V(n) asm volatile("s_waitcnt vmcnt(" #n ")" ::: "memory")
; #define WAIT_L(n) asm volatile("s_waitcnt lgkmcnt(" #n ")" ::: "memory")
; #define BAR __builtin_amdgcn_s_barrier()
; #define SCHED __builtin_amdgcn_sched_barrier(0)
; #define STAGE(P, BASE, br, kt) do { const char* _g = (const char*)((BASE) + (size_t)(br) * GK + (kt) * BK); \
;     __builtin_amdgcn_global_load_lds((const unsigned*)(_g + voff0), (unsigned*)((char*)(P) + tx * 16), 16, 0, 0); \
;     __builtin_amdgcn_global_load_lds((const unsigned*)(_g + voff1), (unsigned*)((char*)(P) + tx * 16 + 8192), 16, 0, 0); } while (0)
; #define LDA(dst, b, h) _Pragma("unroll") for (int m = 0; m < 4; ++m) _Pragma("unroll") for (int k = 0; k < 2; ++k) \
;     dst[m][k] = *reinterpret_cast<const bf16x8*>((char*)shm + abase + (((b) * 2 + (h)) * 16384 + (m * 2 + k) * 1024))
; #define LDB(dst, b, h) _Pragma("unroll") for (int n = 0; n < 2; ++n) _Pragma("unroll") for (int k = 0; k < 2; ++k) \
;     dst[n][k] = *reinterpret_cast<const bf16x8*>((char*)shm + bbase + (((b) * 2 + (h)) * 16384 + (n * 2 + k) * 1024))
; template <bool SWAP>
; __device__ __forceinline__ void gemm_main(const u16* __restrict__ A, const u16* __restrict__ Bt, int brow, int bcol,
;                                           u16* shm, f32x4 (&acc)[2][2][4][2]) {
;     ...
;     WAIT_V(6); BAR; MMA(1, 1, At, B1); BAR;
;     LDB(B0, 1, 0); SCHED; LDA(At, 1, 0); STAGE(SA(0, 1), A, brow + HALF, t + 2);
;     WAIT_L(8); BAR; WAIT_L(0); MMA(0, 0, At, B0); BAR; SCHED;
;     LDB(B1, 1, 1); STAGE(SB(1, 0), Bt, bcol, t + 3);
;     BAR; WAIT_L(0); MMA(0, 1, At, B1); BAR;
;     LDA(At, 1, 1); STAGE(SA(1, 0), A, brow, t + 3);
;     BAR; WAIT_L(0); MMA(1, 0, At, B0); BAR; SCHED;
	v_mfma_f32_16x16x32_bf16 v[28:31], v[198:201], v[164:167], v[28:31]
	v_mfma_f32_16x16x32_bf16 v[24:27], v[206:209], v[164:167], v[24:27]
	v_mfma_f32_16x16x32_bf16 v[20:23], v[198:201], v[172:175], v[20:23]
	v_mfma_f32_16x16x32_bf16 v[16:19], v[206:209], v[172:175], v[16:19]
	v_mfma_f32_16x16x32_bf16 v[12:15], v[198:201], v[180:183], v[12:15]
	v_mfma_f32_16x16x32_bf16 v[8:11], v[206:209], v[180:183], v[8:11]
	v_mfma_f32_16x16x32_bf16 v[4:7], v[198:201], v[188:191], v[4:7]
	v_mfma_f32_16x16x32_bf16 v[0:3], v[206:209], v[188:191], v[0:3]
	v_mfma_f32_16x16x32_bf16 v[28:31], v[202:205], v[168:171], v[28:31]
	ds_read_b128 v[164:167], v137 offset:32768
	v_mfma_f32_16x16x32_bf16 v[24:27], v[226:229], v[168:171], v[24:27]
	v_mfma_f32_16x16x32_bf16 v[20:23], v[202:205], v[176:179], v[20:23]
	ds_read_b128 v[172:175], v137 offset:34816
	v_mfma_f32_16x16x32_bf16 v[16:19], v[226:229], v[176:179], v[16:19]
	v_mfma_f32_16x16x32_bf16 v[12:15], v[202:205], v[184:187], v[12:15]
	ds_read_b128 v[180:183], v137 offset:36864
	v_mfma_f32_16x16x32_bf16 v[8:11], v[226:229], v[184:187], v[8:11]
	v_mfma_f32_16x16x32_bf16 v[4:7], v[202:205], v[194:197], v[4:7]
	ds_read_b128 v[188:191], v137 offset:38912
	v_mfma_f32_16x16x32_bf16 v[0:3], v[226:229], v[194:197], v[0:3]
	s_barrier
	s_setprio 0
	ds_read_b128 v[168:171], v137 offset:33792
	ds_read_b128 v[176:179], v137 offset:35840
	ds_read_b128 v[184:187], v137 offset:37888
	ds_read_b128 v[194:197], v137 offset:39936
	s_add_u32 m0, s3, 0x4000
	s_nop 0
	s_add_u32 vcc_lo, s4, s66
	s_addc_u32 vcc_hi, s5, s67
	global_load_lds_dwordx4 v132, vcc
	s_add_u32 m0, s3, 0x6000
	s_nop 0
	global_load_lds_dwordx4 v134, vcc
	s_waitcnt lgkmcnt(8)
	s_waitcnt vmcnt(8)
	s_setprio 1
	s_barrier
	s_waitcnt lgkmcnt(0)
	v_mfma_f32_16x16x32_bf16 v[124:127], v[148:151], v[164:167], v[124:127]
	v_mfma_f32_16x16x32_bf16 v[120:123], v[156:159], v[164:167], v[120:123]
	v_mfma_f32_16x16x32_bf16 v[116:119], v[148:151], v[172:175], v[116:119]
	v_mfma_f32_16x16x32_bf16 v[112:115], v[156:159], v[172:175], v[112:115]
	v_mfma_f32_16x16x32_bf16 v[108:111], v[148:151], v[180:183], v[108:111]
	v_mfma_f32_16x16x32_bf16 v[104:107], v[156:159], v[180:183], v[104:107]
	v_mfma_f32_16x16x32_bf16 v[100:103], v[148:151], v[188:191], v[100:103]
	v_mfma_f32_16x16x32_bf16 v[96:99], v[156:159], v[188:191], v[96:99]
	v_mfma_f32_16x16x32_bf16 v[124:127], v[152:155], v[168:171], v[124:127]
	v_mfma_f32_16x16x32_bf16 v[120:123], v[160:163], v[168:171], v[120:123]
	v_mfma_f32_16x16x32_bf16 v[116:119], v[152:155], v[176:179], v[116:119]
	v_mfma_f32_16x16x32_bf16 v[112:115], v[160:163], v[176:179], v[112:115]
	v_mfma_f32_16x16x32_bf16 v[108:111], v[152:155], v[184:187], v[108:111]
	v_mfma_f32_16x16x32_bf16 v[104:107], v[160:163], v[184:187], v[104:107]
	v_mfma_f32_16x16x32_bf16 v[100:103], v[152:155], v[194:197], v[100:103]
	v_mfma_f32_16x16x32_bf16 v[96:99], v[160:163], v[194:197], v[96:99]
	s_barrier
	s_setprio 0
	ds_read_b128 v[198:201], v138 offset:49152
	ds_read_b128 v[202:205], v138 offset:50176
	ds_read_b128 v[206:209], v138 offset:51200
	ds_read_b128 v[226:229], v138 offset:52224
	s_add_u32 m0, s3, s30
	s_nop 0
	s_add_u32 vcc_lo, s4, s86
	s_addc_u32 vcc_hi, s5, s87
	global_load_lds_dwordx4 v128, vcc
	v_lshl_add_u64 v[238:239], v[236:237], 0, s[86:87]
	s_add_u32 m0, s3, s30
	s_add_u32 m0, m0, 0x2000
	s_nop 0
	global_load_lds_dwordx4 v130, vcc
	s_setprio 1
	s_barrier
	s_waitcnt lgkmcnt(0)
	v_mfma_f32_16x16x32_bf16 v[92:95], v[198:201], v[164:167], v[92:95]
	v_mfma_f32_16x16x32_bf16 v[88:91], v[206:209], v[164:167], v[88:91]
	v_mfma_f32_16x16x32_bf16 v[84:87], v[198:201], v[172:175], v[84:87]
	v_mfma_f32_16x16x32_bf16 v[80:83], v[206:209], v[172:175], v[80:83]
	v_mfma_f32_16x16x32_bf16 v[76:79], v[198:201], v[180:183], v[76:79]
	v_mfma_f32_16x16x32_bf16 v[72:75], v[206:209], v[180:183], v[72:75]
	v_mfma_f32_16x16x32_bf16 v[68:71], v[198:201], v[188:191], v[68:71]
	v_mfma_f32_16x16x32_bf16 v[64:67], v[206:209], v[188:191], v[64:67]
	v_mfma_f32_16x16x32_bf16 v[92:95], v[202:205], v[168:171], v[92:95]
	ds_read_b128 v[164:167], v137 offset:49152
	v_mfma_f32_16x16x32_bf16 v[88:91], v[226:229], v[168:171], v[88:91]
	v_mfma_f32_16x16x32_bf16 v[84:87], v[202:205], v[176:179], v[84:87]
	ds_read_b128 v[172:175], v137 offset:51200
	v_mfma_f32_16x16x32_bf16 v[80:83], v[226:229], v[176:179], v[80:83]
	v_mfma_f32_16x16x32_bf16 v[76:79], v[202:205], v[184:187], v[76:79]
	ds_read_b128 v[180:183], v137 offset:53248
	v_mfma_f32_16x16x32_bf16 v[72:75], v[226:229], v[184:187], v[72:75]
	v_mfma_f32_16x16x32_bf16 v[68:71], v[202:205], v[194:197], v[68:71]
	ds_read_b128 v[188:191], v137 offset:55296
	v_mfma_f32_16x16x32_bf16 v[64:67], v[226:229], v[194:197], v[64:67]
	s_barrier
	s_setprio 0
	ds_read_b128 v[168:171], v137 offset:50176
	ds_read_b128 v[176:179], v137 offset:52224
	ds_read_b128 v[184:187], v137 offset:54272
	ds_read_b128 v[194:197], v137 offset:56320
	v_add_u32_e32 v225, 0x8000, v192
	s_add_u32 m0, s3, 0x8000
	s_nop 0
	s_add_u32 vcc_lo, s4, s26
	s_addc_u32 vcc_hi, s5, s27
	global_load_lds_dwordx4 v132, vcc
	v_lshl_add_u64 v[230:231], v[232:233], 0, s[26:27]
	s_add_u32 m0, s3, 0xa000
	s_nop 0
	global_load_lds_dwordx4 v134, vcc
	s_waitcnt vmcnt(8)
	s_setprio 1
	s_barrier
; #define WAIT_V(n) asm volatile("s_waitcnt vmcnt(" #n ")" ::: "memory")
; #define WAIT_L(n) asm volatile("s_waitcnt lgkmcnt(" #n ")" ::: "memory")
; #define BAR __builtin_amdgcn_s_barrier()
; #define SCHED __builtin_amdgcn_sched_barrier(0)
; #define STAGE(P, BASE, br, kt) do { const char* _g = (const char*)((BASE) + (size_t)(br) * GK + (kt) * BK); \
;     __builtin_amdgcn_global_load_lds((const unsigned*)(_g + voff0), (unsigned*)((char*)(P) + tx * 16), 16, 0, 0); \
;     __builtin_amdgcn_global_load_lds((const unsigned*)(_g + voff1), (unsigned*)((char*)(P) + tx * 16 + 8192), 16, 0, 0); } while (0)
; #define LDA(dst, b, h) _Pragma("unroll") for (int m = 0; m < 4; ++m) _Pragma("unroll") for (int k = 0; k < 2; ++k) \
;     dst[m][k] = *reinterpret_cast<const bf16x8*>((char*)shm + abase + (((b) * 2 + (h)) * 16384 + (m * 2 + k) * 1024))
; #define LDB(dst, b, h) _Pragma("unroll") for (int n = 0; n < 2; ++n) _Pragma("unroll") for (int k = 0; k < 2; ++k) \
;     dst[n][k] = *reinterpret_cast<const bf16x8*>((char*)shm + bbase + (((b) * 2 + (h)) * 16384 + (n * 2 + k) * 1024))
; template <bool SWAP>
; __device__ __forceinline__ void gemm_main(const u16* __restrict__ A, const u16* __restrict__ Bt, int brow, int bcol,
;                                           u16* shm, f32x4 (&acc)[2][2][4][2]) {
;     ...
;     BAR; WAIT_L(0); MMA(1, 0, At, B0); BAR; SCHED;
;     STAGE(SB(1, 1), Bt, bcol + HALF, t + 3);
;     WAIT_V(6); BAR; MMA(1, 1, At, B1); BAR;
;   }
;   { LDB(B0, 0, 0); LDA(At, 0, 0); STAGE(SA(1, 1), A, brow + HALF, nt - 1);
;     BAR; WAIT_L(0); MMA(0, 0, At, B0); BAR;
	s_waitcnt lgkmcnt(0)
	v_mfma_f32_16x16x32_bf16 v[60:63], v[148:151], v[164:167], v[60:63]
	v_mfma_f32_16x16x32_bf16 v[56:59], v[156:159], v[164:167], v[56:59]
	v_mfma_f32_16x16x32_bf16 v[52:55], v[148:151], v[172:175], v[52:55]
	v_mfma_f32_16x16x32_bf16 v[48:51], v[156:159], v[172:175], v[48:51]
	v_mfma_f32_16x16x32_bf16 v[44:47], v[148:151], v[180:183], v[44:47]
	v_mfma_f32_16x16x32_bf16 v[40:43], v[156:159], v[180:183], v[40:43]
	v_mfma_f32_16x16x32_bf16 v[36:39], v[148:151], v[188:191], v[36:39]
	v_mfma_f32_16x16x32_bf16 v[32:35], v[156:159], v[188:191], v[32:35]
	v_mfma_f32_16x16x32_bf16 v[60:63], v[152:155], v[168:171], v[60:63]
	v_mfma_f32_16x16x32_bf16 v[56:59], v[160:163], v[168:171], v[56:59]
	v_mfma_f32_16x16x32_bf16 v[52:55], v[152:155], v[176:179], v[52:55]
	v_mfma_f32_16x16x32_bf16 v[48:51], v[160:163], v[176:179], v[48:51]
	v_mfma_f32_16x16x32_bf16 v[44:47], v[152:155], v[184:187], v[44:47]
	v_mfma_f32_16x16x32_bf16 v[40:43], v[160:163], v[184:187], v[40:43]
	v_mfma_f32_16x16x32_bf16 v[36:39], v[152:155], v[194:197], v[36:39]
	v_mfma_f32_16x16x32_bf16 v[32:35], v[160:163], v[194:197], v[32:35]
	s_barrier
	s_setprio 0
	ds_read_b128 v[148:151], v138
	ds_read_b128 v[152:155], v138 offset:1024
	ds_read_b128 v[156:159], v138 offset:2048
	ds_read_b128 v[160:163], v138 offset:3072
	s_add_u32 m0, s3, s31
	s_nop 0
	s_add_u32 vcc_lo, s4, s56
	s_addc_u32 vcc_hi, s5, s57
	global_load_lds_dwordx4 v128, vcc
	v_lshl_add_u64 v[254:255], v[236:237], 0, s[56:57]
	s_add_u32 m0, s3, s31
	s_add_u32 m0, m0, 0x2000
	s_nop 0
	global_load_lds_dwordx4 v130, vcc
	s_setprio 1
	s_barrier
	v_mfma_f32_16x16x32_bf16 v[28:31], v[198:201], v[164:167], v[28:31]
	v_mfma_f32_16x16x32_bf16 v[24:27], v[206:209], v[164:167], v[24:27]
	v_mfma_f32_16x16x32_bf16 v[20:23], v[198:201], v[172:175], v[20:23]
	v_mfma_f32_16x16x32_bf16 v[16:19], v[206:209], v[172:175], v[16:19]
	v_mfma_f32_16x16x32_bf16 v[12:15], v[198:201], v[180:183], v[12:15]
	v_mfma_f32_16x16x32_bf16 v[8:11], v[206:209], v[180:183], v[8:11]
	v_mfma_f32_16x16x32_bf16 v[4:7], v[198:201], v[188:191], v[4:7]
	v_mfma_f32_16x16x32_bf16 v[0:3], v[206:209], v[188:191], v[0:3]
	v_mfma_f32_16x16x32_bf16 v[28:31], v[202:205], v[168:171], v[28:31]
	ds_read_b128 v[164:167], v137
	v_mfma_f32_16x16x32_bf16 v[24:27], v[226:229], v[168:171], v[24:27]
	v_mfma_f32_16x16x32_bf16 v[20:23], v[202:205], v[176:179], v[20:23]
	ds_read_b128 v[172:175], v137 offset:2048
	v_mfma_f32_16x16x32_bf16 v[16:19], v[226:229], v[176:179], v[16:19]
	v_mfma_f32_16x16x32_bf16 v[12:15], v[202:205], v[184:187], v[12:15]
	ds_read_b128 v[180:183], v137 offset:4096
	v_mfma_f32_16x16x32_bf16 v[8:11], v[226:229], v[184:187], v[8:11]
	v_mfma_f32_16x16x32_bf16 v[4:7], v[202:205], v[194:197], v[4:7]
	ds_read_b128 v[188:191], v137 offset:6144
	v_mfma_f32_16x16x32_bf16 v[0:3], v[226:229], v[194:197], v[0:3]
	s_add_i32 s2, s2, 2
	s_add_u32 s4, s4, 0x100
	s_addc_u32 s5, s5, 0
	s_cmp_lt_u32 s2, 28
	s_barrier
	s_setprio 0
	s_cbranch_scc1 .LBB0_576
	v_lshlrev_b32_e32 v128, 3, v139
	v_lshlrev_b32_e32 v129, 5, v139
	v_and_b32_e32 v128, 0xffff0, v128
	v_and_b32_e32 v129, 32, v129
	v_add_u32_e32 v129, v129, v142
	v_add_lshl_u32 v128, v141, v128, 12
	v_lshl_add_u32 v192, v129, 1, v128
	v_lshlrev_b32_e32 v128, 3, v143
	v_lshlrev_b32_e32 v129, 5, v143
	v_and_b32_e32 v128, 0xffff0, v128
	v_and_b32_e32 v129, 32, v129
	v_add_u32_e32 v129, v129, v145
	v_add_lshl_u32 v128, v144, v128, 12
	v_lshl_add_u32 v144, v129, 1, v128
	v_mov_b32_e32 v145, v193
	v_lshl_add_u64 v[184:185], s[0:1], 0, v[192:193]
	s_mov_b64 s[4:5], 0xf80
	v_readfirstlane_b32 s2, v146
	v_lshl_add_u64 v[184:185], v[184:185], 0, s[4:5]
	s_mov_b32 m0, s2
	v_lshl_add_u64 v[144:145], s[0:1], 0, v[144:145]
	v_readfirstlane_b32 s0, v147
	ds_read_b128 v[128:131], v138
	ds_read_b128 v[132:135], v138 offset:1024
	ds_read_b128 v[140:143], v138 offset:2048
	ds_read_b128 v[148:151], v138 offset:3072
	ds_read_b128 v[152:155], v137
	ds_read_b128 v[156:159], v137 offset:1024
	ds_read_b128 v[160:163], v137 offset:2048
	ds_read_b128 v[164:167], v137 offset:3072
	ds_read_b128 v[168:171], v137 offset:4096
	ds_read_b128 v[172:175], v137 offset:5120
	ds_read_b128 v[176:179], v137 offset:6144
	ds_read_b128 v[180:183], v137 offset:7168
	global_load_lds_dwordx4 v[184:185], off
	v_lshl_add_u64 v[144:145], v[144:145], 0, s[4:5]
	s_mov_b32 m0, s0
	s_nop 0
	global_load_lds_dwordx4 v[144:145], off
	s_waitcnt vmcnt(8)
	s_barrier
	s_waitcnt lgkmcnt(0)
	s_setprio 1
	s_waitcnt lgkmcnt(0)
	v_mfma_f32_16x16x32_bf16 v[124:127], v[128:131], v[152:155], v[124:127]
	v_mfma_f32_16x16x32_bf16 v[120:123], v[140:143], v[152:155], v[120:123]
	v_mfma_f32_16x16x32_bf16 v[116:119], v[128:131], v[160:163], v[116:119]
	v_mfma_f32_16x16x32_bf16 v[112:115], v[140:143], v[160:163], v[112:115]
	v_mfma_f32_16x16x32_bf16 v[108:111], v[128:131], v[168:171], v[108:111]
	v_mfma_f32_16x16x32_bf16 v[104:107], v[140:143], v[168:171], v[104:107]
	v_mfma_f32_16x16x32_bf16 v[100:103], v[128:131], v[176:179], v[100:103]
	v_mfma_f32_16x16x32_bf16 v[96:99], v[140:143], v[176:179], v[96:99]
	v_mfma_f32_16x16x32_bf16 v[124:127], v[132:135], v[156:159], v[124:127]
	v_mfma_f32_16x16x32_bf16 v[120:123], v[148:151], v[156:159], v[120:123]
	v_mfma_f32_16x16x32_bf16 v[116:119], v[132:135], v[164:167], v[116:119]
	v_mfma_f32_16x16x32_bf16 v[112:115], v[148:151], v[164:167], v[112:115]
	v_mfma_f32_16x16x32_bf16 v[108:111], v[132:135], v[172:175], v[108:111]
	v_mfma_f32_16x16x32_bf16 v[104:107], v[148:151], v[172:175], v[104:107]
	v_mfma_f32_16x16x32_bf16 v[100:103], v[132:135], v[180:183], v[100:103]
	v_mfma_f32_16x16x32_bf16 v[96:99], v[148:151], v[180:183], v[96:99]
	s_setprio 0
	s_barrier
; #define WAIT_V(n) asm volatile("s_waitcnt vmcnt(" #n ")" ::: "memory")
; #define WAIT_L(n) asm volatile("s_waitcnt lgkmcnt(" #n ")" ::: "memory")
; #define BAR __builtin_amdgcn_s_barrier()
; #define LDA(dst, b, h) _Pragma("unroll") for (int m = 0; m < 4; ++m) _Pragma("unroll") for (int k = 0; k < 2; ++k) \
;     dst[m][k] = *reinterpret_cast<const bf16x8*>((char*)shm + abase + (((b) * 2 + (h)) * 16384 + (m * 2 + k) * 1024))
; #define LDB(dst, b, h) _Pragma("unroll") for (int n = 0; n < 2; ++n) _Pragma("unroll") for (int k = 0; k < 2; ++k) \
;     dst[n][k] = *reinterpret_cast<const bf16x8*>((char*)shm + bbase + (((b) * 2 + (h)) * 16384 + (n * 2 + k) * 1024))
; template <bool SWAP>
; __device__ __forceinline__ void gemm_main(const u16* __restrict__ A, const u16* __restrict__ Bt, int brow, int bcol,
;                                           u16* shm, f32x4 (&acc)[2][2][4][2]) {
;     ...
;     BAR; WAIT_L(0); MMA(0, 0, At, B0); BAR;
;     LDB(B1, 0, 1); BAR; WAIT_L(0); MMA(0, 1, At, B1); BAR;
;     LDA(At, 0, 1); WAIT_V(4); BAR; WAIT_L(0); MMA(1, 0, At, B0); MMA(1, 1, At, B1); BAR; }
;   { LDB(B0, 1, 0); LDA(At, 1, 0); WAIT_V(2); BAR; WAIT_L(0); MMA(0, 0, At, B0); BAR;
	ds_read_b128 v[144:147], v138 offset:16384
	ds_read_b128 v[184:187], v138 offset:17408
	ds_read_b128 v[188:191], v138 offset:18432
	ds_read_b128 v[194:197], v138 offset:19456
	s_barrier
	s_waitcnt lgkmcnt(0)
	s_setprio 1
	s_waitcnt lgkmcnt(0)
	v_mfma_f32_16x16x32_bf16 v[92:95], v[144:147], v[152:155], v[92:95]
	v_mfma_f32_16x16x32_bf16 v[88:91], v[188:191], v[152:155], v[88:91]
	v_mfma_f32_16x16x32_bf16 v[84:87], v[144:147], v[160:163], v[84:87]
	v_mfma_f32_16x16x32_bf16 v[80:83], v[188:191], v[160:163], v[80:83]
	v_mfma_f32_16x16x32_bf16 v[76:79], v[144:147], v[168:171], v[76:79]
	v_mfma_f32_16x16x32_bf16 v[72:75], v[188:191], v[168:171], v[72:75]
	v_mfma_f32_16x16x32_bf16 v[68:71], v[144:147], v[176:179], v[68:71]
	v_mfma_f32_16x16x32_bf16 v[64:67], v[188:191], v[176:179], v[64:67]
	v_mfma_f32_16x16x32_bf16 v[92:95], v[184:187], v[156:159], v[92:95]
	v_mfma_f32_16x16x32_bf16 v[88:91], v[194:197], v[156:159], v[88:91]
	v_mfma_f32_16x16x32_bf16 v[84:87], v[184:187], v[164:167], v[84:87]
	v_mfma_f32_16x16x32_bf16 v[80:83], v[194:197], v[164:167], v[80:83]
	v_mfma_f32_16x16x32_bf16 v[76:79], v[184:187], v[172:175], v[76:79]
	v_mfma_f32_16x16x32_bf16 v[72:75], v[194:197], v[172:175], v[72:75]
	v_mfma_f32_16x16x32_bf16 v[68:71], v[184:187], v[180:183], v[68:71]
	v_mfma_f32_16x16x32_bf16 v[64:67], v[194:197], v[180:183], v[64:67]
	s_setprio 0
	s_barrier
	ds_read_b128 v[152:155], v137 offset:16384
	ds_read_b128 v[156:159], v137 offset:17408
	ds_read_b128 v[160:163], v137 offset:18432
	ds_read_b128 v[164:167], v137 offset:19456
	ds_read_b128 v[168:171], v137 offset:20480
	ds_read_b128 v[172:175], v137 offset:21504
	ds_read_b128 v[176:179], v137 offset:22528
	ds_read_b128 v[180:183], v137 offset:23552
	s_waitcnt vmcnt(4)
	s_barrier
	s_waitcnt lgkmcnt(0)
	s_setprio 1
	s_waitcnt lgkmcnt(0)
	v_mfma_f32_16x16x32_bf16 v[60:63], v[128:131], v[152:155], v[60:63]
	v_mfma_f32_16x16x32_bf16 v[56:59], v[140:143], v[152:155], v[56:59]
	v_mfma_f32_16x16x32_bf16 v[52:55], v[128:131], v[160:163], v[52:55]
	v_mfma_f32_16x16x32_bf16 v[48:51], v[140:143], v[160:163], v[48:51]
	v_mfma_f32_16x16x32_bf16 v[44:47], v[128:131], v[168:171], v[44:47]
	v_mfma_f32_16x16x32_bf16 v[40:43], v[140:143], v[168:171], v[40:43]
	v_mfma_f32_16x16x32_bf16 v[36:39], v[128:131], v[176:179], v[36:39]
	v_mfma_f32_16x16x32_bf16 v[32:35], v[140:143], v[176:179], v[32:35]
	v_mfma_f32_16x16x32_bf16 v[60:63], v[132:135], v[156:159], v[60:63]
	v_mfma_f32_16x16x32_bf16 v[56:59], v[148:151], v[156:159], v[56:59]
	v_mfma_f32_16x16x32_bf16 v[52:55], v[132:135], v[164:167], v[52:55]
	v_mfma_f32_16x16x32_bf16 v[48:51], v[148:151], v[164:167], v[48:51]
	v_mfma_f32_16x16x32_bf16 v[44:47], v[132:135], v[172:175], v[44:47]
	v_mfma_f32_16x16x32_bf16 v[40:43], v[148:151], v[172:175], v[40:43]
	v_mfma_f32_16x16x32_bf16 v[36:39], v[132:135], v[180:183], v[36:39]
	v_mfma_f32_16x16x32_bf16 v[32:35], v[148:151], v[180:183], v[32:35]
	s_setprio 0
	s_setprio 1
	v_mfma_f32_16x16x32_bf16 v[28:31], v[144:147], v[152:155], v[28:31]
	v_mfma_f32_16x16x32_bf16 v[24:27], v[188:191], v[152:155], v[24:27]
	v_mfma_f32_16x16x32_bf16 v[20:23], v[144:147], v[160:163], v[20:23]
	v_mfma_f32_16x16x32_bf16 v[16:19], v[188:191], v[160:163], v[16:19]
	v_mfma_f32_16x16x32_bf16 v[12:15], v[144:147], v[168:171], v[12:15]
	v_mfma_f32_16x16x32_bf16 v[8:11], v[188:191], v[168:171], v[8:11]
	v_mfma_f32_16x16x32_bf16 v[4:7], v[144:147], v[176:179], v[4:7]
	v_mfma_f32_16x16x32_bf16 v[0:3], v[188:191], v[176:179], v[0:3]
	v_mfma_f32_16x16x32_bf16 v[28:31], v[184:187], v[156:159], v[28:31]
	v_mfma_f32_16x16x32_bf16 v[24:27], v[194:197], v[156:159], v[24:27]
	v_mfma_f32_16x16x32_bf16 v[20:23], v[184:187], v[164:167], v[20:23]
	v_mfma_f32_16x16x32_bf16 v[16:19], v[194:197], v[164:167], v[16:19]
	v_mfma_f32_16x16x32_bf16 v[12:15], v[184:187], v[172:175], v[12:15]
	v_mfma_f32_16x16x32_bf16 v[8:11], v[194:197], v[172:175], v[8:11]
	v_mfma_f32_16x16x32_bf16 v[4:7], v[184:187], v[180:183], v[4:7]
	v_mfma_f32_16x16x32_bf16 v[0:3], v[194:197], v[180:183], v[0:3]
	s_setprio 0
	s_barrier
	ds_read_b128 v[128:131], v138 offset:32768
	ds_read_b128 v[132:135], v138 offset:33792
	ds_read_b128 v[140:143], v138 offset:34816
	ds_read_b128 v[144:147], v138 offset:35840
	ds_read_b128 v[148:151], v137 offset:32768
	ds_read_b128 v[152:155], v137 offset:33792
	ds_read_b128 v[156:159], v137 offset:34816
	ds_read_b128 v[160:163], v137 offset:35840
	ds_read_b128 v[164:167], v137 offset:36864
	ds_read_b128 v[168:171], v137 offset:37888
	ds_read_b128 v[172:175], v137 offset:38912
	ds_read_b128 v[176:179], v137 offset:39936
	s_waitcnt vmcnt(2)
	s_barrier
; #define WAIT_V(n) asm volatile("s_waitcnt vmcnt(" #n ")" ::: "memory")
; #define WAIT_L(n) asm volatile("s_waitcnt lgkmcnt(" #n ")" ::: "memory")
; #define BAR __builtin_amdgcn_s_barrier()
; #define LDA(dst, b, h) _Pragma("unroll") for (int m = 0; m < 4; ++m) _Pragma("unroll") for (int k = 0; k < 2; ++k) \
;     dst[m][k] = *reinterpret_cast<const bf16x8*>((char*)shm + abase + (((b) * 2 + (h)) * 16384 + (m * 2 + k) * 1024))
; #define LDB(dst, b, h) _Pragma("unroll") for (int n = 0; n < 2; ++n) _Pragma("unroll") for (int k = 0; k < 2; ++k) \
;     dst[n][k] = *reinterpret_cast<const bf16x8*>((char*)shm + bbase + (((b) * 2 + (h)) * 16384 + (n * 2 + k) * 1024))
; template <bool SWAP>
; __device__ __forceinline__ void gemm_main(const u16* __restrict__ A, const u16* __restrict__ Bt, int brow, int bcol,
;                                           u16* shm, f32x4 (&acc)[2][2][4][2]) {
;     ...
;   { LDB(B0, 1, 0); LDA(At, 1, 0); WAIT_V(2); BAR; WAIT_L(0); MMA(0, 0, At, B0); BAR;
;     LDB(B1, 1, 1); WAIT_V(0); BAR; WAIT_L(0); MMA(0, 1, At, B1); BAR;
;     LDA(At, 1, 1); BAR; WAIT_L(0); MMA(1, 0, At, B0); MMA(1, 1, At, B1); BAR; }
;   if (wr == 0) BAR;
	s_waitcnt lgkmcnt(0)
	s_setprio 1
	s_waitcnt lgkmcnt(0)
	v_mfma_f32_16x16x32_bf16 v[124:127], v[128:131], v[148:151], v[124:127]
	v_mfma_f32_16x16x32_bf16 v[120:123], v[140:143], v[148:151], v[120:123]
	v_mfma_f32_16x16x32_bf16 v[116:119], v[128:131], v[156:159], v[116:119]
	v_mfma_f32_16x16x32_bf16 v[112:115], v[140:143], v[156:159], v[112:115]
	v_mfma_f32_16x16x32_bf16 v[108:111], v[128:131], v[164:167], v[108:111]
	v_mfma_f32_16x16x32_bf16 v[104:107], v[140:143], v[164:167], v[104:107]
	v_mfma_f32_16x16x32_bf16 v[100:103], v[128:131], v[172:175], v[100:103]
	v_mfma_f32_16x16x32_bf16 v[96:99], v[140:143], v[172:175], v[96:99]
	v_mfma_f32_16x16x32_bf16 v[124:127], v[132:135], v[152:155], v[124:127]
	v_mfma_f32_16x16x32_bf16 v[120:123], v[144:147], v[152:155], v[120:123]
	v_mfma_f32_16x16x32_bf16 v[116:119], v[132:135], v[160:163], v[116:119]
	v_mfma_f32_16x16x32_bf16 v[112:115], v[144:147], v[160:163], v[112:115]
	v_mfma_f32_16x16x32_bf16 v[108:111], v[132:135], v[168:171], v[108:111]
	v_mfma_f32_16x16x32_bf16 v[104:107], v[144:147], v[168:171], v[104:107]
	v_mfma_f32_16x16x32_bf16 v[100:103], v[132:135], v[176:179], v[100:103]
	v_mfma_f32_16x16x32_bf16 v[96:99], v[144:147], v[176:179], v[96:99]
	s_setprio 0
	s_barrier
	ds_read_b128 v[180:183], v138 offset:49152
	ds_read_b128 v[184:187], v138 offset:50176
	ds_read_b128 v[188:191], v138 offset:51200
	ds_read_b128 v[194:197], v138 offset:52224
	s_waitcnt vmcnt(0)
	s_barrier
	s_waitcnt lgkmcnt(0)
	s_setprio 1
	s_waitcnt lgkmcnt(0)
	v_mfma_f32_16x16x32_bf16 v[92:95], v[180:183], v[148:151], v[92:95]
	v_mfma_f32_16x16x32_bf16 v[88:91], v[188:191], v[148:151], v[88:91]
	v_mfma_f32_16x16x32_bf16 v[84:87], v[180:183], v[156:159], v[84:87]
	v_mfma_f32_16x16x32_bf16 v[80:83], v[188:191], v[156:159], v[80:83]
	v_mfma_f32_16x16x32_bf16 v[76:79], v[180:183], v[164:167], v[76:79]
	v_mfma_f32_16x16x32_bf16 v[72:75], v[188:191], v[164:167], v[72:75]
	v_mfma_f32_16x16x32_bf16 v[68:71], v[180:183], v[172:175], v[68:71]
	v_mfma_f32_16x16x32_bf16 v[64:67], v[188:191], v[172:175], v[64:67]
	v_mfma_f32_16x16x32_bf16 v[92:95], v[184:187], v[152:155], v[92:95]
	v_mfma_f32_16x16x32_bf16 v[88:91], v[194:197], v[152:155], v[88:91]
	v_mfma_f32_16x16x32_bf16 v[84:87], v[184:187], v[160:163], v[84:87]
	v_mfma_f32_16x16x32_bf16 v[80:83], v[194:197], v[160:163], v[80:83]
	v_mfma_f32_16x16x32_bf16 v[76:79], v[184:187], v[168:171], v[76:79]
	v_mfma_f32_16x16x32_bf16 v[72:75], v[194:197], v[168:171], v[72:75]
	v_mfma_f32_16x16x32_bf16 v[68:71], v[184:187], v[176:179], v[68:71]
	v_mfma_f32_16x16x32_bf16 v[64:67], v[194:197], v[176:179], v[64:67]
	s_setprio 0
	s_barrier
	ds_read_b128 v[148:151], v137 offset:49152
	ds_read_b128 v[152:155], v137 offset:50176
	ds_read_b128 v[156:159], v137 offset:51200
	ds_read_b128 v[160:163], v137 offset:52224
	ds_read_b128 v[164:167], v137 offset:53248
	ds_read_b128 v[168:171], v137 offset:54272
	ds_read_b128 v[172:175], v137 offset:55296
	ds_read_b128 v[176:179], v137 offset:56320
	s_barrier
	s_waitcnt lgkmcnt(0)
	s_setprio 1
	s_waitcnt lgkmcnt(0)
	v_mfma_f32_16x16x32_bf16 v[60:63], v[128:131], v[148:151], v[60:63]
	v_mfma_f32_16x16x32_bf16 v[56:59], v[140:143], v[148:151], v[56:59]
	v_mfma_f32_16x16x32_bf16 v[52:55], v[128:131], v[156:159], v[52:55]
	v_mfma_f32_16x16x32_bf16 v[48:51], v[140:143], v[156:159], v[48:51]
	v_mfma_f32_16x16x32_bf16 v[44:47], v[128:131], v[164:167], v[44:47]
	v_mfma_f32_16x16x32_bf16 v[40:43], v[140:143], v[164:167], v[40:43]
	v_mfma_f32_16x16x32_bf16 v[36:39], v[128:131], v[172:175], v[36:39]
	v_mfma_f32_16x16x32_bf16 v[32:35], v[140:143], v[172:175], v[32:35]
	v_mfma_f32_16x16x32_bf16 v[60:63], v[132:135], v[152:155], v[60:63]
	v_mfma_f32_16x16x32_bf16 v[56:59], v[144:147], v[152:155], v[56:59]
	v_mfma_f32_16x16x32_bf16 v[52:55], v[132:135], v[160:163], v[52:55]
	v_mfma_f32_16x16x32_bf16 v[48:51], v[144:147], v[160:163], v[48:51]
	v_mfma_f32_16x16x32_bf16 v[44:47], v[132:135], v[168:171], v[44:47]
	v_mfma_f32_16x16x32_bf16 v[40:43], v[144:147], v[168:171], v[40:43]
	v_mfma_f32_16x16x32_bf16 v[36:39], v[132:135], v[176:179], v[36:39]
	v_mfma_f32_16x16x32_bf16 v[32:35], v[144:147], v[176:179], v[32:35]
	s_setprio 0
	s_setprio 1
	v_mfma_f32_16x16x32_bf16 v[28:31], v[180:183], v[148:151], v[28:31]
	v_mfma_f32_16x16x32_bf16 v[24:27], v[188:191], v[148:151], v[24:27]
	v_mfma_f32_16x16x32_bf16 v[20:23], v[180:183], v[156:159], v[20:23]
	v_mfma_f32_16x16x32_bf16 v[16:19], v[188:191], v[156:159], v[16:19]
	v_mfma_f32_16x16x32_bf16 v[12:15], v[180:183], v[164:167], v[12:15]
	v_mfma_f32_16x16x32_bf16 v[8:11], v[188:191], v[164:167], v[8:11]
	v_mfma_f32_16x16x32_bf16 v[4:7], v[180:183], v[172:175], v[4:7]
	v_mfma_f32_16x16x32_bf16 v[0:3], v[188:191], v[172:175], v[0:3]
	v_mfma_f32_16x16x32_bf16 v[28:31], v[184:187], v[152:155], v[28:31]
	v_mfma_f32_16x16x32_bf16 v[24:27], v[194:197], v[152:155], v[24:27]
	v_mfma_f32_16x16x32_bf16 v[20:23], v[184:187], v[160:163], v[20:23]
	v_mfma_f32_16x16x32_bf16 v[16:19], v[194:197], v[160:163], v[16:19]
	v_mfma_f32_16x16x32_bf16 v[12:15], v[184:187], v[168:171], v[12:15]
	v_mfma_f32_16x16x32_bf16 v[8:11], v[194:197], v[168:171], v[8:11]
	v_mfma_f32_16x16x32_bf16 v[4:7], v[184:187], v[176:179], v[4:7]
	v_mfma_f32_16x16x32_bf16 v[0:3], v[194:197], v[176:179], v[0:3]
	s_setprio 0
	s_movk_i32 s0, 0x100
	v_cmp_gt_u32_e32 vcc, s0, v136
	s_barrier
	s_and_saveexec_b64 s[0:1], vcc
	s_cbranch_execz .LBB0_579
	s_barrier

; #define WAIT_V(n) asm volatile("s_waitcnt vmcnt(" #n ")" ::: "memory")
; #define WAIT_L(n) asm volatile("s_waitcnt lgkmcnt(" #n ")" ::: "memory")
; #define BAR __builtin_amdgcn_s_barrier()
; #define SCHED __builtin_amdgcn_sched_barrier(0)
; #define STAGE(P, BASE, br, kt) do { const char* _g = (const char*)((BASE) + (size_t)(br) * GK + (kt) * BK); \
;     __builtin_amdgcn_global_load_lds((const unsigned*)(_g + voff0), (unsigned*)((char*)(P) + tx * 16), 16, 0, 0); \
;     __builtin_amdgcn_global_load_lds((const unsigned*)(_g + voff1), (unsigned*)((char*)(P) + tx * 16 + 8192), 16, 0, 0); } while (0)
; #define LDA(dst, b, h) _Pragma("unroll") for (int m = 0; m < 4; ++m) _Pragma("unroll") for (int k = 0; k < 2; ++k) \
;     dst[m][k] = *reinterpret_cast<const bf16x8*>((char*)shm + abase + (((b) * 2 + (h)) * 16384 + (m * 2 + k) * 1024))
; #define LDB(dst, b, h) _Pragma("unroll") for (int n = 0; n < 2; ++n) _Pragma("unroll") for (int k = 0; k < 2; ++k) \
;     dst[n][k] = *reinterpret_cast<const bf16x8*>((char*)shm + bbase + (((b) * 2 + (h)) * 16384 + (n * 2 + k) * 1024))
; template <bool SWAP>
; __device__ __forceinline__ void gemm_main(const u16* __restrict__ A, const u16* __restrict__ Bt, int brow, int bcol,
;                                           u16* shm, f32x4 (&acc)[2][2][4][2]) {
;     ...
;   for (int t = 0; t < nt - 2; t += 2) {
;     LDB(B0, 0, 0); SCHED; LDA(At, 0, 0); STAGE(SA(1, 1), A, brow + HALF, t + 1);
;     WAIT_L(8); BAR; WAIT_L(0); MMA(0, 0, At, B0); BAR; SCHED;
;     LDB(B1, 0, 1); STAGE(SB(0, 0), Bt, bcol, t + 2);
;     BAR; WAIT_L(0); MMA(0, 1, At, B1); BAR;
;     LDA(At, 0, 1); STAGE(SA(0, 0), A, brow, t + 2);
;     BAR; WAIT_L(0); MMA(1, 0, At, B0); BAR; SCHED;
;     STAGE(SB(0, 1), Bt, bcol + HALF, t + 2);
;     WAIT_V(6); BAR; MMA(1, 1, At, B1); BAR;
.LBB0_627:
	ds_read_b128 v[170:173], v139 offset:1024
	ds_read_b128 v[178:181], v139 offset:3072
	ds_read_b128 v[186:189], v139 offset:5120
	ds_read_b128 v[198:201], v139 offset:7168
	v_add_u32_e32 v192, 0, v142
	v_add_u32_e32 v148, 0xc000, v192
	v_add_u32_e32 v149, 0xe000, v192
	s_add_u32 m0, s9, 0xc000
	v_lshl_add_u64 v[232:233], s[4:5], 0, v[134:135]
	s_add_u32 vcc_lo, s4, s68
	s_addc_u32 vcc_hi, s5, s69
	global_load_lds_dwordx4 v132, vcc
	s_add_u32 m0, s9, 0xe000
	s_nop 0
	global_load_lds_dwordx4 v134, vcc
	s_waitcnt lgkmcnt(8)
	s_waitcnt vmcnt(8)
	s_setprio 1
	s_barrier
	s_waitcnt lgkmcnt(0)
	v_mfma_f32_16x16x32_bf16 v[124:127], v[150:153], v[166:169], v[124:127]
	v_mfma_f32_16x16x32_bf16 v[120:123], v[158:161], v[166:169], v[120:123]
	v_mfma_f32_16x16x32_bf16 v[116:119], v[150:153], v[174:177], v[116:119]
	v_mfma_f32_16x16x32_bf16 v[112:115], v[158:161], v[174:177], v[112:115]
	v_mfma_f32_16x16x32_bf16 v[108:111], v[150:153], v[182:185], v[108:111]
	v_mfma_f32_16x16x32_bf16 v[104:107], v[158:161], v[182:185], v[104:107]
	v_mfma_f32_16x16x32_bf16 v[100:103], v[150:153], v[194:197], v[100:103]
	v_mfma_f32_16x16x32_bf16 v[96:99], v[158:161], v[194:197], v[96:99]
	v_mfma_f32_16x16x32_bf16 v[124:127], v[154:157], v[170:173], v[124:127]
	v_mfma_f32_16x16x32_bf16 v[120:123], v[162:165], v[170:173], v[120:123]
	v_mfma_f32_16x16x32_bf16 v[116:119], v[154:157], v[178:181], v[116:119]
	v_mfma_f32_16x16x32_bf16 v[112:115], v[162:165], v[178:181], v[112:115]
	v_mfma_f32_16x16x32_bf16 v[108:111], v[154:157], v[186:189], v[108:111]
	v_mfma_f32_16x16x32_bf16 v[104:107], v[162:165], v[186:189], v[104:107]
	v_mfma_f32_16x16x32_bf16 v[100:103], v[154:157], v[198:201], v[100:103]
	v_mfma_f32_16x16x32_bf16 v[96:99], v[162:165], v[198:201], v[96:99]
	s_barrier
	s_setprio 0
	ds_read_b128 v[202:205], v140 offset:16384
	ds_read_b128 v[206:209], v140 offset:17408
	ds_read_b128 v[224:227], v140 offset:18432
	ds_read_b128 v[228:231], v140 offset:19456
	v_lshl_add_u64 v[234:235], s[4:5], 0, v[128:129]
	s_add_u32 m0, s9, s28
	s_nop 0
	s_add_u32 vcc_lo, s4, s94
	s_addc_u32 vcc_hi, s5, s95
	global_load_lds_dwordx4 v128, vcc
	v_lshl_add_u64 v[236:237], s[4:5], 0, v[130:131]
	s_add_u32 m0, s9, s28
	s_add_u32 m0, m0, 0x2000
	s_nop 0
	global_load_lds_dwordx4 v130, vcc
	s_setprio 1
	s_barrier
	s_waitcnt lgkmcnt(0)
	v_mfma_f32_16x16x32_bf16 v[92:95], v[202:205], v[166:169], v[92:95]
	v_mfma_f32_16x16x32_bf16 v[88:91], v[224:227], v[166:169], v[88:91]
	v_mfma_f32_16x16x32_bf16 v[84:87], v[202:205], v[174:177], v[84:87]
	v_mfma_f32_16x16x32_bf16 v[80:83], v[224:227], v[174:177], v[80:83]
	v_mfma_f32_16x16x32_bf16 v[76:79], v[202:205], v[182:185], v[76:79]
	v_mfma_f32_16x16x32_bf16 v[72:75], v[224:227], v[182:185], v[72:75]
	v_mfma_f32_16x16x32_bf16 v[68:71], v[202:205], v[194:197], v[68:71]
	v_mfma_f32_16x16x32_bf16 v[64:67], v[224:227], v[194:197], v[64:67]
	v_mfma_f32_16x16x32_bf16 v[92:95], v[206:209], v[170:173], v[92:95]
	ds_read_b128 v[166:169], v139 offset:16384
	v_mfma_f32_16x16x32_bf16 v[88:91], v[228:231], v[170:173], v[88:91]
	v_mfma_f32_16x16x32_bf16 v[84:87], v[206:209], v[178:181], v[84:87]
	ds_read_b128 v[174:177], v139 offset:18432
	v_mfma_f32_16x16x32_bf16 v[80:83], v[228:231], v[178:181], v[80:83]
	v_mfma_f32_16x16x32_bf16 v[76:79], v[206:209], v[186:189], v[76:79]
	ds_read_b128 v[182:185], v139 offset:20480
	v_mfma_f32_16x16x32_bf16 v[72:75], v[228:231], v[186:189], v[72:75]
	v_mfma_f32_16x16x32_bf16 v[68:71], v[206:209], v[198:201], v[68:71]
	ds_read_b128 v[194:197], v139 offset:22528
	v_mfma_f32_16x16x32_bf16 v[64:67], v[228:231], v[198:201], v[64:67]
	s_barrier
	s_setprio 0
	ds_read_b128 v[170:173], v139 offset:17408
	ds_read_b128 v[178:181], v139 offset:19456
	ds_read_b128 v[186:189], v139 offset:21504
	ds_read_b128 v[198:201], v139 offset:23552
	s_add_u32 m0, s9, 0x0
	s_nop 0
	s_add_u32 vcc_lo, s4, s62
	s_addc_u32 vcc_hi, s5, s63
	global_load_lds_dwordx4 v132, vcc
	s_add_u32 m0, s9, 0x2000
	s_nop 0
	global_load_lds_dwordx4 v134, vcc
	s_waitcnt vmcnt(8)
	s_setprio 1
	s_barrier
	s_waitcnt lgkmcnt(0)
	v_mfma_f32_16x16x32_bf16 v[60:63], v[150:153], v[166:169], v[60:63]
	v_mfma_f32_16x16x32_bf16 v[56:59], v[158:161], v[166:169], v[56:59]
	v_mfma_f32_16x16x32_bf16 v[52:55], v[150:153], v[174:177], v[52:55]
	v_mfma_f32_16x16x32_bf16 v[48:51], v[158:161], v[174:177], v[48:51]
	v_mfma_f32_16x16x32_bf16 v[44:47], v[150:153], v[182:185], v[44:47]
	v_mfma_f32_16x16x32_bf16 v[40:43], v[158:161], v[182:185], v[40:43]
	v_mfma_f32_16x16x32_bf16 v[36:39], v[150:153], v[194:197], v[36:39]
	v_mfma_f32_16x16x32_bf16 v[32:35], v[158:161], v[194:197], v[32:35]
	v_mfma_f32_16x16x32_bf16 v[60:63], v[154:157], v[170:173], v[60:63]
	v_mfma_f32_16x16x32_bf16 v[56:59], v[162:165], v[170:173], v[56:59]
	v_mfma_f32_16x16x32_bf16 v[52:55], v[154:157], v[178:181], v[52:55]
	v_mfma_f32_16x16x32_bf16 v[48:51], v[162:165], v[178:181], v[48:51]
	v_mfma_f32_16x16x32_bf16 v[44:47], v[154:157], v[186:189], v[44:47]
	v_mfma_f32_16x16x32_bf16 v[40:43], v[162:165], v[186:189], v[40:43]
	v_mfma_f32_16x16x32_bf16 v[36:39], v[154:157], v[198:201], v[36:39]
	v_mfma_f32_16x16x32_bf16 v[32:35], v[162:165], v[198:201], v[32:35]
	s_barrier
	s_setprio 0
	ds_read_b128 v[150:153], v140 offset:32768
	ds_read_b128 v[154:157], v140 offset:33792
	ds_read_b128 v[158:161], v140 offset:34816
	ds_read_b128 v[162:165], v140 offset:35840
	s_add_u32 m0, s9, s29
	s_nop 0
	s_add_u32 vcc_lo, s4, s78
	s_addc_u32 vcc_hi, s5, s79
	global_load_lds_dwordx4 v128, vcc
	s_add_u32 m0, s9, s29
	s_add_u32 m0, m0, 0x2000
	s_nop 0
	global_load_lds_dwordx4 v130, vcc
	s_setprio 1
	s_barrier
; #define WAIT_V(n) asm volatile("s_waitcnt vmcnt(" #n ")" ::: "memory")
; #define WAIT_L(n) asm volatile("s_waitcnt lgkmcnt(" #n ")" ::: "memory")
; #define BAR __builtin_amdgcn_s_barrier()
; #define SCHED __builtin_amdgcn_sched_barrier(0)
; #define STAGE(P, BASE, br, kt) do { const char* _g = (const char*)((BASE) + (size_t)(br) * GK + (kt) * BK); \
;     __builtin_amdgcn_global_load_lds((const unsigned*)(_g + voff0), (unsigned*)((char*)(P) + tx * 16), 16, 0, 0); \
;     __builtin_amdgcn_global_load_lds((const unsigned*)(_g + voff1), (unsigned*)((char*)(P) + tx * 16 + 8192), 16, 0, 0); } while (0)
; #define LDA(dst, b, h) _Pragma("unroll") for (int m = 0; m < 4; ++m) _Pragma("unroll") for (int k = 0; k < 2; ++k) \
;     dst[m][k] = *reinterpret_cast<const bf16x8*>((char*)shm + abase + (((b) * 2 + (h)) * 16384 + (m * 2 + k) * 1024))
; #define LDB(dst, b, h) _Pragma("unroll") for (int n = 0; n < 2; ++n) _Pragma("unroll") for (int k = 0; k < 2; ++k) \
;     dst[n][k] = *reinterpret_cast<const bf16x8*>((char*)shm + bbase + (((b) * 2 + (h)) * 16384 + (n * 2 + k) * 1024))
; template <bool SWAP>
; __device__ __forceinline__ void gemm_main(const u16* __restrict__ A, const u16* __restrict__ Bt, int brow, int bcol,
;                                           u16* shm, f32x4 (&acc)[2][2][4][2]) {
;     ...
;     WAIT_V(6); BAR; MMA(1, 1, At, B1); BAR;
;     LDB(B0, 1, 0); SCHED; LDA(At, 1, 0); STAGE(SA(0, 1), A, brow + HALF, t + 2);
;     WAIT_L(8); BAR; WAIT_L(0); MMA(0, 0, At, B0); BAR; SCHED;
;     LDB(B1, 1, 1); STAGE(SB(1, 0), Bt, bcol, t + 3);
;     BAR; WAIT_L(0); MMA(0, 1, At, B1); BAR;
;     LDA(At, 1, 1); STAGE(SA(1, 0), A, brow, t + 3);
;     BAR; WAIT_L(0); MMA(1, 0, At, B0); BAR; SCHED;
	v_mfma_f32_16x16x32_bf16 v[28:31], v[202:205], v[166:169], v[28:31]
	v_mfma_f32_16x16x32_bf16 v[24:27], v[224:227], v[166:169], v[24:27]
	v_mfma_f32_16x16x32_bf16 v[20:23], v[202:205], v[174:177], v[20:23]
	v_mfma_f32_16x16x32_bf16 v[16:19], v[224:227], v[174:177], v[16:19]
	v_mfma_f32_16x16x32_bf16 v[12:15], v[202:205], v[182:185], v[12:15]
	v_mfma_f32_16x16x32_bf16 v[8:11], v[224:227], v[182:185], v[8:11]
	v_mfma_f32_16x16x32_bf16 v[4:7], v[202:205], v[194:197], v[4:7]
	v_mfma_f32_16x16x32_bf16 v[0:3], v[224:227], v[194:197], v[0:3]
	v_mfma_f32_16x16x32_bf16 v[28:31], v[206:209], v[170:173], v[28:31]
	ds_read_b128 v[166:169], v139 offset:32768
	v_mfma_f32_16x16x32_bf16 v[24:27], v[228:231], v[170:173], v[24:27]
	v_mfma_f32_16x16x32_bf16 v[20:23], v[206:209], v[178:181], v[20:23]
	ds_read_b128 v[174:177], v139 offset:34816
	v_mfma_f32_16x16x32_bf16 v[16:19], v[228:231], v[178:181], v[16:19]
	v_mfma_f32_16x16x32_bf16 v[12:15], v[206:209], v[186:189], v[12:15]
	ds_read_b128 v[182:185], v139 offset:36864
	v_mfma_f32_16x16x32_bf16 v[8:11], v[228:231], v[186:189], v[8:11]
	v_mfma_f32_16x16x32_bf16 v[4:7], v[206:209], v[198:201], v[4:7]
	ds_read_b128 v[194:197], v139 offset:38912
	v_mfma_f32_16x16x32_bf16 v[0:3], v[228:231], v[198:201], v[0:3]
	s_barrier
	s_setprio 0
	ds_read_b128 v[170:173], v139 offset:33792
	ds_read_b128 v[178:181], v139 offset:35840
	ds_read_b128 v[186:189], v139 offset:37888
	ds_read_b128 v[198:201], v139 offset:39936
	s_add_u32 m0, s9, 0x4000
	s_nop 0
	s_add_u32 vcc_lo, s4, s88
	s_addc_u32 vcc_hi, s5, s89
	global_load_lds_dwordx4 v132, vcc
	s_add_u32 m0, s9, 0x6000
	s_nop 0
	global_load_lds_dwordx4 v134, vcc
	s_waitcnt lgkmcnt(8)
	s_waitcnt vmcnt(8)
	s_setprio 1
	s_barrier
	s_waitcnt lgkmcnt(0)
	v_mfma_f32_16x16x32_bf16 v[124:127], v[150:153], v[166:169], v[124:127]
	v_mfma_f32_16x16x32_bf16 v[120:123], v[158:161], v[166:169], v[120:123]
	v_mfma_f32_16x16x32_bf16 v[116:119], v[150:153], v[174:177], v[116:119]
	v_mfma_f32_16x16x32_bf16 v[112:115], v[158:161], v[174:177], v[112:115]
	v_mfma_f32_16x16x32_bf16 v[108:111], v[150:153], v[182:185], v[108:111]
	v_mfma_f32_16x16x32_bf16 v[104:107], v[158:161], v[182:185], v[104:107]
	v_mfma_f32_16x16x32_bf16 v[100:103], v[150:153], v[194:197], v[100:103]
	v_mfma_f32_16x16x32_bf16 v[96:99], v[158:161], v[194:197], v[96:99]
	v_mfma_f32_16x16x32_bf16 v[124:127], v[154:157], v[170:173], v[124:127]
	v_mfma_f32_16x16x32_bf16 v[120:123], v[162:165], v[170:173], v[120:123]
	v_mfma_f32_16x16x32_bf16 v[116:119], v[154:157], v[178:181], v[116:119]
	v_mfma_f32_16x16x32_bf16 v[112:115], v[162:165], v[178:181], v[112:115]
	v_mfma_f32_16x16x32_bf16 v[108:111], v[154:157], v[186:189], v[108:111]
	v_mfma_f32_16x16x32_bf16 v[104:107], v[162:165], v[186:189], v[104:107]
	v_mfma_f32_16x16x32_bf16 v[100:103], v[154:157], v[198:201], v[100:103]
	v_mfma_f32_16x16x32_bf16 v[96:99], v[162:165], v[198:201], v[96:99]
	s_barrier
	s_setprio 0
	ds_read_b128 v[202:205], v140 offset:49152
	ds_read_b128 v[206:209], v140 offset:50176
	ds_read_b128 v[224:227], v140 offset:51200
	ds_read_b128 v[228:231], v140 offset:52224
	s_add_u32 m0, s9, s30
	s_nop 0
	s_add_u32 vcc_lo, s4, s52
	s_addc_u32 vcc_hi, s5, s53
	global_load_lds_dwordx4 v128, vcc
	v_lshl_add_u64 v[238:239], v[236:237], 0, s[52:53]
	s_add_u32 m0, s9, s30
	s_add_u32 m0, m0, 0x2000
	s_nop 0
	global_load_lds_dwordx4 v130, vcc
	s_setprio 1
	s_barrier
	s_waitcnt lgkmcnt(0)
	v_mfma_f32_16x16x32_bf16 v[92:95], v[202:205], v[166:169], v[92:95]
	v_mfma_f32_16x16x32_bf16 v[88:91], v[224:227], v[166:169], v[88:91]
	v_mfma_f32_16x16x32_bf16 v[84:87], v[202:205], v[174:177], v[84:87]
	v_mfma_f32_16x16x32_bf16 v[80:83], v[224:227], v[174:177], v[80:83]
	v_mfma_f32_16x16x32_bf16 v[76:79], v[202:205], v[182:185], v[76:79]
	v_mfma_f32_16x16x32_bf16 v[72:75], v[224:227], v[182:185], v[72:75]
	v_mfma_f32_16x16x32_bf16 v[68:71], v[202:205], v[194:197], v[68:71]
	v_mfma_f32_16x16x32_bf16 v[64:67], v[224:227], v[194:197], v[64:67]
	v_mfma_f32_16x16x32_bf16 v[92:95], v[206:209], v[170:173], v[92:95]
	ds_read_b128 v[166:169], v139 offset:49152
	v_mfma_f32_16x16x32_bf16 v[88:91], v[228:231], v[170:173], v[88:91]
	v_mfma_f32_16x16x32_bf16 v[84:87], v[206:209], v[178:181], v[84:87]
	ds_read_b128 v[174:177], v139 offset:51200
	v_mfma_f32_16x16x32_bf16 v[80:83], v[228:231], v[178:181], v[80:83]
	v_mfma_f32_16x16x32_bf16 v[76:79], v[206:209], v[186:189], v[76:79]
	ds_read_b128 v[182:185], v139 offset:53248
	v_mfma_f32_16x16x32_bf16 v[72:75], v[228:231], v[186:189], v[72:75]
	v_mfma_f32_16x16x32_bf16 v[68:71], v[206:209], v[198:201], v[68:71]
	ds_read_b128 v[194:197], v139 offset:55296
	v_mfma_f32_16x16x32_bf16 v[64:67], v[228:231], v[198:201], v[64:67]
	s_barrier
	s_setprio 0
	ds_read_b128 v[170:173], v139 offset:50176
	ds_read_b128 v[178:181], v139 offset:52224
	ds_read_b128 v[186:189], v139 offset:54272
	ds_read_b128 v[198:201], v139 offset:56320
	v_add_u32_e32 v223, 0x8000, v192
	s_add_u32 m0, s9, 0x8000
	s_nop 0
	s_add_u32 vcc_lo, s4, s44
	s_addc_u32 vcc_hi, s5, s45
	global_load_lds_dwordx4 v132, vcc
	v_lshl_add_u64 v[190:191], v[232:233], 0, s[44:45]
	s_add_u32 m0, s9, 0xa000
	s_nop 0
	global_load_lds_dwordx4 v134, vcc
	s_waitcnt vmcnt(8)
	s_setprio 1
	s_barrier
; #define WAIT_V(n) asm volatile("s_waitcnt vmcnt(" #n ")" ::: "memory")
; #define WAIT_L(n) asm volatile("s_waitcnt lgkmcnt(" #n ")" ::: "memory")
; #define BAR __builtin_amdgcn_s_barrier()
; #define SCHED __builtin_amdgcn_sched_barrier(0)
; #define STAGE(P, BASE, br, kt) do { const char* _g = (const char*)((BASE) + (size_t)(br) * GK + (kt) * BK); \
;     __builtin_amdgcn_global_load_lds((const unsigned*)(_g + voff0), (unsigned*)((char*)(P) + tx * 16), 16, 0, 0); \
;     __builtin_amdgcn_global_load_lds((const unsigned*)(_g + voff1), (unsigned*)((char*)(P) + tx * 16 + 8192), 16, 0, 0); } while (0)
; #define LDA(dst, b, h) _Pragma("unroll") for (int m = 0; m < 4; ++m) _Pragma("unroll") for (int k = 0; k < 2; ++k) \
;     dst[m][k] = *reinterpret_cast<const bf16x8*>((char*)shm + abase + (((b) * 2 + (h)) * 16384 + (m * 2 + k) * 1024))
; #define LDB(dst, b, h) _Pragma("unroll") for (int n = 0; n < 2; ++n) _Pragma("unroll") for (int k = 0; k < 2; ++k) \
;     dst[n][k] = *reinterpret_cast<const bf16x8*>((char*)shm + bbase + (((b) * 2 + (h)) * 16384 + (n * 2 + k) * 1024))
; template <bool SWAP>
; __device__ __forceinline__ void gemm_main(const u16* __restrict__ A, const u16* __restrict__ Bt, int brow, int bcol,
;                                           u16* shm, f32x4 (&acc)[2][2][4][2]) {
;     ...
;     BAR; WAIT_L(0); MMA(1, 0, At, B0); BAR; SCHED;
;     STAGE(SB(1, 1), Bt, bcol + HALF, t + 3);
;     WAIT_V(6); BAR; MMA(1, 1, At, B1); BAR;
;   }
;   { LDB(B0, 0, 0); LDA(At, 0, 0); STAGE(SA(1, 1), A, brow + HALF, nt - 1);
;     BAR; WAIT_L(0); MMA(0, 0, At, B0); BAR;
	s_waitcnt lgkmcnt(0)
	v_mfma_f32_16x16x32_bf16 v[60:63], v[150:153], v[166:169], v[60:63]
	v_mfma_f32_16x16x32_bf16 v[56:59], v[158:161], v[166:169], v[56:59]
	v_mfma_f32_16x16x32_bf16 v[52:55], v[150:153], v[174:177], v[52:55]
	v_mfma_f32_16x16x32_bf16 v[48:51], v[158:161], v[174:177], v[48:51]
	v_mfma_f32_16x16x32_bf16 v[44:47], v[150:153], v[182:185], v[44:47]
	v_mfma_f32_16x16x32_bf16 v[40:43], v[158:161], v[182:185], v[40:43]
	v_mfma_f32_16x16x32_bf16 v[36:39], v[150:153], v[194:197], v[36:39]
	v_mfma_f32_16x16x32_bf16 v[32:35], v[158:161], v[194:197], v[32:35]
	v_mfma_f32_16x16x32_bf16 v[60:63], v[154:157], v[170:173], v[60:63]
	v_mfma_f32_16x16x32_bf16 v[56:59], v[162:165], v[170:173], v[56:59]
	v_mfma_f32_16x16x32_bf16 v[52:55], v[154:157], v[178:181], v[52:55]
	v_mfma_f32_16x16x32_bf16 v[48:51], v[162:165], v[178:181], v[48:51]
	v_mfma_f32_16x16x32_bf16 v[44:47], v[154:157], v[186:189], v[44:47]
	v_mfma_f32_16x16x32_bf16 v[40:43], v[162:165], v[186:189], v[40:43]
	v_mfma_f32_16x16x32_bf16 v[36:39], v[154:157], v[198:201], v[36:39]
	v_mfma_f32_16x16x32_bf16 v[32:35], v[162:165], v[198:201], v[32:35]
	s_barrier
	s_setprio 0
	ds_read_b128 v[150:153], v140
	ds_read_b128 v[154:157], v140 offset:1024
	ds_read_b128 v[158:161], v140 offset:2048
	ds_read_b128 v[162:165], v140 offset:3072
	s_add_u32 m0, s9, s31
	s_nop 0
	s_add_u32 vcc_lo, s4, s38
	s_addc_u32 vcc_hi, s5, s39
	global_load_lds_dwordx4 v128, vcc
	v_lshl_add_u64 v[254:255], v[236:237], 0, s[38:39]
	s_add_u32 m0, s9, s31
	s_add_u32 m0, m0, 0x2000
	s_nop 0
	global_load_lds_dwordx4 v130, vcc
	s_setprio 1
	s_barrier
	v_mfma_f32_16x16x32_bf16 v[28:31], v[202:205], v[166:169], v[28:31]
	v_mfma_f32_16x16x32_bf16 v[24:27], v[224:227], v[166:169], v[24:27]
	v_mfma_f32_16x16x32_bf16 v[20:23], v[202:205], v[174:177], v[20:23]
	v_mfma_f32_16x16x32_bf16 v[16:19], v[224:227], v[174:177], v[16:19]
	v_mfma_f32_16x16x32_bf16 v[12:15], v[202:205], v[182:185], v[12:15]
	v_mfma_f32_16x16x32_bf16 v[8:11], v[224:227], v[182:185], v[8:11]
	v_mfma_f32_16x16x32_bf16 v[4:7], v[202:205], v[194:197], v[4:7]
	v_mfma_f32_16x16x32_bf16 v[0:3], v[224:227], v[194:197], v[0:3]
	v_mfma_f32_16x16x32_bf16 v[28:31], v[206:209], v[170:173], v[28:31]
	ds_read_b128 v[166:169], v139
	v_mfma_f32_16x16x32_bf16 v[24:27], v[228:231], v[170:173], v[24:27]
	v_mfma_f32_16x16x32_bf16 v[20:23], v[206:209], v[178:181], v[20:23]
	ds_read_b128 v[174:177], v139 offset:2048
	v_mfma_f32_16x16x32_bf16 v[16:19], v[228:231], v[178:181], v[16:19]
	v_mfma_f32_16x16x32_bf16 v[12:15], v[206:209], v[186:189], v[12:15]
	ds_read_b128 v[182:185], v139 offset:4096
	v_mfma_f32_16x16x32_bf16 v[8:11], v[228:231], v[186:189], v[8:11]
	v_mfma_f32_16x16x32_bf16 v[4:7], v[206:209], v[198:201], v[4:7]
	ds_read_b128 v[194:197], v139 offset:6144
	v_mfma_f32_16x16x32_bf16 v[0:3], v[228:231], v[198:201], v[0:3]
	s_add_i32 s8, s8, 2
	s_add_u32 s4, s4, 0x100
	s_addc_u32 s5, s5, 0
	s_cmp_lt_u32 s8, 28
	s_barrier
	s_setprio 0
	s_cbranch_scc1 .LBB0_627
	s_and_b32 s4, s7, 0xffffe0
	s_and_b32 s5, s6, 31
	s_or_b32 s4, s4, s5
	s_lshl_b32 s10, s4, 8
	v_lshlrev_b32_e32 v128, 3, v141
	v_lshlrev_b32_e32 v129, 5, v141
	v_and_b32_e32 v128, 0xffff0, v128
	v_and_b32_e32 v129, 32, v129
	s_or_b32 s4, s10, 0x80
	v_add_u32_e32 v129, v129, v144
	v_add_lshl_u32 v128, v143, v128, 12
	s_ashr_i32 s5, s4, 31
	v_lshl_add_u32 v192, v129, 1, v128
	v_lshlrev_b32_e32 v128, 3, v145
	v_lshlrev_b32_e32 v129, 5, v145
	s_lshl_b64 s[4:5], s[4:5], 12
	v_and_b32_e32 v128, 0xffff0, v128
	v_and_b32_e32 v129, 32, v129
	s_add_u32 s4, s84, s4
	v_add_u32_e32 v129, v129, v147
	v_add_lshl_u32 v128, v146, v128, 12
	s_addc_u32 s5, s85, s5
	v_lshl_add_u32 v146, v129, 1, v128
	v_mov_b32_e32 v147, v193
	v_lshl_add_u64 v[186:187], s[4:5], 0, v[192:193]
	s_mov_b64 s[8:9], 0xf80
	v_readfirstlane_b32 s7, v148
	v_lshl_add_u64 v[186:187], v[186:187], 0, s[8:9]
	s_mov_b32 m0, s7
	v_lshl_add_u64 v[146:147], s[4:5], 0, v[146:147]
	v_readfirstlane_b32 s4, v149
	ds_read_b128 v[128:131], v140
	ds_read_b128 v[132:135], v140 offset:1024
	ds_read_b128 v[142:145], v140 offset:2048
	ds_read_b128 v[150:153], v140 offset:3072
	ds_read_b128 v[154:157], v139
	ds_read_b128 v[158:161], v139 offset:1024
	ds_read_b128 v[162:165], v139 offset:2048
	ds_read_b128 v[166:169], v139 offset:3072
	ds_read_b128 v[170:173], v139 offset:4096
	ds_read_b128 v[174:177], v139 offset:5120
	ds_read_b128 v[178:181], v139 offset:6144
	ds_read_b128 v[182:185], v139 offset:7168
	global_load_lds_dwordx4 v[186:187], off
	v_lshl_add_u64 v[146:147], v[146:147], 0, s[8:9]
	s_mov_b32 m0, s4
	s_nop 0
	global_load_lds_dwordx4 v[146:147], off
	s_waitcnt vmcnt(8)
	s_barrier
	s_waitcnt lgkmcnt(0)
	s_setprio 1
	s_waitcnt lgkmcnt(0)
	v_mfma_f32_16x16x32_bf16 v[124:127], v[128:131], v[154:157], v[124:127]
	v_mfma_f32_16x16x32_bf16 v[116:119], v[128:131], v[162:165], v[116:119]
	v_mfma_f32_16x16x32_bf16 v[108:111], v[128:131], v[170:173], v[108:111]
	v_mfma_f32_16x16x32_bf16 v[100:103], v[128:131], v[178:181], v[100:103]
	v_mfma_f32_16x16x32_bf16 v[124:127], v[132:135], v[158:161], v[124:127]
	v_mfma_f32_16x16x32_bf16 v[120:123], v[142:145], v[154:157], v[120:123]
	v_mfma_f32_16x16x32_bf16 v[116:119], v[132:135], v[166:169], v[116:119]
	v_mfma_f32_16x16x32_bf16 v[112:115], v[142:145], v[162:165], v[112:115]
	v_mfma_f32_16x16x32_bf16 v[108:111], v[132:135], v[174:177], v[108:111]
	v_mfma_f32_16x16x32_bf16 v[104:107], v[142:145], v[170:173], v[104:107]
	v_mfma_f32_16x16x32_bf16 v[100:103], v[132:135], v[182:185], v[100:103]
	v_mfma_f32_16x16x32_bf16 v[96:99], v[142:145], v[178:181], v[96:99]
	v_mfma_f32_16x16x32_bf16 v[146:149], v[150:153], v[158:161], v[120:123]
	v_mfma_f32_16x16x32_bf16 v[186:189], v[150:153], v[166:169], v[112:115]
	v_mfma_f32_16x16x32_bf16 v[194:197], v[150:153], v[174:177], v[104:107]
	v_mfma_f32_16x16x32_bf16 v[198:201], v[150:153], v[182:185], v[96:99]
	s_setprio 0
	s_barrier
; #define WAIT_V(n) asm volatile("s_waitcnt vmcnt(" #n ")" ::: "memory")
; #define WAIT_L(n) asm volatile("s_waitcnt lgkmcnt(" #n ")" ::: "memory")
; #define BAR __builtin_amdgcn_s_barrier()
; #define LDA(dst, b, h) _Pragma("unroll") for (int m = 0; m < 4; ++m) _Pragma("unroll") for (int k = 0; k < 2; ++k) \
;     dst[m][k] = *reinterpret_cast<const bf16x8*>((char*)shm + abase + (((b) * 2 + (h)) * 16384 + (m * 2 + k) * 1024))
; #define LDB(dst, b, h) _Pragma("unroll") for (int n = 0; n < 2; ++n) _Pragma("unroll") for (int k = 0; k < 2; ++k) \
;     dst[n][k] = *reinterpret_cast<const bf16x8*>((char*)shm + bbase + (((b) * 2 + (h)) * 16384 + (n * 2 + k) * 1024))
; template <bool SWAP>
; __device__ __forceinline__ void gemm_main(const u16* __restrict__ A, const u16* __restrict__ Bt, int brow, int bcol,
;                                           u16* shm, f32x4 (&acc)[2][2][4][2]) {
;     ...
;     BAR; WAIT_L(0); MMA(0, 0, At, B0); BAR;
;     LDB(B1, 0, 1); BAR; WAIT_L(0); MMA(0, 1, At, B1); BAR;
;     LDA(At, 0, 1); WAIT_V(4); BAR; WAIT_L(0); MMA(1, 0, At, B0); MMA(1, 1, At, B1); BAR; }
;   { LDB(B0, 1, 0); LDA(At, 1, 0); WAIT_V(2); BAR; WAIT_L(0); MMA(0, 0, At, B0); BAR;
	s_nop 1
	ds_read_b128 v[96:99], v140 offset:16384
	ds_read_b128 v[104:107], v140 offset:17408
	ds_read_b128 v[112:115], v140 offset:18432
	ds_read_b128 v[120:123], v140 offset:19456
	s_barrier
	s_waitcnt lgkmcnt(0)
	s_setprio 1
	s_waitcnt lgkmcnt(0)
	v_mfma_f32_16x16x32_bf16 v[92:95], v[96:99], v[154:157], v[92:95]
	v_mfma_f32_16x16x32_bf16 v[84:87], v[96:99], v[162:165], v[84:87]
	v_mfma_f32_16x16x32_bf16 v[76:79], v[96:99], v[170:173], v[76:79]
	v_mfma_f32_16x16x32_bf16 v[68:71], v[96:99], v[178:181], v[68:71]
	v_mfma_f32_16x16x32_bf16 v[92:95], v[104:107], v[158:161], v[92:95]
	v_mfma_f32_16x16x32_bf16 v[88:91], v[112:115], v[154:157], v[88:91]
	v_mfma_f32_16x16x32_bf16 v[84:87], v[104:107], v[166:169], v[84:87]
	v_mfma_f32_16x16x32_bf16 v[80:83], v[112:115], v[162:165], v[80:83]
	v_mfma_f32_16x16x32_bf16 v[76:79], v[104:107], v[174:177], v[76:79]
	v_mfma_f32_16x16x32_bf16 v[72:75], v[112:115], v[170:173], v[72:75]
	v_mfma_f32_16x16x32_bf16 v[68:71], v[104:107], v[182:185], v[68:71]
	v_mfma_f32_16x16x32_bf16 v[64:67], v[112:115], v[178:181], v[64:67]
	v_mfma_f32_16x16x32_bf16 v[154:157], v[120:123], v[158:161], v[88:91]
	v_mfma_f32_16x16x32_bf16 v[158:161], v[120:123], v[166:169], v[80:83]
	v_mfma_f32_16x16x32_bf16 v[162:165], v[120:123], v[174:177], v[72:75]
	v_mfma_f32_16x16x32_bf16 v[166:169], v[120:123], v[182:185], v[64:67]
	s_setprio 0
	s_barrier
	s_nop 1
	ds_read_b128 v[64:67], v139 offset:16384
	ds_read_b128 v[72:75], v139 offset:17408
	ds_read_b128 v[80:83], v139 offset:18432
	ds_read_b128 v[88:91], v139 offset:19456
	ds_read_b128 v[170:173], v139 offset:20480
	ds_read_b128 v[174:177], v139 offset:21504
	ds_read_b128 v[178:181], v139 offset:22528
	ds_read_b128 v[182:185], v139 offset:23552
	s_waitcnt vmcnt(4)
	s_barrier
	s_waitcnt lgkmcnt(0)
	s_setprio 1
	s_waitcnt lgkmcnt(0)
	v_mfma_f32_16x16x32_bf16 v[60:63], v[128:131], v[64:67], v[60:63]
	v_mfma_f32_16x16x32_bf16 v[52:55], v[128:131], v[80:83], v[52:55]
	v_mfma_f32_16x16x32_bf16 v[44:47], v[128:131], v[170:173], v[44:47]
	v_mfma_f32_16x16x32_bf16 v[36:39], v[128:131], v[178:181], v[36:39]
	v_mfma_f32_16x16x32_bf16 v[60:63], v[132:135], v[72:75], v[60:63]
	v_mfma_f32_16x16x32_bf16 v[56:59], v[142:145], v[64:67], v[56:59]
	v_mfma_f32_16x16x32_bf16 v[52:55], v[132:135], v[88:91], v[52:55]
	v_mfma_f32_16x16x32_bf16 v[48:51], v[142:145], v[80:83], v[48:51]
	v_mfma_f32_16x16x32_bf16 v[44:47], v[132:135], v[174:177], v[44:47]
	v_mfma_f32_16x16x32_bf16 v[40:43], v[142:145], v[170:173], v[40:43]
	v_mfma_f32_16x16x32_bf16 v[36:39], v[132:135], v[182:185], v[36:39]
	v_mfma_f32_16x16x32_bf16 v[32:35], v[142:145], v[178:181], v[32:35]
	v_mfma_f32_16x16x32_bf16 v[202:205], v[150:153], v[72:75], v[56:59]
	v_mfma_f32_16x16x32_bf16 v[206:209], v[150:153], v[88:91], v[48:51]
	v_mfma_f32_16x16x32_bf16 v[224:227], v[150:153], v[174:177], v[40:43]
	v_mfma_f32_16x16x32_bf16 v[128:131], v[150:153], v[182:185], v[32:35]
	s_setprio 0
	s_setprio 1
	v_mfma_f32_16x16x32_bf16 v[28:31], v[96:99], v[64:67], v[28:31]
	v_mfma_f32_16x16x32_bf16 v[20:23], v[96:99], v[80:83], v[20:23]
	v_mfma_f32_16x16x32_bf16 v[12:15], v[96:99], v[170:173], v[12:15]
	v_mfma_f32_16x16x32_bf16 v[4:7], v[96:99], v[178:181], v[4:7]
	v_mfma_f32_16x16x32_bf16 v[28:31], v[104:107], v[72:75], v[28:31]
	v_mfma_f32_16x16x32_bf16 v[24:27], v[112:115], v[64:67], v[24:27]
	v_mfma_f32_16x16x32_bf16 v[20:23], v[104:107], v[88:91], v[20:23]
	v_mfma_f32_16x16x32_bf16 v[16:19], v[112:115], v[80:83], v[16:19]
	v_mfma_f32_16x16x32_bf16 v[12:15], v[104:107], v[174:177], v[12:15]
	v_mfma_f32_16x16x32_bf16 v[8:11], v[112:115], v[170:173], v[8:11]
	v_mfma_f32_16x16x32_bf16 v[4:7], v[104:107], v[182:185], v[4:7]
	v_mfma_f32_16x16x32_bf16 v[0:3], v[112:115], v[178:181], v[0:3]
	v_mfma_f32_16x16x32_bf16 v[132:135], v[120:123], v[72:75], v[24:27]
	v_mfma_f32_16x16x32_bf16 v[142:145], v[120:123], v[88:91], v[16:19]
	v_mfma_f32_16x16x32_bf16 v[150:153], v[120:123], v[174:177], v[8:11]
	v_mfma_f32_16x16x32_bf16 v[170:173], v[120:123], v[182:185], v[0:3]
	s_setprio 0
	s_barrier
	s_nop 1
	ds_read_b128 v[0:3], v140 offset:32768
	ds_read_b128 v[8:11], v140 offset:33792
	ds_read_b128 v[16:19], v140 offset:34816
	ds_read_b128 v[24:27], v140 offset:35840
	ds_read_b128 v[32:35], v139 offset:32768
	ds_read_b128 v[40:43], v139 offset:33792
	ds_read_b128 v[48:51], v139 offset:34816
	ds_read_b128 v[56:59], v139 offset:35840
	ds_read_b128 v[64:67], v139 offset:36864
	ds_read_b128 v[174:177], v139 offset:37888
	ds_read_b128 v[178:181], v139 offset:38912
	ds_read_b128 v[182:185], v139 offset:39936
	s_waitcnt vmcnt(2)
	s_barrier
; #define WAIT_V(n) asm volatile("s_waitcnt vmcnt(" #n ")" ::: "memory")
; #define WAIT_L(n) asm volatile("s_waitcnt lgkmcnt(" #n ")" ::: "memory")
; #define BAR __builtin_amdgcn_s_barrier()
; #define LDA(dst, b, h) _Pragma("unroll") for (int m = 0; m < 4; ++m) _Pragma("unroll") for (int k = 0; k < 2; ++k) \
;     dst[m][k] = *reinterpret_cast<const bf16x8*>((char*)shm + abase + (((b) * 2 + (h)) * 16384 + (m * 2 + k) * 1024))
; #define LDB(dst, b, h) _Pragma("unroll") for (int n = 0; n < 2; ++n) _Pragma("unroll") for (int k = 0; k < 2; ++k) \
;     dst[n][k] = *reinterpret_cast<const bf16x8*>((char*)shm + bbase + (((b) * 2 + (h)) * 16384 + (n * 2 + k) * 1024))
; template <bool SWAP>
; __device__ __forceinline__ void gemm_main(const u16* __restrict__ A, const u16* __restrict__ Bt, int brow, int bcol,
;                                           u16* shm, f32x4 (&acc)[2][2][4][2]) {
;     ...
;   { LDB(B0, 1, 0); LDA(At, 1, 0); WAIT_V(2); BAR; WAIT_L(0); MMA(0, 0, At, B0); BAR;
;     LDB(B1, 1, 1); WAIT_V(0); BAR; WAIT_L(0); MMA(0, 1, At, B1); BAR;
;     LDA(At, 1, 1); BAR; WAIT_L(0); MMA(1, 0, At, B0); MMA(1, 1, At, B1); BAR; }
;   if (wr == 0) BAR;
	s_waitcnt lgkmcnt(0)
	s_setprio 1
	s_waitcnt lgkmcnt(0)
	v_mfma_f32_16x16x32_bf16 v[72:75], v[0:3], v[32:35], v[124:127]
	v_mfma_f32_16x16x32_bf16 v[120:123], v[8:11], v[40:43], v[72:75]
	v_mfma_f32_16x16x32_bf16 v[72:75], v[16:19], v[32:35], v[146:149]
	v_mfma_f32_16x16x32_bf16 v[124:127], v[24:27], v[40:43], v[72:75]
	v_mfma_f32_16x16x32_bf16 v[72:75], v[0:3], v[48:51], v[116:119]
	v_mfma_f32_16x16x32_bf16 v[112:115], v[8:11], v[56:59], v[72:75]
	v_mfma_f32_16x16x32_bf16 v[72:75], v[16:19], v[48:51], v[186:189]
	v_mfma_f32_16x16x32_bf16 v[116:119], v[24:27], v[56:59], v[72:75]
	v_mfma_f32_16x16x32_bf16 v[72:75], v[0:3], v[64:67], v[108:111]
	v_mfma_f32_16x16x32_bf16 v[104:107], v[8:11], v[174:177], v[72:75]
	v_mfma_f32_16x16x32_bf16 v[72:75], v[16:19], v[64:67], v[194:197]
	v_mfma_f32_16x16x32_bf16 v[108:111], v[24:27], v[174:177], v[72:75]
	v_mfma_f32_16x16x32_bf16 v[72:75], v[0:3], v[178:181], v[100:103]
	v_mfma_f32_16x16x32_bf16 v[96:99], v[8:11], v[182:185], v[72:75]
	v_mfma_f32_16x16x32_bf16 v[72:75], v[16:19], v[178:181], v[198:201]
	v_mfma_f32_16x16x32_bf16 v[100:103], v[24:27], v[182:185], v[72:75]
	s_setprio 0
	s_barrier
	ds_read_b128 v[146:149], v140 offset:49152
	ds_read_b128 v[186:189], v140 offset:50176
	ds_read_b128 v[194:197], v140 offset:51200
	ds_read_b128 v[198:201], v140 offset:52224
	s_waitcnt vmcnt(0)
	s_barrier
	s_waitcnt lgkmcnt(0)
	s_setprio 1
	s_waitcnt lgkmcnt(0)
	v_mfma_f32_16x16x32_bf16 v[72:75], v[146:149], v[32:35], v[92:95]
	v_mfma_f32_16x16x32_bf16 v[32:35], v[194:197], v[32:35], v[154:157]
	v_mfma_f32_16x16x32_bf16 v[92:95], v[198:201], v[40:43], v[32:35]
	v_mfma_f32_16x16x32_bf16 v[32:35], v[146:149], v[48:51], v[84:87]
	v_mfma_f32_16x16x32_bf16 v[80:83], v[186:189], v[56:59], v[32:35]
	v_mfma_f32_16x16x32_bf16 v[32:35], v[194:197], v[48:51], v[158:161]
	v_mfma_f32_16x16x32_bf16 v[84:87], v[198:201], v[56:59], v[32:35]
	v_mfma_f32_16x16x32_bf16 v[32:35], v[146:149], v[64:67], v[76:79]
	v_mfma_f32_16x16x32_bf16 v[88:91], v[186:189], v[40:43], v[72:75]
	v_mfma_f32_16x16x32_bf16 v[72:75], v[186:189], v[174:177], v[32:35]
	v_mfma_f32_16x16x32_bf16 v[32:35], v[194:197], v[64:67], v[162:165]
	v_mfma_f32_16x16x32_bf16 v[76:79], v[198:201], v[174:177], v[32:35]
	v_mfma_f32_16x16x32_bf16 v[32:35], v[146:149], v[178:181], v[68:71]
	v_mfma_f32_16x16x32_bf16 v[64:67], v[186:189], v[182:185], v[32:35]
	v_mfma_f32_16x16x32_bf16 v[32:35], v[194:197], v[178:181], v[166:169]
	v_mfma_f32_16x16x32_bf16 v[68:71], v[198:201], v[182:185], v[32:35]
	s_setprio 0
	s_barrier
	ds_read_b128 v[154:157], v139 offset:49152
	ds_read_b128 v[158:161], v139 offset:50176
	ds_read_b128 v[162:165], v139 offset:51200
	ds_read_b128 v[166:169], v139 offset:52224
	ds_read_b128 v[174:177], v139 offset:53248
	ds_read_b128 v[178:181], v139 offset:54272
	ds_read_b128 v[182:185], v139 offset:55296
	ds_read_b128 v[228:231], v139 offset:56320
	s_barrier
	s_waitcnt lgkmcnt(0)
	s_setprio 1
	s_waitcnt lgkmcnt(0)
	v_mfma_f32_16x16x32_bf16 v[32:35], v[0:3], v[154:157], v[60:63]
	v_mfma_f32_16x16x32_bf16 v[56:59], v[8:11], v[158:161], v[32:35]
	v_mfma_f32_16x16x32_bf16 v[32:35], v[16:19], v[154:157], v[202:205]
	v_mfma_f32_16x16x32_bf16 v[60:63], v[24:27], v[158:161], v[32:35]
	v_mfma_f32_16x16x32_bf16 v[32:35], v[0:3], v[162:165], v[52:55]
	v_mfma_f32_16x16x32_bf16 v[48:51], v[8:11], v[166:169], v[32:35]
	v_mfma_f32_16x16x32_bf16 v[32:35], v[16:19], v[162:165], v[206:209]
	v_mfma_f32_16x16x32_bf16 v[52:55], v[24:27], v[166:169], v[32:35]
	v_mfma_f32_16x16x32_bf16 v[32:35], v[0:3], v[174:177], v[44:47]
	v_mfma_f32_16x16x32_bf16 v[40:43], v[8:11], v[178:181], v[32:35]
	v_mfma_f32_16x16x32_bf16 v[32:35], v[16:19], v[174:177], v[224:227]
	v_mfma_f32_16x16x32_bf16 v[0:3], v[0:3], v[182:185], v[36:39]
	v_mfma_f32_16x16x32_bf16 v[44:47], v[24:27], v[178:181], v[32:35]
	v_mfma_f32_16x16x32_bf16 v[32:35], v[8:11], v[228:231], v[0:3]
	v_mfma_f32_16x16x32_bf16 v[0:3], v[16:19], v[182:185], v[128:131]
	v_mfma_f32_16x16x32_bf16 v[36:39], v[24:27], v[228:231], v[0:3]
	s_setprio 0
	s_setprio 1
	v_mfma_f32_16x16x32_bf16 v[0:3], v[146:149], v[154:157], v[28:31]
	v_mfma_f32_16x16x32_bf16 v[24:27], v[186:189], v[158:161], v[0:3]
	v_mfma_f32_16x16x32_bf16 v[0:3], v[194:197], v[154:157], v[132:135]
	v_mfma_f32_16x16x32_bf16 v[28:31], v[198:201], v[158:161], v[0:3]
	v_mfma_f32_16x16x32_bf16 v[0:3], v[146:149], v[162:165], v[20:23]
	v_mfma_f32_16x16x32_bf16 v[16:19], v[186:189], v[166:169], v[0:3]
	v_mfma_f32_16x16x32_bf16 v[0:3], v[194:197], v[162:165], v[142:145]
	v_mfma_f32_16x16x32_bf16 v[20:23], v[198:201], v[166:169], v[0:3]
	v_mfma_f32_16x16x32_bf16 v[0:3], v[146:149], v[174:177], v[12:15]
	v_mfma_f32_16x16x32_bf16 v[8:11], v[186:189], v[178:181], v[0:3]
	v_mfma_f32_16x16x32_bf16 v[0:3], v[194:197], v[174:177], v[150:153]
	v_mfma_f32_16x16x32_bf16 v[12:15], v[198:201], v[178:181], v[0:3]
	v_mfma_f32_16x16x32_bf16 v[0:3], v[146:149], v[182:185], v[4:7]
	v_mfma_f32_16x16x32_bf16 v[4:7], v[194:197], v[182:185], v[170:173]
	v_mfma_f32_16x16x32_bf16 v[0:3], v[186:189], v[228:231], v[0:3]
	v_mfma_f32_16x16x32_bf16 v[4:7], v[198:201], v[228:231], v[4:7]
	s_setprio 0
	s_movk_i32 s4, 0x100
	v_cmp_gt_u32_e32 vcc, s4, v138
	s_barrier
	s_and_saveexec_b64 s[4:5], vcc
	s_cbranch_execz .LBB0_630
	s_barrier
